# GLA state decay: exp(b_last) computed once by the publishing thread and stored in LDS instead of 32 v_exp per thread per chunk (bit-identical values)
# speedup vs baseline: 1.0057x; 1.0057x over previous
.LBB0_464:
	ds_read_b128 v[94:97], v149 offset:6144
	ds_read_b128 v[98:101], v149 offset:6160
	s_waitcnt vmcnt(5)
	v_lshlrev_b32_e32 v102, 16, v22
	v_and_b32_e32 v103, 0xffff0000, v22
	s_add_i32 s46, s47, s46
	s_waitcnt lgkmcnt(1)
	v_mul_f32_e32 v94, 0xbfb8aa3b, v94
	v_mul_f32_e32 v95, 0xbfb8aa3b, v95
	v_exp_f32_e32 v94, v94
	v_exp_f32_e32 v95, v95
	v_mul_f32_e32 v22, 0xbfb8aa3b, v96
	v_exp_f32_e32 v96, v22
	v_mul_f32_e32 v22, 0xbfb8aa3b, v97
	v_exp_f32_e32 v97, v22
	v_pk_mul_f32 v[94:95], v[94:95], v[102:103]
	s_add_i32 s83, s83, 1
	v_cvt_pk_bf16_f32 v22, v94, v95
	v_lshlrev_b32_e32 v94, 16, v23
	v_and_b32_e32 v95, 0xffff0000, v23
	s_waitcnt lgkmcnt(0)
	v_mul_f32_e32 v23, 0xbfb8aa3b, v98
	v_pk_mul_f32 v[94:95], v[96:97], v[94:95]
	v_exp_f32_e32 v96, v23
	v_mul_f32_e32 v23, 0xbfb8aa3b, v99
	v_exp_f32_e32 v97, v23
	v_cvt_pk_bf16_f32 v23, v94, v95
	v_lshlrev_b32_e32 v94, 16, v24
	v_and_b32_e32 v95, 0xffff0000, v24
	v_mul_f32_e32 v24, 0xbfb8aa3b, v100
	v_pk_mul_f32 v[94:95], v[96:97], v[94:95]
	v_exp_f32_e32 v96, v24
	v_mul_f32_e32 v24, 0xbfb8aa3b, v101
	v_exp_f32_e32 v97, v24
	v_cvt_pk_bf16_f32 v24, v94, v95
	v_lshlrev_b32_e32 v94, 16, v25
	v_and_b32_e32 v95, 0xffff0000, v25
	v_pk_mul_f32 v[94:95], v[96:97], v[94:95]
	s_waitcnt vmcnt(4)
	v_lshlrev_b32_e32 v98, 16, v6
	v_cvt_pk_bf16_f32 v25, v94, v95
	ds_write_b128 v150, v[22:25] offset:56320
	ds_read_b128 v[22:25], v151 offset:6144
	ds_read_b128 v[94:97], v151 offset:6160
	v_and_b32_e32 v99, 0xffff0000, v6
	s_mul_i32 s53, s46, 0x1800
	s_mul_hi_i32 s52, s46, 0x1800
	s_waitcnt lgkmcnt(1)
	v_mul_f32_e32 v22, 0xbfb8aa3b, v22
	v_mul_f32_e32 v23, 0xbfb8aa3b, v23
	v_exp_f32_e32 v22, v22
	v_exp_f32_e32 v23, v23
	v_mul_f32_e32 v6, 0xbfb8aa3b, v24
	v_exp_f32_e32 v24, v6
	v_mul_f32_e32 v6, 0xbfb8aa3b, v25
	v_exp_f32_e32 v25, v6
	v_pk_mul_f32 v[22:23], v[22:23], v[98:99]
	s_add_u32 s50, s80, s53
	v_cvt_pk_bf16_f32 v6, v22, v23
	v_lshlrev_b32_e32 v22, 16, v7
	v_and_b32_e32 v23, 0xffff0000, v7
	s_waitcnt lgkmcnt(0)
	v_mul_f32_e32 v7, 0xbfb8aa3b, v94
	v_pk_mul_f32 v[22:23], v[24:25], v[22:23]
	v_exp_f32_e32 v24, v7
	v_mul_f32_e32 v7, 0xbfb8aa3b, v95
	v_exp_f32_e32 v25, v7
	v_cvt_pk_bf16_f32 v7, v22, v23
	v_lshlrev_b32_e32 v22, 16, v8
	v_and_b32_e32 v23, 0xffff0000, v8
	v_mul_f32_e32 v8, 0xbfb8aa3b, v96
	v_pk_mul_f32 v[22:23], v[24:25], v[22:23]
	v_exp_f32_e32 v24, v8
	v_mul_f32_e32 v8, 0xbfb8aa3b, v97
	v_exp_f32_e32 v25, v8
	v_cvt_pk_bf16_f32 v8, v22, v23
	v_lshlrev_b32_e32 v22, 16, v9
	v_and_b32_e32 v23, 0xffff0000, v9
	v_pk_mul_f32 v[22:23], v[24:25], v[22:23]
	s_addc_u32 s51, s81, s52
	v_cvt_pk_bf16_f32 v9, v22, v23
	ds_write_b128 v152, v[6:9] offset:56320
	s_waitcnt vmcnt(3)
	ds_write_b128 v153, v[2:5]
	s_waitcnt vmcnt(2)
	ds_write_b128 v155, v[10:13]
	s_waitcnt vmcnt(1)
	ds_write_b128 v153, v[14:17] offset:16896
	s_waitcnt vmcnt(0)
	ds_write_b128 v156, v[18:21]
	v_lshl_add_u64 v[2:3], s[50:51], 0, v[112:113]
	s_add_u32 s50, s38, s53
	s_addc_u32 s51, s39, s52
	s_add_u32 s50, s50, s76
	s_addc_u32 s51, s51, 0
	s_add_u32 s50, s50, 0xad20800
	global_load_dwordx4 v[22:25], v[2:3], off offset:1024
	v_add_co_u32_e32 v2, vcc, s63, v2
	s_addc_u32 s51, s51, 0
	s_nop 0
	v_addc_co_u32_e32 v3, vcc, 0, v3, vcc
	v_lshl_add_u64 v[18:19], s[50:51], 0, v[114:115]
	v_add_co_u32_e32 v10, vcc, s64, v18
	global_load_dwordx4 v[6:9], v[2:3], off offset:1024
	s_nop 0
	v_addc_co_u32_e32 v11, vcc, 0, v19, vcc
	v_add_co_u32_e32 v14, vcc, s63, v18
	global_load_dwordx4 v[2:5], v[18:19], off
	s_nop 0
	v_addc_co_u32_e32 v15, vcc, 0, v19, vcc
	v_add_co_u32_e32 v18, vcc, s65, v18
	global_load_dwordx4 v[10:13], v[10:11], off
	s_nop 0
	v_addc_co_u32_e32 v19, vcc, 0, v19, vcc
	global_load_dwordx4 v[14:17], v[14:15], off
	v_lshl_add_u32 v167, s87, 9, v128
	global_load_dwordx4 v[18:21], v[18:19], off
	s_waitcnt lgkmcnt(0)
	s_barrier
	ds_read_b64_tr_b16 v[96:97], v158 offset:57408
	ds_read_b64_tr_b16 v[94:95], v158 offset:56320
	ds_read_b64_tr_b16 v[108:109], v157 offset:2112
	ds_read_b64_tr_b16 v[106:107], v157
	ds_read_b64_tr_b16 v[102:103], v157 offset:32
	ds_read_b64_tr_b16 v[104:105], v157 offset:2144
	s_waitcnt lgkmcnt(2)
	v_mfma_f32_16x16x32_bf16 v[70:73], v[94:97], v[106:109], v[70:73]
	ds_read_b64_tr_b16 v[168:169], v158 offset:65024
	ds_read_b64_tr_b16 v[170:171], v159 offset:57408
	ds_read_b64_tr_b16 v[98:99], v157 offset:16896
	s_cmp_eq_u32 s43, s83
	s_waitcnt lgkmcnt(3)
	v_mfma_f32_16x16x32_bf16 v[74:77], v[94:97], v[102:105], v[74:77]
	ds_read_b64_tr_b16 v[100:101], v157 offset:19008
	ds_read_b64_tr_b16 v[94:95], v157 offset:16928
	ds_read_b64_tr_b16 v[96:97], v157 offset:19040
	ds_read_b64_tr_b16 v[172:173], v158 offset:56352
	ds_read_b64_tr_b16 v[174:175], v158 offset:57440
	s_waitcnt lgkmcnt(4)
	v_mfma_f32_16x16x32_bf16 v[70:73], v[168:171], v[98:101], v[70:73]
	s_waitcnt lgkmcnt(2)
	v_mfma_f32_16x16x32_bf16 v[74:77], v[168:171], v[94:97], v[74:77]
	ds_read_b64_tr_b16 v[170:171], v159 offset:57440
	ds_read_b64_tr_b16 v[168:169], v158 offset:65056
	s_waitcnt lgkmcnt(2)
	v_mfma_f32_16x16x32_bf16 v[58:61], v[172:175], v[106:109], v[58:61]
	v_mfma_f32_16x16x32_bf16 v[82:85], v[172:175], v[102:105], v[82:85]
	s_waitcnt lgkmcnt(0)
	v_mfma_f32_16x16x32_bf16 v[58:61], v[168:171], v[98:101], v[58:61]
	v_mfma_f32_16x16x32_bf16 v[82:85], v[168:171], v[94:97], v[82:85]
	ds_read_b64_tr_b16 v[168:169], v158 offset:56384
	ds_read_b64_tr_b16 v[170:171], v158 offset:57472
	s_waitcnt lgkmcnt(0)
	v_mfma_f32_16x16x32_bf16 v[66:69], v[168:171], v[106:109], v[66:69]
	v_mfma_f32_16x16x32_bf16 v[78:81], v[168:171], v[102:105], v[78:81]
	ds_read_b64_tr_b16 v[168:169], v158 offset:65088
	ds_read_b64_tr_b16 v[170:171], v159 offset:57472
	s_waitcnt lgkmcnt(0)
	v_mfma_f32_16x16x32_bf16 v[66:69], v[168:171], v[98:101], v[66:69]
	v_mfma_f32_16x16x32_bf16 v[78:81], v[168:171], v[94:97], v[78:81]
	ds_read_b64_tr_b16 v[168:169], v158 offset:56416
	ds_read_b64_tr_b16 v[170:171], v158 offset:57504
	s_waitcnt lgkmcnt(0)
	v_mfma_f32_16x16x32_bf16 v[62:65], v[168:171], v[106:109], v[62:65]
	v_mfma_f32_16x16x32_bf16 v[86:89], v[168:171], v[102:105], v[86:89]
	ds_read_b64_tr_b16 v[168:169], v158 offset:65120
	ds_read_b64_tr_b16 v[170:171], v159 offset:57504
	s_waitcnt lgkmcnt(0)
	v_mfma_f32_16x16x32_bf16 v[62:65], v[168:171], v[98:101], v[62:65]
	v_mfma_f32_16x16x32_bf16 v[86:89], v[168:171], v[94:97], v[86:89]
	ds_read_b64_tr_b16 v[168:169], v158 offset:56448
	ds_read_b64_tr_b16 v[170:171], v158 offset:57536
	s_waitcnt lgkmcnt(0)
	v_mfma_f32_16x16x32_bf16 v[38:41], v[168:171], v[106:109], v[38:41]
	v_mfma_f32_16x16x32_bf16 v[50:53], v[168:171], v[102:105], v[50:53]
	ds_read_b64_tr_b16 v[168:169], v158 offset:65152
	ds_read_b64_tr_b16 v[170:171], v159 offset:57536
	s_waitcnt lgkmcnt(0)
	v_mfma_f32_16x16x32_bf16 v[38:41], v[168:171], v[98:101], v[38:41]
	v_mfma_f32_16x16x32_bf16 v[50:53], v[168:171], v[94:97], v[50:53]
	ds_read_b64_tr_b16 v[168:169], v158 offset:56480
	ds_read_b64_tr_b16 v[170:171], v158 offset:57568
	s_waitcnt lgkmcnt(0)
	v_mfma_f32_16x16x32_bf16 v[30:33], v[168:171], v[106:109], v[30:33]
	v_mfma_f32_16x16x32_bf16 v[54:57], v[168:171], v[102:105], v[54:57]
	ds_read_b64_tr_b16 v[168:169], v158 offset:65184
	ds_read_b64_tr_b16 v[170:171], v159 offset:57568
	s_waitcnt lgkmcnt(0)
	v_mfma_f32_16x16x32_bf16 v[30:33], v[168:171], v[98:101], v[30:33]
	v_mfma_f32_16x16x32_bf16 v[54:57], v[168:171], v[94:97], v[54:57]
	ds_read_b64_tr_b16 v[168:169], v158 offset:56512
	ds_read_b64_tr_b16 v[170:171], v158 offset:57600
	s_waitcnt lgkmcnt(0)
	v_mfma_f32_16x16x32_bf16 v[42:45], v[168:171], v[106:109], v[42:45]
	v_mfma_f32_16x16x32_bf16 v[46:49], v[168:171], v[102:105], v[46:49]
	ds_read_b64_tr_b16 v[168:169], v158 offset:65216
	ds_read_b64_tr_b16 v[170:171], v159 offset:57600
	s_waitcnt lgkmcnt(0)
	v_mfma_f32_16x16x32_bf16 v[42:45], v[168:171], v[98:101], v[42:45]
	v_mfma_f32_16x16x32_bf16 v[46:49], v[168:171], v[94:97], v[46:49]
	ds_read_b64_tr_b16 v[168:169], v158 offset:56544
	ds_read_b64_tr_b16 v[170:171], v158 offset:57632
	s_waitcnt lgkmcnt(0)
	v_mfma_f32_16x16x32_bf16 v[34:37], v[168:171], v[106:109], v[34:37]
	ds_read_b64_tr_b16 v[106:107], v158 offset:65248
	ds_read_b64_tr_b16 v[108:109], v159 offset:57632
	v_mfma_f32_16x16x32_bf16 v[102:105], v[168:171], v[102:105], v[26:29]
	ds_read_b128 v[168:171], v167 offset:4096
	s_waitcnt lgkmcnt(1)
	v_mfma_f32_16x16x32_bf16 v[26:29], v[106:109], v[98:101], v[34:37]
	s_waitcnt lgkmcnt(0)
	s_nop 1
	s_nop 0
	v_mov_b32_e32 v98, v168
	s_nop 0
	v_mov_b32_e32 v99, v169
	s_nop 0
	v_mov_b32_e32 v100, v170
	s_nop 0
	v_mov_b32_e32 v101, v171
	ds_read_b128 v[34:37], v167 offset:4160
	v_mfma_f32_16x16x32_bf16 v[94:97], v[106:109], v[94:97], v[102:105]
	v_mul_f32_e64 v70, v70, v98
	v_mul_f32_e64 v71, v71, v99
	v_pk_mul_f32 v[74:75], v[74:75], v[98:99]
	v_pk_mul_f32 v[72:73], v[72:73], v[100:101]
	s_waitcnt lgkmcnt(0)
	s_nop 0
	v_mov_b32_e32 v102, v34
	s_nop 0
	v_mov_b32_e32 v103, v35
	s_nop 0
	v_mov_b32_e32 v104, v36
	s_nop 0
	v_mov_b32_e32 v105, v37
	ds_read_b128 v[34:37], v167 offset:4224
	v_pk_mul_f32 v[76:77], v[76:77], v[100:101]
	v_pk_mul_f32 v[58:59], v[58:59], v[102:103]
	v_pk_mul_f32 v[82:83], v[82:83], v[102:103]
	v_pk_mul_f32 v[60:61], v[60:61], v[104:105]
	s_waitcnt lgkmcnt(0)
	s_nop 0
	v_mov_b32_e32 v98, v34
	s_nop 0
	v_mov_b32_e32 v99, v35
	s_nop 0
	v_mov_b32_e32 v100, v36
	s_nop 0
	v_mov_b32_e32 v101, v37
	ds_read_b128 v[34:37], v167 offset:4288
	v_pk_mul_f32 v[84:85], v[84:85], v[104:105]
	v_pk_mul_f32 v[66:67], v[66:67], v[98:99]
	v_pk_mul_f32 v[78:79], v[78:79], v[98:99]
	v_pk_mul_f32 v[68:69], v[68:69], v[100:101]
	s_waitcnt lgkmcnt(0)
	s_nop 0
	v_mov_b32_e32 v102, v34
	s_nop 0
	v_mov_b32_e32 v103, v35
	s_nop 0
	v_mov_b32_e32 v104, v36
	s_nop 0
	v_mov_b32_e32 v105, v37
	ds_read_b128 v[34:37], v167 offset:4352
	v_pk_mul_f32 v[80:81], v[80:81], v[100:101]
	v_pk_mul_f32 v[62:63], v[62:63], v[102:103]
	v_pk_mul_f32 v[86:87], v[86:87], v[102:103]
	v_pk_mul_f32 v[64:65], v[64:65], v[104:105]
	s_waitcnt lgkmcnt(0)
	s_nop 0
	v_mov_b32_e32 v98, v34
	s_nop 0
	v_mov_b32_e32 v99, v35
	s_nop 0
	v_mov_b32_e32 v100, v36
	s_nop 0
	v_mov_b32_e32 v101, v37
	ds_read_b128 v[34:37], v167 offset:4416
	v_pk_mul_f32 v[88:89], v[88:89], v[104:105]
	v_pk_mul_f32 v[38:39], v[38:39], v[98:99]
	v_pk_mul_f32 v[50:51], v[50:51], v[98:99]
	v_pk_mul_f32 v[40:41], v[40:41], v[100:101]
	s_waitcnt lgkmcnt(0)
	s_nop 0
	v_mov_b32_e32 v102, v34
	s_nop 0
	v_mov_b32_e32 v103, v35
	s_nop 0
	v_mov_b32_e32 v104, v36
	s_nop 0
	v_mov_b32_e32 v105, v37
	ds_read_b128 v[34:37], v167 offset:4480
	v_pk_mul_f32 v[52:53], v[52:53], v[100:101]
	v_pk_mul_f32 v[30:31], v[30:31], v[102:103]
	v_pk_mul_f32 v[54:55], v[54:55], v[102:103]
	v_pk_mul_f32 v[32:33], v[32:33], v[104:105]
	s_waitcnt lgkmcnt(0)
	s_nop 0
	v_mov_b32_e32 v98, v34
	s_nop 0
	v_mov_b32_e32 v99, v35
	s_nop 0
	v_mov_b32_e32 v100, v36
	s_nop 0
	v_mov_b32_e32 v101, v37
	ds_read_b128 v[34:37], v167 offset:4544
	v_pk_mul_f32 v[56:57], v[56:57], v[104:105]
	v_pk_mul_f32 v[42:43], v[42:43], v[98:99]
	v_pk_mul_f32 v[44:45], v[44:45], v[100:101]
	v_pk_mul_f32 v[48:49], v[48:49], v[100:101]
	s_waitcnt lgkmcnt(0)
	s_nop 0
	v_mov_b32_e32 v102, v34
	v_mov_b32_e32 v34, v35
	v_mov_b32_e32 v35, v36
	v_mov_b32_e32 v104, v35
	s_nop 0
	v_mov_b32_e32 v105, v37
	v_mov_b32_e32 v103, v34
	v_pk_mul_f32 v[46:47], v[46:47], v[98:99]
	v_pk_mul_f32 v[36:37], v[28:29], v[104:105]
	v_pk_mul_f32 v[34:35], v[26:27], v[102:103]
	v_pk_mul_f32 v[28:29], v[96:97], v[104:105]
	v_pk_mul_f32 v[26:27], v[94:95], v[102:103]
	s_cbranch_scc1 .LBB0_480

.LBB0_476:
	ds_read_b32 v94, v161 offset:6144
	v_lshl_add_u32 v95, s87, 9, v127
	s_waitcnt lgkmcnt(0)
	v_add_f32_e32 v1, v1, v94
	v_mul_f32_e32 v255, 0x3fb8aa3b, v94
	v_exp_f32_e32 v255, v255
	s_nop 0
	ds_write_b32 v95, v255 offset:4096
	s_or_b64 exec, exec, s[52:53]
	s_and_saveexec_b64 s[52:53], s[2:3]
	s_cbranch_execz .LBB0_475

.LBB0_488:
	s_waitcnt lgkmcnt(1)
	v_add_f32_e32 v91, v167, v90
	v_add_f32_e32 v92, v166, v90
	ds_write2st64_b32 v148, v91, v92 offset0:24 offset1:26
	v_add_f32_e32 v91, v165, v90
	v_add_f32_e32 v92, v164, v90
	ds_write2st64_b32 v148, v91, v92 offset0:28 offset1:30
	v_add_f32_e32 v91, v163, v90
	v_add_f32_e32 v92, v162, v90
	ds_write2st64_b32 v148, v91, v92 offset0:32 offset1:34
	v_add_f32_e32 v91, v109, v90
	v_add_f32_e32 v92, v108, v90
	ds_write2st64_b32 v148, v91, v92 offset0:36 offset1:38
	v_add_f32_e32 v91, v107, v90
	v_add_f32_e32 v92, v106, v90
	ds_write2st64_b32 v148, v91, v92 offset0:40 offset1:42
	v_add_f32_e32 v91, v105, v90
	v_add_f32_e32 v92, v104, v90
	s_and_b32 s30, s43, 1
	ds_write2st64_b32 v148, v91, v92 offset0:44 offset1:46
	v_add_f32_e32 v91, v103, v90
	v_add_f32_e32 v92, v102, v90
	ds_write2st64_b32 v148, v91, v92 offset0:48 offset1:50
	v_add_f32_e32 v91, v101, v90
	v_add_f32_e32 v90, v100, v90
	s_lshl_b32 s43, s30, 9
	ds_write2st64_b32 v148, v91, v90 offset0:52 offset1:54
	s_waitcnt lgkmcnt(0)
	s_barrier
	s_and_saveexec_b64 s[30:31], s[4:5]
	s_cbranch_execz .LBB0_490
	ds_read_b32 v90, v161 offset:6144
	v_add_u32_e32 v91, s43, v127
	s_waitcnt lgkmcnt(0)
	v_add_f32_e32 v1, v1, v90
	v_mul_f32_e32 v255, 0x3fb8aa3b, v90
	v_exp_f32_e32 v255, v255
	s_nop 0
	ds_write_b32 v91, v255 offset:4096
.LBB0_490:
	s_or_b64 exec, exec, s[30:31]
	ds_read_b128 v[90:93], v149 offset:6144
	ds_read_b128 v[94:97], v149 offset:6160
	s_waitcnt vmcnt(5)
	v_lshlrev_b32_e32 v98, 16, v22
	v_and_b32_e32 v99, 0xffff0000, v22
	s_waitcnt lgkmcnt(1)
	v_mul_f32_e32 v90, 0xbfb8aa3b, v90
	v_mul_f32_e32 v91, 0xbfb8aa3b, v91
	v_exp_f32_e32 v90, v90
	v_exp_f32_e32 v91, v91
	v_mul_f32_e32 v22, 0xbfb8aa3b, v92
	v_exp_f32_e32 v92, v22
	v_mul_f32_e32 v22, 0xbfb8aa3b, v93
	v_exp_f32_e32 v93, v22
	v_pk_mul_f32 v[90:91], v[90:91], v[98:99]
	s_nop 0
	v_cvt_pk_bf16_f32 v22, v90, v91
	v_lshlrev_b32_e32 v90, 16, v23
	v_and_b32_e32 v91, 0xffff0000, v23
	s_waitcnt lgkmcnt(0)
	v_mul_f32_e32 v23, 0xbfb8aa3b, v94
	v_pk_mul_f32 v[90:91], v[92:93], v[90:91]
	v_exp_f32_e32 v92, v23
	v_mul_f32_e32 v23, 0xbfb8aa3b, v95
	v_exp_f32_e32 v93, v23
	v_cvt_pk_bf16_f32 v23, v90, v91
	v_lshlrev_b32_e32 v90, 16, v24
	v_and_b32_e32 v91, 0xffff0000, v24
	v_mul_f32_e32 v24, 0xbfb8aa3b, v96
	v_pk_mul_f32 v[90:91], v[92:93], v[90:91]
	v_exp_f32_e32 v92, v24
	v_mul_f32_e32 v24, 0xbfb8aa3b, v97
	v_exp_f32_e32 v93, v24
	v_cvt_pk_bf16_f32 v24, v90, v91
	v_lshlrev_b32_e32 v90, 16, v25
	v_and_b32_e32 v91, 0xffff0000, v25
	v_pk_mul_f32 v[90:91], v[92:93], v[90:91]
	s_waitcnt vmcnt(4)
	v_lshlrev_b32_e32 v94, 16, v6
	v_cvt_pk_bf16_f32 v25, v90, v91
	ds_write_b128 v150, v[22:25] offset:56320
	ds_read_b128 v[22:25], v151 offset:6144
	ds_read_b128 v[90:93], v151 offset:6160
	v_and_b32_e32 v95, 0xffff0000, v6
	s_waitcnt lgkmcnt(1)
	v_mul_f32_e32 v22, 0xbfb8aa3b, v22
	v_mul_f32_e32 v23, 0xbfb8aa3b, v23
	v_exp_f32_e32 v22, v22
	v_exp_f32_e32 v23, v23
	v_mul_f32_e32 v6, 0xbfb8aa3b, v24
	v_exp_f32_e32 v24, v6
	v_mul_f32_e32 v6, 0xbfb8aa3b, v25
	v_exp_f32_e32 v25, v6
	v_pk_mul_f32 v[22:23], v[22:23], v[94:95]
	s_nop 0
	v_cvt_pk_bf16_f32 v6, v22, v23
	v_lshlrev_b32_e32 v22, 16, v7
	v_and_b32_e32 v23, 0xffff0000, v7
	s_waitcnt lgkmcnt(0)
	v_mul_f32_e32 v7, 0xbfb8aa3b, v90
	v_pk_mul_f32 v[22:23], v[24:25], v[22:23]
	v_exp_f32_e32 v24, v7
	v_mul_f32_e32 v7, 0xbfb8aa3b, v91
	v_exp_f32_e32 v25, v7
	v_cvt_pk_bf16_f32 v7, v22, v23
	v_lshlrev_b32_e32 v22, 16, v8
	v_and_b32_e32 v23, 0xffff0000, v8
	v_mul_f32_e32 v8, 0xbfb8aa3b, v92
	v_pk_mul_f32 v[22:23], v[24:25], v[22:23]
	v_exp_f32_e32 v24, v8
	v_mul_f32_e32 v8, 0xbfb8aa3b, v93
	v_exp_f32_e32 v25, v8
	v_cvt_pk_bf16_f32 v8, v22, v23
	v_lshlrev_b32_e32 v22, 16, v9
	v_and_b32_e32 v23, 0xffff0000, v9
	v_pk_mul_f32 v[22:23], v[24:25], v[22:23]
	s_nop 0
	v_cvt_pk_bf16_f32 v9, v22, v23
	ds_write_b128 v152, v[6:9] offset:56320
	s_waitcnt vmcnt(3)
	ds_write_b128 v153, v[2:5]
	s_waitcnt vmcnt(2)
	ds_write_b128 v155, v[10:13]
	s_waitcnt vmcnt(1)
	ds_write_b128 v153, v[14:17] offset:16896
	s_waitcnt vmcnt(0)
	ds_write_b128 v156, v[18:21]
	s_waitcnt lgkmcnt(0)
	s_barrier
	ds_read_b64_tr_b16 v[4:5], v158 offset:57408
	ds_read_b64_tr_b16 v[2:3], v158 offset:56320
	ds_read_b64_tr_b16 v[8:9], v157 offset:2112
	ds_read_b64_tr_b16 v[6:7], v157
	ds_read_b64_tr_b16 v[12:13], v157 offset:2144
	ds_read_b64_tr_b16 v[10:11], v157 offset:32
	ds_read_b64_tr_b16 v[14:15], v158 offset:56352
	ds_read_b64_tr_b16 v[18:19], v158 offset:56384
	ds_read_b64_tr_b16 v[22:23], v158 offset:56416
	ds_read_b64_tr_b16 v[16:17], v158 offset:57440
	ds_read_b64_tr_b16 v[20:21], v158 offset:57472
	ds_read_b64_tr_b16 v[24:25], v158 offset:57504
	ds_read_b64_tr_b16 v[90:91], v158 offset:65024
	ds_read_b64_tr_b16 v[92:93], v159 offset:57408
	ds_read_b64_tr_b16 v[94:95], v157 offset:16896
	ds_read_b64_tr_b16 v[96:97], v157 offset:19008
	ds_read_b64_tr_b16 v[100:101], v157 offset:19040
	ds_read_b64_tr_b16 v[98:99], v157 offset:16928
	s_waitcnt lgkmcnt(8)
	v_mfma_f32_16x16x32_bf16 v[58:61], v[14:17], v[6:9], v[58:61]
	v_mfma_f32_16x16x32_bf16 v[14:17], v[14:17], v[10:13], v[82:85]
	v_mfma_f32_16x16x32_bf16 v[70:73], v[2:5], v[6:9], v[70:73]
	v_mfma_f32_16x16x32_bf16 v[2:5], v[2:5], v[10:13], v[74:77]
	s_nop 2
	ds_read_b64_tr_b16 v[74:75], v158 offset:65056
	ds_read_b64_tr_b16 v[102:103], v158 offset:65088
	ds_read_b64_tr_b16 v[106:107], v158 offset:65120
	ds_read_b64_tr_b16 v[76:77], v159 offset:57440
	ds_read_b64_tr_b16 v[104:105], v159 offset:57472
	ds_read_b64_tr_b16 v[108:109], v159 offset:57504
	s_waitcnt lgkmcnt(2)
	v_mfma_f32_16x16x32_bf16 v[58:61], v[74:77], v[94:97], v[58:61]
	v_mfma_f32_16x16x32_bf16 v[14:17], v[74:77], v[98:101], v[14:17]
	ds_read_b64_tr_b16 v[74:75], v158 offset:56448
	ds_read_b64_tr_b16 v[76:77], v158 offset:57536
	v_mfma_f32_16x16x32_bf16 v[66:69], v[18:21], v[6:9], v[66:69]
	v_mfma_f32_16x16x32_bf16 v[18:21], v[18:21], v[10:13], v[78:81]
	v_mfma_f32_16x16x32_bf16 v[62:65], v[22:25], v[6:9], v[62:65]
	v_mfma_f32_16x16x32_bf16 v[22:25], v[22:25], v[10:13], v[86:89]
	s_nop 0
	ds_read_b64_tr_b16 v[78:79], v158 offset:56480
	ds_read_b64_tr_b16 v[82:83], v158 offset:56512
	ds_read_b64_tr_b16 v[86:87], v158 offset:56544
	ds_read_b64_tr_b16 v[80:81], v158 offset:57568
	ds_read_b64_tr_b16 v[84:85], v158 offset:57600
	ds_read_b64_tr_b16 v[88:89], v158 offset:57632
	s_waitcnt lgkmcnt(1)
	v_mfma_f32_16x16x32_bf16 v[42:45], v[82:85], v[6:9], v[42:45]
	v_mfma_f32_16x16x32_bf16 v[46:49], v[82:85], v[10:13], v[46:49]
	v_add_u32_e32 v82, s43, v128
	s_ashr_i32 s43, s42, 31
	s_lshl_b64 s[30:31], s[42:43], 17
	v_mfma_f32_16x16x32_bf16 v[70:73], v[90:93], v[94:97], v[70:73]
	v_mfma_f32_16x16x32_bf16 v[2:5], v[90:93], v[98:101], v[2:5]
	ds_read_b64_tr_b16 v[90:91], v158 offset:65152
	ds_read_b64_tr_b16 v[92:93], v159 offset:57536
	v_mfma_f32_16x16x32_bf16 v[66:69], v[102:105], v[94:97], v[66:69]
	v_mfma_f32_16x16x32_bf16 v[18:21], v[102:105], v[98:101], v[18:21]
	v_mfma_f32_16x16x32_bf16 v[62:65], v[106:109], v[94:97], v[62:65]
	v_mfma_f32_16x16x32_bf16 v[22:25], v[106:109], v[98:101], v[22:25]
	v_mfma_f32_16x16x32_bf16 v[38:41], v[74:77], v[6:9], v[38:41]
	v_mfma_f32_16x16x32_bf16 v[50:53], v[74:77], v[10:13], v[50:53]
	ds_read_b64_tr_b16 v[74:75], v158 offset:65184
	ds_read_b64_tr_b16 v[102:103], v158 offset:65216
	ds_read_b64_tr_b16 v[106:107], v158 offset:65248
	ds_read_b64_tr_b16 v[76:77], v159 offset:57568
	ds_read_b64_tr_b16 v[104:105], v159 offset:57600
	ds_read_b64_tr_b16 v[108:109], v159 offset:57632
	v_mfma_f32_16x16x32_bf16 v[54:57], v[78:81], v[10:13], v[54:57]
	s_waitcnt lgkmcnt(8)
	v_mfma_f32_16x16x32_bf16 v[10:13], v[86:89], v[10:13], v[26:29]
	s_nop 2
	ds_read_b128 v[26:29], v82 offset:4096
	v_mfma_f32_16x16x32_bf16 v[30:33], v[78:81], v[6:9], v[30:33]
	v_mfma_f32_16x16x32_bf16 v[6:9], v[86:89], v[6:9], v[34:37]
	s_nop 2
	ds_read_b128 v[34:37], v82 offset:4160
	s_waitcnt lgkmcnt(1)
	s_nop 0
	v_mfma_f32_16x16x32_bf16 v[30:33], v[74:77], v[94:97], v[30:33]
	s_waitcnt lgkmcnt(0)
	s_nop 0
	v_mfma_f32_16x16x32_bf16 v[54:57], v[74:77], v[98:101], v[54:57]
	v_mov_b32_e32 v74, v26
	v_mov_b32_e32 v26, v27
	v_mov_b32_e32 v27, v28
	v_mov_b32_e32 v76, v27
	s_nop 0
	v_mov_b32_e32 v77, v29
	v_mov_b32_e32 v75, v26
	v_mfma_f32_16x16x32_bf16 v[38:41], v[90:93], v[94:97], v[38:41]
	v_mul_f32_e64 v28, v72, v76
	v_mul_f32_e64 v29, v73, v77
	v_pk_mul_f32 v[4:5], v[4:5], v[76:77]
	v_mov_b32_e32 v76, v34
	v_mov_b32_e32 v34, v35
	v_mov_b32_e32 v35, v36
	v_mov_b32_e32 v78, v35
	s_nop 0
	v_mov_b32_e32 v79, v37
	v_mov_b32_e32 v77, v34
	ds_read_b128 v[34:37], v82 offset:4224
	v_pk_mul_f32 v[26:27], v[70:71], v[74:75]
	ds_read_b128 v[70:73], v82 offset:4288
	v_pk_mul_f32 v[2:3], v[2:3], v[74:75]
	v_pk_mul_f32 v[60:61], v[60:61], v[78:79]
	s_waitcnt lgkmcnt(1)
	s_nop 0
	v_mov_b32_e32 v74, v34
	v_mov_b32_e32 v34, v35
	v_mov_b32_e32 v35, v36
	v_mov_b32_e32 v75, v34
	v_mov_b32_e32 v80, v35
	s_nop 0
	v_mov_b32_e32 v81, v37
	v_pk_mul_f32 v[34:35], v[66:67], v[74:75]
	s_waitcnt lgkmcnt(0)
	v_mov_b32_e32 v66, v70
	v_mov_b32_e32 v67, v72
	v_pk_mul_f32 v[58:59], v[58:59], v[76:77]
	v_pk_mul_f32 v[16:17], v[16:17], v[78:79]
	v_pk_mul_f32 v[14:15], v[14:15], v[76:77]
	v_mov_b32_e32 v76, v66
	v_mov_b32_e32 v66, v71
	v_mov_b32_e32 v78, v67
	v_mov_b32_e32 v67, v73
	v_pk_mul_f32 v[36:37], v[68:69], v[80:81]
	v_mov_b32_e32 v79, v67
	v_mov_b32_e32 v77, v66
	ds_read_b128 v[66:69], v82 offset:4352
	ds_read_b128 v[70:73], v82 offset:4416
	v_pk_mul_f32 v[18:19], v[18:19], v[74:75]
	v_mfma_f32_16x16x32_bf16 v[50:53], v[90:93], v[98:101], v[50:53]
	v_mul_f32_e64 v64, v64, v78
	v_mul_f32_e64 v65, v65, v79
	s_waitcnt lgkmcnt(1)
	s_nop 0
	v_mov_b32_e32 v74, v66
	v_mov_b32_e32 v75, v67
	v_mov_b32_e32 v66, v68
	v_mov_b32_e32 v67, v69
	s_nop 0
	s_nop 0
	v_pk_mul_f32 v[62:63], v[62:63], v[76:77]
	v_pk_mul_f32 v[24:25], v[24:25], v[78:79]
	v_pk_mul_f32 v[22:23], v[22:23], v[76:77]
	v_pk_mul_f32 v[40:41], v[40:41], v[66:67]
	v_pk_mul_f32 v[52:53], v[52:53], v[66:67]
	s_waitcnt lgkmcnt(0)
	v_mov_b32_e32 v66, v70
	v_mov_b32_e32 v67, v72
	v_mov_b32_e32 v76, v66
	v_mov_b32_e32 v66, v71
	v_mov_b32_e32 v78, v67
	s_nop 0
	v_mov_b32_e32 v79, v73
	v_mov_b32_e32 v77, v66
	ds_read_b128 v[66:69], v82 offset:4480
	ds_read_b128 v[70:73], v82 offset:4544
	v_mfma_f32_16x16x32_bf16 v[42:45], v[102:105], v[94:97], v[42:45]
	v_mul_f32_e64 v20, v20, v80
	v_mul_f32_e64 v21, v21, v81
	s_nop 0
	s_waitcnt lgkmcnt(1)
	s_nop 0
	s_nop 0
	v_mfma_f32_16x16x32_bf16 v[46:49], v[102:105], v[98:101], v[46:49]
	s_nop 0
	s_nop 0
	v_pk_mul_f32 v[38:39], v[38:39], v[74:75]
	v_pk_mul_f32 v[50:51], v[50:51], v[74:75]
	s_nop 0
	v_pk_mul_f32 v[42:43], v[42:43], v[66:67]
	s_nop 1
	v_pk_mul_f32 v[46:47], v[46:47], v[66:67]
	v_lshl_add_u64 v[66:67], v[120:121], 0, s[30:31]
	s_movk_i32 s30, 0x2000
	global_store_dwordx4 v[66:67], v[26:29], off
	s_nop 0
	v_pk_mul_f32 v[32:33], v[32:33], v[78:79]
	v_add_co_u32_e32 v26, vcc, s30, v66
	s_movk_i32 s30, 0x4000
	s_nop 0
	v_addc_co_u32_e32 v27, vcc, 0, v67, vcc
	global_store_dwordx4 v[26:27], v[2:5], off
	v_pk_mul_f32 v[30:31], v[30:31], v[76:77]
	s_nop 0
	v_add_co_u32_e32 v2, vcc, s30, v66
	s_movk_i32 s30, 0x6000
	s_nop 0
	v_addc_co_u32_e32 v3, vcc, 0, v67, vcc
	global_store_dwordx4 v[2:3], v[58:61], off
	v_add_co_u32_e32 v2, vcc, s30, v66
	s_nop 0
	s_nop 0
	v_addc_co_u32_e32 v3, vcc, 0, v67, vcc
	global_store_dwordx4 v[2:3], v[14:17], off
	v_add_co_u32_e32 v2, vcc, s62, v66
	v_pk_mul_f32 v[56:57], v[56:57], v[78:79]
	s_nop 0
	v_addc_co_u32_e32 v3, vcc, 0, v67, vcc
	global_store_dwordx4 v[2:3], v[34:37], off
	v_add_co_u32_e32 v2, vcc, s69, v66
	v_pk_mul_f32 v[54:55], v[54:55], v[76:77]
	s_nop 0
	v_addc_co_u32_e32 v3, vcc, 0, v67, vcc
	global_store_dwordx4 v[2:3], v[18:21], off
	v_add_co_u32_e32 v2, vcc, s70, v66
	s_waitcnt lgkmcnt(0)
	s_nop 0
	v_addc_co_u32_e32 v3, vcc, 0, v67, vcc
	global_store_dwordx4 v[2:3], v[62:65], off
	v_add_co_u32_e32 v2, vcc, s71, v66
	s_nop 0
	s_nop 0
	v_addc_co_u32_e32 v3, vcc, 0, v67, vcc
	global_store_dwordx4 v[2:3], v[22:25], off
	v_add_co_u32_e32 v2, vcc, s72, v66
	s_nop 0
	s_nop 0
	v_addc_co_u32_e32 v3, vcc, 0, v67, vcc
	global_store_dwordx4 v[2:3], v[38:41], off
	v_add_co_u32_e32 v2, vcc, s66, v66
	s_nop 0
	s_nop 0
	v_addc_co_u32_e32 v3, vcc, 0, v67, vcc
	global_store_dwordx4 v[2:3], v[50:53], off
	v_add_co_u32_e32 v2, vcc, s73, v66
	v_mfma_f32_16x16x32_bf16 v[6:9], v[106:109], v[94:97], v[6:9]
	s_nop 0
	v_addc_co_u32_e32 v3, vcc, 0, v67, vcc
	global_store_dwordx4 v[2:3], v[30:33], off
	v_add_co_u32_e32 v2, vcc, s74, v66
	v_pk_mul_f32 v[44:45], v[44:45], v[68:69]
	s_nop 0
	v_addc_co_u32_e32 v3, vcc, 0, v67, vcc
	global_store_dwordx4 v[2:3], v[54:57], off
	v_add_co_u32_e32 v2, vcc, s64, v66
	s_nop 0
	s_nop 0
	s_nop 0
	s_nop 0
	v_addc_co_u32_e32 v3, vcc, 0, v67, vcc
	global_store_dwordx4 v[2:3], v[42:45], off
	v_add_co_u32_e32 v2, vcc, s75, v66
	v_mfma_f32_16x16x32_bf16 v[10:13], v[106:109], v[98:101], v[10:13]
	v_mul_f32_e64 v48, v48, v68
	v_mul_f32_e64 v49, v49, v69
	v_addc_co_u32_e32 v3, vcc, 0, v67, vcc
	global_store_dwordx4 v[2:3], v[46:49], off
	v_add_co_u32_e32 v2, vcc, 0x1c000, v66
	v_pk_mul_f32 v[8:9], v[8:9], v[72:73]
	v_pk_mul_f32 v[6:7], v[6:7], v[70:71]
	v_addc_co_u32_e32 v3, vcc, 0, v67, vcc
	global_store_dwordx4 v[2:3], v[6:9], off
	v_add_co_u32_e32 v2, vcc, 0x1e000, v66
	v_pk_mul_f32 v[12:13], v[12:13], v[72:73]
	v_pk_mul_f32 v[10:11], v[10:11], v[70:71]
	v_addc_co_u32_e32 v3, vcc, 0, v67, vcc
	global_store_dwordx4 v[2:3], v[10:13], off
	s_and_saveexec_b64 s[30:31], s[4:5]
	s_cbranch_execz .LBB0_450
	v_mul_f32_e32 v1, 0x3fb8aa3b, v1
	v_exp_f32_e32 v1, v1
	s_lshl_b64 s[46:47], s[42:43], 9
	v_lshl_add_u64 v[2:3], v[118:119], 0, s[46:47]
	global_store_dword v[2:3], v1, off
	s_branch .LBB0_450

.LBB0_501:
	ds_read_b128 v[160:163], v149 offset:6144
	ds_read_b128 v[164:167], v149 offset:6160
	s_waitcnt vmcnt(6)
	v_lshlrev_b32_e32 v108, 16, v98
	v_and_b32_e32 v109, 0xffff0000, v98
	v_cvt_pk_bf16_f32 v180, v34, v35
	s_waitcnt lgkmcnt(1)
	v_mul_f32_e32 v1, 0xbfb8aa3b, v160
	v_mul_f32_e32 v107, 0xbfb8aa3b, v161
	v_exp_f32_e32 v168, v1
	v_exp_f32_e32 v169, v107
	v_mul_f32_e32 v1, 0xbfb8aa3b, v162
	v_exp_f32_e32 v170, v1
	v_mul_f32_e32 v1, 0xbfb8aa3b, v163
	v_exp_f32_e32 v171, v1
	s_waitcnt lgkmcnt(0)
	v_mul_f32_e32 v1, 0xbfb8aa3b, v164
	v_pk_mul_f32 v[108:109], v[168:169], v[108:109]
	v_exp_f32_e32 v168, v1
	v_mul_f32_e32 v1, 0xbfb8aa3b, v165
	v_exp_f32_e32 v169, v1
	v_cvt_pk_bf16_f32 v98, v108, v109
	v_lshlrev_b32_e32 v108, 16, v99
	v_and_b32_e32 v109, 0xffff0000, v99
	v_pk_mul_f32 v[108:109], v[170:171], v[108:109]
	v_mul_f32_e32 v1, 0xbfb8aa3b, v166
	v_cvt_pk_bf16_f32 v99, v108, v109
	v_lshlrev_b32_e32 v108, 16, v100
	v_and_b32_e32 v109, 0xffff0000, v100
	v_pk_mul_f32 v[108:109], v[168:169], v[108:109]
	v_exp_f32_e32 v168, v1
	v_mul_f32_e32 v1, 0xbfb8aa3b, v167
	v_exp_f32_e32 v169, v1
	v_cvt_pk_bf16_f32 v100, v108, v109
	v_lshlrev_b32_e32 v108, 16, v101
	v_and_b32_e32 v109, 0xffff0000, v101
	v_pk_mul_f32 v[108:109], v[168:169], v[108:109]
	v_mul_f32_e32 v1, 0x3fb8aa3b, v160
	v_cvt_pk_bf16_f32 v101, v108, v109
	v_exp_f32_e32 v108, v1
	v_mul_f32_e32 v1, 0x3fb8aa3b, v161
	v_exp_f32_e32 v109, v1
	ds_write_b128 v135, v[98:101] offset:56320
	v_lshlrev_b32_e32 v98, 16, v94
	v_and_b32_e32 v99, 0xffff0000, v94
	v_pk_mul_f32 v[100:101], v[108:109], s[40:41] op_sel_hi:[1,0]
	v_mul_f32_e32 v1, 0x3fb8aa3b, v162
	v_pk_mul_f32 v[98:99], v[100:101], v[98:99]
	v_exp_f32_e32 v100, v1
	v_mul_f32_e32 v1, 0x3fb8aa3b, v163
	v_exp_f32_e32 v101, v1
	v_cvt_pk_bf16_f32 v94, v98, v99
	v_lshlrev_b32_e32 v98, 16, v95
	v_and_b32_e32 v99, 0xffff0000, v95
	v_pk_mul_f32 v[100:101], v[100:101], s[40:41] op_sel_hi:[1,0]
	v_mul_f32_e32 v1, 0x3fb8aa3b, v164
	v_pk_mul_f32 v[98:99], v[100:101], v[98:99]
	v_exp_f32_e32 v100, v1
	v_mul_f32_e32 v1, 0x3fb8aa3b, v165
	v_exp_f32_e32 v101, v1
	v_cvt_pk_bf16_f32 v95, v98, v99
	v_lshlrev_b32_e32 v98, 16, v96
	v_and_b32_e32 v99, 0xffff0000, v96
	v_pk_mul_f32 v[100:101], v[100:101], s[40:41] op_sel_hi:[1,0]
	v_mul_f32_e32 v1, 0x3fb8aa3b, v166
	v_pk_mul_f32 v[98:99], v[100:101], v[98:99]
	v_exp_f32_e32 v100, v1
	v_mul_f32_e32 v1, 0x3fb8aa3b, v167
	v_exp_f32_e32 v101, v1
	v_cvt_pk_bf16_f32 v96, v98, v99
	v_lshlrev_b32_e32 v98, 16, v97
	v_and_b32_e32 v99, 0xffff0000, v97
	v_pk_mul_f32 v[100:101], v[100:101], s[40:41] op_sel_hi:[1,0]
	s_waitcnt vmcnt(4)
	v_lshlrev_b32_e32 v160, 16, v90
	v_pk_mul_f32 v[98:99], v[100:101], v[98:99]
	v_and_b32_e32 v161, 0xffff0000, v90
	v_cvt_pk_bf16_f32 v97, v98, v99
	ds_write_b128 v135, v[94:97] offset:38912
	ds_read_b128 v[94:97], v151 offset:6144
	ds_read_b128 v[98:101], v151 offset:6160
	v_cvt_pk_bf16_f32 v181, v36, v37
	v_cvt_pk_bf16_f32 v182, v30, v31
	v_cvt_pk_bf16_f32 v183, v32, v33
	s_waitcnt lgkmcnt(1)
	v_mul_f32_e32 v1, 0xbfb8aa3b, v94
	v_exp_f32_e32 v108, v1
	v_mul_f32_e32 v1, 0xbfb8aa3b, v95
	v_exp_f32_e32 v109, v1
	v_mul_f32_e32 v1, 0xbfb8aa3b, v96
	v_add_u32_e32 v107, 0xa800, v147
	s_add_u32 s46, s46, 0x60000
	v_pk_mul_f32 v[108:109], v[108:109], v[160:161]
	v_exp_f32_e32 v160, v1
	v_mul_f32_e32 v1, 0xbfb8aa3b, v97
	v_exp_f32_e32 v161, v1
	v_cvt_pk_bf16_f32 v90, v108, v109
	v_lshlrev_b32_e32 v108, 16, v91
	v_and_b32_e32 v109, 0xffff0000, v91
	s_waitcnt lgkmcnt(0)
	v_mul_f32_e32 v1, 0xbfb8aa3b, v98
	v_pk_mul_f32 v[108:109], v[160:161], v[108:109]
	v_exp_f32_e32 v160, v1
	v_mul_f32_e32 v1, 0xbfb8aa3b, v99
	v_exp_f32_e32 v161, v1
	v_cvt_pk_bf16_f32 v91, v108, v109
	v_lshlrev_b32_e32 v108, 16, v92
	v_and_b32_e32 v109, 0xffff0000, v92
	v_mul_f32_e32 v1, 0xbfb8aa3b, v100
	v_pk_mul_f32 v[108:109], v[160:161], v[108:109]
	v_exp_f32_e32 v160, v1
	v_mul_f32_e32 v1, 0xbfb8aa3b, v101
	v_exp_f32_e32 v161, v1
	v_mul_f32_e32 v1, 0x3fb8aa3b, v94
	v_exp_f32_e32 v94, v1
	v_mul_f32_e32 v1, 0x3fb8aa3b, v95
	v_exp_f32_e32 v95, v1
	v_cvt_pk_bf16_f32 v92, v108, v109
	v_lshlrev_b32_e32 v108, 16, v93
	v_and_b32_e32 v109, 0xffff0000, v93
	v_pk_mul_f32 v[108:109], v[160:161], v[108:109]
	v_mul_f32_e32 v1, 0x3fb8aa3b, v96
	v_cvt_pk_bf16_f32 v93, v108, v109
	ds_write_b128 v136, v[90:93] offset:56320
	v_lshlrev_b32_e32 v90, 16, v86
	v_and_b32_e32 v91, 0xffff0000, v86
	v_pk_mul_f32 v[92:93], v[94:95], s[40:41] op_sel_hi:[1,0]
	v_add_u32_e32 v108, 0xb800, v147
	v_pk_mul_f32 v[90:91], v[92:93], v[90:91]
	v_exp_f32_e32 v92, v1
	v_mul_f32_e32 v1, 0x3fb8aa3b, v97
	v_exp_f32_e32 v93, v1
	v_cvt_pk_bf16_f32 v86, v90, v91
	v_lshlrev_b32_e32 v90, 16, v87
	v_and_b32_e32 v91, 0xffff0000, v87
	v_pk_mul_f32 v[92:93], v[92:93], s[40:41] op_sel_hi:[1,0]
	v_mul_f32_e32 v1, 0x3fb8aa3b, v98
	v_pk_mul_f32 v[90:91], v[92:93], v[90:91]
	v_exp_f32_e32 v92, v1
	v_mul_f32_e32 v1, 0x3fb8aa3b, v99
	v_exp_f32_e32 v93, v1
	v_cvt_pk_bf16_f32 v87, v90, v91
	v_lshlrev_b32_e32 v90, 16, v88
	v_and_b32_e32 v91, 0xffff0000, v88
	v_pk_mul_f32 v[92:93], v[92:93], s[40:41] op_sel_hi:[1,0]
	v_mul_f32_e32 v1, 0x3fb8aa3b, v100
	v_pk_mul_f32 v[90:91], v[92:93], v[90:91]
	v_exp_f32_e32 v92, v1
	v_mul_f32_e32 v1, 0x3fb8aa3b, v101
	v_exp_f32_e32 v93, v1
	v_cvt_pk_bf16_f32 v88, v90, v91
	v_lshlrev_b32_e32 v90, 16, v89
	v_and_b32_e32 v91, 0xffff0000, v89
	v_pk_mul_f32 v[92:93], v[92:93], s[40:41] op_sel_hi:[1,0]
	v_add_u32_e32 v109, 0xc800, v147
	v_pk_mul_f32 v[90:91], v[92:93], v[90:91]
	s_addc_u32 s47, s47, 0
	v_cvt_pk_bf16_f32 v89, v90, v91
	ds_write_b128 v136, v[86:89] offset:38912
	s_waitcnt vmcnt(3)
	ds_write_b128 v153, v[70:73]
	s_waitcnt vmcnt(2)
	ds_write_b128 v155, v[74:77]
	s_waitcnt vmcnt(1)
	ds_write_b128 v153, v[78:81] offset:16896
	s_waitcnt vmcnt(0)
	ds_write_b128 v156, v[82:85]
	s_waitcnt lgkmcnt(0)
	s_barrier
	ds_read_b128 v[70:73], v142 offset:56320
	ds_read_b128 v[74:77], v142 offset:56384
	ds_read_b128 v[78:81], v134 offset:38912
	ds_read_b128 v[82:85], v134 offset:38976
	ds_read_b128 v[86:89], v142 offset:56448
	s_waitcnt lgkmcnt(2)
	v_mfma_f32_16x16x32_bf16 v[70:73], v[70:73], v[78:81], 0
	s_add_i32 s30, s30, 64
	s_waitcnt lgkmcnt(1)
	v_mfma_f32_16x16x32_bf16 v[70:73], v[74:77], v[82:85], v[70:73]
	ds_read_b128 v[74:77], v142 offset:56512
	ds_read_b128 v[90:93], v134 offset:39040
	ds_read_b128 v[94:97], v134 offset:39104
	s_waitcnt lgkmcnt(1)
	v_mfma_f32_16x16x32_bf16 v[70:73], v[86:89], v[90:93], v[70:73]
	s_waitcnt lgkmcnt(0)
	v_mfma_f32_16x16x32_bf16 v[70:73], v[74:77], v[94:97], v[70:73]
	v_mov_b32_e32 v74, s59
	s_nop 6
	v_cndmask_b32_e64 v1, v70, v74, s[14:15]
	v_cndmask_b32_e64 v1, v1, v70, s[16:17]
	v_cndmask_b32_e64 v70, 0, v71, s[16:17]
	v_cndmask_b32_e64 v71, v72, 0, s[18:19]
	v_cndmask_b32_e64 v72, v73, 0, s[20:21]
	v_cvt_pk_bf16_f32 v70, v1, v70
	v_cvt_pk_bf16_f32 v71, v71, v72
	ds_write_b64 v143, v[70:71]
	ds_read_b128 v[70:73], v144 offset:56320
	ds_read_b128 v[74:77], v144 offset:56384
	s_waitcnt lgkmcnt(1)
	v_mfma_f32_16x16x32_bf16 v[70:73], v[70:73], v[78:81], 0
	ds_read_b128 v[78:81], v144 offset:56448
	s_waitcnt lgkmcnt(1)
	v_mfma_f32_16x16x32_bf16 v[70:73], v[74:77], v[82:85], v[70:73]
	ds_read_b128 v[74:77], v144 offset:56512
	s_waitcnt lgkmcnt(1)
	v_mfma_f32_16x16x32_bf16 v[70:73], v[78:81], v[90:93], v[70:73]
	s_waitcnt lgkmcnt(0)
	v_mfma_f32_16x16x32_bf16 v[70:73], v[74:77], v[94:97], v[70:73]
	v_mov_b32_e32 v74, s59
	s_nop 6
	v_cndmask_b32_e64 v1, v70, v74, s[22:23]
	v_cndmask_b32_e64 v1, v1, v70, s[24:25]
	v_cndmask_b32_e64 v70, 0, v71, s[24:25]
	v_cndmask_b32_e64 v71, v72, 0, s[26:27]
	v_cndmask_b32_e64 v72, v73, 0, s[28:29]
	v_cvt_pk_bf16_f32 v70, v1, v70
	v_cvt_pk_bf16_f32 v71, v71, v72
	ds_write_b64 v145, v[70:71]
	s_waitcnt lgkmcnt(0)
	s_barrier
	ds_read_b64_tr_b16 v[76:77], v157 offset:2112
	ds_read_b64_tr_b16 v[74:75], v157
	ds_read_b64_tr_b16 v[80:81], v157 offset:2144
	ds_read_b64_tr_b16 v[78:79], v157 offset:32
	ds_read_b128 v[70:73], v146
	ds_read_b128 v[86:89], v146 offset:64
	s_waitcnt lgkmcnt(1)
	v_mfma_f32_16x16x32_bf16 v[90:93], v[74:77], v[70:73], 0
	ds_read_b64_tr_b16 v[82:83], v157 offset:16896
	ds_read_b64_tr_b16 v[84:85], v157 offset:19008
	v_add_u32_e32 v1, 0x9800, v147
	v_mfma_f32_16x16x32_bf16 v[94:97], v[78:81], v[70:73], 0
	ds_read_b64_tr_b16 v[72:73], v157 offset:19040
	ds_read_b64_tr_b16 v[70:71], v157 offset:16928
	s_waitcnt lgkmcnt(2)
	v_mfma_f32_16x16x32_bf16 v[90:93], v[82:85], v[86:89], v[90:93]
	s_waitcnt lgkmcnt(0)
	v_mfma_f32_16x16x32_bf16 v[86:89], v[70:73], v[86:89], v[94:97]
	s_nop 2
	ds_read_b128 v[94:97], v146 offset:2304
	ds_read_b128 v[98:101], v146 offset:2368
	s_waitcnt lgkmcnt(1)
	v_mfma_f32_16x16x32_bf16 v[160:163], v[74:77], v[94:97], 0
	v_mfma_f32_16x16x32_bf16 v[94:97], v[78:81], v[94:97], 0
	s_waitcnt lgkmcnt(0)
	v_mfma_f32_16x16x32_bf16 v[160:163], v[82:85], v[98:101], v[160:163]
	v_mfma_f32_16x16x32_bf16 v[94:97], v[70:73], v[98:101], v[94:97]
	ds_read_b128 v[98:101], v146 offset:4608
	ds_read_b128 v[164:167], v146 offset:4672
	s_waitcnt lgkmcnt(1)
	v_mfma_f32_16x16x32_bf16 v[168:171], v[74:77], v[98:101], 0
	v_mfma_f32_16x16x32_bf16 v[98:101], v[78:81], v[98:101], 0
	s_waitcnt lgkmcnt(0)
	v_mfma_f32_16x16x32_bf16 v[168:171], v[82:85], v[164:167], v[168:171]
	v_mfma_f32_16x16x32_bf16 v[98:101], v[70:73], v[164:167], v[98:101]
	ds_read_b128 v[164:167], v146 offset:6912
	ds_read_b128 v[172:175], v146 offset:6976
	ds_read2_b64 v[184:187], v1 offset1:4
	ds_read2_b64 v[188:191], v1 offset0:8 offset1:12
	s_waitcnt lgkmcnt(3)
	v_mfma_f32_16x16x32_bf16 v[176:179], v[74:77], v[164:167], 0
	v_mfma_f32_16x16x32_bf16 v[164:167], v[78:81], v[164:167], 0
	s_waitcnt lgkmcnt(2)
	v_mfma_f32_16x16x32_bf16 v[176:179], v[82:85], v[172:175], v[176:179]
	v_mfma_f32_16x16x32_bf16 v[164:167], v[70:73], v[172:175], v[164:167]
	v_cvt_pk_bf16_f32 v172, v14, v15
	v_cvt_pk_bf16_f32 v173, v16, v17
	v_cvt_pk_bf16_f32 v174, v58, v59
	v_cvt_pk_bf16_f32 v175, v60, v61
	s_waitcnt lgkmcnt(1)
	v_mfma_f32_16x16x32_bf16 v[90:93], v[180:183], v[184:187], v[90:93]
	v_mfma_f32_16x16x32_bf16 v[86:89], v[172:175], v[184:187], v[86:89]
	ds_read2_b64 v[184:187], v107 offset0:32 offset1:36
	s_waitcnt lgkmcnt(0)
	v_mfma_f32_16x16x32_bf16 v[160:163], v[180:183], v[184:187], v[160:163]
	v_mfma_f32_16x16x32_bf16 v[94:97], v[172:175], v[184:187], v[94:97]
	ds_read2_b64 v[184:187], v108 offset0:64 offset1:68
	s_waitcnt lgkmcnt(0)
	v_mfma_f32_16x16x32_bf16 v[168:171], v[180:183], v[184:187], v[168:171]
	v_mfma_f32_16x16x32_bf16 v[98:101], v[172:175], v[184:187], v[98:101]
	ds_read2_b64 v[184:187], v109 offset0:96 offset1:100
	s_waitcnt lgkmcnt(0)
	v_mfma_f32_16x16x32_bf16 v[176:179], v[180:183], v[184:187], v[176:179]
	v_cvt_pk_bf16_f32 v180, v54, v55
	v_cvt_pk_bf16_f32 v181, v56, v57
	v_cvt_pk_bf16_f32 v182, v62, v63
	v_cvt_pk_bf16_f32 v183, v64, v65
	v_mfma_f32_16x16x32_bf16 v[164:167], v[172:175], v[184:187], v[164:167]
	v_cvt_pk_bf16_f32 v172, v46, v47
	v_cvt_pk_bf16_f32 v173, v48, v49
	v_cvt_pk_bf16_f32 v174, v66, v67
	v_cvt_pk_bf16_f32 v175, v68, v69
	ds_read2_b64 v[184:187], v107 offset0:40 offset1:44
	s_waitcnt lgkmcnt(0)
	v_mfma_f32_16x16x32_bf16 v[160:163], v[180:183], v[184:187], v[160:163]
	v_mfma_f32_16x16x32_bf16 v[94:97], v[172:175], v[184:187], v[94:97]
	ds_read2_b64 v[184:187], v108 offset0:72 offset1:76
	s_waitcnt lgkmcnt(0)
	v_mfma_f32_16x16x32_bf16 v[168:171], v[180:183], v[184:187], v[168:171]
	v_mfma_f32_16x16x32_bf16 v[98:101], v[172:175], v[184:187], v[98:101]
	ds_read2_b64 v[184:187], v109 offset0:104 offset1:108
	v_mfma_f32_16x16x32_bf16 v[90:93], v[180:183], v[188:191], v[90:93]
	v_mfma_f32_16x16x32_bf16 v[86:89], v[172:175], v[188:191], v[86:89]
	ds_read2_b64 v[188:191], v1 offset0:16 offset1:20
	s_waitcnt lgkmcnt(1)
	v_mfma_f32_16x16x32_bf16 v[176:179], v[180:183], v[184:187], v[176:179]
	v_cvt_pk_bf16_f32 v180, v22, v23
	v_cvt_pk_bf16_f32 v181, v24, v25
	v_cvt_pk_bf16_f32 v182, v18, v19
	v_cvt_pk_bf16_f32 v183, v20, v21
	v_mfma_f32_16x16x32_bf16 v[164:167], v[172:175], v[184:187], v[164:167]
	v_cvt_pk_bf16_f32 v172, v10, v11
	v_cvt_pk_bf16_f32 v173, v12, v13
	v_cvt_pk_bf16_f32 v174, v50, v51
	v_cvt_pk_bf16_f32 v175, v52, v53
	ds_read2_b64 v[184:187], v107 offset0:48 offset1:52
	s_waitcnt lgkmcnt(0)
	v_mfma_f32_16x16x32_bf16 v[160:163], v[180:183], v[184:187], v[160:163]
	v_mfma_f32_16x16x32_bf16 v[94:97], v[172:175], v[184:187], v[94:97]
	ds_read2_b64 v[184:187], v108 offset0:80 offset1:84
	s_waitcnt lgkmcnt(0)
	v_mfma_f32_16x16x32_bf16 v[168:171], v[180:183], v[184:187], v[168:171]
	v_mfma_f32_16x16x32_bf16 v[98:101], v[172:175], v[184:187], v[98:101]
	ds_read2_b64 v[184:187], v109 offset0:112 offset1:116
	v_mfma_f32_16x16x32_bf16 v[90:93], v[180:183], v[188:191], v[90:93]
	v_mfma_f32_16x16x32_bf16 v[86:89], v[172:175], v[188:191], v[86:89]
	ds_read2_b64 v[188:191], v1 offset0:24 offset1:28
	v_lshl_add_u32 v1, s79, 9, v128
	s_waitcnt lgkmcnt(1)
	v_mfma_f32_16x16x32_bf16 v[176:179], v[180:183], v[184:187], v[176:179]
	v_cvt_pk_bf16_f32 v180, v38, v39
	v_cvt_pk_bf16_f32 v181, v40, v41
	v_cvt_pk_bf16_f32 v182, v26, v27
	v_cvt_pk_bf16_f32 v183, v28, v29
	v_mfma_f32_16x16x32_bf16 v[164:167], v[172:175], v[184:187], v[164:167]
	v_cvt_pk_bf16_f32 v172, v42, v43
	v_cvt_pk_bf16_f32 v173, v44, v45
	v_cvt_pk_bf16_f32 v174, v6, v7
	v_cvt_pk_bf16_f32 v175, v8, v9
	ds_read2_b64 v[184:187], v107 offset0:56 offset1:60
	s_waitcnt lgkmcnt(0)
	v_mfma_f32_16x16x32_bf16 v[160:163], v[180:183], v[184:187], v[160:163]
	v_mfma_f32_16x16x32_bf16 v[94:97], v[172:175], v[184:187], v[94:97]
	ds_read2_b64 v[184:187], v108 offset0:88 offset1:92
	s_waitcnt lgkmcnt(0)
	v_mfma_f32_16x16x32_bf16 v[168:171], v[180:183], v[184:187], v[168:171]
	v_mfma_f32_16x16x32_bf16 v[98:101], v[172:175], v[184:187], v[98:101]
	ds_read2_b64 v[184:187], v109 offset0:120 offset1:124
	v_mfma_f32_16x16x32_bf16 v[90:93], v[180:183], v[188:191], v[90:93]
	s_waitcnt lgkmcnt(0)
	v_mfma_f32_16x16x32_bf16 v[176:179], v[180:183], v[184:187], v[176:179]
	ds_read_b64_tr_b16 v[182:183], v158 offset:57408
	ds_read_b64_tr_b16 v[180:181], v158 offset:56320
	s_nop 3
	v_cvt_pk_bf16_f32 v90, v90, v91
	v_cvt_pk_bf16_f32 v91, v92, v93
	v_mfma_f32_16x16x32_bf16 v[86:89], v[172:175], v[188:191], v[86:89]
	v_lshl_add_u64 v[92:93], s[44:45], 0, v[116:117]
	s_add_u32 s44, s44, 0x20000
	s_addc_u32 s45, s45, 0
	v_mfma_f32_16x16x32_bf16 v[164:167], v[172:175], v[184:187], v[164:167]
	ds_read_b64_tr_b16 v[172:173], v158 offset:56352
	ds_read_b64_tr_b16 v[184:185], v158 offset:56384
	ds_read_b64_tr_b16 v[188:189], v158 offset:56416
	ds_read_b64_tr_b16 v[174:175], v158 offset:57440
	ds_read_b64_tr_b16 v[186:187], v158 offset:57472
	ds_read_b64_tr_b16 v[190:191], v158 offset:57504
	ds_read_b64_tr_b16 v[192:193], v158 offset:65024
	ds_read_b64_tr_b16 v[194:195], v159 offset:57408
	v_cvt_pk_bf16_f32 v86, v86, v87
	s_waitcnt lgkmcnt(4)
	v_mfma_f32_16x16x32_bf16 v[30:33], v[172:175], v[74:77], v[30:33]
	v_cvt_pk_bf16_f32 v87, v88, v89
	v_add_co_u32_e32 v88, vcc, s62, v92
	v_mfma_f32_16x16x32_bf16 v[58:61], v[172:175], v[78:81], v[58:61]
	s_nop 0
	v_addc_co_u32_e32 v89, vcc, 0, v93, vcc
	s_add_i32 s78, s78, 1
	v_mfma_f32_16x16x32_bf16 v[34:37], v[180:183], v[74:77], v[34:37]
	s_cmp_lg_u32 s46, 0x180000
	v_mfma_f32_16x16x32_bf16 v[14:17], v[180:183], v[78:81], v[14:17]
	ds_read_b64_tr_b16 v[180:181], v158 offset:65056
	ds_read_b64_tr_b16 v[196:197], v158 offset:65088
	ds_read_b64_tr_b16 v[200:201], v158 offset:65120
	ds_read_b64_tr_b16 v[182:183], v159 offset:57440
	ds_read_b64_tr_b16 v[198:199], v159 offset:57472
	ds_read_b64_tr_b16 v[202:203], v159 offset:57504
	ds_read_b64_tr_b16 v[172:173], v158 offset:56448
	ds_read_b64_tr_b16 v[174:175], v158 offset:57536
	s_waitcnt lgkmcnt(4)
	v_mfma_f32_16x16x32_bf16 v[30:33], v[180:183], v[82:85], v[30:33]
	v_mfma_f32_16x16x32_bf16 v[58:61], v[180:183], v[70:73], v[58:61]
	v_mfma_f32_16x16x32_bf16 v[54:57], v[184:187], v[74:77], v[54:57]
	v_mfma_f32_16x16x32_bf16 v[46:49], v[184:187], v[78:81], v[46:49]
	v_mfma_f32_16x16x32_bf16 v[62:65], v[188:191], v[74:77], v[62:65]
	v_mfma_f32_16x16x32_bf16 v[66:69], v[188:191], v[78:81], v[66:69]
	ds_read_b64_tr_b16 v[180:181], v158 offset:56480
	ds_read_b64_tr_b16 v[184:185], v158 offset:56512
	ds_read_b64_tr_b16 v[188:189], v158 offset:56544
	ds_read_b64_tr_b16 v[182:183], v158 offset:57568
	ds_read_b64_tr_b16 v[186:187], v158 offset:57600
	ds_read_b64_tr_b16 v[190:191], v158 offset:57632
	v_mfma_f32_16x16x32_bf16 v[34:37], v[192:195], v[82:85], v[34:37]
	v_mfma_f32_16x16x32_bf16 v[14:17], v[192:195], v[70:73], v[14:17]
	ds_read_b64_tr_b16 v[192:193], v158 offset:65152
	ds_read_b64_tr_b16 v[194:195], v159 offset:57536
	s_waitcnt lgkmcnt(11)
	v_mfma_f32_16x16x32_bf16 v[54:57], v[196:199], v[82:85], v[54:57]
	v_mfma_f32_16x16x32_bf16 v[46:49], v[196:199], v[70:73], v[46:49]
	s_waitcnt lgkmcnt(10)
	v_mfma_f32_16x16x32_bf16 v[62:65], v[200:203], v[82:85], v[62:65]
	v_mfma_f32_16x16x32_bf16 v[66:69], v[200:203], v[70:73], v[66:69]
	s_waitcnt lgkmcnt(8)
	v_mfma_f32_16x16x32_bf16 v[22:25], v[172:175], v[74:77], v[22:25]
	v_mfma_f32_16x16x32_bf16 v[10:13], v[172:175], v[78:81], v[10:13]
	ds_read_b64_tr_b16 v[172:173], v158 offset:65184
	ds_read_b64_tr_b16 v[196:197], v158 offset:65216
	ds_read_b64_tr_b16 v[200:201], v158 offset:65248
	ds_read_b64_tr_b16 v[174:175], v159 offset:57568
	ds_read_b64_tr_b16 v[198:199], v159 offset:57600
	ds_read_b64_tr_b16 v[202:203], v159 offset:57632
	global_store_dwordx2 v[92:93], v[86:87], off offset:32
	v_cvt_pk_bf16_f32 v86, v160, v161
	s_waitcnt lgkmcnt(10)
	v_mfma_f32_16x16x32_bf16 v[18:21], v[180:183], v[74:77], v[18:21]
	v_cvt_pk_bf16_f32 v87, v162, v163
	global_store_dwordx2 v[88:89], v[86:87], off
	v_cvt_pk_bf16_f32 v86, v94, v95
	v_mfma_f32_16x16x32_bf16 v[50:53], v[180:183], v[78:81], v[50:53]
	v_cvt_pk_bf16_f32 v87, v96, v97
	global_store_dwordx2 v[88:89], v[86:87], off offset:32
	v_add_co_u32_e32 v88, vcc, s72, v92
	s_waitcnt lgkmcnt(9)
	v_mfma_f32_16x16x32_bf16 v[38:41], v[184:187], v[74:77], v[38:41]
	v_cvt_pk_bf16_f32 v86, v168, v169
	v_cvt_pk_bf16_f32 v87, v170, v171
	v_addc_co_u32_e32 v89, vcc, 0, v93, vcc
	v_mfma_f32_16x16x32_bf16 v[42:45], v[184:187], v[78:81], v[42:45]
	global_store_dwordx2 v[88:89], v[86:87], off
	v_cvt_pk_bf16_f32 v86, v98, v99
	v_cvt_pk_bf16_f32 v87, v100, v101
	s_waitcnt lgkmcnt(8)
	v_mfma_f32_16x16x32_bf16 v[26:29], v[188:191], v[74:77], v[26:29]
	ds_read_b128 v[74:77], v1 offset:4096
	global_store_dwordx2 v[88:89], v[86:87], off offset:32
	v_add_co_u32_e32 v88, vcc, s64, v92
	v_mfma_f32_16x16x32_bf16 v[6:9], v[188:191], v[78:81], v[6:9]
	ds_read_b128 v[78:81], v1 offset:4160
	s_waitcnt lgkmcnt(1)
	s_nop 0
	s_nop 0
	v_mfma_f32_16x16x32_bf16 v[10:13], v[192:195], v[70:73], v[10:13]
	s_nop 0
	s_nop 0
	s_nop 0
	v_mfma_f32_16x16x32_bf16 v[50:53], v[172:175], v[70:73], v[50:53]
	s_nop 0
	s_nop 0
	s_nop 0
	v_mfma_f32_16x16x32_bf16 v[42:45], v[196:199], v[70:73], v[42:45]
	v_cvt_pk_bf16_f32 v86, v176, v177
	v_pk_mul_f32 v[36:37], v[36:37], v[76:77]
	v_pk_mul_f32 v[34:35], v[34:35], v[74:75]
	v_mfma_f32_16x16x32_bf16 v[6:9], v[200:203], v[70:73], v[6:9]
	s_waitcnt lgkmcnt(0)
	v_mov_b32_e32 v70, v78
	v_mov_b32_e32 v71, v80
	v_mov_b32_e32 v78, v70
	v_mov_b32_e32 v70, v79
	v_mov_b32_e32 v80, v71
	s_nop 0
	v_mov_b32_e32 v81, v81
	v_mov_b32_e32 v79, v70
	ds_read_b128 v[70:73], v1 offset:4224
	v_pk_mul_f32 v[16:17], v[16:17], v[76:77]
	v_pk_mul_f32 v[14:15], v[14:15], v[74:75]
	ds_read_b128 v[74:77], v1 offset:4288
	v_mfma_f32_16x16x32_bf16 v[22:25], v[192:195], v[82:85], v[22:25]
	s_waitcnt lgkmcnt(1)
	s_nop 0
	v_pk_mul_f32 v[32:33], v[32:33], v[80:81]
	v_pk_mul_f32 v[30:31], v[30:31], v[78:79]
	v_mfma_f32_16x16x32_bf16 v[18:21], v[172:175], v[82:85], v[18:21]
	v_mul_f32_e64 v60, v60, v80
	v_mul_f32_e64 v61, v61, v81
	v_pk_mul_f32 v[58:59], v[58:59], v[78:79]
	v_cvt_pk_bf16_f32 v87, v178, v179
	v_mfma_f32_16x16x32_bf16 v[38:41], v[196:199], v[82:85], v[38:41]
	v_addc_co_u32_e32 v89, vcc, 0, v93, vcc
	global_store_dwordx2 v[88:89], v[86:87], off
	v_mfma_f32_16x16x32_bf16 v[26:29], v[200:203], v[82:85], v[26:29]
	v_mov_b32_e32 v82, v70
	v_mov_b32_e32 v83, v71
	v_mov_b32_e32 v70, v72
	v_mov_b32_e32 v71, v73
	s_nop 0
	s_nop 0
	s_nop 0
	v_cvt_pk_bf16_f32 v86, v164, v165
	v_cvt_pk_bf16_f32 v87, v166, v167
	v_pk_mul_f32 v[56:57], v[56:57], v[70:71]
	v_pk_mul_f32 v[48:49], v[48:49], v[70:71]
	s_waitcnt lgkmcnt(0)
	v_mov_b32_e32 v70, v74
	v_mov_b32_e32 v71, v76
	v_mov_b32_e32 v78, v70
	v_mov_b32_e32 v70, v75
	v_mov_b32_e32 v80, v71
	s_nop 0
	v_mov_b32_e32 v81, v77
	v_mov_b32_e32 v79, v70
	ds_read_b128 v[70:73], v1 offset:4352
	ds_read_b128 v[74:77], v1 offset:4416
	v_pk_mul_f32 v[54:55], v[54:55], v[82:83]
	v_pk_mul_f32 v[46:47], v[46:47], v[82:83]
	v_pk_mul_f32 v[64:65], v[64:65], v[80:81]
	s_waitcnt lgkmcnt(1)
	s_nop 0
	v_mov_b32_e32 v82, v70
	v_mov_b32_e32 v83, v71
	v_mov_b32_e32 v70, v72
	v_mov_b32_e32 v71, v73
	s_nop 0
	s_nop 0
	v_pk_mul_f32 v[62:63], v[62:63], v[78:79]
	v_pk_mul_f32 v[68:69], v[68:69], v[80:81]
	v_pk_mul_f32 v[66:67], v[66:67], v[78:79]
	v_pk_mul_f32 v[24:25], v[24:25], v[70:71]
	v_pk_mul_f32 v[12:13], v[12:13], v[70:71]
	s_waitcnt lgkmcnt(0)
	v_mov_b32_e32 v70, v74
	v_mov_b32_e32 v71, v76
	v_mov_b32_e32 v78, v70
	v_mov_b32_e32 v70, v75
	v_mov_b32_e32 v80, v71
	s_nop 0
	v_mov_b32_e32 v81, v77
	v_mov_b32_e32 v79, v70
	ds_read_b128 v[70:73], v1 offset:4480
	ds_read_b128 v[74:77], v1 offset:4544
	s_nop 0
	v_pk_mul_f32 v[20:21], v[20:21], v[80:81]
	v_pk_mul_f32 v[18:19], v[18:19], v[78:79]
	s_waitcnt lgkmcnt(1)
	s_nop 0
	v_mov_b32_e32 v70, v70
	v_mov_b32_e32 v1, v71
	v_mov_b32_e32 v71, v72
	v_mov_b32_e32 v72, v71
	s_nop 0
	v_mov_b32_e32 v73, v73
	v_mov_b32_e32 v71, v1
	s_waitcnt lgkmcnt(0)
	s_nop 0
	v_mov_b32_e32 v74, v74
	v_mov_b32_e32 v1, v75
	v_mov_b32_e32 v75, v76
	v_mov_b32_e32 v76, v75
	s_nop 0
	v_mov_b32_e32 v77, v77
	v_mov_b32_e32 v75, v1
	v_pk_mul_f32 v[22:23], v[22:23], v[82:83]
	v_pk_mul_f32 v[10:11], v[10:11], v[82:83]
	v_pk_mul_f32 v[52:53], v[52:53], v[80:81]
	v_pk_mul_f32 v[50:51], v[50:51], v[78:79]
	v_pk_mul_f32 v[40:41], v[40:41], v[72:73]
	v_pk_mul_f32 v[38:39], v[38:39], v[70:71]
	v_pk_mul_f32 v[44:45], v[44:45], v[72:73]
	v_pk_mul_f32 v[42:43], v[42:43], v[70:71]
	v_pk_mul_f32 v[28:29], v[28:29], v[76:77]
	v_pk_mul_f32 v[26:27], v[26:27], v[74:75]
	v_pk_mul_f32 v[8:9], v[8:9], v[76:77]
	v_pk_mul_f32 v[6:7], v[6:7], v[74:75]
	global_store_dwordx2 v[92:93], v[90:91], off
	global_store_dwordx2 v[88:89], v[86:87], off offset:32
	s_cbranch_scc0 .LBB0_451
.LBB0_502:
	s_add_u32 s50, s53, s46
	s_addc_u32 s51, s77, s47
	s_add_u32 s31, s43, s46
	s_addc_u32 s48, s52, s47
	s_add_u32 s80, s31, s76
	s_addc_u32 s81, s48, 0
	s_and_b32 s79, s78, 1
	s_cmp_eq_u32 s79, 0
	s_cselect_b64 s[48:49], -1, 0
	s_and_b64 s[82:83], s[48:49], exec
	s_cselect_b32 s31, 0xf0, s67
	v_add3_u32 v1, s31, v126, v133
	ds_read2_b32 v[74:75], v1 offset1:4
	v_lshl_add_u64 v[76:77], s[50:51], 0, v[112:113]
	ds_read2_b32 v[82:83], v1 offset0:64 offset1:68
	global_load_dwordx4 v[94:97], v[76:77], off
	global_load_dwordx4 v[98:101], v[76:77], off offset:1024
	ds_read2_b32 v[108:109], v1 offset0:8 offset1:12
	v_lshl_add_u64 v[84:85], s[80:81], 0, v[114:115]
	s_mov_b32 s31, 0x3d800000
	s_waitcnt vmcnt(6) lgkmcnt(2)
	v_mfma_f32_16x16x4_f32 v[70:73], v74, v102, 0
	v_add_co_u32_e32 v74, vcc, s63, v76
	s_waitcnt vmcnt(5)
	v_mfma_f32_16x16x4_f32 v[70:73], v75, v103, v[70:73]
	v_addc_co_u32_e32 v75, vcc, 0, v77, vcc
	global_load_dwordx4 v[86:89], v[74:75], off
	global_load_dwordx4 v[90:93], v[74:75], off offset:1024
	v_add_co_u32_e32 v74, vcc, s64, v84
	s_nop 1
	v_addc_co_u32_e32 v75, vcc, 0, v85, vcc
	s_waitcnt vmcnt(6) lgkmcnt(0)
	v_mfma_f32_16x16x4_f32 v[160:163], v108, v104, v[70:73]
	v_add_co_u32_e32 v168, vcc, s63, v84
	global_load_dwordx4 v[70:73], v[84:85], off
	s_nop 0
	global_load_dwordx4 v[74:77], v[74:75], off
	v_addc_co_u32_e32 v169, vcc, 0, v85, vcc
	v_mfma_f32_16x16x4_f32 v[78:81], v82, v102, 0
	v_add_co_u32_e32 v82, vcc, s65, v84
	s_waitcnt vmcnt(7)
	v_mfma_f32_16x16x4_f32 v[160:163], v109, v105, v[160:163]
	v_mfma_f32_16x16x4_f32 v[164:167], v83, v103, v[78:81]
	v_addc_co_u32_e32 v83, vcc, 0, v85, vcc
	s_nop 4
	global_load_dwordx4 v[78:81], v[168:169], off
	s_nop 0
	global_load_dwordx4 v[82:85], v[82:83], off
	ds_read2_b32 v[168:169], v1 offset0:72 offset1:76
	s_waitcnt vmcnt(8)
	v_add_f32_e32 v107, v106, v160
	v_min_f32_e32 v170, 0, v107
	v_mul_f32_e64 v107, |v107|, s68
	v_exp_f32_e32 v107, v107
	v_add_f32_e32 v108, v106, v161
	v_add_f32_e32 v109, v106, v162
	v_mul_f32_e64 v160, |v108|, s68
	v_mul_f32_e64 v161, |v109|, s68
	v_exp_f32_e32 v160, v160
	v_exp_f32_e32 v161, v161
	v_add_f32_e32 v107, 1.0, v107
	v_log_f32_e32 v107, v107
	s_waitcnt lgkmcnt(0)
	v_mfma_f32_16x16x4_f32 v[164:167], v168, v104, v[164:167]
	v_add_f32_e32 v160, 1.0, v160
	v_add_f32_e32 v161, 1.0, v161
	v_log_f32_e32 v160, v160
	v_fmac_f32_e32 v170, 0xbf317218, v107
	v_log_f32_e32 v107, v161
	v_min_f32_e32 v171, 0, v108
	v_min_f32_e32 v172, 0, v109
	v_fmac_f32_e32 v171, 0xbf317218, v160
	v_fmac_f32_e32 v172, 0xbf317218, v107
	v_add_f32_e32 v107, v106, v163
	v_mfma_f32_16x16x4_f32 v[160:163], v169, v105, v[164:167]
	v_mul_f32_e64 v108, |v107|, s68
	v_exp_f32_e32 v168, v108
	v_min_f32_e32 v107, 0, v107
	v_add_f32_e32 v165, 1.0, v168
	v_log_f32_e32 v165, v165
	s_nop 4
	v_add_f32_e32 v160, v106, v160
	v_mul_f32_e64 v108, |v160|, s68
	v_exp_f32_e32 v164, v108
	ds_read2_b32 v[108:109], v1 offset0:128 offset1:132
	v_min_f32_e32 v173, 0, v160
	v_fmac_f32_e32 v107, 0xbf317218, v165
	v_add_f32_e32 v164, 1.0, v164
	v_log_f32_e32 v164, v164
	ds_read2_b32 v[168:169], v1 offset0:136 offset1:140
	v_add_f32_e32 v174, v106, v162
	v_add_f32_e32 v176, v106, v163
	v_fmac_f32_e32 v173, 0xbf317218, v164
	s_waitcnt lgkmcnt(1)
	v_mfma_f32_16x16x4_f32 v[164:167], v108, v102, 0
	v_add_f32_e32 v108, v106, v161
	v_mul_f32_e64 v160, |v108|, s68
	v_mul_f32_e64 v161, |v174|, s68
	v_exp_f32_e32 v160, v160
	v_exp_f32_e32 v161, v161
	v_min_f32_e32 v175, 0, v108
	v_mul_f32_e64 v177, |v176|, s68
	v_mfma_f32_16x16x4_f32 v[164:167], v109, v103, v[164:167]
	v_add_f32_e32 v108, 1.0, v160
	v_add_f32_e32 v109, 1.0, v161
	v_log_f32_e32 v108, v108
	v_log_f32_e32 v109, v109
	v_min_f32_e32 v174, 0, v174
	v_min_f32_e32 v176, 0, v176
	v_fmac_f32_e32 v175, 0xbf317218, v108
	s_waitcnt lgkmcnt(0)
	v_mfma_f32_16x16x4_f32 v[160:163], v168, v104, v[164:167]
	s_nop 0
	v_exp_f32_e32 v164, v177
	v_fmac_f32_e32 v174, 0xbf317218, v109
	v_add_f32_e32 v108, 1.0, v164
	v_log_f32_e32 v164, v108
	ds_read2_b32 v[108:109], v1 offset0:192 offset1:196
	v_mfma_f32_16x16x4_f32 v[160:163], v169, v105, v[160:163]
	v_fmac_f32_e32 v176, 0xbf317218, v164
	s_nop 8
	v_add_f32_e32 v160, v106, v160
	v_mul_f32_e64 v164, |v160|, s68
	v_exp_f32_e32 v168, v164
	s_waitcnt lgkmcnt(0)
	v_mfma_f32_16x16x4_f32 v[164:167], v108, v102, 0
	v_add_f32_e32 v161, v106, v161
	v_mul_f32_e64 v169, |v161|, s68
	v_exp_f32_e32 v108, v169
	v_min_f32_e32 v177, 0, v160
	v_add_f32_e32 v160, 1.0, v168
	ds_read2_b32 v[168:169], v1 offset0:200 offset1:204
	v_add_f32_e32 v108, 1.0, v108
	v_mfma_f32_16x16x4_f32 v[164:167], v109, v103, v[164:167]
	v_log_f32_e32 v160, v160
	v_log_f32_e32 v108, v108
	v_min_f32_e32 v1, 0, v161
	v_add_f32_e32 v178, v106, v163
	v_fmac_f32_e32 v177, 0xbf317218, v160
	v_fmac_f32_e32 v1, 0xbf317218, v108
	v_add_f32_e32 v108, v106, v162
	s_waitcnt lgkmcnt(0)
	v_mfma_f32_16x16x4_f32 v[160:163], v168, v104, v[164:167]
	v_mul_f32_e64 v109, |v108|, s68
	v_exp_f32_e32 v109, v109
	v_mul_f32_e64 v164, |v178|, s68
	v_exp_f32_e32 v164, v164
	v_min_f32_e32 v108, 0, v108
	v_add_f32_e32 v109, 1.0, v109
	v_log_f32_e32 v109, v109
	v_mfma_f32_16x16x4_f32 v[160:163], v169, v105, v[160:163]
	v_add_f32_e32 v164, 1.0, v164
	v_log_f32_e32 v164, v164
	v_fmac_f32_e32 v108, 0xbf317218, v109
	v_min_f32_e32 v109, 0, v178
	v_fmac_f32_e32 v109, 0xbf317218, v164
	s_nop 4
	v_add_f32_e32 v160, v106, v160
	v_mul_f32_e64 v165, |v160|, s68
	v_exp_f32_e32 v165, v165
	v_add_f32_e32 v161, v106, v161
	v_min_f32_e32 v160, 0, v160
	v_add_f32_e32 v162, v106, v162
	v_add_f32_e32 v164, 1.0, v165
	v_mul_f32_e64 v165, |v161|, s68
	v_log_f32_e32 v164, v164
	v_exp_f32_e32 v165, v165
	v_add_f32_e32 v163, v106, v163
	v_mul_f32_e64 v166, |v163|, s68
	v_fmac_f32_e32 v160, 0xbf317218, v164
	v_add_f32_e32 v164, 1.0, v165
	v_mul_f32_e64 v165, |v162|, s68
	v_log_f32_e32 v164, v164
	v_exp_f32_e32 v165, v165
	v_exp_f32_e32 v166, v166
	v_min_f32_e32 v161, 0, v161
	v_fmac_f32_e32 v161, 0xbf317218, v164
	v_add_f32_e32 v164, 1.0, v165
	v_log_f32_e32 v164, v164
	v_add_f32_e32 v165, 1.0, v166
	v_log_f32_e32 v165, v165
	v_min_f32_e32 v162, 0, v162
	v_fmac_f32_e32 v162, 0xbf317218, v164
	v_min_f32_e32 v163, 0, v163
	v_fma_f32 v164, v170, s31, 0
	v_fmac_f32_e32 v163, 0xbf317218, v165
	v_fmamk_f32 v165, v171, 0x3d800000, v164
	v_fmamk_f32 v166, v172, 0x3d800000, v165
	v_fmamk_f32 v107, v107, 0x3d800000, v166
	v_fmamk_f32 v167, v173, 0x3d800000, v107
	v_fmamk_f32 v168, v175, 0x3d800000, v167
	v_fmamk_f32 v169, v174, 0x3d800000, v168
	v_fmamk_f32 v170, v176, 0x3d800000, v169
	v_fmamk_f32 v171, v177, 0x3d800000, v170
	v_fmamk_f32 v1, v1, 0x3d800000, v171
	v_fmamk_f32 v108, v108, 0x3d800000, v1
	v_fmamk_f32 v109, v109, 0x3d800000, v108
	v_fmamk_f32 v160, v160, 0x3d800000, v109
	v_fmamk_f32 v161, v161, 0x3d800000, v160
	v_fmamk_f32 v162, v162, 0x3d800000, v161
	v_fmamk_f32 v163, v163, 0x3d800000, v162
	ds_bpermute_b32 v172, v137, v163
	ds_bpermute_b32 v173, v138, v163
	ds_bpermute_b32 v174, v139, v163
	s_waitcnt lgkmcnt(2)
	v_cndmask_b32_e64 v172, v172, 0, s[10:11]
	s_waitcnt lgkmcnt(1)
	v_cndmask_b32_e64 v173, 0, v173, s[12:13]
	v_add_f32_e32 v172, v172, v173
	s_waitcnt lgkmcnt(0)
	v_cndmask_b32_e64 v173, 0, v174, s[6:7]
	v_add_f32_e32 v172, v172, v173
	v_add_f32_e32 v164, v164, v172
	v_add_f32_e32 v165, v165, v172
	ds_write2st64_b32 v141, v164, v165 offset0:24 offset1:26
	v_add_f32_e32 v164, v166, v172
	v_add_f32_e32 v107, v107, v172
	ds_write2st64_b32 v141, v164, v107 offset0:28 offset1:30
	v_add_f32_e32 v107, v167, v172
	v_add_f32_e32 v164, v168, v172
	ds_write2st64_b32 v141, v107, v164 offset0:32 offset1:34
	v_add_f32_e32 v107, v169, v172
	v_add_f32_e32 v164, v170, v172
	ds_write2st64_b32 v141, v107, v164 offset0:36 offset1:38
	v_add_f32_e32 v107, v171, v172
	v_add_f32_e32 v1, v1, v172
	ds_write2st64_b32 v141, v107, v1 offset0:40 offset1:42
	v_add_f32_e32 v1, v172, v108
	v_add_f32_e32 v107, v172, v109
	ds_write2st64_b32 v141, v1, v107 offset0:44 offset1:46
	v_add_f32_e32 v1, v172, v160
	v_add_f32_e32 v107, v172, v161
	ds_write2st64_b32 v141, v1, v107 offset0:48 offset1:50
	v_add_f32_e32 v1, v172, v162
	v_add_f32_e32 v107, v172, v163
	ds_write2st64_b32 v141, v1, v107 offset0:52 offset1:54
	s_waitcnt lgkmcnt(0)
	s_barrier
	s_and_saveexec_b64 s[50:51], s[4:5]
	s_cbranch_execz .LBB0_504
	ds_read_b32 v1, v127 offset:38400
	v_lshl_add_u32 v107, s79, 9, v127
	s_waitcnt lgkmcnt(0)
	v_mul_f32_e32 v255, 0x3fb8aa3b, v1
	v_exp_f32_e32 v255, v255
	s_nop 0
	ds_write_b32 v107, v255 offset:4096

.LBB0_579:
	s_or_b64 exec, exec, s[0:1]
	s_waitcnt lgkmcnt(0)
	s_barrier
	ds_read_b128 v[132:135], v180
	ds_read_b128 v[138:141], v180 offset:16
	s_add_i32 s58, s58, 1
	s_add_u32 s38, s38, 0xfffa0000
	s_addc_u32 s39, s39, -1
	s_waitcnt lgkmcnt(1)
	v_mov_b32_e32 v78, v133
	v_mov_b32_e32 v79, v134
	v_mov_b32_e32 v133, v135
	s_waitcnt vmcnt(9)
	v_lshlrev_b32_e32 v134, 16, v162
	v_and_b32_e32 v135, 0xffff0000, v162
	v_pk_add_f32 v[78:79], v[78:79], v[132:133]
	s_waitcnt lgkmcnt(0)
	v_mov_b32_e32 v132, v140
	v_mov_b32_e32 v133, v138
	v_mov_b32_e32 v138, v141
	v_mul_f32_e32 v140, 0xbfb8aa3b, v134
	v_mul_f32_e32 v141, 0xbfb8aa3b, v135
	v_exp_f32_e32 v140, v140
	v_exp_f32_e32 v141, v141
	v_pk_add_f32 v[144:145], v[132:133], v[138:139]
	v_lshlrev_b32_e32 v138, 16, v163
	v_and_b32_e32 v139, 0xffff0000, v163
	v_add_f32_e32 v132, 1.0, v140
	v_add_f32_e32 v133, 1.0, v141
	v_mul_f32_e32 v140, 0xbfb8aa3b, v138
	v_mul_f32_e32 v141, 0xbfb8aa3b, v139
	v_rcp_f32_e32 v132, v132
	v_rcp_f32_e32 v133, v133
	v_exp_f32_e32 v140, v140
	v_exp_f32_e32 v141, v141
	s_waitcnt vmcnt(8)
	v_lshlrev_b32_e32 v162, 16, v152
	v_pk_mul_f32 v[146:147], v[132:133], v[134:135]
	v_add_f32_e32 v132, 1.0, v140
	v_add_f32_e32 v133, 1.0, v141
	v_and_b32_e32 v163, 0xffff0000, v152
	v_mul_f32_e32 v134, 0xbfb8aa3b, v162
	v_rcp_f32_e32 v132, v132
	v_rcp_f32_e32 v133, v133
	v_exp_f32_e32 v134, v134
	v_mul_f32_e32 v135, 0xbfb8aa3b, v163
	v_exp_f32_e32 v135, v135
	v_pk_mul_f32 v[200:201], v[132:133], v[138:139]
	v_add_f32_e32 v132, 1.0, v134
	v_rcp_f32_e32 v202, v132
	v_add_f32_e32 v132, 1.0, v135
	v_lshlrev_b32_e32 v152, 16, v153
	v_and_b32_e32 v153, 0xffff0000, v153
	v_rcp_f32_e32 v203, v132
	v_mul_f32_e32 v132, 0xbfb8aa3b, v152
	v_mul_f32_e32 v133, 0xbfb8aa3b, v153
	v_exp_f32_e32 v132, v132
	v_exp_f32_e32 v138, v133
	s_sub_i32 s30, s30, 64
	v_add_f32_e32 v139, 1.0, v132
	ds_read_b128 v[132:135], v180 offset:512
	v_add_f32_e32 v138, 1.0, v138
	v_rcp_f32_e32 v204, v139
	v_rcp_f32_e32 v205, v138
	ds_read_b128 v[138:141], v180 offset:528
	s_waitcnt lgkmcnt(1)
	v_mov_b32_e32 v206, v133
	v_mov_b32_e32 v207, v134
	v_mov_b32_e32 v133, v135
	v_pk_add_f32 v[132:133], v[206:207], v[132:133]
	s_waitcnt lgkmcnt(0)
	v_mov_b32_e32 v134, v140
	v_mov_b32_e32 v135, v138
	v_mov_b32_e32 v138, v141
	v_pk_add_f32 v[134:135], v[134:135], v[138:139]
	v_mov_b32_e32 v138, v132
	v_mov_b32_e32 v139, v78
	v_mov_b32_e32 v78, v133
	v_pk_add_f32 v[78:79], v[138:139], v[78:79]
	v_mov_b32_e32 v132, v135
	v_mov_b32_e32 v133, v145
	v_pk_add_f32 v[78:79], v[78:79], v[132:133]
	v_mov_b32_e32 v135, v144
	v_pk_add_f32 v[132:133], v[134:135], v[78:79]
	v_mov_b64_e32 v[78:79], s[42:43]
	v_pk_fma_f32 v[132:133], v[132:133], s[40:41], v[78:79] op_sel_hi:[1,0,0]
	v_pk_mul_f32 v[138:139], v[202:203], v[162:163]
	v_mul_f32_e32 v134, 0x4b800000, v133
	v_cmp_gt_f32_e64 s[0:1], s57, v133
	v_pk_mul_f32 v[140:141], v[204:205], v[152:153]
	v_lshl_add_u64 v[152:153], s[34:35], 0, v[116:117]
	v_cndmask_b32_e64 v133, v133, v134, s[0:1]
	v_rsq_f32_e32 v133, v133
	v_lshl_add_u64 v[134:135], s[34:35], 0, v[106:107]
	v_mul_f32_e32 v144, 0x45800000, v133
	v_cndmask_b32_e64 v144, v133, v144, s[0:1]
	v_pk_mul_f32 v[148:149], v[148:149], v[144:145] op_sel_hi:[1,0]
	v_mul_f32_e32 v133, 0x4b800000, v132
	s_waitcnt vmcnt(1)
	v_pk_mul_f32 v[148:149], v[72:73], v[148:149]
	v_cmp_gt_f32_e64 s[0:1], s57, v132
	v_pk_mul_f32 v[146:147], v[146:147], v[148:149]
	v_pk_mul_f32 v[148:149], v[150:151], v[144:145] op_sel_hi:[1,0]
	v_cvt_pk_bf16_f32 v146, v146, v147
	v_pk_mul_f32 v[148:149], v[74:75], v[148:149]
	v_cndmask_b32_e64 v132, v132, v133, s[0:1]
	v_pk_mul_f32 v[148:149], v[200:201], v[148:149]
	v_rsq_f32_e32 v133, v132
	v_cvt_pk_bf16_f32 v147, v148, v149
	global_store_dwordx2 v[134:135], v[146:147], off
	v_pk_mul_f32 v[146:147], v[156:157], v[144:145] op_sel_hi:[1,0]
	v_pk_mul_f32 v[144:145], v[158:159], v[144:145] op_sel_hi:[1,0]
	s_waitcnt vmcnt(1)
	v_pk_mul_f32 v[146:147], v[68:69], v[146:147]
	v_pk_mul_f32 v[144:145], v[70:71], v[144:145]
	v_pk_mul_f32 v[138:139], v[138:139], v[146:147]
	v_pk_mul_f32 v[140:141], v[140:141], v[144:145]
	v_cvt_pk_bf16_f32 v138, v138, v139
	v_cvt_pk_bf16_f32 v139, v140, v141
	v_lshlrev_b32_e32 v132, 16, v142
	global_store_dwordx2 v[134:135], v[138:139], off offset:32
	v_mul_f32_e32 v134, 0xbfb8aa3b, v132
	v_exp_f32_e32 v135, v134
	v_mul_f32_e32 v134, 0x45800000, v133
	v_cndmask_b32_e64 v134, v133, v134, s[0:1]
	v_and_b32_e32 v133, 0xffff0000, v142
	v_mul_f32_e32 v138, 0xbfb8aa3b, v133
	v_exp_f32_e32 v139, v138
	v_add_f32_e32 v135, 1.0, v135
	v_rcp_f32_e32 v138, v135
	v_pk_mul_f32 v[140:141], v[160:161], v[134:135] op_sel_hi:[1,0]
	v_add_f32_e32 v135, 1.0, v139
	v_lshlrev_b32_e32 v142, 16, v143
	v_rcp_f32_e32 v139, v135
	v_and_b32_e32 v143, 0xffff0000, v143
	v_mul_f32_e32 v135, 0xbfb8aa3b, v142
	v_exp_f32_e32 v135, v135
	v_mul_f32_e32 v144, 0xbfb8aa3b, v143
	v_exp_f32_e32 v144, v144
	v_pk_mul_f32 v[132:133], v[138:139], v[132:133]
	v_add_f32_e32 v135, 1.0, v135
	v_rcp_f32_e32 v138, v135
	v_add_f32_e32 v135, 1.0, v144
	v_rcp_f32_e32 v139, v135
	v_pk_mul_f32 v[98:99], v[98:99], v[134:135] op_sel_hi:[1,0]
	v_pk_mul_f32 v[140:141], v[72:73], v[140:141]
	v_pk_mul_f32 v[98:99], v[74:75], v[98:99]
	v_pk_mul_f32 v[138:139], v[138:139], v[142:143]
	v_pk_mul_f32 v[132:133], v[132:133], v[140:141]
	v_pk_mul_f32 v[98:99], v[138:139], v[98:99]
	v_cvt_pk_bf16_f32 v132, v132, v133
	v_cvt_pk_bf16_f32 v133, v98, v99
	v_lshlrev_b32_e32 v98, 16, v136
	v_mul_f32_e32 v99, 0xbfb8aa3b, v98
	v_exp_f32_e32 v135, v99
	v_lshl_add_u64 v[138:139], s[34:35], 0, v[110:111]
	v_and_b32_e32 v99, 0xffff0000, v136
	global_store_dwordx2 v[138:139], v[132:133], off
	v_mul_f32_e32 v133, 0xbfb8aa3b, v99
	v_exp_f32_e32 v133, v133
	v_lshlrev_b32_e32 v136, 16, v137
	v_and_b32_e32 v137, 0xffff0000, v137
	v_add_f32_e32 v132, 1.0, v135
	v_pk_mul_f32 v[96:97], v[96:97], v[134:135] op_sel_hi:[1,0]
	v_add_f32_e32 v133, 1.0, v133
	v_mul_f32_e32 v135, 0xbfb8aa3b, v136
	v_mul_f32_e32 v138, 0xbfb8aa3b, v137
	v_rcp_f32_e32 v132, v132
	v_rcp_f32_e32 v133, v133
	v_exp_f32_e32 v135, v135
	v_exp_f32_e32 v138, v138
	v_pk_mul_f32 v[96:97], v[68:69], v[96:97]
	v_pk_mul_f32 v[98:99], v[132:133], v[98:99]
	v_add_f32_e32 v132, 1.0, v135
	v_add_f32_e32 v133, 1.0, v138
	v_rcp_f32_e32 v132, v132
	v_rcp_f32_e32 v133, v133
	v_pk_mul_f32 v[94:95], v[94:95], v[134:135] op_sel_hi:[1,0]
	v_pk_mul_f32 v[96:97], v[98:99], v[96:97]
	v_pk_mul_f32 v[94:95], v[70:71], v[94:95]
	v_pk_mul_f32 v[98:99], v[132:133], v[136:137]
	v_cvt_pk_bf16_f32 v132, v96, v97
	v_pk_mul_f32 v[98:99], v[98:99], v[94:95]
	ds_read_b128 v[94:97], v180 offset:1024
	v_cvt_pk_bf16_f32 v133, v98, v99
	v_lshl_add_u64 v[98:99], s[34:35], 0, v[112:113]
	global_store_dwordx2 v[98:99], v[132:133], off
	ds_read_b128 v[132:135], v180 offset:1040
	s_waitcnt lgkmcnt(1)
	v_mov_b32_e32 v98, v95
	v_mov_b32_e32 v99, v96
	v_mov_b32_e32 v95, v97
	v_lshlrev_b32_e32 v96, 16, v130
	v_pk_add_f32 v[98:99], v[98:99], v[94:95]
	v_and_b32_e32 v97, 0xffff0000, v130
	v_mul_f32_e32 v95, 0xbfb8aa3b, v96
	v_exp_f32_e32 v130, v95
	v_mul_f32_e32 v95, 0xbfb8aa3b, v97
	s_waitcnt lgkmcnt(0)
	v_mov_b32_e32 v94, v134
	v_exp_f32_e32 v134, v95
	v_lshlrev_b32_e32 v136, 16, v131
	v_and_b32_e32 v137, 0xffff0000, v131
	v_mul_f32_e32 v131, 0xbfb8aa3b, v136
	v_mov_b32_e32 v95, v132
	v_add_f32_e32 v132, 1.0, v134
	v_exp_f32_e32 v134, v131
	v_mul_f32_e32 v131, 0xbfb8aa3b, v137
	v_exp_f32_e32 v139, v131
	v_rcp_f32_e32 v131, v132
	v_add_f32_e32 v132, 1.0, v134
	v_rcp_f32_e32 v138, v132
	v_add_f32_e32 v132, 1.0, v139
	v_rcp_f32_e32 v139, v132
	v_mov_b32_e32 v132, v135
	v_pk_add_f32 v[132:133], v[94:95], v[132:133]
	v_lshlrev_b32_e32 v144, 16, v129
	v_pk_mul_f32 v[136:137], v[138:139], v[136:137]
	v_lshlrev_b32_e32 v138, 16, v128
	v_and_b32_e32 v139, 0xffff0000, v128
	v_mul_f32_e32 v94, 0xbfb8aa3b, v138
	v_exp_f32_e32 v94, v94
	v_mul_f32_e32 v95, 0xbfb8aa3b, v139
	v_exp_f32_e32 v95, v95
	v_and_b32_e32 v145, 0xffff0000, v129
	v_add_f32_e32 v94, 1.0, v94
	v_rcp_f32_e32 v142, v94
	v_add_f32_e32 v94, 1.0, v95
	v_add_f32_e32 v130, 1.0, v130
	v_rcp_f32_e32 v143, v94
	v_mul_f32_e32 v94, 0xbfb8aa3b, v144
	v_mul_f32_e32 v95, 0xbfb8aa3b, v145
	v_rcp_f32_e32 v130, v130
	v_exp_f32_e32 v94, v94
	v_exp_f32_e32 v128, v95
	v_lshl_add_u64 v[140:141], s[34:35], 0, v[114:115]
	v_pk_mul_f32 v[134:135], v[130:131], v[96:97]
	v_add_f32_e32 v129, 1.0, v94
	ds_read_b128 v[94:97], v180 offset:1536
	v_add_f32_e32 v128, 1.0, v128
	v_rcp_f32_e32 v146, v129
	v_rcp_f32_e32 v147, v128
	ds_read_b128 v[128:131], v180 offset:1552
	s_waitcnt lgkmcnt(1)
	v_mov_b32_e32 v148, v95
	v_mov_b32_e32 v149, v96
	v_mov_b32_e32 v95, v97
	v_pk_add_f32 v[94:95], v[148:149], v[94:95]
	s_waitcnt lgkmcnt(0)
	v_mov_b32_e32 v96, v130
	v_mov_b32_e32 v97, v128
	v_mov_b32_e32 v128, v131
	v_pk_add_f32 v[96:97], v[96:97], v[128:129]
	v_mov_b32_e32 v128, v94
	v_mov_b32_e32 v129, v98
	v_mov_b32_e32 v98, v95
	v_pk_add_f32 v[94:95], v[128:129], v[98:99]
	v_mov_b32_e32 v98, v97
	v_mov_b32_e32 v99, v133
	v_pk_add_f32 v[94:95], v[94:95], v[98:99]
	v_mov_b32_e32 v97, v132
	v_pk_add_f32 v[94:95], v[96:97], v[94:95]
	v_pk_mul_f32 v[98:99], v[146:147], v[144:145]
	v_pk_fma_f32 v[78:79], v[94:95], s[40:41], v[78:79] op_sel_hi:[1,0,0]
	s_nop 0
	v_mul_f32_e32 v94, 0x4b800000, v79
	v_cmp_gt_f32_e64 s[0:1], s57, v79
	s_nop 1
	v_cndmask_b32_e64 v79, v79, v94, s[0:1]
	v_rsq_f32_e32 v79, v79
	v_pk_mul_f32 v[94:95], v[142:143], v[138:139]
	v_mul_f32_e32 v96, 0x45800000, v79
	v_cndmask_b32_e64 v96, v79, v96, s[0:1]
	v_pk_mul_f32 v[88:89], v[88:89], v[96:97] op_sel_hi:[1,0]
	v_pk_mul_f32 v[92:93], v[92:93], v[96:97] op_sel_hi:[1,0]
	v_pk_mul_f32 v[88:89], v[72:73], v[88:89]
	v_pk_mul_f32 v[92:93], v[74:75], v[92:93]
	v_pk_mul_f32 v[88:89], v[134:135], v[88:89]
	v_pk_mul_f32 v[92:93], v[136:137], v[92:93]
	v_cvt_pk_bf16_f32 v88, v88, v89
	v_cvt_pk_bf16_f32 v89, v92, v93
	global_store_dwordx2 v[140:141], v[88:89], off
	v_pk_mul_f32 v[88:89], v[90:91], v[96:97] op_sel_hi:[1,0]
	v_mul_f32_e32 v79, 0x4b800000, v78
	v_cmp_gt_f32_e64 s[0:1], s57, v78
	v_pk_mul_f32 v[88:89], v[68:69], v[88:89]
	v_pk_mul_f32 v[86:87], v[86:87], v[96:97] op_sel_hi:[1,0]
	v_cndmask_b32_e64 v78, v78, v79, s[0:1]
	v_pk_mul_f32 v[200:201], v[94:95], v[88:89]
	v_pk_mul_f32 v[202:203], v[70:71], v[86:87]
	ds_read_b64_tr_b16 v[88:89], v196 offset:57408
	ds_read_b64_tr_b16 v[86:87], v196 offset:56320
	ds_read_b64_tr_b16 v[92:93], v198 offset:2112
	ds_read_b64_tr_b16 v[90:91], v198
	ds_read_b64_tr_b16 v[96:97], v198 offset:2144
	ds_read_b64_tr_b16 v[94:95], v198 offset:32
	ds_read_b64_tr_b16 v[128:129], v196 offset:56352
	ds_read_b64_tr_b16 v[132:133], v196 offset:56384
	ds_read_b64_tr_b16 v[136:137], v196 offset:56416
	ds_read_b64_tr_b16 v[130:131], v196 offset:57440
	ds_read_b64_tr_b16 v[134:135], v196 offset:57472
	ds_read_b64_tr_b16 v[138:139], v196 offset:57504
	v_rsq_f32_e32 v78, v78
	ds_read_b64_tr_b16 v[140:141], v196 offset:65024
	ds_read_b64_tr_b16 v[142:143], v197 offset:57408
	ds_read_b64_tr_b16 v[144:145], v198 offset:16896
	ds_read_b64_tr_b16 v[146:147], v198 offset:19008
	ds_read_b64_tr_b16 v[150:151], v198 offset:19040
	ds_read_b64_tr_b16 v[148:149], v198 offset:16928
	v_pk_mul_f32 v[98:99], v[98:99], v[202:203]
	s_waitcnt lgkmcnt(8)
	v_mfma_f32_16x16x32_bf16 v[12:15], v[128:131], v[90:93], v[12:15]
	v_cvt_pk_bf16_f32 v200, v200, v201
	v_cvt_pk_bf16_f32 v201, v98, v99
	v_mul_f32_e32 v79, 0x45800000, v78
	v_mfma_f32_16x16x32_bf16 v[36:39], v[128:131], v[94:97], v[36:39]
	v_lshlrev_b32_e32 v98, 16, v126
	v_cndmask_b32_e64 v78, v78, v79, s[0:1]
	v_and_b32_e32 v99, 0xffff0000, v126
	v_mfma_f32_16x16x32_bf16 v[8:11], v[86:89], v[90:93], v[8:11]
	v_mul_f32_e32 v79, 0xbfb8aa3b, v98
	v_exp_f32_e32 v79, v79
	v_mul_f32_e32 v126, 0xbfb8aa3b, v99
	v_mfma_f32_16x16x32_bf16 v[4:7], v[86:89], v[94:97], v[4:7]
	ds_read_b64_tr_b16 v[86:87], v196 offset:65056
	ds_read_b64_tr_b16 v[156:157], v196 offset:65088
	ds_read_b64_tr_b16 v[160:161], v196 offset:65120
	ds_read_b64_tr_b16 v[88:89], v197 offset:57440
	ds_read_b64_tr_b16 v[158:159], v197 offset:57472
	ds_read_b64_tr_b16 v[162:163], v197 offset:57504
	v_add_f32_e32 v79, 1.0, v79
	global_store_dwordx2 v[152:153], v[200:201], off
	s_waitcnt lgkmcnt(2)
	v_mfma_f32_16x16x32_bf16 v[12:15], v[86:89], v[144:147], v[12:15]
	v_mfma_f32_16x16x32_bf16 v[36:39], v[86:89], v[148:151], v[36:39]
	v_exp_f32_e32 v87, v126
	v_rcp_f32_e32 v86, v79
	v_add_f32_e32 v79, 1.0, v87
	v_rcp_f32_e32 v87, v79
	v_pk_mul_f32 v[84:85], v[84:85], v[78:79] op_sel_hi:[1,0]
	v_mfma_f32_16x16x32_bf16 v[24:27], v[132:135], v[90:93], v[24:27]
	v_mul_f32_e64 v72, v72, v84
	v_mul_f32_e64 v73, v73, v85
	v_pk_mul_f32 v[84:85], v[86:87], v[98:99]
	v_lshlrev_b32_e32 v86, 16, v127
	v_mul_f32_e32 v79, 0xbfb8aa3b, v86
	v_exp_f32_e32 v79, v79
	v_pk_mul_f32 v[98:99], v[84:85], v[72:73]
	v_and_b32_e32 v87, 0xffff0000, v127
	v_mfma_f32_16x16x32_bf16 v[32:35], v[132:135], v[94:97], v[32:35]
	v_add_f32_e32 v72, 1.0, v79
	v_rcp_f32_e32 v84, v72
	v_mul_f32_e32 v72, 0xbfb8aa3b, v87
	v_exp_f32_e32 v79, v72
	v_mfma_f32_16x16x32_bf16 v[40:43], v[136:139], v[90:93], v[40:43]
	v_cvt_pk_bf16_f32 v98, v98, v99
	v_pk_mul_f32 v[72:73], v[82:83], v[78:79] op_sel_hi:[1,0]
	s_nop 0
	v_pk_mul_f32 v[134:135], v[74:75], v[72:73]
	v_add_f32_e32 v72, 1.0, v79
	v_rcp_f32_e32 v85, v72
	ds_read_b64_tr_b16 v[72:73], v196 offset:56448
	ds_read_b64_tr_b16 v[74:75], v196 offset:57536
	v_mfma_f32_16x16x32_bf16 v[64:67], v[136:139], v[94:97], v[64:67]
	v_mul_f32_e64 v136, v84, v86
	v_mul_f32_e64 v137, v85, v87
	ds_read_b64_tr_b16 v[82:83], v196 offset:56480
	ds_read_b64_tr_b16 v[86:87], v196 offset:56512
	ds_read_b64_tr_b16 v[126:127], v196 offset:56544
	ds_read_b64_tr_b16 v[84:85], v196 offset:57568
	ds_read_b64_tr_b16 v[88:89], v196 offset:57600
	ds_read_b64_tr_b16 v[128:129], v196 offset:57632
	v_mfma_f32_16x16x32_bf16 v[8:11], v[140:143], v[144:147], v[8:11]
	ds_read_b64_tr_b16 v[130:131], v196 offset:65152
	ds_read_b64_tr_b16 v[132:133], v197 offset:57536
	v_mfma_f32_16x16x32_bf16 v[4:7], v[140:143], v[148:151], v[4:7]
	v_mul_f32_e64 v142, v136, v134
	v_mul_f32_e64 v143, v137, v135
	v_cvt_pk_bf16_f32 v99, v142, v143
	v_lshl_add_u64 v[142:143], s[34:35], 0, v[118:119]
	s_waitcnt lgkmcnt(8)
	v_mfma_f32_16x16x32_bf16 v[16:19], v[72:75], v[90:93], v[16:19]
	v_mfma_f32_16x16x32_bf16 v[20:23], v[72:75], v[94:97], v[20:23]
	ds_read_b64_tr_b16 v[72:73], v196 offset:65184
	ds_read_b64_tr_b16 v[134:135], v196 offset:65216
	ds_read_b64_tr_b16 v[138:139], v196 offset:65248
	ds_read_b64_tr_b16 v[74:75], v197 offset:57568
	ds_read_b64_tr_b16 v[136:137], v197 offset:57600
	ds_read_b64_tr_b16 v[140:141], v197 offset:57632
	global_store_dwordx2 v[142:143], v[98:99], off
	v_lshlrev_b32_e32 v98, 16, v124
	v_and_b32_e32 v99, 0xffff0000, v124
	v_mul_f32_e32 v79, 0xbfb8aa3b, v98
	v_exp_f32_e32 v79, v79
	v_mul_f32_e32 v124, 0xbfb8aa3b, v99
	s_waitcnt lgkmcnt(10)
	v_mfma_f32_16x16x32_bf16 v[28:31], v[82:85], v[90:93], v[28:31]
	v_add_f32_e32 v79, 1.0, v79
	v_mfma_f32_16x16x32_bf16 v[48:51], v[82:85], v[94:97], v[48:51]
	v_exp_f32_e32 v83, v124
	v_rcp_f32_e32 v82, v79
	v_add_f32_e32 v79, 1.0, v83
	v_rcp_f32_e32 v83, v79
	v_pk_mul_f32 v[80:81], v[80:81], v[78:79] op_sel_hi:[1,0]
	s_waitcnt lgkmcnt(2)
	v_mfma_f32_16x16x32_bf16 v[28:31], v[72:75], v[144:147], v[28:31]
	v_mul_f32_e64 v68, v68, v80
	v_mul_f32_e64 v69, v69, v81
	v_pk_mul_f32 v[76:77], v[76:77], v[78:79] op_sel_hi:[1,0]
	v_lshl_add_u64 v[78:79], s[34:35], 0, v[120:121]
	v_mfma_f32_16x16x32_bf16 v[48:51], v[72:75], v[148:151], v[48:51]
	v_mul_f32_e64 v72, v82, v98
	v_mul_f32_e64 v73, v83, v99
	v_pk_mul_f32 v[70:71], v[70:71], v[76:77]
	v_pk_mul_f32 v[68:69], v[72:73], v[68:69]
	v_lshlrev_b32_e32 v72, 16, v125
	v_and_b32_e32 v73, 0xffff0000, v125
	v_mul_f32_e32 v74, 0xbfb8aa3b, v72
	v_mul_f32_e32 v75, 0xbfb8aa3b, v73
	v_exp_f32_e32 v74, v74
	v_exp_f32_e32 v75, v75
	v_lshl_add_u32 v82, s59, 9, v176
	v_cvt_pk_bf16_f32 v76, v68, v69
	v_add_f32_e32 v74, 1.0, v74
	v_add_f32_e32 v75, 1.0, v75
	v_rcp_f32_e32 v74, v74
	v_rcp_f32_e32 v75, v75
	v_mfma_f32_16x16x32_bf16 v[24:27], v[156:159], v[144:147], v[24:27]
	s_add_u32 s34, s34, 0xfffe0000
	s_addc_u32 s35, s35, -1
	v_pk_mul_f32 v[72:73], v[74:75], v[72:73]
	v_mfma_f32_16x16x32_bf16 v[32:35], v[156:159], v[148:151], v[32:35]
	v_mul_f32_e64 v72, v72, v70
	v_mul_f32_e64 v73, v73, v71
	ds_read_b128 v[68:71], v82 offset:4096
	v_cvt_pk_bf16_f32 v77, v72, v73
	ds_read_b128 v[72:75], v82 offset:4160
	global_store_dwordx2 v[78:79], v[76:77], off
	v_mfma_f32_16x16x32_bf16 v[16:19], v[130:133], v[144:147], v[16:19]
	s_waitcnt lgkmcnt(1)
	s_nop 0
	v_mov_b32_e32 v80, v68
	v_mov_b32_e32 v81, v69
	v_mov_b32_e32 v68, v70
	v_mov_b32_e32 v69, v71
	s_nop 0
	s_nop 0
	s_nop 0
	v_mfma_f32_16x16x32_bf16 v[20:23], v[130:133], v[148:151], v[20:23]
	s_add_u32 s36, s36, 0xfffe0000
	v_pk_mul_f32 v[10:11], v[10:11], v[68:69]
	v_pk_mul_f32 v[6:7], v[6:7], v[68:69]
	s_waitcnt lgkmcnt(0)
	v_mov_b32_e32 v68, v72
	v_mov_b32_e32 v69, v74
	v_mov_b32_e32 v76, v68
	v_mov_b32_e32 v68, v73
	v_mov_b32_e32 v78, v69
	s_nop 0
	v_mov_b32_e32 v79, v75
	v_mov_b32_e32 v77, v68
	ds_read_b128 v[68:71], v82 offset:4224
	ds_read_b128 v[72:75], v82 offset:4288
	v_pk_mul_f32 v[8:9], v[8:9], v[80:81]
	v_pk_mul_f32 v[4:5], v[4:5], v[80:81]
	v_pk_mul_f32 v[14:15], v[14:15], v[78:79]
	s_waitcnt lgkmcnt(1)
	s_nop 0
	v_mov_b32_e32 v80, v68
	v_mov_b32_e32 v81, v69
	v_mov_b32_e32 v68, v70
	v_mov_b32_e32 v69, v71
	s_nop 0
	s_nop 0
	v_pk_mul_f32 v[12:13], v[12:13], v[76:77]
	v_pk_mul_f32 v[38:39], v[38:39], v[78:79]
	v_pk_mul_f32 v[36:37], v[36:37], v[76:77]
	v_pk_mul_f32 v[26:27], v[26:27], v[68:69]
	v_pk_mul_f32 v[34:35], v[34:35], v[68:69]
	s_waitcnt lgkmcnt(0)
	v_mov_b32_e32 v68, v72
	v_mov_b32_e32 v69, v74
	v_mov_b32_e32 v76, v68
	v_mov_b32_e32 v68, v73
	v_mov_b32_e32 v78, v69
	s_nop 0
	v_mov_b32_e32 v79, v75
	v_mov_b32_e32 v77, v68
	ds_read_b128 v[68:71], v82 offset:4352
	ds_read_b128 v[72:75], v82 offset:4416
	s_nop 0
	v_mfma_f32_16x16x32_bf16 v[40:43], v[160:163], v[144:147], v[40:43]
	s_addc_u32 s37, s37, -1
	s_waitcnt lgkmcnt(1)
	s_nop 0
	v_pk_mul_f32 v[24:25], v[24:25], v[80:81]
	v_pk_mul_f32 v[32:33], v[32:33], v[80:81]
	v_mov_b32_e32 v80, v68
	v_mov_b32_e32 v81, v69
	v_mov_b32_e32 v68, v70
	v_mov_b32_e32 v69, v71
	s_nop 0
	s_nop 0
	v_mfma_f32_16x16x32_bf16 v[64:67], v[160:163], v[148:151], v[64:67]
	v_mul_f32_e64 v42, v42, v78
	v_mul_f32_e64 v43, v43, v79
	v_pk_mul_f32 v[40:41], v[40:41], v[76:77]
	v_pk_mul_f32 v[18:19], v[18:19], v[68:69]
	v_pk_mul_f32 v[22:23], v[22:23], v[68:69]
	s_waitcnt lgkmcnt(0)
	v_mov_b32_e32 v68, v72
	v_mov_b32_e32 v69, v74
	v_pk_mul_f32 v[66:67], v[66:67], v[78:79]
	v_pk_mul_f32 v[64:65], v[64:65], v[76:77]
	v_mov_b32_e32 v76, v68
	v_mov_b32_e32 v68, v73
	v_mov_b32_e32 v78, v69
	s_nop 0
	v_mov_b32_e32 v79, v75
	v_mov_b32_e32 v77, v68
	ds_read_b128 v[68:71], v82 offset:4480
	ds_read_b128 v[72:75], v82 offset:4544
	v_mfma_f32_16x16x32_bf16 v[44:47], v[86:89], v[90:93], v[44:47]
	s_nop 0
	v_pk_mul_f32 v[30:31], v[30:31], v[78:79]
	s_waitcnt lgkmcnt(1)
	s_nop 0
	v_mfma_f32_16x16x32_bf16 v[56:59], v[86:89], v[94:97], v[56:59]
	s_nop 0
	s_nop 0
	s_nop 0
	v_mfma_f32_16x16x32_bf16 v[52:55], v[126:129], v[90:93], v[52:55]
	s_waitcnt lgkmcnt(0)
	s_nop 0
	s_nop 0
	s_nop 0
	v_mfma_f32_16x16x32_bf16 v[60:63], v[126:129], v[94:97], v[60:63]
	s_nop 0
	s_nop 0
	s_nop 0
	v_mfma_f32_16x16x32_bf16 v[44:47], v[134:137], v[144:147], v[44:47]
	s_nop 0
	s_nop 0
	s_nop 0
	v_mfma_f32_16x16x32_bf16 v[56:59], v[134:137], v[148:151], v[56:59]
	s_nop 0
	s_nop 0
	s_nop 0
	v_mfma_f32_16x16x32_bf16 v[52:55], v[138:141], v[144:147], v[52:55]
	v_mul_f32_e64 v16, v16, v80
	v_mul_f32_e64 v17, v17, v81
	v_pk_mul_f32 v[20:21], v[20:21], v[80:81]
	v_pk_mul_f32 v[28:29], v[28:29], v[76:77]
	v_mfma_f32_16x16x32_bf16 v[60:63], v[138:141], v[148:151], v[60:63]
	v_mul_f32_e64 v50, v50, v78
	v_mul_f32_e64 v51, v51, v79
	v_pk_mul_f32 v[48:49], v[48:49], v[76:77]
	v_pk_mul_f32 v[46:47], v[46:47], v[70:71]
	v_pk_mul_f32 v[44:45], v[44:45], v[68:69]
	v_pk_mul_f32 v[58:59], v[58:59], v[70:71]
	v_pk_mul_f32 v[56:57], v[56:57], v[68:69]
	v_pk_mul_f32 v[54:55], v[54:55], v[74:75]
	v_pk_mul_f32 v[52:53], v[52:53], v[72:73]
	v_pk_mul_f32 v[62:63], v[62:63], v[74:75]
	s_cmp_eq_u32 s58, 4
	v_pk_mul_f32 v[60:61], v[60:61], v[72:73]
	s_cbranch_scc1 .LBB0_597
.LBB0_580:
	s_add_u32 s0, s50, s38
	s_addc_u32 s1, s51, s39
	s_add_u32 s60, s48, s38
	s_addc_u32 s61, s49, s39
	s_add_u32 s31, s60, s46
	s_addc_u32 s44, s61, 0
	s_add_u32 s62, s31, 0x16e40800
	s_addc_u32 s63, s44, 0
	s_and_b32 s59, s58, 1
	s_cmp_eq_u32 s59, 0
	s_cselect_b64 s[44:45], -1, 0
	s_and_b64 s[64:65], s[44:45], exec
	s_cselect_b32 s31, 0xf0, s54
	v_add3_u32 v136, s31, v171, v170
	ds_read2_b32 v[72:73], v136 offset1:4
	v_lshl_add_u64 v[74:75], s[0:1], 0, v[102:103]
	ds_read2_b32 v[80:81], v136 offset0:64 offset1:68
	global_load_dwordx4 v[92:95], v[74:75], off
	global_load_dwordx4 v[96:99], v[74:75], off offset:1024
	ds_read2_b32 v[132:133], v136 offset0:8 offset1:12
	v_lshl_add_u64 v[82:83], s[62:63], 0, v[104:105]
	s_waitcnt lgkmcnt(2)
	v_mfma_f32_16x16x4_f32 v[68:71], v72, v155, 0
	v_add_co_u32_e64 v72, s[0:1], s52, v74
	v_mfma_f32_16x16x4_f32 v[68:71], v73, v164, v[68:71]
	s_nop 0
	v_addc_co_u32_e64 v73, s[0:1], 0, v75, s[0:1]
	global_load_dwordx4 v[84:87], v[72:73], off
	global_load_dwordx4 v[88:91], v[72:73], off offset:1024
	v_add_co_u32_e64 v72, s[0:1], s47, v82
	s_nop 1
	v_addc_co_u32_e64 v73, s[0:1], 0, v83, s[0:1]
	s_waitcnt lgkmcnt(0)
	v_mfma_f32_16x16x4_f32 v[124:127], v132, v165, v[68:71]
	v_add_co_u32_e64 v134, s[0:1], s52, v82
	global_load_dwordx4 v[68:71], v[82:83], off
	s_nop 0
	global_load_dwordx4 v[72:75], v[72:73], off
	v_addc_co_u32_e64 v135, s[0:1], 0, v83, s[0:1]
	v_mfma_f32_16x16x4_f32 v[76:79], v80, v155, 0
	v_add_co_u32_e64 v80, s[0:1], s53, v82
	v_mfma_f32_16x16x4_f32 v[124:127], v133, v166, v[124:127]
	v_mfma_f32_16x16x4_f32 v[128:131], v81, v164, v[76:79]
	v_addc_co_u32_e64 v81, s[0:1], 0, v83, s[0:1]
	s_nop 5
	global_load_dwordx4 v[76:79], v[134:135], off
	s_nop 0
	global_load_dwordx4 v[80:83], v[80:81], off
	ds_read2_b32 v[134:135], v136 offset0:72 offset1:76
	v_add_f32_e32 v124, v167, v124
	v_min_f32_e32 v137, 0, v124
	v_mul_f32_e64 v124, |v124|, s55
	v_exp_f32_e32 v124, v124
	v_add_f32_e32 v126, v167, v126
	v_mul_f32_e64 v133, |v126|, s55
	v_exp_f32_e32 v133, v133
	v_add_f32_e32 v124, 1.0, v124
	v_log_f32_e32 v124, v124
	s_waitcnt lgkmcnt(0)
	v_mfma_f32_16x16x4_f32 v[128:131], v134, v165, v[128:131]
	v_add_f32_e32 v133, 1.0, v133
	v_min_f32_e32 v139, 0, v126
	v_fmac_f32_e32 v137, 0xbf317218, v124
	v_log_f32_e32 v124, v133
	v_add_f32_e32 v134, v167, v127
	v_add_f32_e32 v125, v167, v125
	v_mul_f32_e64 v132, |v125|, s55
	v_fmac_f32_e32 v139, 0xbf317218, v124
	v_mul_f32_e64 v124, |v134|, s55
	v_min_f32_e32 v138, 0, v125
	v_exp_f32_e32 v140, v124
	v_mfma_f32_16x16x4_f32 v[124:127], v135, v166, v[128:131]
	v_exp_f32_e32 v132, v132
	v_add_f32_e32 v129, 1.0, v140
	v_log_f32_e32 v129, v129
	v_add_f32_e32 v132, 1.0, v132
	v_log_f32_e32 v132, v132
	v_min_f32_e32 v140, 0, v134
	s_nop 3
	v_add_f32_e32 v124, v167, v124
	v_mul_f32_e64 v128, |v124|, s55
	v_fmac_f32_e32 v138, 0xbf317218, v132
	v_exp_f32_e32 v128, v128
	ds_read2_b32 v[132:133], v136 offset0:128 offset1:132
	v_min_f32_e32 v141, 0, v124
	v_fmac_f32_e32 v140, 0xbf317218, v129
	v_add_f32_e32 v128, 1.0, v128
	v_log_f32_e32 v128, v128
	ds_read2_b32 v[134:135], v136 offset0:136 offset1:140
	v_add_f32_e32 v124, v167, v125
	v_mul_f32_e64 v125, |v124|, s55
	v_fmac_f32_e32 v141, 0xbf317218, v128
	s_waitcnt lgkmcnt(1)
	v_mfma_f32_16x16x4_f32 v[128:131], v132, v155, 0
	v_add_f32_e32 v132, v167, v126
	v_exp_f32_e32 v125, v125
	v_mul_f32_e64 v126, |v132|, s55
	v_exp_f32_e32 v126, v126
	v_min_f32_e32 v142, 0, v124
	v_add_f32_e32 v124, 1.0, v125
	v_add_f32_e32 v144, v167, v127
	v_mfma_f32_16x16x4_f32 v[128:131], v133, v164, v[128:131]
	v_log_f32_e32 v133, v124
	v_add_f32_e32 v124, 1.0, v126
	v_log_f32_e32 v143, v124
	v_mul_f32_e64 v145, |v144|, s55
	v_fmac_f32_e32 v142, 0xbf317218, v133
	s_waitcnt lgkmcnt(0)
	v_mfma_f32_16x16x4_f32 v[124:127], v134, v165, v[128:131]
	s_nop 2
	v_exp_f32_e32 v128, v145
	v_min_f32_e32 v145, 0, v132
	ds_read2_b32 v[132:133], v136 offset0:192 offset1:196
	v_fmac_f32_e32 v145, 0xbf317218, v143
	v_add_f32_e32 v128, 1.0, v128
	v_log_f32_e32 v128, v128
	v_min_f32_e32 v143, 0, v144
	v_mfma_f32_16x16x4_f32 v[124:127], v135, v166, v[124:127]
	v_fmac_f32_e32 v143, 0xbf317218, v128
	s_nop 8
	v_add_f32_e32 v124, v167, v124
	v_mul_f32_e64 v128, |v124|, s55
	v_exp_f32_e32 v134, v128
	s_waitcnt lgkmcnt(0)
	v_mfma_f32_16x16x4_f32 v[128:131], v132, v155, 0
	v_add_f32_e32 v125, v167, v125
	v_mul_f32_e64 v135, |v125|, s55
	v_exp_f32_e32 v132, v135
	v_min_f32_e32 v144, 0, v124
	v_add_f32_e32 v124, 1.0, v134
	ds_read2_b32 v[134:135], v136 offset0:200 offset1:204
	v_add_f32_e32 v132, 1.0, v132
	v_mfma_f32_16x16x4_f32 v[128:131], v133, v164, v[128:131]
	v_log_f32_e32 v132, v132
	v_log_f32_e32 v124, v124
	v_min_f32_e32 v133, 0, v125
	v_add_f32_e32 v146, v167, v127
	v_fmac_f32_e32 v133, 0xbf317218, v132
	v_add_f32_e32 v132, v167, v126
	v_fmac_f32_e32 v144, 0xbf317218, v124
	v_mul_f32_e64 v124, |v132|, s55
	v_exp_f32_e32 v136, v124
	s_waitcnt lgkmcnt(0)
	v_mfma_f32_16x16x4_f32 v[124:127], v134, v165, v[128:131]
	v_mul_f32_e64 v128, |v146|, s55
	v_exp_f32_e32 v128, v128
	v_add_f32_e32 v130, 1.0, v136
	v_log_f32_e32 v130, v130
	v_min_f32_e32 v129, 0, v132
	v_add_f32_e32 v128, 1.0, v128
	v_log_f32_e32 v128, v128
	v_mfma_f32_16x16x4_f32 v[124:127], v135, v166, v[124:127]
	v_fmac_f32_e32 v129, 0xbf317218, v130
	v_min_f32_e32 v130, 0, v146
	v_fmac_f32_e32 v130, 0xbf317218, v128
	s_nop 6
	v_add_f32_e32 v124, v167, v124
	v_mul_f32_e64 v131, |v124|, s55
	v_exp_f32_e32 v131, v131
	v_add_f32_e32 v125, v167, v125
	v_min_f32_e32 v124, 0, v124
	v_add_f32_e32 v126, v167, v126
	v_add_f32_e32 v128, 1.0, v131
	v_mul_f32_e64 v131, |v125|, s55
	v_log_f32_e32 v128, v128
	v_exp_f32_e32 v131, v131
	v_add_f32_e32 v127, v167, v127
	v_mul_f32_e64 v132, |v127|, s55
	v_fmac_f32_e32 v124, 0xbf317218, v128
	v_add_f32_e32 v128, 1.0, v131
	v_mul_f32_e64 v131, |v126|, s55
	v_log_f32_e32 v128, v128
	v_exp_f32_e32 v131, v131
	v_exp_f32_e32 v132, v132
	v_min_f32_e32 v125, 0, v125
	v_fmac_f32_e32 v125, 0xbf317218, v128
	v_add_f32_e32 v128, 1.0, v131
	v_add_f32_e32 v131, 1.0, v132
	v_log_f32_e32 v131, v131
	v_log_f32_e32 v128, v128
	v_min_f32_e32 v127, 0, v127
	v_min_f32_e32 v126, 0, v126
	v_fmac_f32_e32 v127, 0xbf317218, v131
	v_fmac_f32_e32 v126, 0xbf317218, v128
	v_fma_f32 v127, v127, s56, 0
	v_fmamk_f32 v126, v126, 0x3d800000, v127
	v_fmamk_f32 v125, v125, 0x3d800000, v126
	v_fmamk_f32 v124, v124, 0x3d800000, v125
	v_fmamk_f32 v128, v130, 0x3d800000, v124
	v_fmamk_f32 v129, v129, 0x3d800000, v128
	v_fmamk_f32 v130, v133, 0x3d800000, v129
	v_fmamk_f32 v131, v144, 0x3d800000, v130
	v_fmamk_f32 v132, v143, 0x3d800000, v131
	v_fmamk_f32 v133, v145, 0x3d800000, v132
	v_fmamk_f32 v134, v142, 0x3d800000, v133
	v_fmamk_f32 v135, v141, 0x3d800000, v134
	v_fmamk_f32 v136, v140, 0x3d800000, v135
	v_fmamk_f32 v139, v139, 0x3d800000, v136
	v_fmamk_f32 v138, v138, 0x3d800000, v139
	v_fmamk_f32 v137, v137, 0x3d800000, v138
	ds_bpermute_b32 v140, v174, v137
	ds_bpermute_b32 v141, v173, v137
	ds_bpermute_b32 v142, v172, v137
	s_waitcnt lgkmcnt(2)
	v_cndmask_b32_e64 v140, v140, 0, s[2:3]
	s_waitcnt lgkmcnt(1)
	v_cndmask_b32_e64 v141, 0, v141, s[4:5]
	v_add_f32_e32 v140, v141, v140
	s_waitcnt lgkmcnt(0)
	v_cndmask_b32_e64 v141, 0, v142, s[6:7]
	v_add_f32_e32 v140, v141, v140
	v_add_f32_e32 v137, v140, v137
	v_add_f32_e32 v138, v140, v138
	v_add_f32_e32 v124, v140, v124
	v_add_f32_e32 v125, v140, v125
	ds_write2st64_b32 v184, v137, v138 offset0:24 offset1:26
	v_add_f32_e32 v137, v140, v139
	v_add_f32_e32 v136, v140, v136
	v_add_f32_e32 v135, v140, v135
	v_add_f32_e32 v134, v140, v134
	v_add_f32_e32 v133, v140, v133
	v_add_f32_e32 v132, v140, v132
	v_add_f32_e32 v131, v140, v131
	v_add_f32_e32 v130, v140, v130
	v_add_f32_e32 v129, v140, v129
	v_add_f32_e32 v128, v140, v128
	ds_write2st64_b32 v184, v124, v125 offset0:48 offset1:50
	v_add_f32_e32 v124, v140, v126
	v_add_f32_e32 v125, v140, v127
	ds_write2st64_b32 v184, v137, v136 offset0:28 offset1:30
	ds_write2st64_b32 v184, v135, v134 offset0:32 offset1:34
	ds_write2st64_b32 v184, v133, v132 offset0:36 offset1:38
	ds_write2st64_b32 v184, v131, v130 offset0:40 offset1:42
	ds_write2st64_b32 v184, v129, v128 offset0:44 offset1:46
	ds_write2st64_b32 v184, v124, v125 offset0:52 offset1:54
	s_waitcnt lgkmcnt(0)
	s_barrier
	s_and_saveexec_b64 s[0:1], s[8:9]
	s_cbranch_execz .LBB0_582
	ds_read_b32 v124, v175 offset:6144
	v_lshl_add_u32 v125, s59, 9, v175
	s_waitcnt lgkmcnt(0)
	v_mul_f32_e32 v255, 0x3fb8aa3b, v124
	v_exp_f32_e32 v255, v255
	s_nop 0
	ds_write_b32 v125, v255 offset:4096

.LBB0_663:
	ds_read_b128 v[134:137], v201 offset:6144
	ds_read_b128 v[138:141], v201 offset:6160
	s_waitcnt vmcnt(6)
	v_lshlrev_b32_e32 v144, 16, v98
	v_and_b32_e32 v145, 0xffff0000, v98
	v_add_u32_e32 v215, 0x9800, v212
	s_waitcnt lgkmcnt(1)
	v_mul_f32_e32 v109, 0xbfb8aa3b, v134
	v_exp_f32_e32 v142, v109
	v_mul_f32_e32 v109, 0xbfb8aa3b, v135
	v_exp_f32_e32 v143, v109
	v_mul_f32_e32 v109, 0xbfb8aa3b, v136
	v_cvt_pk_bf16_f32 v156, v10, v11
	v_cvt_pk_bf16_f32 v157, v12, v13
	v_pk_mul_f32 v[142:143], v[142:143], v[144:145]
	v_lshlrev_b32_e32 v144, 16, v99
	v_cvt_pk_bf16_f32 v98, v142, v143
	v_exp_f32_e32 v142, v109
	v_mul_f32_e32 v109, 0xbfb8aa3b, v137
	v_exp_f32_e32 v143, v109
	v_and_b32_e32 v145, 0xffff0000, v99
	s_waitcnt lgkmcnt(0)
	v_mul_f32_e32 v109, 0xbfb8aa3b, v138
	v_cvt_pk_bf16_f32 v158, v26, v27
	v_pk_mul_f32 v[142:143], v[142:143], v[144:145]
	v_lshlrev_b32_e32 v144, 16, v100
	v_cvt_pk_bf16_f32 v99, v142, v143
	v_exp_f32_e32 v142, v109
	v_mul_f32_e32 v109, 0xbfb8aa3b, v139
	v_exp_f32_e32 v143, v109
	v_and_b32_e32 v145, 0xffff0000, v100
	v_mul_f32_e32 v109, 0xbfb8aa3b, v140
	v_cvt_pk_bf16_f32 v159, v28, v29
	v_pk_mul_f32 v[142:143], v[142:143], v[144:145]
	v_lshlrev_b32_e32 v144, 16, v101
	v_cvt_pk_bf16_f32 v100, v142, v143
	v_exp_f32_e32 v142, v109
	v_mul_f32_e32 v109, 0xbfb8aa3b, v141
	v_exp_f32_e32 v143, v109
	v_and_b32_e32 v145, 0xffff0000, v101
	v_add_u32_e32 v216, 0xa800, v212
	v_add_u32_e32 v217, 0xb800, v212
	v_pk_mul_f32 v[142:143], v[142:143], v[144:145]
	v_add_u32_e32 v218, 0xc800, v212
	v_cvt_pk_bf16_f32 v101, v142, v143
	ds_write_b128 v181, v[98:101] offset:56320
	v_mul_f32_e32 v98, 0x3fb8aa3b, v134
	v_mul_f32_e32 v99, 0x3fb8aa3b, v135
	v_exp_f32_e32 v98, v98
	v_exp_f32_e32 v99, v99
	v_lshlrev_b32_e32 v100, 16, v94
	v_and_b32_e32 v101, 0xffff0000, v94
	s_mov_b32 s62, 0x8000
	v_pk_mul_f32 v[98:99], v[98:99], s[50:51] op_sel_hi:[1,0]
	s_add_u32 s76, s76, 0x60000
	v_pk_mul_f32 v[98:99], v[98:99], v[100:101]
	v_lshlrev_b32_e32 v100, 16, v95
	v_cvt_pk_bf16_f32 v94, v98, v99
	v_mul_f32_e32 v98, 0x3fb8aa3b, v136
	v_mul_f32_e32 v99, 0x3fb8aa3b, v137
	v_exp_f32_e32 v98, v98
	v_exp_f32_e32 v99, v99
	v_and_b32_e32 v101, 0xffff0000, v95
	s_waitcnt vmcnt(4)
	v_lshlrev_b32_e32 v136, 16, v90
	v_and_b32_e32 v137, 0xffff0000, v90
	v_pk_mul_f32 v[98:99], v[98:99], s[50:51] op_sel_hi:[1,0]
	s_addc_u32 s77, s77, 0
	v_pk_mul_f32 v[98:99], v[98:99], v[100:101]
	v_lshlrev_b32_e32 v100, 16, v96
	v_cvt_pk_bf16_f32 v95, v98, v99
	v_mul_f32_e32 v98, 0x3fb8aa3b, v138
	v_mul_f32_e32 v99, 0x3fb8aa3b, v139
	v_exp_f32_e32 v98, v98
	v_exp_f32_e32 v99, v99
	v_and_b32_e32 v101, 0xffff0000, v96
	s_add_i32 s64, s64, 64
	v_pk_mul_f32 v[98:99], v[98:99], s[50:51] op_sel_hi:[1,0]
	s_nop 0
	v_pk_mul_f32 v[98:99], v[98:99], v[100:101]
	v_lshlrev_b32_e32 v100, 16, v97
	v_cvt_pk_bf16_f32 v96, v98, v99
	v_mul_f32_e32 v98, 0x3fb8aa3b, v140
	v_mul_f32_e32 v99, 0x3fb8aa3b, v141
	v_exp_f32_e32 v98, v98
	v_exp_f32_e32 v99, v99
	v_and_b32_e32 v101, 0xffff0000, v97
	v_pk_mul_f32 v[98:99], v[98:99], s[50:51] op_sel_hi:[1,0]
	s_nop 0
	v_pk_mul_f32 v[98:99], v[98:99], v[100:101]
	s_nop 0
	v_cvt_pk_bf16_f32 v97, v98, v99
	ds_write_b128 v181, v[94:97] offset:38912
	ds_read_b128 v[94:97], v202 offset:6144
	ds_read_b128 v[98:101], v202 offset:6160
	s_waitcnt lgkmcnt(1)
	v_mul_f32_e32 v109, 0xbfb8aa3b, v94
	v_exp_f32_e32 v134, v109
	v_mul_f32_e32 v109, 0xbfb8aa3b, v95
	v_exp_f32_e32 v135, v109
	v_mul_f32_e32 v109, 0xbfb8aa3b, v96
	v_pk_mul_f32 v[134:135], v[134:135], v[136:137]
	s_nop 0
	v_cvt_pk_bf16_f32 v90, v134, v135
	v_exp_f32_e32 v134, v109
	v_mul_f32_e32 v109, 0xbfb8aa3b, v97
	v_exp_f32_e32 v135, v109
	v_lshlrev_b32_e32 v136, 16, v91
	v_and_b32_e32 v137, 0xffff0000, v91
	s_waitcnt lgkmcnt(0)
	v_mul_f32_e32 v109, 0xbfb8aa3b, v98
	v_pk_mul_f32 v[134:135], v[134:135], v[136:137]
	v_lshlrev_b32_e32 v136, 16, v92
	v_cvt_pk_bf16_f32 v91, v134, v135
	v_exp_f32_e32 v134, v109
	v_mul_f32_e32 v109, 0xbfb8aa3b, v99
	v_exp_f32_e32 v135, v109
	v_and_b32_e32 v137, 0xffff0000, v92
	v_mul_f32_e32 v109, 0xbfb8aa3b, v100
	v_pk_mul_f32 v[134:135], v[134:135], v[136:137]
	s_nop 0
	v_cvt_pk_bf16_f32 v92, v134, v135
	v_exp_f32_e32 v134, v109
	v_mul_f32_e32 v109, 0xbfb8aa3b, v101
	v_exp_f32_e32 v135, v109
	v_lshlrev_b32_e32 v136, 16, v93
	v_and_b32_e32 v137, 0xffff0000, v93
	v_pk_mul_f32 v[134:135], v[134:135], v[136:137]
	s_nop 0
	v_cvt_pk_bf16_f32 v93, v134, v135
	ds_write_b128 v182, v[90:93] offset:56320
	v_mul_f32_e32 v90, 0x3fb8aa3b, v94
	v_mul_f32_e32 v91, 0x3fb8aa3b, v95
	v_exp_f32_e32 v90, v90
	v_exp_f32_e32 v91, v91
	v_lshlrev_b32_e32 v92, 16, v70
	v_and_b32_e32 v93, 0xffff0000, v70
	v_pk_mul_f32 v[90:91], v[90:91], s[50:51] op_sel_hi:[1,0]
	s_nop 0
	v_pk_mul_f32 v[90:91], v[90:91], v[92:93]
	v_lshlrev_b32_e32 v92, 16, v71
	v_cvt_pk_bf16_f32 v70, v90, v91
	v_mul_f32_e32 v90, 0x3fb8aa3b, v96
	v_mul_f32_e32 v91, 0x3fb8aa3b, v97
	v_exp_f32_e32 v90, v90
	v_exp_f32_e32 v91, v91
	v_and_b32_e32 v93, 0xffff0000, v71
	v_pk_mul_f32 v[90:91], v[90:91], s[50:51] op_sel_hi:[1,0]
	s_nop 0
	v_pk_mul_f32 v[90:91], v[90:91], v[92:93]
	v_lshlrev_b32_e32 v92, 16, v72
	v_cvt_pk_bf16_f32 v71, v90, v91
	v_mul_f32_e32 v90, 0x3fb8aa3b, v98
	v_mul_f32_e32 v91, 0x3fb8aa3b, v99
	v_exp_f32_e32 v90, v90
	v_exp_f32_e32 v91, v91
	v_and_b32_e32 v93, 0xffff0000, v72
	v_pk_mul_f32 v[90:91], v[90:91], s[50:51] op_sel_hi:[1,0]
	s_nop 0
	v_pk_mul_f32 v[90:91], v[90:91], v[92:93]
	v_lshlrev_b32_e32 v92, 16, v73
	v_cvt_pk_bf16_f32 v72, v90, v91
	v_mul_f32_e32 v90, 0x3fb8aa3b, v100
	v_mul_f32_e32 v91, 0x3fb8aa3b, v101
	v_exp_f32_e32 v90, v90
	v_exp_f32_e32 v91, v91
	v_and_b32_e32 v93, 0xffff0000, v73
	v_pk_mul_f32 v[90:91], v[90:91], s[50:51] op_sel_hi:[1,0]
	s_nop 0
	v_pk_mul_f32 v[90:91], v[90:91], v[92:93]
	s_nop 0
	v_cvt_pk_bf16_f32 v73, v90, v91
	ds_write_b128 v182, v[70:73] offset:38912
	s_waitcnt vmcnt(3)
	ds_write_b128 v203, v[74:77]
	s_waitcnt vmcnt(2)
	ds_write_b128 v204, v[78:81]
	s_waitcnt vmcnt(1)
	ds_write_b128 v203, v[82:85] offset:16896
	s_waitcnt vmcnt(0)
	ds_write_b128 v205, v[86:89]
	s_waitcnt lgkmcnt(0)
	s_barrier
	ds_read_b128 v[70:73], v206 offset:56320
	ds_read_b128 v[74:77], v180 offset:38912
	ds_read_b128 v[78:81], v206 offset:56384
	ds_read_b128 v[82:85], v180 offset:38976
	s_waitcnt lgkmcnt(2)
	v_mfma_f32_16x16x32_bf16 v[70:73], v[70:73], v[74:77], 0
	s_waitcnt lgkmcnt(0)
	v_mfma_f32_16x16x32_bf16 v[70:73], v[78:81], v[82:85], v[70:73]
	ds_read_b128 v[78:81], v206 offset:56448
	ds_read_b128 v[86:89], v180 offset:39040
	s_waitcnt lgkmcnt(0)
	v_mfma_f32_16x16x32_bf16 v[70:73], v[78:81], v[86:89], v[70:73]
	ds_read_b128 v[78:81], v206 offset:56512
	ds_read_b128 v[90:93], v180 offset:39104
	s_waitcnt lgkmcnt(0)
	v_mfma_f32_16x16x32_bf16 v[70:73], v[78:81], v[90:93], v[70:73]
	v_mov_b32_e32 v78, s49
	s_nop 6
	v_cndmask_b32_e64 v78, v70, v78, s[12:13]
	v_cndmask_b32_e64 v70, v78, v70, s[14:15]
	v_cndmask_b32_e64 v71, 0, v71, s[14:15]
	v_cndmask_b32_e64 v72, v72, 0, s[16:17]
	v_cndmask_b32_e64 v73, v73, 0, s[18:19]
	v_cvt_pk_bf16_f32 v70, v70, v71
	v_cvt_pk_bf16_f32 v71, v72, v73
	ds_write_b64 v207, v[70:71]
	ds_read_b128 v[70:73], v208 offset:56320
	s_waitcnt lgkmcnt(0)
	v_mfma_f32_16x16x32_bf16 v[70:73], v[70:73], v[74:77], 0
	ds_read_b128 v[74:77], v208 offset:56384
	s_waitcnt lgkmcnt(0)
	v_mfma_f32_16x16x32_bf16 v[70:73], v[74:77], v[82:85], v[70:73]
	ds_read_b128 v[74:77], v208 offset:56448
	s_waitcnt lgkmcnt(0)
	v_mfma_f32_16x16x32_bf16 v[70:73], v[74:77], v[86:89], v[70:73]
	ds_read_b128 v[74:77], v208 offset:56512
	s_waitcnt lgkmcnt(0)
	v_mfma_f32_16x16x32_bf16 v[70:73], v[74:77], v[90:93], v[70:73]
	v_mov_b32_e32 v74, s49
	s_nop 6
	v_cndmask_b32_e64 v74, v70, v74, s[20:21]
	v_cndmask_b32_e64 v70, v74, v70, s[22:23]
	v_cndmask_b32_e64 v71, 0, v71, s[22:23]
	v_cndmask_b32_e64 v72, v72, 0, s[24:25]
	v_cndmask_b32_e64 v73, v73, 0, s[26:27]
	v_cvt_pk_bf16_f32 v70, v70, v71
	v_cvt_pk_bf16_f32 v71, v72, v73
	ds_write_b64 v209, v[70:71]
	s_waitcnt lgkmcnt(0)
	s_barrier
	ds_read_b64_tr_b16 v[80:81], v210 offset:2112
	ds_read_b64_tr_b16 v[78:79], v210
	ds_read_b64_tr_b16 v[82:83], v210 offset:32
	ds_read_b64_tr_b16 v[70:71], v210 offset:16896
	ds_read_b64_tr_b16 v[72:73], v210 offset:19008
	ds_read_b64_tr_b16 v[84:85], v210 offset:2144
	ds_read_b64_tr_b16 v[74:75], v210 offset:16928
	ds_read_b64_tr_b16 v[76:77], v210 offset:19040
	ds_read_b128 v[86:89], v211
	ds_read_b128 v[94:97], v211 offset:64
	ds_read_b128 v[134:137], v211 offset:2368
	s_waitcnt lgkmcnt(2)
	v_mfma_f32_16x16x32_bf16 v[90:93], v[78:81], v[86:89], 0
	ds_read_b128 v[142:145], v211 offset:4672
	ds_read_b128 v[150:153], v211 offset:6976
	ds_read2_b64 v[160:163], v215 offset1:4
	v_mfma_f32_16x16x32_bf16 v[86:89], v[82:85], v[86:89], 0
	s_waitcnt lgkmcnt(4)
	v_mfma_f32_16x16x32_bf16 v[90:93], v[70:73], v[94:97], v[90:93]
	v_mfma_f32_16x16x32_bf16 v[86:89], v[74:77], v[94:97], v[86:89]
	ds_read_b128 v[94:97], v211 offset:2304
	s_waitcnt lgkmcnt(0)
	v_mfma_f32_16x16x32_bf16 v[98:101], v[78:81], v[94:97], 0
	v_mfma_f32_16x16x32_bf16 v[94:97], v[82:85], v[94:97], 0
	v_mfma_f32_16x16x32_bf16 v[98:101], v[70:73], v[134:137], v[98:101]
	v_mfma_f32_16x16x32_bf16 v[94:97], v[74:77], v[134:137], v[94:97]
	ds_read_b128 v[134:137], v211 offset:4608
	s_waitcnt lgkmcnt(0)
	v_mfma_f32_16x16x32_bf16 v[138:141], v[78:81], v[134:137], 0
	v_mfma_f32_16x16x32_bf16 v[134:137], v[82:85], v[134:137], 0
	v_mfma_f32_16x16x32_bf16 v[138:141], v[70:73], v[142:145], v[138:141]
	v_mfma_f32_16x16x32_bf16 v[134:137], v[74:77], v[142:145], v[134:137]
	ds_read_b128 v[142:145], v211 offset:6912
	s_waitcnt lgkmcnt(0)
	v_mfma_f32_16x16x32_bf16 v[146:149], v[78:81], v[142:145], 0
	v_mfma_f32_16x16x32_bf16 v[142:145], v[82:85], v[142:145], 0
	v_mfma_f32_16x16x32_bf16 v[146:149], v[70:73], v[150:153], v[146:149]
	v_mfma_f32_16x16x32_bf16 v[142:145], v[74:77], v[150:153], v[142:145]
	v_cvt_pk_bf16_f32 v150, v6, v7
	v_cvt_pk_bf16_f32 v151, v8, v9
	v_cvt_pk_bf16_f32 v152, v22, v23
	v_cvt_pk_bf16_f32 v153, v24, v25
	v_mfma_f32_16x16x32_bf16 v[86:89], v[156:159], v[160:163], v[86:89]
	s_nop 0
	v_mfma_f32_16x16x32_bf16 v[90:93], v[150:153], v[160:163], v[90:93]
	ds_read2_b64 v[160:163], v216 offset0:32 offset1:36
	s_waitcnt lgkmcnt(0)
	v_mfma_f32_16x16x32_bf16 v[98:101], v[150:153], v[160:163], v[98:101]
	v_mfma_f32_16x16x32_bf16 v[94:97], v[156:159], v[160:163], v[94:97]
	ds_read2_b64 v[160:163], v217 offset0:64 offset1:68
	s_waitcnt lgkmcnt(0)
	v_mfma_f32_16x16x32_bf16 v[138:141], v[150:153], v[160:163], v[138:141]
	v_mfma_f32_16x16x32_bf16 v[134:137], v[156:159], v[160:163], v[134:137]
	ds_read2_b64 v[160:163], v218 offset0:96 offset1:100
	s_waitcnt lgkmcnt(0)
	v_mfma_f32_16x16x32_bf16 v[146:149], v[150:153], v[160:163], v[146:149]
	v_cvt_pk_bf16_f32 v150, v14, v15
	v_cvt_pk_bf16_f32 v151, v16, v17
	v_cvt_pk_bf16_f32 v152, v38, v39
	v_mfma_f32_16x16x32_bf16 v[142:145], v[156:159], v[160:163], v[142:145]
	v_cvt_pk_bf16_f32 v153, v40, v41
	v_cvt_pk_bf16_f32 v156, v18, v19
	v_cvt_pk_bf16_f32 v157, v20, v21
	v_cvt_pk_bf16_f32 v158, v42, v43
	v_cvt_pk_bf16_f32 v159, v44, v45
	ds_read2_b64 v[160:163], v215 offset0:8 offset1:12
	s_waitcnt lgkmcnt(0)
	v_mfma_f32_16x16x32_bf16 v[90:93], v[150:153], v[160:163], v[90:93]
	v_mfma_f32_16x16x32_bf16 v[86:89], v[156:159], v[160:163], v[86:89]
	ds_read2_b64 v[160:163], v216 offset0:40 offset1:44
	s_waitcnt lgkmcnt(0)
	v_mfma_f32_16x16x32_bf16 v[98:101], v[150:153], v[160:163], v[98:101]
	v_mfma_f32_16x16x32_bf16 v[94:97], v[156:159], v[160:163], v[94:97]
	ds_read2_b64 v[160:163], v217 offset0:72 offset1:76
	s_waitcnt lgkmcnt(0)
	v_mfma_f32_16x16x32_bf16 v[138:141], v[150:153], v[160:163], v[138:141]
	v_mfma_f32_16x16x32_bf16 v[134:137], v[156:159], v[160:163], v[134:137]
	ds_read2_b64 v[160:163], v218 offset0:104 offset1:108
	s_waitcnt lgkmcnt(0)
	v_mfma_f32_16x16x32_bf16 v[146:149], v[150:153], v[160:163], v[146:149]
	v_cvt_pk_bf16_f32 v150, v30, v31
	v_cvt_pk_bf16_f32 v151, v32, v33
	v_cvt_pk_bf16_f32 v152, v46, v47
	v_mfma_f32_16x16x32_bf16 v[142:145], v[156:159], v[160:163], v[142:145]
	v_cvt_pk_bf16_f32 v153, v48, v49
	v_cvt_pk_bf16_f32 v156, v34, v35
	v_cvt_pk_bf16_f32 v157, v36, v37
	v_cvt_pk_bf16_f32 v158, v54, v55
	v_cvt_pk_bf16_f32 v159, v56, v57
	ds_read2_b64 v[160:163], v215 offset0:16 offset1:20
	s_waitcnt lgkmcnt(0)
	v_mfma_f32_16x16x32_bf16 v[90:93], v[150:153], v[160:163], v[90:93]
	v_mfma_f32_16x16x32_bf16 v[86:89], v[156:159], v[160:163], v[86:89]
	ds_read2_b64 v[160:163], v216 offset0:48 offset1:52
	s_waitcnt lgkmcnt(0)
	v_mfma_f32_16x16x32_bf16 v[98:101], v[150:153], v[160:163], v[98:101]
	v_mfma_f32_16x16x32_bf16 v[94:97], v[156:159], v[160:163], v[94:97]
	ds_read2_b64 v[160:163], v217 offset0:80 offset1:84
	s_waitcnt lgkmcnt(0)
	v_mfma_f32_16x16x32_bf16 v[138:141], v[150:153], v[160:163], v[138:141]
	v_mfma_f32_16x16x32_bf16 v[134:137], v[156:159], v[160:163], v[134:137]
	ds_read2_b64 v[160:163], v218 offset0:112 offset1:116
	s_waitcnt lgkmcnt(0)
	v_mfma_f32_16x16x32_bf16 v[146:149], v[150:153], v[160:163], v[146:149]
	v_cvt_pk_bf16_f32 v150, v50, v51
	v_cvt_pk_bf16_f32 v151, v52, v53
	v_cvt_pk_bf16_f32 v152, v62, v63
	v_mfma_f32_16x16x32_bf16 v[142:145], v[156:159], v[160:163], v[142:145]
	v_cvt_pk_bf16_f32 v153, v64, v65
	v_cvt_pk_bf16_f32 v156, v58, v59
	v_cvt_pk_bf16_f32 v157, v60, v61
	v_cvt_pk_bf16_f32 v158, v66, v67
	v_cvt_pk_bf16_f32 v159, v68, v69
	ds_read2_b64 v[160:163], v215 offset0:24 offset1:28
	s_waitcnt lgkmcnt(0)
	v_mfma_f32_16x16x32_bf16 v[90:93], v[150:153], v[160:163], v[90:93]
	v_mfma_f32_16x16x32_bf16 v[86:89], v[156:159], v[160:163], v[86:89]
	ds_read2_b64 v[160:163], v216 offset0:56 offset1:60
	s_nop 5
	v_cvt_pk_bf16_f32 v90, v90, v91
	v_cvt_pk_bf16_f32 v91, v92, v93
	s_waitcnt lgkmcnt(0)
	v_mfma_f32_16x16x32_bf16 v[98:101], v[150:153], v[160:163], v[98:101]
	v_lshl_add_u64 v[92:93], s[74:75], 0, v[116:117]
	v_cvt_pk_bf16_f32 v86, v86, v87
	v_cvt_pk_bf16_f32 v87, v88, v89
	v_mfma_f32_16x16x32_bf16 v[94:97], v[156:159], v[160:163], v[94:97]
	ds_read2_b64 v[160:163], v217 offset0:88 offset1:92
	v_add_co_u32_e32 v88, vcc, s62, v92
	s_waitcnt lgkmcnt(0)
	v_mfma_f32_16x16x32_bf16 v[138:141], v[150:153], v[160:163], v[138:141]
	global_store_dwordx2 v[92:93], v[86:87], off offset:32
	v_cvt_pk_bf16_f32 v86, v98, v99
	v_cvt_pk_bf16_f32 v87, v100, v101
	v_mfma_f32_16x16x32_bf16 v[134:137], v[156:159], v[160:163], v[134:137]
	ds_read2_b64 v[160:163], v218 offset0:120 offset1:124
	v_addc_co_u32_e32 v89, vcc, 0, v93, vcc
	global_store_dwordx2 v[88:89], v[86:87], off
	v_cvt_pk_bf16_f32 v86, v94, v95
	v_cvt_pk_bf16_f32 v87, v96, v97
	s_mov_b32 s62, 0x10000
	s_waitcnt lgkmcnt(0)
	v_mfma_f32_16x16x32_bf16 v[146:149], v[150:153], v[160:163], v[146:149]
	global_store_dwordx2 v[88:89], v[86:87], off offset:32
	v_add_co_u32_e32 v88, vcc, s62, v92
	v_mfma_f32_16x16x32_bf16 v[142:145], v[156:159], v[160:163], v[142:145]
	v_cvt_pk_bf16_f32 v86, v138, v139
	v_cvt_pk_bf16_f32 v87, v140, v141
	v_addc_co_u32_e32 v89, vcc, 0, v93, vcc
	global_store_dwordx2 v[88:89], v[86:87], off
	v_cvt_pk_bf16_f32 v86, v134, v135
	v_cvt_pk_bf16_f32 v87, v136, v137
	global_store_dwordx2 v[88:89], v[86:87], off offset:32
	v_add_co_u32_e32 v88, vcc, s81, v92
	v_cvt_pk_bf16_f32 v86, v146, v147
	v_cvt_pk_bf16_f32 v87, v148, v149
	v_addc_co_u32_e32 v89, vcc, 0, v93, vcc
	global_store_dwordx2 v[88:89], v[86:87], off
	v_cvt_pk_bf16_f32 v86, v142, v143
	v_cvt_pk_bf16_f32 v87, v144, v145
	global_store_dwordx2 v[92:93], v[90:91], off
	global_store_dwordx2 v[88:89], v[86:87], off offset:32
	ds_read_b64_tr_b16 v[88:89], v213 offset:57408
	ds_read_b64_tr_b16 v[86:87], v213 offset:56320
	ds_read_b64_tr_b16 v[90:91], v213 offset:56352
	s_waitcnt lgkmcnt(1)
	v_mfma_f32_16x16x32_bf16 v[6:9], v[86:89], v[78:81], v[6:9]
	s_add_u32 s74, s74, 0x20000
	s_addc_u32 s75, s75, 0
	s_add_i32 s92, s92, 1
	v_mfma_f32_16x16x32_bf16 v[10:13], v[86:89], v[82:85], v[10:13]
	ds_read_b64_tr_b16 v[86:87], v213 offset:65024
	ds_read_b64_tr_b16 v[88:89], v214 offset:57408
	ds_read_b64_tr_b16 v[94:95], v214 offset:57440
	ds_read_b64_tr_b16 v[92:93], v213 offset:57440
	s_cmp_lg_u32 s76, 0x300000
	s_waitcnt lgkmcnt(2)
	v_mfma_f32_16x16x32_bf16 v[6:9], v[86:89], v[70:73], v[6:9]
	v_mfma_f32_16x16x32_bf16 v[10:13], v[86:89], v[74:77], v[10:13]
	s_waitcnt lgkmcnt(0)
	v_mfma_f32_16x16x32_bf16 v[22:25], v[90:93], v[78:81], v[22:25]
	v_mfma_f32_16x16x32_bf16 v[26:29], v[90:93], v[82:85], v[26:29]
	ds_read_b64_tr_b16 v[92:93], v213 offset:65056
	ds_read_b64_tr_b16 v[86:87], v213 offset:56384
	ds_read_b64_tr_b16 v[88:89], v213 offset:57472
	s_waitcnt lgkmcnt(0)
	v_mfma_f32_16x16x32_bf16 v[14:17], v[86:89], v[78:81], v[14:17]
	v_mfma_f32_16x16x32_bf16 v[18:21], v[86:89], v[82:85], v[18:21]
	ds_read_b64_tr_b16 v[86:87], v213 offset:65088
	ds_read_b64_tr_b16 v[88:89], v214 offset:57472
	s_waitcnt lgkmcnt(0)
	v_mfma_f32_16x16x32_bf16 v[14:17], v[86:89], v[70:73], v[14:17]
	v_mfma_f32_16x16x32_bf16 v[18:21], v[86:89], v[74:77], v[18:21]
	ds_read_b64_tr_b16 v[86:87], v213 offset:56416
	ds_read_b64_tr_b16 v[88:89], v213 offset:57504
	s_waitcnt lgkmcnt(0)
	v_mfma_f32_16x16x32_bf16 v[38:41], v[86:89], v[78:81], v[38:41]
	v_mfma_f32_16x16x32_bf16 v[42:45], v[86:89], v[82:85], v[42:45]
	ds_read_b64_tr_b16 v[86:87], v213 offset:65120
	ds_read_b64_tr_b16 v[88:89], v214 offset:57504
	s_waitcnt lgkmcnt(0)
	v_mfma_f32_16x16x32_bf16 v[38:41], v[86:89], v[70:73], v[38:41]
	v_mfma_f32_16x16x32_bf16 v[42:45], v[86:89], v[74:77], v[42:45]
	ds_read_b64_tr_b16 v[86:87], v213 offset:56448
	ds_read_b64_tr_b16 v[88:89], v213 offset:57536
	s_waitcnt lgkmcnt(0)
	v_mfma_f32_16x16x32_bf16 v[30:33], v[86:89], v[78:81], v[30:33]
	v_mfma_f32_16x16x32_bf16 v[34:37], v[86:89], v[82:85], v[34:37]
	ds_read_b64_tr_b16 v[86:87], v213 offset:65152
	ds_read_b64_tr_b16 v[88:89], v214 offset:57536
	s_waitcnt lgkmcnt(0)
	v_mfma_f32_16x16x32_bf16 v[30:33], v[86:89], v[70:73], v[30:33]
	v_mfma_f32_16x16x32_bf16 v[34:37], v[86:89], v[74:77], v[34:37]
	ds_read_b64_tr_b16 v[86:87], v213 offset:56480
	ds_read_b64_tr_b16 v[88:89], v213 offset:57568
	s_waitcnt lgkmcnt(0)
	v_mfma_f32_16x16x32_bf16 v[46:49], v[86:89], v[78:81], v[46:49]
	v_mfma_f32_16x16x32_bf16 v[54:57], v[86:89], v[82:85], v[54:57]
	ds_read_b64_tr_b16 v[86:87], v213 offset:65184
	ds_read_b64_tr_b16 v[88:89], v214 offset:57568
	s_waitcnt lgkmcnt(0)
	v_mfma_f32_16x16x32_bf16 v[46:49], v[86:89], v[70:73], v[46:49]
	v_mfma_f32_16x16x32_bf16 v[54:57], v[86:89], v[74:77], v[54:57]
	ds_read_b64_tr_b16 v[86:87], v213 offset:56512
	ds_read_b64_tr_b16 v[88:89], v213 offset:57600
	s_waitcnt lgkmcnt(0)
	v_mfma_f32_16x16x32_bf16 v[50:53], v[86:89], v[78:81], v[50:53]
	v_mfma_f32_16x16x32_bf16 v[58:61], v[86:89], v[82:85], v[58:61]
	ds_read_b64_tr_b16 v[86:87], v213 offset:65216
	ds_read_b64_tr_b16 v[88:89], v214 offset:57600
	s_waitcnt lgkmcnt(0)
	v_mfma_f32_16x16x32_bf16 v[50:53], v[86:89], v[70:73], v[50:53]
	v_mfma_f32_16x16x32_bf16 v[58:61], v[86:89], v[74:77], v[58:61]
	ds_read_b64_tr_b16 v[86:87], v213 offset:56544
	ds_read_b64_tr_b16 v[88:89], v213 offset:57632
	s_waitcnt lgkmcnt(0)
	v_mfma_f32_16x16x32_bf16 v[62:65], v[86:89], v[78:81], v[62:65]
	ds_read_b64_tr_b16 v[78:79], v213 offset:65248
	ds_read_b64_tr_b16 v[80:81], v214 offset:57632
	v_mfma_f32_16x16x32_bf16 v[66:69], v[86:89], v[82:85], v[66:69]
	v_mfma_f32_16x16x32_bf16 v[22:25], v[92:95], v[70:73], v[22:25]
	s_waitcnt lgkmcnt(0)
	v_mfma_f32_16x16x32_bf16 v[62:65], v[78:81], v[70:73], v[62:65]
	v_lshl_add_u32 v70, s93, 9, v179
	v_mfma_f32_16x16x32_bf16 v[26:29], v[92:95], v[74:77], v[26:29]
	v_mfma_f32_16x16x32_bf16 v[66:69], v[78:81], v[74:77], v[66:69]
	ds_read_b128 v[72:75], v70 offset:4096
	s_waitcnt lgkmcnt(0)
	s_nop 0
	v_mov_b32_e32 v72, v72
	s_nop 0
	v_mov_b32_e32 v73, v73
	s_nop 0
	v_mov_b32_e32 v74, v74
	s_nop 0
	v_mov_b32_e32 v75, v75
	v_pk_mul_f32 v[6:7], v[6:7], v[72:73]
	v_pk_mul_f32 v[10:11], v[10:11], v[72:73]
	v_pk_mul_f32 v[8:9], v[8:9], v[74:75]
	v_pk_mul_f32 v[12:13], v[12:13], v[74:75]
	ds_read_b128 v[72:75], v70 offset:4160
	s_waitcnt lgkmcnt(0)
	s_nop 0
	v_mov_b32_e32 v72, v72
	s_nop 0
	v_mov_b32_e32 v73, v73
	s_nop 0
	v_mov_b32_e32 v74, v74
	s_nop 0
	v_mov_b32_e32 v75, v75
	v_pk_mul_f32 v[22:23], v[22:23], v[72:73]
	v_pk_mul_f32 v[26:27], v[26:27], v[72:73]
	v_pk_mul_f32 v[24:25], v[24:25], v[74:75]
	v_pk_mul_f32 v[28:29], v[28:29], v[74:75]
	ds_read_b128 v[72:75], v70 offset:4224
	s_waitcnt lgkmcnt(0)
	s_nop 0
	v_mov_b32_e32 v72, v72
	s_nop 0
	v_mov_b32_e32 v73, v73
	s_nop 0
	v_mov_b32_e32 v74, v74
	s_nop 0
	v_mov_b32_e32 v75, v75
	v_pk_mul_f32 v[14:15], v[14:15], v[72:73]
	v_pk_mul_f32 v[18:19], v[18:19], v[72:73]
	v_pk_mul_f32 v[16:17], v[16:17], v[74:75]
	v_pk_mul_f32 v[20:21], v[20:21], v[74:75]
	ds_read_b128 v[72:75], v70 offset:4288
	s_waitcnt lgkmcnt(0)
	s_nop 0
	v_mov_b32_e32 v72, v72
	s_nop 0
	v_mov_b32_e32 v73, v73
	s_nop 0
	v_mov_b32_e32 v74, v74
	s_nop 0
	v_mov_b32_e32 v75, v75
	v_pk_mul_f32 v[38:39], v[38:39], v[72:73]
	v_pk_mul_f32 v[42:43], v[42:43], v[72:73]
	v_pk_mul_f32 v[40:41], v[40:41], v[74:75]
	v_pk_mul_f32 v[44:45], v[44:45], v[74:75]
	ds_read_b128 v[72:75], v70 offset:4352
	s_waitcnt lgkmcnt(0)
	s_nop 0
	v_mov_b32_e32 v72, v72
	s_nop 0
	v_mov_b32_e32 v73, v73
	s_nop 0
	v_mov_b32_e32 v74, v74
	s_nop 0
	v_mov_b32_e32 v75, v75
	v_pk_mul_f32 v[30:31], v[30:31], v[72:73]
	v_pk_mul_f32 v[34:35], v[34:35], v[72:73]
	v_pk_mul_f32 v[32:33], v[32:33], v[74:75]
	v_pk_mul_f32 v[36:37], v[36:37], v[74:75]
	ds_read_b128 v[72:75], v70 offset:4416
	s_waitcnt lgkmcnt(0)
	s_nop 0
	v_mov_b32_e32 v72, v72
	s_nop 0
	v_mov_b32_e32 v73, v73
	s_nop 0
	v_mov_b32_e32 v74, v74
	s_nop 0
	v_mov_b32_e32 v75, v75
	v_pk_mul_f32 v[46:47], v[46:47], v[72:73]
	v_pk_mul_f32 v[54:55], v[54:55], v[72:73]
	v_pk_mul_f32 v[48:49], v[48:49], v[74:75]
	v_pk_mul_f32 v[56:57], v[56:57], v[74:75]
	ds_read_b128 v[72:75], v70 offset:4480
	s_waitcnt lgkmcnt(0)
	s_nop 0
	v_mov_b32_e32 v72, v72
	s_nop 0
	v_mov_b32_e32 v73, v73
	s_nop 0
	v_mov_b32_e32 v74, v74
	s_nop 0
	v_mov_b32_e32 v75, v75
	v_pk_mul_f32 v[50:51], v[50:51], v[72:73]
	v_pk_mul_f32 v[58:59], v[58:59], v[72:73]
	ds_read_b128 v[70:73], v70 offset:4544
	v_pk_mul_f32 v[52:53], v[52:53], v[74:75]
	v_pk_mul_f32 v[60:61], v[60:61], v[74:75]
	s_waitcnt lgkmcnt(0)
	s_nop 0
	s_nop 0
	s_nop 0
	s_nop 0
	s_nop 0
	s_nop 0
	s_nop 0
	s_nop 0
	v_pk_mul_f32 v[62:63], v[62:63], v[70:71]
	v_pk_mul_f32 v[66:67], v[66:67], v[70:71]
	v_pk_mul_f32 v[64:65], v[64:65], v[72:73]
	v_pk_mul_f32 v[68:69], v[68:69], v[72:73]
	s_cbranch_scc0 .LBB0_672
.LBB0_664:
	s_add_u32 s62, s61, s76
	s_addc_u32 s63, s91, s77
	v_lshl_add_u64 v[70:71], s[62:63], 0, v[112:113]
	s_add_u32 s62, s55, s76
	s_addc_u32 s63, s57, s77
	s_add_u32 s62, s62, s68
	v_add_co_u32_e32 v74, vcc, s95, v70
	s_addc_u32 s63, s63, 0
	s_nop 0
	v_addc_co_u32_e32 v75, vcc, 0, v71, vcc
	v_lshl_add_u64 v[86:87], s[62:63], 0, v[114:115]
	v_add_co_u32_e32 v78, vcc, s81, v86
	s_and_b32 s93, s92, 1
	s_add_i32 s69, s66, 0xf0
	v_addc_co_u32_e32 v79, vcc, 0, v87, vcc
	s_cmp_eq_u32 s93, 0
	v_add_co_u32_e32 v82, vcc, s95, v86
	s_cselect_b64 s[78:79], -1, 0
	s_nop 0
	v_addc_co_u32_e32 v83, vcc, 0, v87, vcc
	s_and_b64 s[62:63], s[78:79], exec
	global_load_dwordx4 v[94:97], v[70:71], off
	global_load_dwordx4 v[98:101], v[70:71], off offset:1024
	s_nop 0
	global_load_dwordx4 v[70:73], v[74:75], off
	global_load_dwordx4 v[90:93], v[74:75], off offset:1024
	s_cselect_b32 s62, 0xf0, s69
	global_load_dwordx4 v[74:77], v[86:87], off
	v_add_co_u32_e32 v86, vcc, s96, v86
	v_add3_u32 v137, s62, v177, v175
	s_nop 0
	v_addc_co_u32_e32 v87, vcc, 0, v87, vcc
	global_load_dwordx4 v[78:81], v[78:79], off
	s_nop 0
	global_load_dwordx4 v[82:85], v[82:83], off
	s_nop 0
	global_load_dwordx4 v[86:89], v[86:87], off
	ds_read2_b32 v[134:135], v137 offset1:4
	ds_read2_b32 v[142:143], v137 offset0:8 offset1:12
	s_waitcnt lgkmcnt(1)
	v_mfma_f32_16x16x4_f32 v[138:141], v134, v104, 0
	ds_read2_b32 v[146:147], v137 offset0:128 offset1:132
	v_mfma_f32_16x16x4_f32 v[138:141], v135, v105, v[138:141]
	s_waitcnt lgkmcnt(1)
	v_mfma_f32_16x16x4_f32 v[138:141], v142, v106, v[138:141]
	v_mfma_f32_16x16x4_f32 v[138:141], v143, v107, v[138:141]
	ds_read2_b32 v[142:143], v137 offset0:64 offset1:68
	s_nop 8
	v_add_f32_e32 v134, v108, v138
	v_min_f32_e32 v109, 0, v134
	v_mul_f32_e64 v134, |v134|, s97
	v_exp_f32_e32 v134, v134
	v_add_f32_e32 v135, v108, v139
	v_add_f32_e32 v136, v108, v140
	v_add_f32_e32 v138, v108, v141
	v_add_f32_e32 v134, 1.0, v134
	v_log_f32_e32 v134, v134
	s_nop 0
	v_fmac_f32_e32 v109, 0xbf317218, v134
	v_min_f32_e32 v134, 0, v135
	v_mul_f32_e64 v135, |v135|, s97
	v_exp_f32_e32 v135, v135
	v_fma_f32 v109, v109, s0, 0
	v_add_f32_e32 v135, 1.0, v135
	v_log_f32_e32 v135, v135
	s_nop 0
	v_fmac_f32_e32 v134, 0xbf317218, v135
	v_min_f32_e32 v135, 0, v136
	v_mul_f32_e64 v136, |v136|, s97
	v_exp_f32_e32 v136, v136
	v_fmamk_f32 v134, v134, 0x3d800000, v109
	v_add_f32_e32 v136, 1.0, v136
	v_log_f32_e32 v136, v136
	s_nop 0
	v_fmac_f32_e32 v135, 0xbf317218, v136
	v_min_f32_e32 v136, 0, v138
	v_mul_f32_e64 v138, |v138|, s97
	v_exp_f32_e32 v138, v138
	v_fmamk_f32 v135, v135, 0x3d800000, v134
	v_add_f32_e32 v138, 1.0, v138
	v_log_f32_e32 v138, v138
	s_nop 0
	v_fmac_f32_e32 v136, 0xbf317218, v138
	s_waitcnt lgkmcnt(0)
	v_mfma_f32_16x16x4_f32 v[138:141], v142, v104, 0
	v_fmamk_f32 v136, v136, 0x3d800000, v135
	v_mfma_f32_16x16x4_f32 v[138:141], v143, v105, v[138:141]
	ds_read2_b32 v[142:143], v137 offset0:72 offset1:76
	s_waitcnt lgkmcnt(0)
	v_mfma_f32_16x16x4_f32 v[138:141], v142, v106, v[138:141]
	v_mfma_f32_16x16x4_f32 v[138:141], v143, v107, v[138:141]
	s_nop 9
	v_add_f32_e32 v142, v108, v138
	v_min_f32_e32 v138, 0, v142
	v_mul_f32_e64 v142, |v142|, s97
	v_exp_f32_e32 v142, v142
	s_nop 0
	v_add_f32_e32 v142, 1.0, v142
	v_log_f32_e32 v142, v142
	s_nop 0
	v_fmac_f32_e32 v138, 0xbf317218, v142
	v_add_f32_e32 v142, v108, v139
	v_min_f32_e32 v139, 0, v142
	v_mul_f32_e64 v142, |v142|, s97
	v_exp_f32_e32 v142, v142
	s_nop 0
	v_add_f32_e32 v142, 1.0, v142
	v_log_f32_e32 v142, v142
	s_nop 0
	v_fmac_f32_e32 v139, 0xbf317218, v142
	v_add_f32_e32 v142, v108, v140
	v_min_f32_e32 v140, 0, v142
	v_mul_f32_e64 v142, |v142|, s97
	v_exp_f32_e32 v142, v142
	s_nop 0
	v_add_f32_e32 v142, 1.0, v142
	v_log_f32_e32 v142, v142
	s_nop 0
	v_fmac_f32_e32 v140, 0xbf317218, v142
	v_add_f32_e32 v142, v108, v141
	v_min_f32_e32 v141, 0, v142
	v_mul_f32_e64 v142, |v142|, s97
	v_exp_f32_e32 v142, v142
	s_nop 0
	v_add_f32_e32 v142, 1.0, v142
	v_log_f32_e32 v142, v142
	s_nop 0
	v_fmac_f32_e32 v141, 0xbf317218, v142
	v_mfma_f32_16x16x4_f32 v[142:145], v146, v104, 0
	v_mfma_f32_16x16x4_f32 v[142:145], v147, v105, v[142:145]
	ds_read2_b32 v[146:147], v137 offset0:136 offset1:140
	s_waitcnt lgkmcnt(0)
	v_mfma_f32_16x16x4_f32 v[142:145], v146, v106, v[142:145]
	v_mfma_f32_16x16x4_f32 v[142:145], v147, v107, v[142:145]
	ds_read2_b32 v[146:147], v137 offset0:192 offset1:196
	s_nop 8
	v_add_f32_e32 v142, v108, v142
	v_min_f32_e32 v148, 0, v142
	v_mul_f32_e64 v142, |v142|, s97
	v_exp_f32_e32 v142, v142
	s_nop 0
	v_add_f32_e32 v142, 1.0, v142
	v_log_f32_e32 v142, v142
	s_nop 0
	v_fmac_f32_e32 v148, 0xbf317218, v142
	v_add_f32_e32 v142, v108, v143
	v_min_f32_e32 v149, 0, v142
	v_mul_f32_e64 v142, |v142|, s97
	v_exp_f32_e32 v142, v142
	s_nop 0
	v_add_f32_e32 v142, 1.0, v142
	v_log_f32_e32 v142, v142
	s_nop 0
	v_fmac_f32_e32 v149, 0xbf317218, v142
	v_add_f32_e32 v142, v108, v144
	v_min_f32_e32 v150, 0, v142
	v_mul_f32_e64 v142, |v142|, s97
	v_exp_f32_e32 v142, v142
	s_nop 0
	v_add_f32_e32 v142, 1.0, v142
	v_log_f32_e32 v142, v142
	s_nop 0
	v_fmac_f32_e32 v150, 0xbf317218, v142
	v_add_f32_e32 v142, v108, v145
	v_min_f32_e32 v151, 0, v142
	v_mul_f32_e64 v142, |v142|, s97
	v_exp_f32_e32 v142, v142
	s_nop 0
	v_add_f32_e32 v142, 1.0, v142
	v_log_f32_e32 v142, v142
	s_nop 0
	v_fmac_f32_e32 v151, 0xbf317218, v142
	s_waitcnt lgkmcnt(0)
	v_mfma_f32_16x16x4_f32 v[142:145], v146, v104, 0
	v_mfma_f32_16x16x4_f32 v[142:145], v147, v105, v[142:145]
	ds_read2_b32 v[146:147], v137 offset0:200 offset1:204
	s_waitcnt lgkmcnt(0)
	v_mfma_f32_16x16x4_f32 v[142:145], v146, v106, v[142:145]
	v_mfma_f32_16x16x4_f32 v[142:145], v147, v107, v[142:145]
	s_nop 9
	v_add_f32_e32 v137, v108, v142
	v_min_f32_e32 v142, 0, v137
	v_mul_f32_e64 v137, |v137|, s97
	v_exp_f32_e32 v137, v137
	s_nop 0
	v_add_f32_e32 v137, 1.0, v137
	v_log_f32_e32 v137, v137
	s_nop 0
	v_fmac_f32_e32 v142, 0xbf317218, v137
	v_add_f32_e32 v137, v108, v143
	v_min_f32_e32 v143, 0, v137
	v_mul_f32_e64 v137, |v137|, s97
	v_exp_f32_e32 v137, v137
	s_nop 0
	v_add_f32_e32 v137, 1.0, v137
	v_log_f32_e32 v137, v137
	s_nop 0
	v_fmac_f32_e32 v143, 0xbf317218, v137
	v_add_f32_e32 v137, v108, v144
	v_min_f32_e32 v144, 0, v137
	v_mul_f32_e64 v137, |v137|, s97
	v_exp_f32_e32 v137, v137
	s_nop 0
	v_add_f32_e32 v137, 1.0, v137
	v_log_f32_e32 v137, v137
	s_nop 0
	v_fmac_f32_e32 v144, 0xbf317218, v137
	v_add_f32_e32 v137, v108, v145
	v_min_f32_e32 v145, 0, v137
	v_mul_f32_e64 v137, |v137|, s97
	v_exp_f32_e32 v137, v137
	s_nop 0
	v_add_f32_e32 v137, 1.0, v137
	v_log_f32_e32 v137, v137
	s_nop 0
	v_fmac_f32_e32 v145, 0xbf317218, v137
	v_fmamk_f32 v137, v138, 0x3d800000, v136
	v_fmamk_f32 v138, v139, 0x3d800000, v137
	v_fmamk_f32 v139, v140, 0x3d800000, v138
	v_fmamk_f32 v140, v141, 0x3d800000, v139
	v_fmamk_f32 v141, v148, 0x3d800000, v140
	v_fmamk_f32 v146, v149, 0x3d800000, v141
	v_fmamk_f32 v147, v150, 0x3d800000, v146
	v_fmamk_f32 v148, v151, 0x3d800000, v147
	v_fmamk_f32 v142, v142, 0x3d800000, v148
	v_fmamk_f32 v143, v143, 0x3d800000, v142
	v_fmamk_f32 v144, v144, 0x3d800000, v143
	v_fmamk_f32 v145, v145, 0x3d800000, v144
	ds_bpermute_b32 v149, v186, v145
	ds_bpermute_b32 v150, v187, v145
	ds_bpermute_b32 v151, v188, v145
	s_waitcnt lgkmcnt(2)
	v_cndmask_b32_e64 v149, v149, 0, s[4:5]
	s_waitcnt lgkmcnt(1)
	v_cndmask_b32_e64 v150, 0, v150, s[6:7]
	v_add_f32_e32 v149, v149, v150
	s_waitcnt lgkmcnt(0)
	v_cndmask_b32_e64 v150, 0, v151, s[8:9]
	v_add_f32_e32 v149, v149, v150
	v_add_f32_e32 v109, v109, v149
	v_add_f32_e32 v134, v134, v149
	ds_write2st64_b32 v200, v109, v134 offset0:24 offset1:26
	v_add_f32_e32 v109, v135, v149
	v_add_f32_e32 v134, v136, v149
	ds_write2st64_b32 v200, v109, v134 offset0:28 offset1:30
	v_add_f32_e32 v109, v137, v149
	v_add_f32_e32 v134, v138, v149
	ds_write2st64_b32 v200, v109, v134 offset0:32 offset1:34
	v_add_f32_e32 v109, v139, v149
	v_add_f32_e32 v134, v140, v149
	ds_write2st64_b32 v200, v109, v134 offset0:36 offset1:38
	v_add_f32_e32 v109, v141, v149
	v_add_f32_e32 v134, v146, v149
	ds_write2st64_b32 v200, v109, v134 offset0:40 offset1:42
	v_add_f32_e32 v109, v149, v147
	v_add_f32_e32 v134, v149, v148
	ds_write2st64_b32 v200, v109, v134 offset0:44 offset1:46
	v_add_f32_e32 v109, v149, v142
	v_add_f32_e32 v134, v149, v143
	ds_write2st64_b32 v200, v109, v134 offset0:48 offset1:50
	v_add_f32_e32 v109, v149, v144
	v_add_f32_e32 v134, v149, v145
	ds_write2st64_b32 v200, v109, v134 offset0:52 offset1:54
	s_waitcnt lgkmcnt(0)
	s_barrier
	s_and_saveexec_b64 s[62:63], s[10:11]
	s_cbranch_execz .LBB0_666
	ds_read_b32 v109, v178 offset:38400
	v_lshl_add_u32 v134, s93, 9, v178
	s_waitcnt lgkmcnt(0)
	v_mul_f32_e32 v255, 0x3fb8aa3b, v109
	v_exp_f32_e32 v255, v255
	s_nop 0
	ds_write_b32 v134, v255 offset:4096

.LBB0_679:
	s_or_b64 exec, exec, s[62:63]
	s_waitcnt lgkmcnt(0)
	s_barrier
	ds_read_b128 v[136:139], v184
	ds_read_b128 v[142:145], v184 offset:16
	s_waitcnt vmcnt(8)
	v_lshlrev_b32_e32 v156, 16, v166
	v_and_b32_e32 v157, 0xffff0000, v166
	v_lshlrev_b32_e32 v166, 16, v167
	s_waitcnt lgkmcnt(1)
	v_mov_b32_e32 v81, v138
	v_lshlrev_b32_e32 v138, 16, v168
	v_mov_b32_e32 v80, v137
	v_mov_b32_e32 v137, v139
	v_and_b32_e32 v139, 0xffff0000, v168
	v_mul_f32_e32 v0, 0xbfb8aa3b, v138
	v_pk_add_f32 v[80:81], v[80:81], v[136:137]
	s_waitcnt lgkmcnt(0)
	v_mov_b32_e32 v136, v144
	v_exp_f32_e32 v0, v0
	v_mul_f32_e32 v144, 0xbfb8aa3b, v139
	v_exp_f32_e32 v144, v144
	v_mov_b32_e32 v137, v142
	v_mov_b32_e32 v142, v145
	v_add_f32_e32 v0, 1.0, v0
	v_pk_add_f32 v[146:147], v[136:137], v[142:143]
	v_rcp_f32_e32 v136, v0
	v_add_f32_e32 v0, 1.0, v144
	v_lshlrev_b32_e32 v142, 16, v169
	v_rcp_f32_e32 v137, v0
	v_and_b32_e32 v143, 0xffff0000, v169
	v_mul_f32_e32 v0, 0xbfb8aa3b, v142
	v_exp_f32_e32 v0, v0
	v_mul_f32_e32 v144, 0xbfb8aa3b, v143
	v_exp_f32_e32 v144, v144
	v_pk_mul_f32 v[148:149], v[136:137], v[138:139]
	v_add_f32_e32 v0, 1.0, v0
	v_rcp_f32_e32 v136, v0
	v_add_f32_e32 v0, 1.0, v144
	v_rcp_f32_e32 v137, v0
	v_mul_f32_e32 v0, 0xbfb8aa3b, v156
	v_exp_f32_e32 v0, v0
	v_mul_f32_e32 v138, 0xbfb8aa3b, v157
	v_exp_f32_e32 v138, v138
	v_and_b32_e32 v167, 0xffff0000, v167
	v_add_f32_e32 v0, 1.0, v0
	v_rcp_f32_e32 v224, v0
	v_add_f32_e32 v0, 1.0, v138
	v_rcp_f32_e32 v225, v0
	v_mul_f32_e32 v0, 0xbfb8aa3b, v166
	v_pk_mul_f32 v[168:169], v[136:137], v[142:143]
	v_exp_f32_e32 v0, v0
	v_mul_f32_e32 v136, 0xbfb8aa3b, v167
	v_exp_f32_e32 v142, v136
	ds_read_b128 v[136:139], v184 offset:512
	v_add_f32_e32 v0, 1.0, v0
	v_rcp_f32_e32 v226, v0
	v_add_f32_e32 v0, 1.0, v142
	ds_read_b128 v[142:145], v184 offset:528
	s_waitcnt lgkmcnt(1)
	v_mov_b32_e32 v228, v137
	v_mov_b32_e32 v229, v138
	v_mov_b32_e32 v137, v139
	v_pk_add_f32 v[136:137], v[228:229], v[136:137]
	s_waitcnt lgkmcnt(0)
	v_mov_b32_e32 v138, v144
	v_mov_b32_e32 v139, v142
	v_mov_b32_e32 v142, v145
	v_pk_add_f32 v[138:139], v[138:139], v[142:143]
	v_mov_b32_e32 v142, v136
	v_mov_b32_e32 v143, v80
	v_mov_b32_e32 v80, v137
	v_pk_add_f32 v[80:81], v[142:143], v[80:81]
	v_mov_b32_e32 v136, v139
	v_mov_b32_e32 v137, v147
	v_pk_add_f32 v[80:81], v[80:81], v[136:137]
	v_mov_b32_e32 v139, v146
	s_mov_b32 s62, 0x358637bd
	v_pk_add_f32 v[136:137], v[138:139], v[80:81]
	v_mov_b64_e32 v[80:81], s[62:63]
	v_pk_fma_f32 v[136:137], v[136:137], s[52:53], v[80:81] op_sel_hi:[1,0,0]
	v_rcp_f32_e32 v227, v0
	v_mul_f32_e32 v0, 0x4b800000, v137
	v_cmp_gt_f32_e32 vcc, s1, v137
	v_pk_mul_f32 v[142:143], v[224:225], v[156:157]
	v_pk_mul_f32 v[144:145], v[226:227], v[166:167]
	v_cndmask_b32_e32 v0, v137, v0, vcc
	v_rsq_f32_e32 v0, v0
	v_lshl_add_u64 v[138:139], s[56:57], 0, v[116:117]
	s_waitcnt vmcnt(4)
	v_lshlrev_b32_e32 v146, 16, v159
	v_and_b32_e32 v147, 0xffff0000, v159
	v_mul_f32_e32 v137, 0x45800000, v0
	v_cndmask_b32_e32 v0, v0, v137, vcc
	v_pk_mul_f32 v[106:107], v[106:107], v[0:1] op_sel_hi:[1,0]
	v_pk_mul_f32 v[108:109], v[108:109], v[0:1] op_sel_hi:[1,0]
	v_pk_mul_f32 v[102:103], v[102:103], v[0:1] op_sel_hi:[1,0]
	v_pk_mul_f32 v[104:105], v[104:105], v[0:1] op_sel_hi:[1,0]
	v_mul_f32_e32 v0, 0x4b800000, v136
	v_cmp_gt_f32_e32 vcc, s1, v136
	s_waitcnt vmcnt(0)
	v_pk_mul_f32 v[102:103], v[70:71], v[102:103]
	v_pk_mul_f32 v[104:105], v[72:73], v[104:105]
	v_cndmask_b32_e32 v0, v136, v0, vcc
	v_pk_mul_f32 v[102:103], v[142:143], v[102:103]
	v_pk_mul_f32 v[104:105], v[144:145], v[104:105]
	v_rsq_f32_e32 v0, v0
	v_cvt_pk_bf16_f32 v102, v102, v103
	v_cvt_pk_bf16_f32 v103, v104, v105
	global_store_dwordx2 v[138:139], v[102:103], off offset:32
	v_lshlrev_b32_e32 v102, 16, v164
	v_mul_f32_e32 v103, 0xbfb8aa3b, v102
	v_exp_f32_e32 v104, v103
	v_mul_f32_e32 v103, 0x45800000, v0
	v_cndmask_b32_e32 v0, v0, v103, vcc
	v_and_b32_e32 v103, 0xffff0000, v164
	v_mul_f32_e32 v105, 0xbfb8aa3b, v103
	v_exp_f32_e32 v105, v105
	v_pk_mul_f32 v[106:107], v[74:75], v[106:107]
	v_pk_mul_f32 v[108:109], v[76:77], v[108:109]
	v_pk_mul_f32 v[106:107], v[148:149], v[106:107]
	v_pk_mul_f32 v[108:109], v[168:169], v[108:109]
	v_cvt_pk_bf16_f32 v106, v106, v107
	v_cvt_pk_bf16_f32 v107, v108, v109
	v_lshlrev_b32_e32 v108, 16, v165
	v_and_b32_e32 v109, 0xffff0000, v165
	v_add_f32_e32 v104, 1.0, v104
	v_add_f32_e32 v105, 1.0, v105
	v_mul_f32_e32 v136, 0xbfb8aa3b, v108
	v_mul_f32_e32 v137, 0xbfb8aa3b, v109
	v_rcp_f32_e32 v104, v104
	v_rcp_f32_e32 v105, v105
	v_exp_f32_e32 v136, v136
	v_exp_f32_e32 v137, v137
	global_store_dwordx2 v[138:139], v[106:107], off
	v_pk_mul_f32 v[102:103], v[104:105], v[102:103]
	v_add_f32_e32 v104, 1.0, v136
	v_add_f32_e32 v105, 1.0, v137
	v_rcp_f32_e32 v104, v104
	v_rcp_f32_e32 v105, v105
	v_pk_mul_f32 v[106:107], v[152:153], v[0:1] op_sel_hi:[1,0]
	v_pk_mul_f32 v[100:101], v[100:101], v[0:1] op_sel_hi:[1,0]
	v_pk_mul_f32 v[106:107], v[74:75], v[106:107]
	v_pk_mul_f32 v[100:101], v[76:77], v[100:101]
	v_pk_mul_f32 v[104:105], v[104:105], v[108:109]
	v_pk_mul_f32 v[102:103], v[102:103], v[106:107]
	v_pk_mul_f32 v[100:101], v[104:105], v[100:101]
	v_cvt_pk_bf16_f32 v102, v102, v103
	v_cvt_pk_bf16_f32 v103, v100, v101
	v_lshlrev_b32_e32 v100, 16, v162
	v_mul_f32_e32 v101, 0xbfb8aa3b, v100
	v_exp_f32_e32 v106, v101
	v_lshl_add_u64 v[104:105], s[56:57], 0, v[120:121]
	v_and_b32_e32 v101, 0xffff0000, v162
	global_store_dwordx2 v[104:105], v[102:103], off
	v_mul_f32_e32 v103, 0xbfb8aa3b, v101
	v_exp_f32_e32 v103, v103
	v_lshlrev_b32_e32 v104, 16, v163
	v_and_b32_e32 v105, 0xffff0000, v163
	v_add_f32_e32 v102, 1.0, v106
	v_add_f32_e32 v103, 1.0, v103
	v_mul_f32_e32 v106, 0xbfb8aa3b, v104
	v_mul_f32_e32 v107, 0xbfb8aa3b, v105
	v_rcp_f32_e32 v102, v102
	v_rcp_f32_e32 v103, v103
	v_exp_f32_e32 v106, v106
	v_exp_f32_e32 v107, v107
	v_pk_mul_f32 v[98:99], v[98:99], v[0:1] op_sel_hi:[1,0]
	v_pk_mul_f32 v[100:101], v[102:103], v[100:101]
	v_add_f32_e32 v102, 1.0, v106
	v_add_f32_e32 v103, 1.0, v107
	v_rcp_f32_e32 v102, v102
	v_rcp_f32_e32 v103, v103
	v_pk_mul_f32 v[98:99], v[70:71], v[98:99]
	v_pk_mul_f32 v[96:97], v[96:97], v[0:1] op_sel_hi:[1,0]
	v_pk_mul_f32 v[98:99], v[100:101], v[98:99]
	v_pk_mul_f32 v[96:97], v[72:73], v[96:97]
	v_pk_mul_f32 v[100:101], v[102:103], v[104:105]
	v_cvt_pk_bf16_f32 v102, v98, v99
	v_pk_mul_f32 v[100:101], v[100:101], v[96:97]
	ds_read_b128 v[96:99], v184 offset:1024
	v_cvt_pk_bf16_f32 v103, v100, v101
	v_lshl_add_u64 v[100:101], s[56:57], 0, v[122:123]
	global_store_dwordx2 v[100:101], v[102:103], off
	ds_read_b128 v[100:103], v184 offset:1040
	s_waitcnt lgkmcnt(1)
	v_mov_b32_e32 v105, v98
	v_lshlrev_b32_e32 v98, 16, v160
	v_mov_b32_e32 v104, v97
	v_mov_b32_e32 v97, v99
	v_and_b32_e32 v99, 0xffff0000, v160
	v_mul_f32_e32 v0, 0xbfb8aa3b, v98
	v_pk_add_f32 v[104:105], v[104:105], v[96:97]
	v_exp_f32_e32 v0, v0
	v_mul_f32_e32 v97, 0xbfb8aa3b, v99
	s_waitcnt lgkmcnt(0)
	v_mov_b32_e32 v96, v102
	v_exp_f32_e32 v102, v97
	v_lshlrev_b32_e32 v108, 16, v161
	v_mov_b32_e32 v97, v100
	v_add_f32_e32 v0, 1.0, v0
	v_and_b32_e32 v109, 0xffff0000, v161
	v_mul_f32_e32 v100, 0xbfb8aa3b, v108
	v_rcp_f32_e32 v106, v0
	v_add_f32_e32 v0, 1.0, v102
	v_exp_f32_e32 v100, v100
	v_mul_f32_e32 v102, 0xbfb8aa3b, v109
	v_exp_f32_e32 v102, v102
	v_rcp_f32_e32 v107, v0
	v_add_f32_e32 v0, 1.0, v100
	v_rcp_f32_e32 v136, v0
	v_add_f32_e32 v0, 1.0, v102
	v_rcp_f32_e32 v137, v0
	v_mov_b32_e32 v100, v103
	v_pk_add_f32 v[138:139], v[96:97], v[100:101]
	v_pk_mul_f32 v[106:107], v[106:107], v[98:99]
	v_pk_mul_f32 v[108:109], v[136:137], v[108:109]
	v_lshlrev_b32_e32 v136, 16, v158
	v_and_b32_e32 v137, 0xffff0000, v158
	v_mul_f32_e32 v0, 0xbfb8aa3b, v136
	v_exp_f32_e32 v0, v0
	v_mul_f32_e32 v96, 0xbfb8aa3b, v137
	v_exp_f32_e32 v96, v96
	v_lshl_add_u64 v[142:143], s[56:57], 0, v[124:125]
	v_add_f32_e32 v0, 1.0, v0
	v_rcp_f32_e32 v144, v0
	v_add_f32_e32 v0, 1.0, v96
	v_rcp_f32_e32 v145, v0
	v_mul_f32_e32 v0, 0xbfb8aa3b, v146
	v_exp_f32_e32 v0, v0
	v_mul_f32_e32 v96, 0xbfb8aa3b, v147
	v_exp_f32_e32 v100, v96
	ds_read_b128 v[96:99], v184 offset:1536
	v_add_f32_e32 v0, 1.0, v0
	v_rcp_f32_e32 v148, v0
	v_add_f32_e32 v0, 1.0, v100
	ds_read_b128 v[100:103], v184 offset:1552
	s_waitcnt lgkmcnt(1)
	v_mov_b32_e32 v152, v97
	v_mov_b32_e32 v153, v98
	v_mov_b32_e32 v97, v99
	v_pk_add_f32 v[96:97], v[152:153], v[96:97]
	s_waitcnt lgkmcnt(0)
	v_mov_b32_e32 v98, v102
	v_mov_b32_e32 v99, v100
	v_mov_b32_e32 v100, v103
	v_pk_add_f32 v[98:99], v[98:99], v[100:101]
	v_mov_b32_e32 v100, v96
	v_mov_b32_e32 v101, v104
	v_mov_b32_e32 v104, v97
	v_pk_add_f32 v[96:97], v[100:101], v[104:105]
	v_mov_b32_e32 v100, v99
	v_mov_b32_e32 v101, v139
	v_pk_add_f32 v[96:97], v[96:97], v[100:101]
	v_mov_b32_e32 v99, v138
	v_pk_add_f32 v[96:97], v[98:99], v[96:97]
	v_rcp_f32_e32 v149, v0
	v_pk_fma_f32 v[80:81], v[96:97], s[52:53], v[80:81] op_sel_hi:[1,0,0]
	v_pk_mul_f32 v[96:97], v[144:145], v[136:137]
	v_mul_f32_e32 v0, 0x4b800000, v81
	v_cmp_gt_f32_e32 vcc, s1, v81
	v_pk_mul_f32 v[152:153], v[148:149], v[146:147]
	v_lshl_add_u64 v[168:169], s[56:57], 0, v[126:127]
	v_cndmask_b32_e32 v0, v81, v0, vcc
	v_rsq_f32_e32 v0, v0
	s_add_i32 s75, s75, 1
	s_add_u32 s60, s60, 0xfffa0000
	s_addc_u32 s61, s61, -1
	v_mul_f32_e32 v81, 0x45800000, v0
	v_cndmask_b32_e32 v0, v0, v81, vcc
	v_pk_mul_f32 v[90:91], v[90:91], v[0:1] op_sel_hi:[1,0]
	v_pk_mul_f32 v[94:95], v[94:95], v[0:1] op_sel_hi:[1,0]
	v_pk_mul_f32 v[90:91], v[74:75], v[90:91]
	v_pk_mul_f32 v[94:95], v[76:77], v[94:95]
	v_pk_mul_f32 v[90:91], v[106:107], v[90:91]
	v_pk_mul_f32 v[94:95], v[108:109], v[94:95]
	v_cvt_pk_bf16_f32 v90, v90, v91
	v_cvt_pk_bf16_f32 v91, v94, v95
	global_store_dwordx2 v[142:143], v[90:91], off
	v_pk_mul_f32 v[90:91], v[92:93], v[0:1] op_sel_hi:[1,0]
	v_pk_mul_f32 v[88:89], v[88:89], v[0:1] op_sel_hi:[1,0]
	v_mul_f32_e32 v0, 0x4b800000, v80
	v_cmp_gt_f32_e32 vcc, s1, v80
	v_pk_mul_f32 v[90:91], v[70:71], v[90:91]
	v_pk_mul_f32 v[224:225], v[72:73], v[88:89]
	v_cndmask_b32_e32 v0, v80, v0, vcc
	v_pk_mul_f32 v[108:109], v[96:97], v[90:91]
	ds_read_b64_tr_b16 v[90:91], v213 offset:57408
	ds_read_b64_tr_b16 v[88:89], v213 offset:56320
	ds_read_b64_tr_b16 v[94:95], v210 offset:2112
	ds_read_b64_tr_b16 v[92:93], v210
	ds_read_b64_tr_b16 v[98:99], v210 offset:2144
	ds_read_b64_tr_b16 v[96:97], v210 offset:32
	ds_read_b64_tr_b16 v[100:101], v213 offset:56352
	ds_read_b64_tr_b16 v[104:105], v213 offset:56384
	ds_read_b64_tr_b16 v[136:137], v213 offset:56416
	ds_read_b64_tr_b16 v[102:103], v213 offset:57440
	ds_read_b64_tr_b16 v[106:107], v213 offset:57472
	ds_read_b64_tr_b16 v[138:139], v213 offset:57504
	v_rsq_f32_e32 v0, v0
	ds_read_b64_tr_b16 v[142:143], v213 offset:65024
	ds_read_b64_tr_b16 v[144:145], v214 offset:57408
	ds_read_b64_tr_b16 v[146:147], v210 offset:16896
	ds_read_b64_tr_b16 v[148:149], v210 offset:19008
	ds_read_b64_tr_b16 v[158:159], v210 offset:19040
	ds_read_b64_tr_b16 v[156:157], v210 offset:16928
	s_waitcnt lgkmcnt(8)
	v_mfma_f32_16x16x32_bf16 v[10:13], v[100:103], v[92:95], v[10:13]
	v_and_b32_e32 v81, 0xffff0000, v150
	v_mul_f32_e32 v80, 0x45800000, v0
	v_cndmask_b32_e32 v0, v0, v80, vcc
	v_mfma_f32_16x16x32_bf16 v[18:21], v[100:103], v[96:99], v[18:21]
	v_lshlrev_b32_e32 v80, 16, v150
	v_mul_f32_e32 v100, 0xbfb8aa3b, v80
	v_mul_f32_e32 v101, 0xbfb8aa3b, v81
	v_mfma_f32_16x16x32_bf16 v[30:33], v[88:91], v[92:95], v[30:33]
	v_exp_f32_e32 v100, v100
	v_pk_mul_f32 v[86:87], v[86:87], v[0:1] op_sel_hi:[1,0]
	v_pk_mul_f32 v[152:153], v[152:153], v[224:225]
	v_mfma_f32_16x16x32_bf16 v[6:9], v[88:91], v[96:99], v[6:9]
	ds_read_b64_tr_b16 v[88:89], v213 offset:65056
	ds_read_b64_tr_b16 v[160:161], v213 offset:65088
	ds_read_b64_tr_b16 v[164:165], v213 offset:65120
	ds_read_b64_tr_b16 v[90:91], v214 offset:57440
	ds_read_b64_tr_b16 v[162:163], v214 offset:57472
	ds_read_b64_tr_b16 v[166:167], v214 offset:57504
	v_pk_mul_f32 v[74:75], v[74:75], v[86:87]
	v_lshlrev_b32_e32 v86, 16, v151
	s_waitcnt lgkmcnt(2)
	v_mfma_f32_16x16x32_bf16 v[10:13], v[88:91], v[146:149], v[10:13]
	v_mul_f32_e32 v87, 0xbfb8aa3b, v86
	v_cvt_pk_bf16_f32 v108, v108, v109
	v_cvt_pk_bf16_f32 v109, v152, v153
	v_mfma_f32_16x16x32_bf16 v[18:21], v[88:91], v[156:159], v[18:21]
	v_exp_f32_e32 v89, v101
	v_add_f32_e32 v88, 1.0, v100
	v_rcp_f32_e32 v88, v88
	global_store_dwordx2 v[168:169], v[108:109], off
	v_add_f32_e32 v89, 1.0, v89
	v_rcp_f32_e32 v89, v89
	v_mfma_f32_16x16x32_bf16 v[14:17], v[104:107], v[92:95], v[14:17]
	v_mul_f32_e64 v82, v82, v0
	v_mul_f32_e64 v83, v83, v0
	v_pk_mul_f32 v[78:79], v[78:79], v[0:1] op_sel_hi:[1,0]
	v_pk_mul_f32 v[80:81], v[88:89], v[80:81]
	v_exp_f32_e32 v88, v87
	v_pk_mul_f32 v[80:81], v[80:81], v[74:75]
	v_and_b32_e32 v87, 0xffff0000, v151
	v_mfma_f32_16x16x32_bf16 v[26:29], v[104:107], v[96:99], v[26:29]
	v_add_f32_e32 v74, 1.0, v88
	v_rcp_f32_e32 v88, v74
	v_mul_f32_e32 v74, 0xbfb8aa3b, v87
	v_exp_f32_e32 v89, v74
	v_pk_mul_f32 v[74:75], v[84:85], v[0:1] op_sel_hi:[1,0]
	v_mfma_f32_16x16x32_bf16 v[38:41], v[136:139], v[92:95], v[38:41]
	v_mul_f32_e64 v108, v76, v74
	v_mul_f32_e64 v109, v77, v75
	v_add_f32_e32 v74, 1.0, v89
	v_rcp_f32_e32 v89, v74
	ds_read_b64_tr_b16 v[74:75], v213 offset:56448
	ds_read_b64_tr_b16 v[76:77], v213 offset:57536
	v_mfma_f32_16x16x32_bf16 v[50:53], v[136:139], v[96:99], v[50:53]
	v_cvt_pk_bf16_f32 v80, v80, v81
	v_pk_mul_f32 v[136:137], v[88:89], v[86:87]
	ds_read_b64_tr_b16 v[84:85], v213 offset:56480
	ds_read_b64_tr_b16 v[88:89], v213 offset:56512
	ds_read_b64_tr_b16 v[100:101], v213 offset:56544
	ds_read_b64_tr_b16 v[86:87], v213 offset:57568
	ds_read_b64_tr_b16 v[90:91], v213 offset:57600
	ds_read_b64_tr_b16 v[102:103], v213 offset:57632
	ds_read_b64_tr_b16 v[104:105], v213 offset:65152
	ds_read_b64_tr_b16 v[106:107], v214 offset:57536
	s_waitcnt lgkmcnt(8)
	v_mfma_f32_16x16x32_bf16 v[22:25], v[74:77], v[92:95], v[22:25]
	v_mul_f32_e64 v108, v136, v108
	v_mul_f32_e64 v109, v137, v109
	v_pk_mul_f32 v[70:71], v[70:71], v[82:83]
	v_cvt_pk_bf16_f32 v81, v108, v109
	v_mfma_f32_16x16x32_bf16 v[34:37], v[74:77], v[96:99], v[34:37]
	v_lshl_add_u64 v[108:109], s[56:57], 0, v[128:129]
	v_pk_mul_f32 v[72:73], v[72:73], v[78:79]
	v_lshl_add_u32 v0, s67, 9, v179
	v_mfma_f32_16x16x32_bf16 v[30:33], v[142:145], v[146:149], v[30:33]
	s_sub_i32 s54, s54, 64
	v_mfma_f32_16x16x32_bf16 v[6:9], v[142:145], v[156:159], v[6:9]
	ds_read_b64_tr_b16 v[74:75], v213 offset:65184
	ds_read_b64_tr_b16 v[136:137], v213 offset:65216
	ds_read_b64_tr_b16 v[142:143], v213 offset:65248
	ds_read_b64_tr_b16 v[76:77], v214 offset:57568
	ds_read_b64_tr_b16 v[138:139], v214 offset:57600
	ds_read_b64_tr_b16 v[144:145], v214 offset:57632
	global_store_dwordx2 v[108:109], v[80:81], off
	v_lshlrev_b32_e32 v80, 16, v140
	v_and_b32_e32 v81, 0xffff0000, v140
	s_waitcnt lgkmcnt(6)
	v_mfma_f32_16x16x32_bf16 v[22:25], v[104:107], v[146:149], v[22:25]
	v_mfma_f32_16x16x32_bf16 v[34:37], v[104:107], v[156:159], v[34:37]
	v_mul_f32_e32 v104, 0xbfb8aa3b, v80
	v_mul_f32_e32 v105, 0xbfb8aa3b, v81
	v_exp_f32_e32 v104, v104
	v_mfma_f32_16x16x32_bf16 v[42:45], v[84:87], v[92:95], v[42:45]
	v_mfma_f32_16x16x32_bf16 v[54:57], v[84:87], v[96:99], v[54:57]
	v_exp_f32_e32 v85, v105
	v_add_f32_e32 v84, 1.0, v104
	v_rcp_f32_e32 v84, v84
	s_waitcnt lgkmcnt(2)
	v_mfma_f32_16x16x32_bf16 v[42:45], v[74:77], v[146:149], v[42:45]
	v_add_f32_e32 v85, 1.0, v85
	v_rcp_f32_e32 v85, v85
	v_mfma_f32_16x16x32_bf16 v[54:57], v[74:77], v[156:159], v[54:57]
	v_mul_f32_e64 v74, v84, v80
	v_mul_f32_e64 v75, v85, v81
	v_pk_mul_f32 v[70:71], v[74:75], v[70:71]
	v_lshlrev_b32_e32 v74, 16, v141
	v_and_b32_e32 v75, 0xffff0000, v141
	v_mul_f32_e32 v76, 0xbfb8aa3b, v74
	v_mul_f32_e32 v77, 0xbfb8aa3b, v75
	v_exp_f32_e32 v76, v76
	v_exp_f32_e32 v77, v77
	v_cvt_pk_bf16_f32 v78, v70, v71
	v_lshl_add_u64 v[80:81], s[56:57], 0, v[130:131]
	v_add_f32_e32 v76, 1.0, v76
	v_add_f32_e32 v77, 1.0, v77
	v_rcp_f32_e32 v76, v76
	v_rcp_f32_e32 v77, v77
	v_mfma_f32_16x16x32_bf16 v[14:17], v[160:163], v[146:149], v[14:17]
	s_add_u32 s56, s56, 0xfffe0000
	s_addc_u32 s57, s57, -1
	v_pk_mul_f32 v[74:75], v[76:77], v[74:75]
	v_mfma_f32_16x16x32_bf16 v[26:29], v[160:163], v[156:159], v[26:29]
	v_mul_f32_e64 v74, v74, v72
	v_mul_f32_e64 v75, v75, v73
	ds_read_b128 v[70:73], v0 offset:4096
	v_cvt_pk_bf16_f32 v79, v74, v75
	ds_read_b128 v[74:77], v0 offset:4160
	global_store_dwordx2 v[80:81], v[78:79], off
	v_mfma_f32_16x16x32_bf16 v[38:41], v[164:167], v[146:149], v[38:41]
	s_waitcnt lgkmcnt(1)
	s_nop 0
	v_mov_b32_e32 v82, v70
	v_mov_b32_e32 v83, v71
	v_mov_b32_e32 v70, v72
	v_mov_b32_e32 v71, v73
	s_nop 0
	s_nop 0
	s_nop 0
	v_mfma_f32_16x16x32_bf16 v[50:53], v[164:167], v[156:159], v[50:53]
	s_add_u32 s58, s58, 0xfffe0000
	v_pk_mul_f32 v[32:33], v[32:33], v[70:71]
	v_pk_mul_f32 v[8:9], v[8:9], v[70:71]
	s_waitcnt lgkmcnt(0)
	v_mov_b32_e32 v70, v74
	v_mov_b32_e32 v71, v76
	v_mov_b32_e32 v78, v70
	v_mov_b32_e32 v70, v75
	v_mov_b32_e32 v80, v71
	s_nop 0
	v_mov_b32_e32 v81, v77
	v_mov_b32_e32 v79, v70
	ds_read_b128 v[70:73], v0 offset:4224
	ds_read_b128 v[74:77], v0 offset:4288
	v_pk_mul_f32 v[30:31], v[30:31], v[82:83]
	v_pk_mul_f32 v[6:7], v[6:7], v[82:83]
	v_pk_mul_f32 v[12:13], v[12:13], v[80:81]
	s_waitcnt lgkmcnt(1)
	s_nop 0
	v_mov_b32_e32 v82, v70
	v_mov_b32_e32 v83, v71
	v_mov_b32_e32 v70, v72
	v_mov_b32_e32 v71, v73
	s_nop 0
	s_nop 0
	v_pk_mul_f32 v[10:11], v[10:11], v[78:79]
	v_pk_mul_f32 v[20:21], v[20:21], v[80:81]
	v_pk_mul_f32 v[18:19], v[18:19], v[78:79]
	v_pk_mul_f32 v[16:17], v[16:17], v[70:71]
	v_pk_mul_f32 v[28:29], v[28:29], v[70:71]
	s_waitcnt lgkmcnt(0)
	v_mov_b32_e32 v70, v74
	v_mov_b32_e32 v71, v76
	v_mov_b32_e32 v78, v70
	v_mov_b32_e32 v70, v75
	v_mov_b32_e32 v80, v71
	s_nop 0
	v_mov_b32_e32 v81, v77
	v_mov_b32_e32 v79, v70
	ds_read_b128 v[70:73], v0 offset:4352
	ds_read_b128 v[74:77], v0 offset:4416
	s_nop 0
	v_pk_mul_f32 v[40:41], v[40:41], v[80:81]
	v_pk_mul_f32 v[38:39], v[38:39], v[78:79]
	s_waitcnt lgkmcnt(1)
	s_nop 0
	v_pk_mul_f32 v[14:15], v[14:15], v[82:83]
	v_pk_mul_f32 v[26:27], v[26:27], v[82:83]
	v_mov_b32_e32 v82, v70
	v_mov_b32_e32 v83, v71
	v_mov_b32_e32 v70, v72
	v_mov_b32_e32 v71, v73
	s_nop 0
	s_nop 0
	v_pk_mul_f32 v[52:53], v[52:53], v[80:81]
	v_pk_mul_f32 v[50:51], v[50:51], v[78:79]
	v_mfma_f32_16x16x32_bf16 v[46:49], v[88:91], v[92:95], v[46:49]
	v_mul_f32_e64 v24, v24, v70
	v_mul_f32_e64 v25, v25, v71
	v_pk_mul_f32 v[36:37], v[36:37], v[70:71]
	s_waitcnt lgkmcnt(0)
	v_mov_b32_e32 v70, v74
	v_mov_b32_e32 v71, v76
	v_mov_b32_e32 v78, v70
	v_mov_b32_e32 v70, v75
	v_mov_b32_e32 v80, v71
	s_nop 0
	v_mov_b32_e32 v81, v77
	v_mov_b32_e32 v79, v70
	ds_read_b128 v[70:73], v0 offset:4480
	ds_read_b128 v[74:77], v0 offset:4544
	v_mfma_f32_16x16x32_bf16 v[62:65], v[88:91], v[96:99], v[62:65]
	s_nop 0
	s_addc_u32 s59, s59, -1
	s_waitcnt lgkmcnt(1)
	s_nop 0
	v_mov_b32_e32 v70, v70
	v_mov_b32_e32 v0, v71
	v_mov_b32_e32 v71, v72
	v_mfma_f32_16x16x32_bf16 v[58:61], v[100:103], v[92:95], v[58:61]
	v_mov_b32_e32 v72, v71
	s_nop 0
	v_mov_b32_e32 v73, v73
	v_mfma_f32_16x16x32_bf16 v[66:69], v[100:103], v[96:99], v[66:69]
	v_mov_b32_e32 v71, v0
	s_waitcnt lgkmcnt(0)
	s_nop 0
	v_mov_b32_e32 v74, v74
	v_mov_b32_e32 v0, v75
	v_mov_b32_e32 v75, v76
	v_mov_b32_e32 v76, v75
	v_mov_b32_e32 v75, v77
	v_mfma_f32_16x16x32_bf16 v[46:49], v[136:139], v[146:149], v[46:49]
	v_mov_b32_e32 v77, v75
	v_mov_b32_e32 v75, v0
	v_pk_mul_f32 v[22:23], v[22:23], v[82:83]
	v_mfma_f32_16x16x32_bf16 v[62:65], v[136:139], v[156:159], v[62:65]
	v_mul_f32_e64 v34, v34, v82
	v_mul_f32_e64 v35, v35, v83
	v_pk_mul_f32 v[44:45], v[44:45], v[80:81]
	v_pk_mul_f32 v[42:43], v[42:43], v[78:79]
	v_mfma_f32_16x16x32_bf16 v[58:61], v[142:145], v[146:149], v[58:61]
	v_mul_f32_e64 v56, v56, v80
	v_mul_f32_e64 v57, v57, v81
	v_pk_mul_f32 v[54:55], v[54:55], v[78:79]
	v_pk_mul_f32 v[48:49], v[48:49], v[72:73]
	v_mfma_f32_16x16x32_bf16 v[66:69], v[142:145], v[156:159], v[66:69]
	v_mul_f32_e64 v46, v46, v70
	v_mul_f32_e64 v47, v47, v71
	v_pk_mul_f32 v[64:65], v[64:65], v[72:73]
	v_pk_mul_f32 v[62:63], v[62:63], v[70:71]
	v_pk_mul_f32 v[60:61], v[60:61], v[76:77]
	v_pk_mul_f32 v[58:59], v[58:59], v[74:75]
	s_nop 1
	v_pk_mul_f32 v[68:69], v[68:69], v[76:77]
	s_cmp_lg_u32 s75, 8
	v_pk_mul_f32 v[66:67], v[66:67], v[74:75]
	s_cbranch_scc0 .LBB0_654
.LBB0_680:
	s_add_u32 s62, s71, s60
	s_addc_u32 s63, s74, s61
	s_add_u32 s72, s48, s60
	s_addc_u32 s73, s70, s61
	s_add_u32 s55, s72, s68
	v_lshl_add_u64 v[70:71], s[62:63], 0, v[112:113]
	s_addc_u32 s63, s73, 0
	s_add_u32 s62, s55, 0xafc0800
	v_add_co_u32_e32 v74, vcc, s95, v70
	s_addc_u32 s63, s63, 0
	s_nop 0
	v_addc_co_u32_e32 v75, vcc, 0, v71, vcc
	v_lshl_add_u64 v[86:87], s[62:63], 0, v[114:115]
	v_add_co_u32_e32 v78, vcc, s81, v86
	s_and_b32 s67, s75, 1
	s_nop 0
	v_addc_co_u32_e32 v79, vcc, 0, v87, vcc
	s_cmp_eq_u32 s67, 0
	v_add_co_u32_e32 v82, vcc, s95, v86
	s_cselect_b64 s[64:65], -1, 0
	s_nop 0
	v_addc_co_u32_e32 v83, vcc, 0, v87, vcc
	s_and_b64 s[62:63], s[64:65], exec
	global_load_dwordx4 v[94:97], v[70:71], off
	global_load_dwordx4 v[98:101], v[70:71], off offset:1024
	s_nop 0
	global_load_dwordx4 v[70:73], v[74:75], off
	global_load_dwordx4 v[90:93], v[74:75], off offset:1024
	s_cselect_b32 s55, 0xf0, s69
	global_load_dwordx4 v[74:77], v[86:87], off
	v_add_co_u32_e32 v86, vcc, s96, v86
	v_add3_u32 v105, s55, v177, v175
	s_nop 0
	v_addc_co_u32_e32 v87, vcc, 0, v87, vcc
	global_load_dwordx4 v[78:81], v[78:79], off
	s_nop 0
	global_load_dwordx4 v[82:85], v[82:83], off
	s_nop 0
	global_load_dwordx4 v[86:89], v[86:87], off
	ds_read2_b32 v[102:103], v105 offset1:4
	ds_read2_b32 v[136:137], v105 offset0:8 offset1:12
	s_waitcnt vmcnt(12) lgkmcnt(1)
	v_mfma_f32_16x16x4_f32 v[106:109], v102, v219, 0
	ds_read2_b32 v[140:141], v105 offset0:128 offset1:132
	s_waitcnt vmcnt(11)
	v_mfma_f32_16x16x4_f32 v[106:109], v103, v220, v[106:109]
	s_waitcnt vmcnt(10) lgkmcnt(1)
	v_mfma_f32_16x16x4_f32 v[106:109], v136, v221, v[106:109]
	s_waitcnt vmcnt(9)
	v_mfma_f32_16x16x4_f32 v[106:109], v137, v222, v[106:109]
	ds_read2_b32 v[136:137], v105 offset0:64 offset1:68
	s_waitcnt vmcnt(8)
	s_nop 7
	v_add_f32_e32 v102, v223, v106
	v_min_f32_e32 v0, 0, v102
	v_mul_f32_e64 v102, |v102|, s97
	v_exp_f32_e32 v102, v102
	v_add_f32_e32 v103, v223, v107
	v_add_f32_e32 v104, v223, v108
	v_add_f32_e32 v106, v223, v109
	v_add_f32_e32 v102, 1.0, v102
	v_log_f32_e32 v102, v102
	s_nop 0
	v_fmac_f32_e32 v0, 0xbf317218, v102
	v_min_f32_e32 v102, 0, v103
	v_mul_f32_e64 v103, |v103|, s97
	v_exp_f32_e32 v103, v103
	s_nop 0
	v_add_f32_e32 v103, 1.0, v103
	v_log_f32_e32 v103, v103
	s_nop 0
	v_fmac_f32_e32 v102, 0xbf317218, v103
	v_min_f32_e32 v103, 0, v104
	v_mul_f32_e64 v104, |v104|, s97
	v_exp_f32_e32 v104, v104
	s_nop 0
	v_add_f32_e32 v104, 1.0, v104
	v_log_f32_e32 v104, v104
	s_nop 0
	v_fmac_f32_e32 v103, 0xbf317218, v104
	v_min_f32_e32 v104, 0, v106
	v_mul_f32_e64 v106, |v106|, s97
	v_exp_f32_e32 v106, v106
	s_nop 0
	v_add_f32_e32 v106, 1.0, v106
	v_log_f32_e32 v106, v106
	s_nop 0
	v_fmac_f32_e32 v104, 0xbf317218, v106
	s_waitcnt lgkmcnt(0)
	v_mfma_f32_16x16x4_f32 v[106:109], v136, v219, 0
	v_mfma_f32_16x16x4_f32 v[106:109], v137, v220, v[106:109]
	ds_read2_b32 v[136:137], v105 offset0:72 offset1:76
	s_waitcnt lgkmcnt(0)
	v_mfma_f32_16x16x4_f32 v[106:109], v136, v221, v[106:109]
	v_mfma_f32_16x16x4_f32 v[106:109], v137, v222, v[106:109]
	s_nop 9
	v_add_f32_e32 v136, v223, v106
	v_min_f32_e32 v106, 0, v136
	v_mul_f32_e64 v136, |v136|, s97
	v_exp_f32_e32 v136, v136
	s_nop 0
	v_add_f32_e32 v136, 1.0, v136
	v_log_f32_e32 v136, v136
	s_nop 0
	v_fmac_f32_e32 v106, 0xbf317218, v136
	v_add_f32_e32 v136, v223, v107
	v_min_f32_e32 v107, 0, v136
	v_mul_f32_e64 v136, |v136|, s97
	v_exp_f32_e32 v136, v136
	s_nop 0
	v_add_f32_e32 v136, 1.0, v136
	v_log_f32_e32 v136, v136
	s_nop 0
	v_fmac_f32_e32 v107, 0xbf317218, v136
	v_add_f32_e32 v136, v223, v108
	v_min_f32_e32 v108, 0, v136
	v_mul_f32_e64 v136, |v136|, s97
	v_exp_f32_e32 v136, v136
	s_nop 0
	v_add_f32_e32 v136, 1.0, v136
	v_log_f32_e32 v136, v136
	s_nop 0
	v_fmac_f32_e32 v108, 0xbf317218, v136
	v_add_f32_e32 v136, v223, v109
	v_min_f32_e32 v109, 0, v136
	v_mul_f32_e64 v136, |v136|, s97
	v_exp_f32_e32 v136, v136
	s_nop 0
	v_add_f32_e32 v136, 1.0, v136
	v_log_f32_e32 v136, v136
	s_nop 0
	v_fmac_f32_e32 v109, 0xbf317218, v136
	v_mfma_f32_16x16x4_f32 v[136:139], v140, v219, 0
	v_mfma_f32_16x16x4_f32 v[136:139], v141, v220, v[136:139]
	ds_read2_b32 v[140:141], v105 offset0:136 offset1:140
	s_waitcnt lgkmcnt(0)
	v_mfma_f32_16x16x4_f32 v[136:139], v140, v221, v[136:139]
	v_mfma_f32_16x16x4_f32 v[136:139], v141, v222, v[136:139]
	ds_read2_b32 v[140:141], v105 offset0:192 offset1:196
	s_nop 8
	v_add_f32_e32 v136, v223, v136
	v_min_f32_e32 v142, 0, v136
	v_mul_f32_e64 v136, |v136|, s97
	v_exp_f32_e32 v136, v136
	s_nop 0
	v_add_f32_e32 v136, 1.0, v136
	v_log_f32_e32 v136, v136
	s_nop 0
	v_fmac_f32_e32 v142, 0xbf317218, v136
	v_add_f32_e32 v136, v223, v137
	v_min_f32_e32 v143, 0, v136
	v_mul_f32_e64 v136, |v136|, s97
	v_exp_f32_e32 v136, v136
	s_nop 0
	v_add_f32_e32 v136, 1.0, v136
	v_log_f32_e32 v136, v136
	s_nop 0
	v_fmac_f32_e32 v143, 0xbf317218, v136
	v_add_f32_e32 v136, v223, v138
	v_min_f32_e32 v144, 0, v136
	v_mul_f32_e64 v136, |v136|, s97
	v_exp_f32_e32 v136, v136
	s_nop 0
	v_add_f32_e32 v136, 1.0, v136
	v_log_f32_e32 v136, v136
	s_nop 0
	v_fmac_f32_e32 v144, 0xbf317218, v136
	v_add_f32_e32 v136, v223, v139
	v_min_f32_e32 v145, 0, v136
	v_mul_f32_e64 v136, |v136|, s97
	v_exp_f32_e32 v136, v136
	s_nop 0
	v_add_f32_e32 v136, 1.0, v136
	v_log_f32_e32 v136, v136
	s_nop 0
	v_fmac_f32_e32 v145, 0xbf317218, v136
	s_waitcnt lgkmcnt(0)
	v_mfma_f32_16x16x4_f32 v[136:139], v140, v219, 0
	v_mfma_f32_16x16x4_f32 v[136:139], v141, v220, v[136:139]
	ds_read2_b32 v[140:141], v105 offset0:200 offset1:204
	s_waitcnt lgkmcnt(0)
	v_mfma_f32_16x16x4_f32 v[136:139], v140, v221, v[136:139]
	v_mfma_f32_16x16x4_f32 v[136:139], v141, v222, v[136:139]
	s_nop 9
	v_add_f32_e32 v105, v223, v136
	v_min_f32_e32 v136, 0, v105
	v_mul_f32_e64 v105, |v105|, s97
	v_exp_f32_e32 v105, v105
	s_nop 0
	v_add_f32_e32 v105, 1.0, v105
	v_log_f32_e32 v105, v105
	s_nop 0
	v_fmac_f32_e32 v136, 0xbf317218, v105
	v_add_f32_e32 v105, v223, v137
	v_min_f32_e32 v137, 0, v105
	v_mul_f32_e64 v105, |v105|, s97
	v_exp_f32_e32 v105, v105
	s_nop 0
	v_add_f32_e32 v105, 1.0, v105
	v_log_f32_e32 v105, v105
	s_nop 0
	v_fmac_f32_e32 v137, 0xbf317218, v105
	v_add_f32_e32 v105, v223, v138
	v_min_f32_e32 v138, 0, v105
	v_mul_f32_e64 v105, |v105|, s97
	v_exp_f32_e32 v105, v105
	s_nop 0
	v_add_f32_e32 v105, 1.0, v105
	v_log_f32_e32 v105, v105
	s_nop 0
	v_fmac_f32_e32 v138, 0xbf317218, v105
	v_add_f32_e32 v105, v223, v139
	v_min_f32_e32 v139, 0, v105
	v_mul_f32_e64 v105, |v105|, s97
	v_exp_f32_e32 v105, v105
	s_nop 0
	v_add_f32_e32 v105, 1.0, v105
	v_log_f32_e32 v105, v105
	s_nop 0
	v_fmac_f32_e32 v139, 0xbf317218, v105
	v_fma_f32 v105, v139, s0, 0
	v_fmamk_f32 v138, v138, 0x3d800000, v105
	v_fmamk_f32 v137, v137, 0x3d800000, v138
	v_fmamk_f32 v136, v136, 0x3d800000, v137
	v_fmamk_f32 v139, v145, 0x3d800000, v136
	v_fmamk_f32 v140, v144, 0x3d800000, v139
	v_fmamk_f32 v141, v143, 0x3d800000, v140
	v_fmamk_f32 v142, v142, 0x3d800000, v141
	v_fmamk_f32 v109, v109, 0x3d800000, v142
	v_fmamk_f32 v108, v108, 0x3d800000, v109
	v_fmamk_f32 v107, v107, 0x3d800000, v108
	v_fmamk_f32 v106, v106, 0x3d800000, v107
	v_fmamk_f32 v104, v104, 0x3d800000, v106
	v_fmamk_f32 v103, v103, 0x3d800000, v104
	v_fmamk_f32 v102, v102, 0x3d800000, v103
	v_fmamk_f32 v0, v0, 0x3d800000, v102
	ds_bpermute_b32 v144, v188, v0
	ds_bpermute_b32 v145, v189, v0
	ds_bpermute_b32 v143, v187, v0
	s_waitcnt lgkmcnt(2)
	v_cndmask_b32_e64 v144, 0, v144, s[28:29]
	s_waitcnt lgkmcnt(1)
	v_cndmask_b32_e64 v145, v145, 0, s[8:9]
	v_add_f32_e32 v144, v144, v145
	s_waitcnt lgkmcnt(0)
	v_cndmask_b32_e64 v143, 0, v143, s[4:5]
	v_add_f32_e32 v143, v143, v144
	v_add_f32_e32 v0, v143, v0
	v_add_f32_e32 v102, v143, v102
	ds_write2st64_b32 v200, v0, v102 offset0:24 offset1:26
	v_add_f32_e32 v0, v143, v103
	v_add_f32_e32 v102, v143, v104
	ds_write2st64_b32 v200, v0, v102 offset0:28 offset1:30
	v_add_f32_e32 v0, v143, v106
	v_add_f32_e32 v102, v143, v107
	ds_write2st64_b32 v200, v0, v102 offset0:32 offset1:34
	v_add_f32_e32 v0, v143, v108
	v_add_f32_e32 v102, v143, v109
	ds_write2st64_b32 v200, v0, v102 offset0:36 offset1:38
	v_add_f32_e32 v0, v143, v142
	v_add_f32_e32 v102, v143, v141
	ds_write2st64_b32 v200, v0, v102 offset0:40 offset1:42
	v_add_f32_e32 v0, v143, v140
	v_add_f32_e32 v102, v143, v139
	ds_write2st64_b32 v200, v0, v102 offset0:44 offset1:46
	v_add_f32_e32 v0, v143, v136
	v_add_f32_e32 v102, v143, v137
	ds_write2st64_b32 v200, v0, v102 offset0:48 offset1:50
	v_add_f32_e32 v0, v143, v138
	v_add_f32_e32 v102, v143, v105
	ds_write2st64_b32 v200, v0, v102 offset0:52 offset1:54
	s_waitcnt lgkmcnt(0)
	s_barrier
	s_and_saveexec_b64 s[62:63], s[10:11]
	s_cbranch_execz .LBB0_682
	ds_read_b32 v0, v178 offset:6144
	v_lshl_add_u32 v102, s67, 9, v178
	s_waitcnt lgkmcnt(0)
	v_mul_f32_e32 v255, 0x3fb8aa3b, v0
	v_exp_f32_e32 v255, v255
	s_nop 0
	ds_write_b32 v102, v255 offset:4096

.LBB0_2085:
	ds_read_b128 v[136:139], v119 offset:6144
	ds_read_b128 v[140:143], v119 offset:6160
	s_waitcnt vmcnt(5)
	v_lshlrev_b32_e32 v144, 16, v54
	v_and_b32_e32 v145, 0xffff0000, v54
	s_add_i32 s24, s25, s24
	s_waitcnt lgkmcnt(1)
	v_mul_f32_e32 v136, 0xbfb8aa3b, v136
	v_mul_f32_e32 v137, 0xbfb8aa3b, v137
	v_exp_f32_e32 v136, v136
	v_exp_f32_e32 v137, v137
	v_mul_f32_e32 v54, 0xbfb8aa3b, v138
	v_exp_f32_e32 v138, v54
	v_mul_f32_e32 v54, 0xbfb8aa3b, v139
	v_exp_f32_e32 v139, v54
	v_pk_mul_f32 v[136:137], v[136:137], v[144:145]
	s_add_i32 s57, s57, 1
	v_cvt_pk_bf16_f32 v54, v136, v137
	v_lshlrev_b32_e32 v136, 16, v55
	v_and_b32_e32 v137, 0xffff0000, v55
	s_waitcnt lgkmcnt(0)
	v_mul_f32_e32 v55, 0xbfb8aa3b, v140
	v_pk_mul_f32 v[136:137], v[138:139], v[136:137]
	v_exp_f32_e32 v138, v55
	v_mul_f32_e32 v55, 0xbfb8aa3b, v141
	v_exp_f32_e32 v139, v55
	v_cvt_pk_bf16_f32 v55, v136, v137
	v_lshlrev_b32_e32 v136, 16, v56
	v_and_b32_e32 v137, 0xffff0000, v56
	v_mul_f32_e32 v56, 0xbfb8aa3b, v142
	v_pk_mul_f32 v[136:137], v[138:139], v[136:137]
	v_exp_f32_e32 v138, v56
	v_mul_f32_e32 v56, 0xbfb8aa3b, v143
	v_exp_f32_e32 v139, v56
	v_cvt_pk_bf16_f32 v56, v136, v137
	v_lshlrev_b32_e32 v136, 16, v57
	v_and_b32_e32 v137, 0xffff0000, v57
	v_pk_mul_f32 v[136:137], v[138:139], v[136:137]
	s_waitcnt vmcnt(4)
	v_lshlrev_b32_e32 v140, 16, v6
	v_cvt_pk_bf16_f32 v57, v136, v137
	ds_write_b128 v120, v[54:57] offset:56320
	ds_read_b128 v[54:57], v121 offset:6144
	ds_read_b128 v[136:139], v121 offset:6160
	v_and_b32_e32 v141, 0xffff0000, v6
	s_mul_i32 s31, s24, 0x1800
	s_mul_hi_i32 s30, s24, 0x1800
	s_waitcnt lgkmcnt(1)
	v_mul_f32_e32 v54, 0xbfb8aa3b, v54
	v_mul_f32_e32 v55, 0xbfb8aa3b, v55
	v_exp_f32_e32 v54, v54
	v_exp_f32_e32 v55, v55
	v_mul_f32_e32 v6, 0xbfb8aa3b, v56
	v_exp_f32_e32 v56, v6
	v_mul_f32_e32 v6, 0xbfb8aa3b, v57
	v_exp_f32_e32 v57, v6
	v_pk_mul_f32 v[54:55], v[54:55], v[140:141]
	s_add_u32 s28, s61, s31
	v_cvt_pk_bf16_f32 v6, v54, v55
	v_lshlrev_b32_e32 v54, 16, v7
	v_and_b32_e32 v55, 0xffff0000, v7
	s_waitcnt lgkmcnt(0)
	v_mul_f32_e32 v7, 0xbfb8aa3b, v136
	v_pk_mul_f32 v[54:55], v[56:57], v[54:55]
	v_exp_f32_e32 v56, v7
	v_mul_f32_e32 v7, 0xbfb8aa3b, v137
	v_exp_f32_e32 v57, v7
	v_cvt_pk_bf16_f32 v7, v54, v55
	v_lshlrev_b32_e32 v54, 16, v8
	v_and_b32_e32 v55, 0xffff0000, v8
	v_mul_f32_e32 v8, 0xbfb8aa3b, v138
	v_pk_mul_f32 v[54:55], v[56:57], v[54:55]
	v_exp_f32_e32 v56, v8
	v_mul_f32_e32 v8, 0xbfb8aa3b, v139
	v_exp_f32_e32 v57, v8
	v_cvt_pk_bf16_f32 v8, v54, v55
	v_lshlrev_b32_e32 v54, 16, v9
	v_and_b32_e32 v55, 0xffff0000, v9
	v_pk_mul_f32 v[54:55], v[56:57], v[54:55]
	s_addc_u32 s29, s62, s30
	v_cvt_pk_bf16_f32 v9, v54, v55
	ds_write_b128 v122, v[6:9] offset:56320
	s_waitcnt vmcnt(3)
	ds_write_b128 v123, v[2:5]
	s_waitcnt vmcnt(2)
	ds_write_b128 v124, v[10:13]
	s_waitcnt vmcnt(1)
	ds_write_b128 v123, v[14:17] offset:16896
	s_waitcnt vmcnt(0)
	ds_write_b128 v125, v[18:21]
	v_lshl_add_u64 v[2:3], s[28:29], 0, v[96:97]
	s_add_u32 s28, s20, s31
	s_addc_u32 s29, s21, s30
	s_add_u32 s28, s28, s56
	s_addc_u32 s29, s29, 0
	s_add_u32 s28, s28, 0xad20800
	v_add_co_u32_e32 v4, vcc, s42, v2
	s_addc_u32 s29, s29, 0
	s_nop 0
	v_addc_co_u32_e32 v5, vcc, 0, v3, vcc
	v_lshl_add_u64 v[14:15], s[28:29], 0, v[98:99]
	v_add_co_u32_e32 v10, vcc, s43, v14
	global_load_dwordx4 v[54:57], v[2:3], off offset:1024
	global_load_dwordx4 v[6:9], v[4:5], off offset:1024
	v_addc_co_u32_e32 v11, vcc, 0, v15, vcc
	v_add_co_u32_e32 v16, vcc, s42, v14
	global_load_dwordx4 v[2:5], v[14:15], off
	s_nop 0
	global_load_dwordx4 v[10:13], v[10:11], off
	v_addc_co_u32_e32 v17, vcc, 0, v15, vcc
	v_add_co_u32_e32 v18, vcc, s44, v14
	s_cmp_eq_u32 s23, s57
	s_nop 0
	v_addc_co_u32_e32 v19, vcc, 0, v15, vcc
	global_load_dwordx4 v[14:17], v[16:17], off
	s_nop 0
	global_load_dwordx4 v[18:21], v[18:19], off
	s_waitcnt lgkmcnt(0)
	s_barrier
	ds_read_b64_tr_b16 v[138:139], v127 offset:57408
	ds_read_b64_tr_b16 v[136:137], v127 offset:56320
	ds_read_b64_tr_b16 v[142:143], v126 offset:2112
	ds_read_b64_tr_b16 v[140:141], v126
	ds_read_b64_tr_b16 v[146:147], v126 offset:2144
	ds_read_b64_tr_b16 v[144:145], v126 offset:32
	ds_read_b64_tr_b16 v[148:149], v127 offset:56352
	ds_read_b64_tr_b16 v[156:157], v127 offset:56384
	ds_read_b64_tr_b16 v[160:161], v127 offset:56416
	ds_read_b64_tr_b16 v[150:151], v127 offset:57440
	ds_read_b64_tr_b16 v[158:159], v127 offset:57472
	ds_read_b64_tr_b16 v[162:163], v127 offset:57504
	ds_read_b64_tr_b16 v[164:165], v127 offset:65024
	ds_read_b64_tr_b16 v[166:167], v128 offset:57408
	ds_read_b64_tr_b16 v[168:169], v126 offset:16896
	ds_read_b64_tr_b16 v[170:171], v126 offset:19008
	ds_read_b64_tr_b16 v[174:175], v126 offset:19040
	ds_read_b64_tr_b16 v[172:173], v126 offset:16928
	s_waitcnt lgkmcnt(8)
	v_mfma_f32_16x16x32_bf16 v[58:61], v[148:151], v[140:143], v[58:61]
	v_mfma_f32_16x16x32_bf16 v[78:81], v[148:151], v[144:147], v[78:81]
	v_mfma_f32_16x16x32_bf16 v[66:69], v[136:139], v[140:143], v[66:69]
	v_mfma_f32_16x16x32_bf16 v[62:65], v[136:139], v[144:147], v[62:65]
	ds_read_b64_tr_b16 v[136:137], v127 offset:65056
	ds_read_b64_tr_b16 v[176:177], v127 offset:65088
	ds_read_b64_tr_b16 v[180:181], v127 offset:65120
	ds_read_b64_tr_b16 v[138:139], v128 offset:57440
	ds_read_b64_tr_b16 v[178:179], v128 offset:57472
	ds_read_b64_tr_b16 v[182:183], v128 offset:57504
	s_waitcnt lgkmcnt(2)
	v_mfma_f32_16x16x32_bf16 v[58:61], v[136:139], v[168:171], v[58:61]
	v_mfma_f32_16x16x32_bf16 v[78:81], v[136:139], v[172:175], v[78:81]
	ds_read_b64_tr_b16 v[136:137], v127 offset:56448
	ds_read_b64_tr_b16 v[138:139], v127 offset:57536
	v_mfma_f32_16x16x32_bf16 v[74:77], v[156:159], v[140:143], v[74:77]
	v_mfma_f32_16x16x32_bf16 v[70:73], v[156:159], v[144:147], v[70:73]
	v_mfma_f32_16x16x32_bf16 v[82:85], v[160:163], v[140:143], v[82:85]
	v_mfma_f32_16x16x32_bf16 v[86:89], v[160:163], v[144:147], v[86:89]
	ds_read_b64_tr_b16 v[148:149], v127 offset:56480
	ds_read_b64_tr_b16 v[156:157], v127 offset:56512
	ds_read_b64_tr_b16 v[160:161], v127 offset:56544
	ds_read_b64_tr_b16 v[150:151], v127 offset:57568
	ds_read_b64_tr_b16 v[158:159], v127 offset:57600
	ds_read_b64_tr_b16 v[162:163], v127 offset:57632
	s_waitcnt lgkmcnt(2)
	v_mfma_f32_16x16x32_bf16 v[22:25], v[148:151], v[140:143], v[22:25]
	v_mfma_f32_16x16x32_bf16 v[50:53], v[148:151], v[144:147], v[50:53]
	v_lshl_add_u32 v150, s63, 9, v111
	v_mfma_f32_16x16x32_bf16 v[66:69], v[164:167], v[168:171], v[66:69]
	v_mfma_f32_16x16x32_bf16 v[62:65], v[164:167], v[172:175], v[62:65]
	ds_read_b64_tr_b16 v[164:165], v127 offset:65152
	ds_read_b64_tr_b16 v[166:167], v128 offset:57536
	v_mfma_f32_16x16x32_bf16 v[74:77], v[176:179], v[168:171], v[74:77]
	v_mfma_f32_16x16x32_bf16 v[70:73], v[176:179], v[172:175], v[70:73]
	v_mfma_f32_16x16x32_bf16 v[82:85], v[180:183], v[168:171], v[82:85]
	v_mfma_f32_16x16x32_bf16 v[86:89], v[180:183], v[172:175], v[86:89]
	v_mfma_f32_16x16x32_bf16 v[30:33], v[136:139], v[140:143], v[30:33]
	v_mfma_f32_16x16x32_bf16 v[26:29], v[136:139], v[144:147], v[26:29]
	ds_read_b64_tr_b16 v[136:137], v127 offset:65184
	ds_read_b64_tr_b16 v[176:177], v127 offset:65216
	ds_read_b64_tr_b16 v[180:181], v127 offset:65248
	ds_read_b64_tr_b16 v[138:139], v128 offset:57568
	ds_read_b64_tr_b16 v[178:179], v128 offset:57600
	ds_read_b64_tr_b16 v[182:183], v128 offset:57632
	s_waitcnt lgkmcnt(2)
	v_mfma_f32_16x16x32_bf16 v[22:25], v[136:139], v[168:171], v[22:25]
	v_mfma_f32_16x16x32_bf16 v[50:53], v[136:139], v[172:175], v[50:53]
	ds_read_b128 v[136:139], v150 offset:4096
	v_mfma_f32_16x16x32_bf16 v[34:37], v[156:159], v[140:143], v[34:37]
	v_mfma_f32_16x16x32_bf16 v[38:41], v[160:163], v[140:143], v[38:41]
	ds_read_b128 v[140:143], v150 offset:4160
	s_waitcnt lgkmcnt(1)
	s_nop 0
	v_mfma_f32_16x16x32_bf16 v[46:49], v[156:159], v[144:147], v[46:49]
	v_mfma_f32_16x16x32_bf16 v[42:45], v[160:163], v[144:147], v[42:45]
	v_mov_b32_e32 v144, v136
	v_mov_b32_e32 v145, v137
	v_mov_b32_e32 v136, v138
	v_mov_b32_e32 v137, v139
	s_nop 0
	s_nop 0
	s_nop 0
	v_mfma_f32_16x16x32_bf16 v[30:33], v[164:167], v[168:171], v[30:33]
	v_mul_f32_e64 v68, v68, v136
	v_mul_f32_e64 v69, v69, v137
	v_pk_mul_f32 v[64:65], v[64:65], v[136:137]
	s_waitcnt lgkmcnt(0)
	v_mov_b32_e32 v136, v140
	v_mov_b32_e32 v137, v142
	v_mov_b32_e32 v146, v136
	v_mov_b32_e32 v136, v141
	v_mov_b32_e32 v148, v137
	s_nop 0
	v_mov_b32_e32 v149, v143
	v_mov_b32_e32 v147, v136
	ds_read_b128 v[136:139], v150 offset:4224
	ds_read_b128 v[140:143], v150 offset:4288
	v_pk_mul_f32 v[66:67], v[66:67], v[144:145]
	v_pk_mul_f32 v[62:63], v[62:63], v[144:145]
	v_pk_mul_f32 v[60:61], v[60:61], v[148:149]
	s_waitcnt lgkmcnt(1)
	s_nop 0
	v_mov_b32_e32 v144, v136
	v_mov_b32_e32 v145, v137
	v_mov_b32_e32 v136, v138
	v_mov_b32_e32 v137, v139
	s_nop 0
	s_nop 0
	v_pk_mul_f32 v[58:59], v[58:59], v[146:147]
	v_pk_mul_f32 v[80:81], v[80:81], v[148:149]
	v_pk_mul_f32 v[78:79], v[78:79], v[146:147]
	v_pk_mul_f32 v[76:77], v[76:77], v[136:137]
	v_pk_mul_f32 v[72:73], v[72:73], v[136:137]
	s_waitcnt lgkmcnt(0)
	v_mov_b32_e32 v136, v140
	v_mov_b32_e32 v137, v142
	v_mov_b32_e32 v146, v136
	v_mov_b32_e32 v136, v141
	v_mov_b32_e32 v148, v137
	s_nop 0
	v_mov_b32_e32 v149, v143
	v_mov_b32_e32 v147, v136
	ds_read_b128 v[136:139], v150 offset:4352
	ds_read_b128 v[140:143], v150 offset:4416
	s_nop 0
	v_mfma_f32_16x16x32_bf16 v[26:29], v[164:167], v[172:175], v[26:29]
	v_mul_f32_e64 v84, v84, v148
	v_mul_f32_e64 v85, v85, v149
	s_waitcnt lgkmcnt(1)
	s_nop 0
	v_pk_mul_f32 v[74:75], v[74:75], v[144:145]
	v_pk_mul_f32 v[70:71], v[70:71], v[144:145]
	v_mov_b32_e32 v144, v136
	v_mov_b32_e32 v145, v137
	v_mov_b32_e32 v136, v138
	v_mov_b32_e32 v137, v139
	s_nop 0
	s_nop 0
	v_pk_mul_f32 v[82:83], v[82:83], v[146:147]
	v_pk_mul_f32 v[88:89], v[88:89], v[148:149]
	v_pk_mul_f32 v[86:87], v[86:87], v[146:147]
	v_pk_mul_f32 v[32:33], v[32:33], v[136:137]
	v_pk_mul_f32 v[28:29], v[28:29], v[136:137]
	s_waitcnt lgkmcnt(0)
	v_mov_b32_e32 v136, v140
	v_mov_b32_e32 v137, v142
	v_mov_b32_e32 v146, v136
	v_mov_b32_e32 v136, v141
	v_mov_b32_e32 v148, v137
	s_nop 0
	v_mov_b32_e32 v149, v143
	v_mov_b32_e32 v147, v136
	ds_read_b128 v[136:139], v150 offset:4480
	ds_read_b128 v[140:143], v150 offset:4544
	v_mfma_f32_16x16x32_bf16 v[34:37], v[176:179], v[168:171], v[34:37]
	s_nop 0
	v_pk_mul_f32 v[24:25], v[24:25], v[148:149]
	s_waitcnt lgkmcnt(1)
	s_nop 0
	s_nop 0
	s_nop 0
	s_nop 0
	s_waitcnt lgkmcnt(0)
	s_nop 0
	s_nop 0
	s_nop 0
	s_nop 0
	v_mfma_f32_16x16x32_bf16 v[46:49], v[176:179], v[172:175], v[46:49]
	s_nop 0
	s_nop 0
	s_nop 0
	v_mfma_f32_16x16x32_bf16 v[38:41], v[180:183], v[168:171], v[38:41]
	s_nop 0
	s_nop 0
	s_nop 0
	v_mfma_f32_16x16x32_bf16 v[42:45], v[180:183], v[172:175], v[42:45]
	s_nop 0
	s_nop 0
	v_pk_mul_f32 v[30:31], v[30:31], v[144:145]
	v_pk_mul_f32 v[26:27], v[26:27], v[144:145]
	v_pk_mul_f32 v[22:23], v[22:23], v[146:147]
	v_pk_mul_f32 v[52:53], v[52:53], v[148:149]
	v_pk_mul_f32 v[50:51], v[50:51], v[146:147]
	v_pk_mul_f32 v[36:37], v[36:37], v[138:139]
	v_pk_mul_f32 v[34:35], v[34:35], v[136:137]
	v_pk_mul_f32 v[48:49], v[48:49], v[138:139]
	v_pk_mul_f32 v[46:47], v[46:47], v[136:137]
	v_pk_mul_f32 v[40:41], v[40:41], v[142:143]
	v_pk_mul_f32 v[38:39], v[38:39], v[140:141]
	v_pk_mul_f32 v[44:45], v[44:45], v[142:143]
	v_pk_mul_f32 v[42:43], v[42:43], v[140:141]
	s_cbranch_scc1 .LBB0_2101

.LBB0_2097:
	ds_read_b32 v136, v129 offset:6144
	v_lshl_add_u32 v137, s63, 9, v110
	s_waitcnt lgkmcnt(0)
	v_add_f32_e32 v1, v1, v136
	v_mul_f32_e32 v255, 0x3fb8aa3b, v136
	v_exp_f32_e32 v255, v255
	s_nop 0
	ds_write_b32 v137, v255 offset:4096
	s_or_b64 exec, exec, s[30:31]
	s_and_saveexec_b64 s[30:31], s[2:3]
	s_cbranch_execz .LBB0_2096

.LBB0_2109:
	s_waitcnt lgkmcnt(1)
	v_add_f32_e32 v91, v151, v90
	v_add_f32_e32 v92, v150, v90
	ds_write2st64_b32 v118, v91, v92 offset0:24 offset1:26
	v_add_f32_e32 v91, v149, v90
	v_add_f32_e32 v92, v148, v90
	ds_write2st64_b32 v118, v91, v92 offset0:28 offset1:30
	v_add_f32_e32 v91, v147, v90
	v_add_f32_e32 v92, v146, v90
	ds_write2st64_b32 v118, v91, v92 offset0:32 offset1:34
	v_add_f32_e32 v91, v145, v90
	v_add_f32_e32 v92, v144, v90
	ds_write2st64_b32 v118, v91, v92 offset0:36 offset1:38
	v_add_f32_e32 v91, v143, v90
	v_add_f32_e32 v92, v142, v90
	ds_write2st64_b32 v118, v91, v92 offset0:40 offset1:42
	v_add_f32_e32 v91, v141, v90
	v_add_f32_e32 v92, v140, v90
	s_and_b32 s14, s23, 1
	ds_write2st64_b32 v118, v91, v92 offset0:44 offset1:46
	v_add_f32_e32 v91, v133, v90
	v_add_f32_e32 v92, v132, v90
	ds_write2st64_b32 v118, v91, v92 offset0:48 offset1:50
	v_add_f32_e32 v91, v131, v90
	v_add_f32_e32 v90, v130, v90
	s_lshl_b32 s23, s14, 9
	ds_write2st64_b32 v118, v91, v90 offset0:52 offset1:54
	s_waitcnt lgkmcnt(0)
	s_barrier
	s_and_saveexec_b64 s[14:15], s[4:5]
	s_cbranch_execz .LBB0_2111
	ds_read_b32 v90, v129 offset:6144
	v_add_u32_e32 v91, s23, v110
	s_waitcnt lgkmcnt(0)
	v_add_f32_e32 v1, v1, v90
	v_mul_f32_e32 v255, 0x3fb8aa3b, v90
	v_exp_f32_e32 v255, v255
	s_nop 0
	ds_write_b32 v91, v255 offset:4096
.LBB0_2111:
	s_or_b64 exec, exec, s[14:15]
	ds_read_b128 v[90:93], v119 offset:6144
	ds_read_b128 v[130:133], v119 offset:6160
	s_waitcnt vmcnt(5)
	v_lshlrev_b32_e32 v134, 16, v54
	v_and_b32_e32 v135, 0xffff0000, v54
	s_waitcnt lgkmcnt(1)
	v_mul_f32_e32 v90, 0xbfb8aa3b, v90
	v_mul_f32_e32 v91, 0xbfb8aa3b, v91
	v_exp_f32_e32 v90, v90
	v_exp_f32_e32 v91, v91
	v_mul_f32_e32 v54, 0xbfb8aa3b, v92
	v_exp_f32_e32 v92, v54
	v_mul_f32_e32 v54, 0xbfb8aa3b, v93
	v_exp_f32_e32 v93, v54
	v_pk_mul_f32 v[90:91], v[90:91], v[134:135]
	s_nop 0
	v_cvt_pk_bf16_f32 v54, v90, v91
	v_lshlrev_b32_e32 v90, 16, v55
	v_and_b32_e32 v91, 0xffff0000, v55
	s_waitcnt lgkmcnt(0)
	v_mul_f32_e32 v55, 0xbfb8aa3b, v130
	v_pk_mul_f32 v[90:91], v[92:93], v[90:91]
	v_exp_f32_e32 v92, v55
	v_mul_f32_e32 v55, 0xbfb8aa3b, v131
	v_exp_f32_e32 v93, v55
	v_cvt_pk_bf16_f32 v55, v90, v91
	v_lshlrev_b32_e32 v90, 16, v56
	v_and_b32_e32 v91, 0xffff0000, v56
	v_mul_f32_e32 v56, 0xbfb8aa3b, v132
	v_pk_mul_f32 v[90:91], v[92:93], v[90:91]
	v_exp_f32_e32 v92, v56
	v_mul_f32_e32 v56, 0xbfb8aa3b, v133
	v_exp_f32_e32 v93, v56
	v_cvt_pk_bf16_f32 v56, v90, v91
	v_lshlrev_b32_e32 v90, 16, v57
	v_and_b32_e32 v91, 0xffff0000, v57
	v_pk_mul_f32 v[90:91], v[92:93], v[90:91]
	s_waitcnt vmcnt(4)
	v_lshlrev_b32_e32 v130, 16, v6
	v_cvt_pk_bf16_f32 v57, v90, v91
	ds_write_b128 v120, v[54:57] offset:56320
	ds_read_b128 v[54:57], v121 offset:6144
	ds_read_b128 v[90:93], v121 offset:6160
	v_and_b32_e32 v131, 0xffff0000, v6
	s_waitcnt lgkmcnt(1)
	v_mul_f32_e32 v54, 0xbfb8aa3b, v54
	v_mul_f32_e32 v55, 0xbfb8aa3b, v55
	v_exp_f32_e32 v54, v54
	v_exp_f32_e32 v55, v55
	v_mul_f32_e32 v6, 0xbfb8aa3b, v56
	v_exp_f32_e32 v56, v6
	v_mul_f32_e32 v6, 0xbfb8aa3b, v57
	v_exp_f32_e32 v57, v6
	v_pk_mul_f32 v[54:55], v[54:55], v[130:131]
	s_nop 0
	v_cvt_pk_bf16_f32 v6, v54, v55
	v_lshlrev_b32_e32 v54, 16, v7
	v_and_b32_e32 v55, 0xffff0000, v7
	s_waitcnt lgkmcnt(0)
	v_mul_f32_e32 v7, 0xbfb8aa3b, v90
	v_pk_mul_f32 v[54:55], v[56:57], v[54:55]
	v_exp_f32_e32 v56, v7
	v_mul_f32_e32 v7, 0xbfb8aa3b, v91
	v_exp_f32_e32 v57, v7
	v_cvt_pk_bf16_f32 v7, v54, v55
	v_lshlrev_b32_e32 v54, 16, v8
	v_and_b32_e32 v55, 0xffff0000, v8
	v_mul_f32_e32 v8, 0xbfb8aa3b, v92
	v_pk_mul_f32 v[54:55], v[56:57], v[54:55]
	v_exp_f32_e32 v56, v8
	v_mul_f32_e32 v8, 0xbfb8aa3b, v93
	v_exp_f32_e32 v57, v8
	v_cvt_pk_bf16_f32 v8, v54, v55
	v_lshlrev_b32_e32 v54, 16, v9
	v_and_b32_e32 v55, 0xffff0000, v9
	v_pk_mul_f32 v[54:55], v[56:57], v[54:55]
	s_nop 0
	v_cvt_pk_bf16_f32 v9, v54, v55
	ds_write_b128 v122, v[6:9] offset:56320
	s_waitcnt vmcnt(3)
	ds_write_b128 v123, v[2:5]
	s_waitcnt vmcnt(2)
	ds_write_b128 v124, v[10:13]
	s_waitcnt vmcnt(1)
	ds_write_b128 v123, v[14:17] offset:16896
	s_waitcnt vmcnt(0)
	ds_write_b128 v125, v[18:21]
	s_waitcnt lgkmcnt(0)
	s_barrier
	ds_read_b64_tr_b16 v[4:5], v127 offset:57408
	ds_read_b64_tr_b16 v[2:3], v127 offset:56320
	ds_read_b64_tr_b16 v[8:9], v126 offset:2112
	ds_read_b64_tr_b16 v[6:7], v126
	ds_read_b64_tr_b16 v[12:13], v126 offset:2144
	ds_read_b64_tr_b16 v[10:11], v126 offset:32
	ds_read_b64_tr_b16 v[14:15], v127 offset:56352
	ds_read_b64_tr_b16 v[18:19], v127 offset:56384
	ds_read_b64_tr_b16 v[54:55], v127 offset:56416
	ds_read_b64_tr_b16 v[16:17], v127 offset:57440
	ds_read_b64_tr_b16 v[20:21], v127 offset:57472
	ds_read_b64_tr_b16 v[56:57], v127 offset:57504
	ds_read_b64_tr_b16 v[90:91], v127 offset:65024
	ds_read_b64_tr_b16 v[92:93], v128 offset:57408
	ds_read_b64_tr_b16 v[130:131], v126 offset:16896
	ds_read_b64_tr_b16 v[132:133], v126 offset:19008
	ds_read_b64_tr_b16 v[136:137], v126 offset:19040
	ds_read_b64_tr_b16 v[134:135], v126 offset:16928
	s_waitcnt lgkmcnt(8)
	v_mfma_f32_16x16x32_bf16 v[58:61], v[14:17], v[6:9], v[58:61]
	v_mfma_f32_16x16x32_bf16 v[14:17], v[14:17], v[10:13], v[78:81]
	v_mfma_f32_16x16x32_bf16 v[66:69], v[2:5], v[6:9], v[66:69]
	v_mfma_f32_16x16x32_bf16 v[2:5], v[2:5], v[10:13], v[62:65]
	s_nop 2
	ds_read_b64_tr_b16 v[62:63], v127 offset:65056
	ds_read_b64_tr_b16 v[138:139], v127 offset:65088
	ds_read_b64_tr_b16 v[142:143], v127 offset:65120
	ds_read_b64_tr_b16 v[64:65], v128 offset:57440
	ds_read_b64_tr_b16 v[140:141], v128 offset:57472
	ds_read_b64_tr_b16 v[144:145], v128 offset:57504
	s_waitcnt lgkmcnt(2)
	v_mfma_f32_16x16x32_bf16 v[58:61], v[62:65], v[130:133], v[58:61]
	v_mfma_f32_16x16x32_bf16 v[14:17], v[62:65], v[134:137], v[14:17]
	v_mfma_f32_16x16x32_bf16 v[62:65], v[18:21], v[6:9], v[74:77]
	s_nop 2
	ds_read_b64_tr_b16 v[74:75], v127 offset:56448
	ds_read_b64_tr_b16 v[76:77], v127 offset:57536
	v_mfma_f32_16x16x32_bf16 v[18:21], v[18:21], v[10:13], v[70:73]
	v_mfma_f32_16x16x32_bf16 v[70:73], v[54:57], v[6:9], v[82:85]
	v_mfma_f32_16x16x32_bf16 v[54:57], v[54:57], v[10:13], v[86:89]
	ds_read_b64_tr_b16 v[78:79], v127 offset:56480
	s_nop 0
	ds_read_b64_tr_b16 v[82:83], v127 offset:56512
	ds_read_b64_tr_b16 v[86:87], v127 offset:56544
	ds_read_b64_tr_b16 v[80:81], v127 offset:57568
	ds_read_b64_tr_b16 v[84:85], v127 offset:57600
	ds_read_b64_tr_b16 v[88:89], v127 offset:57632
	s_waitcnt lgkmcnt(1)
	v_mfma_f32_16x16x32_bf16 v[34:37], v[82:85], v[6:9], v[34:37]
	v_mfma_f32_16x16x32_bf16 v[46:49], v[82:85], v[10:13], v[46:49]
	v_add_u32_e32 v82, s23, v111
	s_ashr_i32 s23, s22, 31
	s_lshl_b64 s[14:15], s[22:23], 17
	v_mfma_f32_16x16x32_bf16 v[66:69], v[90:93], v[130:133], v[66:69]
	v_mfma_f32_16x16x32_bf16 v[2:5], v[90:93], v[134:137], v[2:5]
	ds_read_b64_tr_b16 v[90:91], v127 offset:65152
	ds_read_b64_tr_b16 v[92:93], v128 offset:57536
	v_mfma_f32_16x16x32_bf16 v[62:65], v[138:141], v[130:133], v[62:65]
	v_mfma_f32_16x16x32_bf16 v[18:21], v[138:141], v[134:137], v[18:21]
	v_mfma_f32_16x16x32_bf16 v[70:73], v[142:145], v[130:133], v[70:73]
	v_mfma_f32_16x16x32_bf16 v[54:57], v[142:145], v[134:137], v[54:57]
	v_mfma_f32_16x16x32_bf16 v[30:33], v[74:77], v[6:9], v[30:33]
	v_mfma_f32_16x16x32_bf16 v[26:29], v[74:77], v[10:13], v[26:29]
	ds_read_b64_tr_b16 v[74:75], v127 offset:65184
	ds_read_b64_tr_b16 v[138:139], v127 offset:65216
	ds_read_b64_tr_b16 v[142:143], v127 offset:65248
	ds_read_b64_tr_b16 v[76:77], v128 offset:57568
	ds_read_b64_tr_b16 v[140:141], v128 offset:57600
	ds_read_b64_tr_b16 v[144:145], v128 offset:57632
	v_mfma_f32_16x16x32_bf16 v[22:25], v[78:81], v[6:9], v[22:25]
	s_waitcnt lgkmcnt(8)
	v_mfma_f32_16x16x32_bf16 v[6:9], v[86:89], v[6:9], v[38:41]
	s_nop 2
	ds_read_b128 v[38:41], v82 offset:4096
	v_mfma_f32_16x16x32_bf16 v[50:53], v[78:81], v[10:13], v[50:53]
	v_mfma_f32_16x16x32_bf16 v[10:13], v[86:89], v[10:13], v[42:45]
	s_nop 2
	ds_read_b128 v[42:45], v82 offset:4160
	s_waitcnt lgkmcnt(1)
	s_nop 0
	v_mfma_f32_16x16x32_bf16 v[22:25], v[74:77], v[130:133], v[22:25]
	s_waitcnt lgkmcnt(0)
	s_nop 0
	v_mfma_f32_16x16x32_bf16 v[50:53], v[74:77], v[134:137], v[50:53]
	v_mov_b32_e32 v74, v38
	v_mov_b32_e32 v38, v39
	v_mov_b32_e32 v39, v40
	v_mov_b32_e32 v76, v39
	s_nop 0
	v_mov_b32_e32 v77, v41
	v_mov_b32_e32 v75, v38
	v_mfma_f32_16x16x32_bf16 v[30:33], v[90:93], v[130:133], v[30:33]
	v_mul_f32_e64 v40, v68, v76
	v_mul_f32_e64 v41, v69, v77
	v_pk_mul_f32 v[4:5], v[4:5], v[76:77]
	v_mov_b32_e32 v76, v42
	v_mov_b32_e32 v42, v43
	v_mov_b32_e32 v43, v44
	v_mov_b32_e32 v78, v43
	s_nop 0
	v_mov_b32_e32 v79, v45
	v_mov_b32_e32 v77, v42
	ds_read_b128 v[42:45], v82 offset:4224
	v_pk_mul_f32 v[38:39], v[66:67], v[74:75]
	ds_read_b128 v[66:69], v82 offset:4288
	v_pk_mul_f32 v[2:3], v[2:3], v[74:75]
	v_pk_mul_f32 v[60:61], v[60:61], v[78:79]
	s_waitcnt lgkmcnt(1)
	s_nop 0
	v_mov_b32_e32 v74, v42
	v_mov_b32_e32 v42, v43
	v_mov_b32_e32 v43, v44
	v_mov_b32_e32 v75, v42
	v_mov_b32_e32 v80, v43
	s_nop 0
	v_mov_b32_e32 v81, v45
	v_pk_mul_f32 v[42:43], v[62:63], v[74:75]
	s_waitcnt lgkmcnt(0)
	v_mov_b32_e32 v62, v66
	v_mov_b32_e32 v63, v68
	v_pk_mul_f32 v[58:59], v[58:59], v[76:77]
	v_pk_mul_f32 v[16:17], v[16:17], v[78:79]
	v_pk_mul_f32 v[14:15], v[14:15], v[76:77]
	v_mov_b32_e32 v76, v62
	v_mov_b32_e32 v62, v67
	v_mov_b32_e32 v78, v63
	v_mov_b32_e32 v63, v69
	v_pk_mul_f32 v[44:45], v[64:65], v[80:81]
	v_mov_b32_e32 v79, v63
	v_mov_b32_e32 v77, v62
	ds_read_b128 v[62:65], v82 offset:4352
	v_pk_mul_f32 v[18:19], v[18:19], v[74:75]
	v_pk_mul_f32 v[68:69], v[72:73], v[78:79]
	v_pk_mul_f32 v[66:67], v[70:71], v[76:77]
	ds_read_b128 v[70:73], v82 offset:4416
	s_waitcnt lgkmcnt(1)
	s_nop 0
	v_mov_b32_e32 v74, v62
	v_mov_b32_e32 v75, v63
	v_mov_b32_e32 v62, v64
	v_mov_b32_e32 v63, v65
	v_mfma_f32_16x16x32_bf16 v[26:29], v[90:93], v[134:137], v[26:29]
	s_nop 0
	s_nop 0
	v_pk_mul_f32 v[56:57], v[56:57], v[78:79]
	v_pk_mul_f32 v[54:55], v[54:55], v[76:77]
	v_mfma_f32_16x16x32_bf16 v[34:37], v[138:141], v[130:133], v[34:37]
	v_mul_f32_e64 v32, v32, v62
	v_mul_f32_e64 v33, v33, v63
	s_nop 0
	v_pk_mul_f32 v[28:29], v[28:29], v[62:63]
	s_waitcnt lgkmcnt(0)
	v_mov_b32_e32 v62, v70
	v_mov_b32_e32 v63, v72
	v_mov_b32_e32 v76, v62
	v_mov_b32_e32 v62, v71
	v_mov_b32_e32 v78, v63
	s_nop 0
	v_mov_b32_e32 v79, v73
	v_mov_b32_e32 v77, v62
	ds_read_b128 v[62:65], v82 offset:4480
	ds_read_b128 v[70:73], v82 offset:4544
	v_mfma_f32_16x16x32_bf16 v[46:49], v[138:141], v[134:137], v[46:49]
	v_mul_f32_e64 v20, v20, v80
	v_mul_f32_e64 v21, v21, v81
	s_nop 0
	s_waitcnt lgkmcnt(1)
	s_nop 0
	s_nop 0
	s_nop 0
	s_nop 0
	v_pk_mul_f32 v[30:31], v[30:31], v[74:75]
	v_pk_mul_f32 v[26:27], v[26:27], v[74:75]
	s_nop 0
	v_pk_mul_f32 v[34:35], v[34:35], v[62:63]
	v_pk_mul_f32 v[46:47], v[46:47], v[62:63]
	v_lshl_add_u64 v[62:63], v[102:103], 0, s[14:15]
	global_store_dwordx4 v[62:63], v[38:41], off
	s_nop 0
	v_pk_mul_f32 v[24:25], v[24:25], v[78:79]
	v_add_co_u32_e32 v38, vcc, s40, v62
	v_pk_mul_f32 v[22:23], v[22:23], v[76:77]
	s_nop 0
	v_addc_co_u32_e32 v39, vcc, 0, v63, vcc
	global_store_dwordx4 v[38:39], v[2:5], off
	s_nop 0
	s_nop 0
	v_add_co_u32_e32 v2, vcc, s34, v62
	v_pk_mul_f32 v[52:53], v[52:53], v[78:79]
	s_nop 0
	v_addc_co_u32_e32 v3, vcc, 0, v63, vcc
	global_store_dwordx4 v[2:3], v[58:61], off
	v_add_co_u32_e32 v2, vcc, s41, v62
	v_pk_mul_f32 v[50:51], v[50:51], v[76:77]
	s_nop 0
	v_addc_co_u32_e32 v3, vcc, 0, v63, vcc
	global_store_dwordx4 v[2:3], v[14:17], off
	v_add_co_u32_e32 v2, vcc, s39, v62
	s_waitcnt lgkmcnt(0)
	s_nop 0
	v_addc_co_u32_e32 v3, vcc, 0, v63, vcc
	global_store_dwordx4 v[2:3], v[42:45], off
	v_add_co_u32_e32 v2, vcc, s48, v62
	s_nop 0
	s_nop 0
	v_addc_co_u32_e32 v3, vcc, 0, v63, vcc
	global_store_dwordx4 v[2:3], v[18:21], off
	v_add_co_u32_e32 v2, vcc, s49, v62
	s_nop 0
	s_nop 0
	v_addc_co_u32_e32 v3, vcc, 0, v63, vcc
	global_store_dwordx4 v[2:3], v[66:69], off
	v_add_co_u32_e32 v2, vcc, s50, v62
	s_nop 0
	s_nop 0
	v_addc_co_u32_e32 v3, vcc, 0, v63, vcc
	global_store_dwordx4 v[2:3], v[54:57], off
	v_add_co_u32_e32 v2, vcc, s51, v62
	v_mfma_f32_16x16x32_bf16 v[6:9], v[142:145], v[130:133], v[6:9]
	s_nop 0
	v_addc_co_u32_e32 v3, vcc, 0, v63, vcc
	global_store_dwordx4 v[2:3], v[30:33], off
	v_add_co_u32_e32 v2, vcc, s45, v62
	v_pk_mul_f32 v[36:37], v[36:37], v[64:65]
	s_nop 0
	v_addc_co_u32_e32 v3, vcc, 0, v63, vcc
	global_store_dwordx4 v[2:3], v[26:29], off
	v_add_co_u32_e32 v2, vcc, s52, v62
	s_nop 0
	s_nop 0
	v_addc_co_u32_e32 v3, vcc, 0, v63, vcc
	global_store_dwordx4 v[2:3], v[22:25], off
	v_add_co_u32_e32 v2, vcc, s53, v62
	s_nop 0
	s_nop 0
	v_addc_co_u32_e32 v3, vcc, 0, v63, vcc
	global_store_dwordx4 v[2:3], v[50:53], off
	v_add_co_u32_e32 v2, vcc, s43, v62
	s_nop 0
	s_nop 0
	v_addc_co_u32_e32 v3, vcc, 0, v63, vcc
	global_store_dwordx4 v[2:3], v[34:37], off
	v_add_co_u32_e32 v2, vcc, s54, v62
	v_mfma_f32_16x16x32_bf16 v[10:13], v[142:145], v[134:137], v[10:13]
	v_mul_f32_e64 v48, v48, v64
	v_mul_f32_e64 v49, v49, v65
	v_addc_co_u32_e32 v3, vcc, 0, v63, vcc
	global_store_dwordx4 v[2:3], v[46:49], off
	v_add_co_u32_e32 v2, vcc, 0x1c000, v62
	v_pk_mul_f32 v[8:9], v[8:9], v[72:73]
	v_pk_mul_f32 v[6:7], v[6:7], v[70:71]
	v_addc_co_u32_e32 v3, vcc, 0, v63, vcc
	global_store_dwordx4 v[2:3], v[6:9], off
	v_add_co_u32_e32 v2, vcc, 0x1e000, v62
	v_pk_mul_f32 v[12:13], v[12:13], v[72:73]
	v_pk_mul_f32 v[10:11], v[10:11], v[70:71]
	v_addc_co_u32_e32 v3, vcc, 0, v63, vcc
	global_store_dwordx4 v[2:3], v[10:13], off
	s_and_saveexec_b64 s[14:15], s[4:5]
	s_cbranch_execz .LBB0_2073
	v_mul_f32_e32 v1, 0x3fb8aa3b, v1
	v_exp_f32_e32 v1, v1
	s_lshl_b64 s[24:25], s[22:23], 9
	v_lshl_add_u64 v[2:3], v[100:101], 0, s[24:25]
	global_store_dword v[2:3], v1, off
	s_branch .LBB0_2073

.LBB0_2182:
	s_or_b64 exec, exec, s[0:1]
	s_waitcnt lgkmcnt(0)
	s_barrier
	ds_read_b128 v[132:135], v180
	ds_read_b128 v[138:141], v180 offset:16
	s_add_i32 s56, s56, 1
	s_add_u32 s46, s46, 0xffffe000
	s_addc_u32 s47, s47, -1
	s_waitcnt lgkmcnt(1)
	v_mov_b32_e32 v78, v133
	v_mov_b32_e32 v79, v134
	v_mov_b32_e32 v133, v135
	s_waitcnt vmcnt(9)
	v_lshlrev_b32_e32 v134, 16, v162
	v_and_b32_e32 v135, 0xffff0000, v162
	v_pk_add_f32 v[78:79], v[78:79], v[132:133]
	s_waitcnt lgkmcnt(0)
	v_mov_b32_e32 v132, v140
	v_mov_b32_e32 v133, v138
	v_mov_b32_e32 v138, v141
	v_mul_f32_e32 v140, 0xbfb8aa3b, v134
	v_mul_f32_e32 v141, 0xbfb8aa3b, v135
	v_exp_f32_e32 v140, v140
	v_exp_f32_e32 v141, v141
	v_pk_add_f32 v[144:145], v[132:133], v[138:139]
	v_lshlrev_b32_e32 v138, 16, v163
	v_and_b32_e32 v139, 0xffff0000, v163
	v_add_f32_e32 v132, 1.0, v140
	v_add_f32_e32 v133, 1.0, v141
	v_mul_f32_e32 v140, 0xbfb8aa3b, v138
	v_mul_f32_e32 v141, 0xbfb8aa3b, v139
	v_rcp_f32_e32 v132, v132
	v_rcp_f32_e32 v133, v133
	v_exp_f32_e32 v140, v140
	v_exp_f32_e32 v141, v141
	s_waitcnt vmcnt(8)
	v_lshlrev_b32_e32 v162, 16, v152
	v_pk_mul_f32 v[146:147], v[132:133], v[134:135]
	v_add_f32_e32 v132, 1.0, v140
	v_add_f32_e32 v133, 1.0, v141
	v_and_b32_e32 v163, 0xffff0000, v152
	v_mul_f32_e32 v134, 0xbfb8aa3b, v162
	v_rcp_f32_e32 v132, v132
	v_rcp_f32_e32 v133, v133
	v_exp_f32_e32 v134, v134
	v_mul_f32_e32 v135, 0xbfb8aa3b, v163
	v_exp_f32_e32 v135, v135
	v_pk_mul_f32 v[200:201], v[132:133], v[138:139]
	v_add_f32_e32 v132, 1.0, v134
	v_rcp_f32_e32 v202, v132
	v_add_f32_e32 v132, 1.0, v135
	v_lshlrev_b32_e32 v152, 16, v153
	v_and_b32_e32 v153, 0xffff0000, v153
	v_rcp_f32_e32 v203, v132
	v_mul_f32_e32 v132, 0xbfb8aa3b, v152
	v_mul_f32_e32 v133, 0xbfb8aa3b, v153
	v_exp_f32_e32 v132, v132
	v_exp_f32_e32 v138, v133
	s_add_u32 s34, s34, 0xfffa0000
	s_addc_u32 s35, s35, -1
	v_add_f32_e32 v139, 1.0, v132
	ds_read_b128 v[132:135], v180 offset:512
	v_add_f32_e32 v138, 1.0, v138
	v_rcp_f32_e32 v204, v139
	v_rcp_f32_e32 v205, v138
	ds_read_b128 v[138:141], v180 offset:528
	s_waitcnt lgkmcnt(1)
	v_mov_b32_e32 v206, v133
	v_mov_b32_e32 v207, v134
	v_mov_b32_e32 v133, v135
	v_pk_add_f32 v[132:133], v[206:207], v[132:133]
	s_waitcnt lgkmcnt(0)
	v_mov_b32_e32 v134, v140
	v_mov_b32_e32 v135, v138
	v_mov_b32_e32 v138, v141
	v_pk_add_f32 v[134:135], v[134:135], v[138:139]
	v_mov_b32_e32 v138, v132
	v_mov_b32_e32 v139, v78
	v_mov_b32_e32 v78, v133
	v_pk_add_f32 v[78:79], v[138:139], v[78:79]
	v_mov_b32_e32 v132, v135
	v_mov_b32_e32 v133, v145
	v_pk_add_f32 v[78:79], v[78:79], v[132:133]
	v_mov_b32_e32 v135, v144
	v_pk_add_f32 v[132:133], v[134:135], v[78:79]
	v_mov_b64_e32 v[78:79], s[40:41]
	v_pk_fma_f32 v[132:133], v[132:133], s[38:39], v[78:79] op_sel_hi:[1,0,0]
	v_pk_mul_f32 v[138:139], v[202:203], v[162:163]
	v_mul_f32_e32 v134, 0x4b800000, v133
	v_cmp_gt_f32_e64 s[0:1], s55, v133
	v_pk_mul_f32 v[140:141], v[204:205], v[152:153]
	v_lshl_add_u64 v[152:153], s[28:29], 0, v[116:117]
	v_cndmask_b32_e64 v133, v133, v134, s[0:1]
	v_rsq_f32_e32 v133, v133
	v_lshl_add_u64 v[134:135], s[28:29], 0, v[106:107]
	v_mul_f32_e32 v144, 0x45800000, v133
	v_cndmask_b32_e64 v144, v133, v144, s[0:1]
	v_pk_mul_f32 v[148:149], v[148:149], v[144:145] op_sel_hi:[1,0]
	v_mul_f32_e32 v133, 0x4b800000, v132
	s_waitcnt vmcnt(1)
	v_pk_mul_f32 v[148:149], v[72:73], v[148:149]
	v_cmp_gt_f32_e64 s[0:1], s55, v132
	v_pk_mul_f32 v[146:147], v[146:147], v[148:149]
	v_pk_mul_f32 v[148:149], v[150:151], v[144:145] op_sel_hi:[1,0]
	v_cvt_pk_bf16_f32 v146, v146, v147
	v_pk_mul_f32 v[148:149], v[74:75], v[148:149]
	v_cndmask_b32_e64 v132, v132, v133, s[0:1]
	v_pk_mul_f32 v[148:149], v[200:201], v[148:149]
	v_rsq_f32_e32 v133, v132
	v_cvt_pk_bf16_f32 v147, v148, v149
	global_store_dwordx2 v[134:135], v[146:147], off
	v_pk_mul_f32 v[146:147], v[156:157], v[144:145] op_sel_hi:[1,0]
	v_pk_mul_f32 v[144:145], v[158:159], v[144:145] op_sel_hi:[1,0]
	s_waitcnt vmcnt(1)
	v_pk_mul_f32 v[146:147], v[68:69], v[146:147]
	v_pk_mul_f32 v[144:145], v[70:71], v[144:145]
	v_pk_mul_f32 v[138:139], v[138:139], v[146:147]
	v_pk_mul_f32 v[140:141], v[140:141], v[144:145]
	v_cvt_pk_bf16_f32 v138, v138, v139
	v_cvt_pk_bf16_f32 v139, v140, v141
	v_lshlrev_b32_e32 v132, 16, v142
	global_store_dwordx2 v[134:135], v[138:139], off offset:32
	v_mul_f32_e32 v134, 0xbfb8aa3b, v132
	v_exp_f32_e32 v135, v134
	v_mul_f32_e32 v134, 0x45800000, v133
	v_cndmask_b32_e64 v134, v133, v134, s[0:1]
	v_and_b32_e32 v133, 0xffff0000, v142
	v_mul_f32_e32 v138, 0xbfb8aa3b, v133
	v_exp_f32_e32 v139, v138
	v_add_f32_e32 v135, 1.0, v135
	v_rcp_f32_e32 v138, v135
	v_pk_mul_f32 v[140:141], v[160:161], v[134:135] op_sel_hi:[1,0]
	v_add_f32_e32 v135, 1.0, v139
	v_lshlrev_b32_e32 v142, 16, v143
	v_rcp_f32_e32 v139, v135
	v_and_b32_e32 v143, 0xffff0000, v143
	v_mul_f32_e32 v135, 0xbfb8aa3b, v142
	v_exp_f32_e32 v135, v135
	v_mul_f32_e32 v144, 0xbfb8aa3b, v143
	v_exp_f32_e32 v144, v144
	v_pk_mul_f32 v[132:133], v[138:139], v[132:133]
	v_add_f32_e32 v135, 1.0, v135
	v_rcp_f32_e32 v138, v135
	v_add_f32_e32 v135, 1.0, v144
	v_rcp_f32_e32 v139, v135
	v_pk_mul_f32 v[98:99], v[98:99], v[134:135] op_sel_hi:[1,0]
	v_pk_mul_f32 v[140:141], v[72:73], v[140:141]
	v_pk_mul_f32 v[98:99], v[74:75], v[98:99]
	v_pk_mul_f32 v[138:139], v[138:139], v[142:143]
	v_pk_mul_f32 v[132:133], v[132:133], v[140:141]
	v_pk_mul_f32 v[98:99], v[138:139], v[98:99]
	v_cvt_pk_bf16_f32 v132, v132, v133
	v_cvt_pk_bf16_f32 v133, v98, v99
	v_lshlrev_b32_e32 v98, 16, v136
	v_mul_f32_e32 v99, 0xbfb8aa3b, v98
	v_exp_f32_e32 v135, v99
	v_lshl_add_u64 v[138:139], s[28:29], 0, v[110:111]
	v_and_b32_e32 v99, 0xffff0000, v136
	global_store_dwordx2 v[138:139], v[132:133], off
	v_mul_f32_e32 v133, 0xbfb8aa3b, v99
	v_exp_f32_e32 v133, v133
	v_lshlrev_b32_e32 v136, 16, v137
	v_and_b32_e32 v137, 0xffff0000, v137
	v_add_f32_e32 v132, 1.0, v135
	v_pk_mul_f32 v[96:97], v[96:97], v[134:135] op_sel_hi:[1,0]
	v_add_f32_e32 v133, 1.0, v133
	v_mul_f32_e32 v135, 0xbfb8aa3b, v136
	v_mul_f32_e32 v138, 0xbfb8aa3b, v137
	v_rcp_f32_e32 v132, v132
	v_rcp_f32_e32 v133, v133
	v_exp_f32_e32 v135, v135
	v_exp_f32_e32 v138, v138
	v_pk_mul_f32 v[96:97], v[68:69], v[96:97]
	v_pk_mul_f32 v[98:99], v[132:133], v[98:99]
	v_add_f32_e32 v132, 1.0, v135
	v_add_f32_e32 v133, 1.0, v138
	v_rcp_f32_e32 v132, v132
	v_rcp_f32_e32 v133, v133
	v_pk_mul_f32 v[94:95], v[94:95], v[134:135] op_sel_hi:[1,0]
	v_pk_mul_f32 v[96:97], v[98:99], v[96:97]
	v_pk_mul_f32 v[94:95], v[70:71], v[94:95]
	v_pk_mul_f32 v[98:99], v[132:133], v[136:137]
	v_cvt_pk_bf16_f32 v132, v96, v97
	v_pk_mul_f32 v[98:99], v[98:99], v[94:95]
	ds_read_b128 v[94:97], v180 offset:1024
	v_cvt_pk_bf16_f32 v133, v98, v99
	v_lshl_add_u64 v[98:99], s[28:29], 0, v[112:113]
	global_store_dwordx2 v[98:99], v[132:133], off
	ds_read_b128 v[132:135], v180 offset:1040
	s_waitcnt lgkmcnt(1)
	v_mov_b32_e32 v98, v95
	v_mov_b32_e32 v99, v96
	v_mov_b32_e32 v95, v97
	v_lshlrev_b32_e32 v96, 16, v130
	v_pk_add_f32 v[98:99], v[98:99], v[94:95]
	v_and_b32_e32 v97, 0xffff0000, v130
	v_mul_f32_e32 v95, 0xbfb8aa3b, v96
	v_exp_f32_e32 v130, v95
	v_mul_f32_e32 v95, 0xbfb8aa3b, v97
	s_waitcnt lgkmcnt(0)
	v_mov_b32_e32 v94, v134
	v_exp_f32_e32 v134, v95
	v_lshlrev_b32_e32 v136, 16, v131
	v_and_b32_e32 v137, 0xffff0000, v131
	v_mul_f32_e32 v131, 0xbfb8aa3b, v136
	v_mov_b32_e32 v95, v132
	v_add_f32_e32 v132, 1.0, v134
	v_exp_f32_e32 v134, v131
	v_mul_f32_e32 v131, 0xbfb8aa3b, v137
	v_exp_f32_e32 v139, v131
	v_rcp_f32_e32 v131, v132
	v_add_f32_e32 v132, 1.0, v134
	v_rcp_f32_e32 v138, v132
	v_add_f32_e32 v132, 1.0, v139
	v_rcp_f32_e32 v139, v132
	v_mov_b32_e32 v132, v135
	v_pk_add_f32 v[132:133], v[94:95], v[132:133]
	v_lshlrev_b32_e32 v144, 16, v129
	v_pk_mul_f32 v[136:137], v[138:139], v[136:137]
	v_lshlrev_b32_e32 v138, 16, v128
	v_and_b32_e32 v139, 0xffff0000, v128
	v_mul_f32_e32 v94, 0xbfb8aa3b, v138
	v_exp_f32_e32 v94, v94
	v_mul_f32_e32 v95, 0xbfb8aa3b, v139
	v_exp_f32_e32 v95, v95
	v_and_b32_e32 v145, 0xffff0000, v129
	v_add_f32_e32 v94, 1.0, v94
	v_rcp_f32_e32 v142, v94
	v_add_f32_e32 v94, 1.0, v95
	v_add_f32_e32 v130, 1.0, v130
	v_rcp_f32_e32 v143, v94
	v_mul_f32_e32 v94, 0xbfb8aa3b, v144
	v_mul_f32_e32 v95, 0xbfb8aa3b, v145
	v_rcp_f32_e32 v130, v130
	v_exp_f32_e32 v94, v94
	v_exp_f32_e32 v128, v95
	v_lshl_add_u64 v[140:141], s[28:29], 0, v[114:115]
	v_pk_mul_f32 v[134:135], v[130:131], v[96:97]
	v_add_f32_e32 v129, 1.0, v94
	ds_read_b128 v[94:97], v180 offset:1536
	v_add_f32_e32 v128, 1.0, v128
	v_rcp_f32_e32 v146, v129
	v_rcp_f32_e32 v147, v128
	ds_read_b128 v[128:131], v180 offset:1552
	s_waitcnt lgkmcnt(1)
	v_mov_b32_e32 v148, v95
	v_mov_b32_e32 v149, v96
	v_mov_b32_e32 v95, v97
	v_pk_add_f32 v[94:95], v[148:149], v[94:95]
	s_waitcnt lgkmcnt(0)
	v_mov_b32_e32 v96, v130
	v_mov_b32_e32 v97, v128
	v_mov_b32_e32 v128, v131
	v_pk_add_f32 v[96:97], v[96:97], v[128:129]
	v_mov_b32_e32 v128, v94
	v_mov_b32_e32 v129, v98
	v_mov_b32_e32 v98, v95
	v_pk_add_f32 v[94:95], v[128:129], v[98:99]
	v_mov_b32_e32 v98, v97
	v_mov_b32_e32 v99, v133
	v_pk_add_f32 v[94:95], v[94:95], v[98:99]
	v_mov_b32_e32 v97, v132
	v_pk_add_f32 v[94:95], v[96:97], v[94:95]
	v_pk_mul_f32 v[98:99], v[146:147], v[144:145]
	v_pk_fma_f32 v[78:79], v[94:95], s[38:39], v[78:79] op_sel_hi:[1,0,0]
	s_nop 0
	v_mul_f32_e32 v94, 0x4b800000, v79
	v_cmp_gt_f32_e64 s[0:1], s55, v79
	s_nop 1
	v_cndmask_b32_e64 v79, v79, v94, s[0:1]
	v_rsq_f32_e32 v79, v79
	v_pk_mul_f32 v[94:95], v[142:143], v[138:139]
	v_mul_f32_e32 v96, 0x45800000, v79
	v_cndmask_b32_e64 v96, v79, v96, s[0:1]
	v_pk_mul_f32 v[88:89], v[88:89], v[96:97] op_sel_hi:[1,0]
	v_pk_mul_f32 v[92:93], v[92:93], v[96:97] op_sel_hi:[1,0]
	v_pk_mul_f32 v[88:89], v[72:73], v[88:89]
	v_pk_mul_f32 v[92:93], v[74:75], v[92:93]
	v_pk_mul_f32 v[88:89], v[134:135], v[88:89]
	v_pk_mul_f32 v[92:93], v[136:137], v[92:93]
	v_cvt_pk_bf16_f32 v88, v88, v89
	v_cvt_pk_bf16_f32 v89, v92, v93
	global_store_dwordx2 v[140:141], v[88:89], off
	v_pk_mul_f32 v[88:89], v[90:91], v[96:97] op_sel_hi:[1,0]
	v_mul_f32_e32 v79, 0x4b800000, v78
	v_cmp_gt_f32_e64 s[0:1], s55, v78
	v_pk_mul_f32 v[88:89], v[68:69], v[88:89]
	v_pk_mul_f32 v[86:87], v[86:87], v[96:97] op_sel_hi:[1,0]
	v_cndmask_b32_e64 v78, v78, v79, s[0:1]
	v_pk_mul_f32 v[200:201], v[94:95], v[88:89]
	v_pk_mul_f32 v[202:203], v[70:71], v[86:87]
	ds_read_b64_tr_b16 v[88:89], v196 offset:57408
	ds_read_b64_tr_b16 v[86:87], v196 offset:56320
	ds_read_b64_tr_b16 v[92:93], v198 offset:2112
	ds_read_b64_tr_b16 v[90:91], v198
	ds_read_b64_tr_b16 v[96:97], v198 offset:2144
	ds_read_b64_tr_b16 v[94:95], v198 offset:32
	ds_read_b64_tr_b16 v[128:129], v196 offset:56352
	ds_read_b64_tr_b16 v[132:133], v196 offset:56384
	ds_read_b64_tr_b16 v[136:137], v196 offset:56416
	ds_read_b64_tr_b16 v[130:131], v196 offset:57440
	ds_read_b64_tr_b16 v[134:135], v196 offset:57472
	ds_read_b64_tr_b16 v[138:139], v196 offset:57504
	v_rsq_f32_e32 v78, v78
	ds_read_b64_tr_b16 v[140:141], v196 offset:65024
	ds_read_b64_tr_b16 v[142:143], v197 offset:57408
	ds_read_b64_tr_b16 v[144:145], v198 offset:16896
	ds_read_b64_tr_b16 v[146:147], v198 offset:19008
	ds_read_b64_tr_b16 v[150:151], v198 offset:19040
	ds_read_b64_tr_b16 v[148:149], v198 offset:16928
	v_pk_mul_f32 v[98:99], v[98:99], v[202:203]
	s_waitcnt lgkmcnt(8)
	v_mfma_f32_16x16x32_bf16 v[12:15], v[128:131], v[90:93], v[12:15]
	v_cvt_pk_bf16_f32 v200, v200, v201
	v_cvt_pk_bf16_f32 v201, v98, v99
	v_mul_f32_e32 v79, 0x45800000, v78
	v_mfma_f32_16x16x32_bf16 v[36:39], v[128:131], v[94:97], v[36:39]
	v_lshlrev_b32_e32 v98, 16, v126
	v_cndmask_b32_e64 v78, v78, v79, s[0:1]
	v_and_b32_e32 v99, 0xffff0000, v126
	v_mfma_f32_16x16x32_bf16 v[8:11], v[86:89], v[90:93], v[8:11]
	v_mul_f32_e32 v79, 0xbfb8aa3b, v98
	v_exp_f32_e32 v79, v79
	v_mul_f32_e32 v126, 0xbfb8aa3b, v99
	v_mfma_f32_16x16x32_bf16 v[4:7], v[86:89], v[94:97], v[4:7]
	ds_read_b64_tr_b16 v[86:87], v196 offset:65056
	ds_read_b64_tr_b16 v[156:157], v196 offset:65088
	ds_read_b64_tr_b16 v[160:161], v196 offset:65120
	ds_read_b64_tr_b16 v[88:89], v197 offset:57440
	ds_read_b64_tr_b16 v[158:159], v197 offset:57472
	ds_read_b64_tr_b16 v[162:163], v197 offset:57504
	v_add_f32_e32 v79, 1.0, v79
	global_store_dwordx2 v[152:153], v[200:201], off
	s_waitcnt lgkmcnt(2)
	v_mfma_f32_16x16x32_bf16 v[12:15], v[86:89], v[144:147], v[12:15]
	v_mfma_f32_16x16x32_bf16 v[36:39], v[86:89], v[148:151], v[36:39]
	v_exp_f32_e32 v87, v126
	v_rcp_f32_e32 v86, v79
	v_add_f32_e32 v79, 1.0, v87
	v_rcp_f32_e32 v87, v79
	v_pk_mul_f32 v[84:85], v[84:85], v[78:79] op_sel_hi:[1,0]
	v_mfma_f32_16x16x32_bf16 v[24:27], v[132:135], v[90:93], v[24:27]
	v_mul_f32_e64 v72, v72, v84
	v_mul_f32_e64 v73, v73, v85
	v_pk_mul_f32 v[84:85], v[86:87], v[98:99]
	v_lshlrev_b32_e32 v86, 16, v127
	v_mul_f32_e32 v79, 0xbfb8aa3b, v86
	v_exp_f32_e32 v79, v79
	v_pk_mul_f32 v[98:99], v[84:85], v[72:73]
	v_and_b32_e32 v87, 0xffff0000, v127
	v_mfma_f32_16x16x32_bf16 v[32:35], v[132:135], v[94:97], v[32:35]
	v_add_f32_e32 v72, 1.0, v79
	v_rcp_f32_e32 v84, v72
	v_mul_f32_e32 v72, 0xbfb8aa3b, v87
	v_exp_f32_e32 v79, v72
	v_mfma_f32_16x16x32_bf16 v[40:43], v[136:139], v[90:93], v[40:43]
	v_cvt_pk_bf16_f32 v98, v98, v99
	v_pk_mul_f32 v[72:73], v[82:83], v[78:79] op_sel_hi:[1,0]
	s_nop 0
	v_pk_mul_f32 v[134:135], v[74:75], v[72:73]
	v_add_f32_e32 v72, 1.0, v79
	v_rcp_f32_e32 v85, v72
	ds_read_b64_tr_b16 v[72:73], v196 offset:56448
	ds_read_b64_tr_b16 v[74:75], v196 offset:57536
	v_mfma_f32_16x16x32_bf16 v[64:67], v[136:139], v[94:97], v[64:67]
	v_mul_f32_e64 v136, v84, v86
	v_mul_f32_e64 v137, v85, v87
	ds_read_b64_tr_b16 v[82:83], v196 offset:56480
	ds_read_b64_tr_b16 v[86:87], v196 offset:56512
	ds_read_b64_tr_b16 v[126:127], v196 offset:56544
	ds_read_b64_tr_b16 v[84:85], v196 offset:57568
	ds_read_b64_tr_b16 v[88:89], v196 offset:57600
	ds_read_b64_tr_b16 v[128:129], v196 offset:57632
	v_mfma_f32_16x16x32_bf16 v[8:11], v[140:143], v[144:147], v[8:11]
	ds_read_b64_tr_b16 v[130:131], v196 offset:65152
	ds_read_b64_tr_b16 v[132:133], v197 offset:57536
	v_mfma_f32_16x16x32_bf16 v[4:7], v[140:143], v[148:151], v[4:7]
	v_mul_f32_e64 v142, v136, v134
	v_mul_f32_e64 v143, v137, v135
	v_cvt_pk_bf16_f32 v99, v142, v143
	v_lshl_add_u64 v[142:143], s[28:29], 0, v[118:119]
	s_waitcnt lgkmcnt(8)
	v_mfma_f32_16x16x32_bf16 v[16:19], v[72:75], v[90:93], v[16:19]
	v_mfma_f32_16x16x32_bf16 v[20:23], v[72:75], v[94:97], v[20:23]
	ds_read_b64_tr_b16 v[72:73], v196 offset:65184
	ds_read_b64_tr_b16 v[134:135], v196 offset:65216
	ds_read_b64_tr_b16 v[138:139], v196 offset:65248
	ds_read_b64_tr_b16 v[74:75], v197 offset:57568
	ds_read_b64_tr_b16 v[136:137], v197 offset:57600
	ds_read_b64_tr_b16 v[140:141], v197 offset:57632
	global_store_dwordx2 v[142:143], v[98:99], off
	v_lshlrev_b32_e32 v98, 16, v124
	v_and_b32_e32 v99, 0xffff0000, v124
	v_mul_f32_e32 v79, 0xbfb8aa3b, v98
	v_exp_f32_e32 v79, v79
	v_mul_f32_e32 v124, 0xbfb8aa3b, v99
	s_waitcnt lgkmcnt(10)
	v_mfma_f32_16x16x32_bf16 v[28:31], v[82:85], v[90:93], v[28:31]
	v_add_f32_e32 v79, 1.0, v79
	v_mfma_f32_16x16x32_bf16 v[48:51], v[82:85], v[94:97], v[48:51]
	v_exp_f32_e32 v83, v124
	v_rcp_f32_e32 v82, v79
	v_add_f32_e32 v79, 1.0, v83
	v_rcp_f32_e32 v83, v79
	v_pk_mul_f32 v[80:81], v[80:81], v[78:79] op_sel_hi:[1,0]
	s_waitcnt lgkmcnt(2)
	v_mfma_f32_16x16x32_bf16 v[28:31], v[72:75], v[144:147], v[28:31]
	v_mul_f32_e64 v68, v68, v80
	v_mul_f32_e64 v69, v69, v81
	v_pk_mul_f32 v[76:77], v[76:77], v[78:79] op_sel_hi:[1,0]
	v_lshl_add_u64 v[78:79], s[28:29], 0, v[120:121]
	v_mfma_f32_16x16x32_bf16 v[48:51], v[72:75], v[148:151], v[48:51]
	v_mul_f32_e64 v72, v82, v98
	v_mul_f32_e64 v73, v83, v99
	v_pk_mul_f32 v[70:71], v[70:71], v[76:77]
	v_pk_mul_f32 v[68:69], v[72:73], v[68:69]
	v_lshlrev_b32_e32 v72, 16, v125
	v_and_b32_e32 v73, 0xffff0000, v125
	v_mul_f32_e32 v74, 0xbfb8aa3b, v72
	v_mul_f32_e32 v75, 0xbfb8aa3b, v73
	v_exp_f32_e32 v74, v74
	v_exp_f32_e32 v75, v75
	v_lshl_add_u32 v82, s57, 9, v176
	v_cvt_pk_bf16_f32 v76, v68, v69
	v_add_f32_e32 v74, 1.0, v74
	v_add_f32_e32 v75, 1.0, v75
	v_rcp_f32_e32 v74, v74
	v_rcp_f32_e32 v75, v75
	v_mfma_f32_16x16x32_bf16 v[24:27], v[156:159], v[144:147], v[24:27]
	s_add_u32 s28, s28, 0xfffe0000
	s_addc_u32 s29, s29, -1
	v_pk_mul_f32 v[72:73], v[74:75], v[72:73]
	v_mfma_f32_16x16x32_bf16 v[32:35], v[156:159], v[148:151], v[32:35]
	v_mul_f32_e64 v72, v72, v70
	v_mul_f32_e64 v73, v73, v71
	ds_read_b128 v[68:71], v82 offset:4096
	v_cvt_pk_bf16_f32 v77, v72, v73
	ds_read_b128 v[72:75], v82 offset:4160
	global_store_dwordx2 v[78:79], v[76:77], off
	v_mfma_f32_16x16x32_bf16 v[16:19], v[130:133], v[144:147], v[16:19]
	s_waitcnt lgkmcnt(1)
	s_nop 0
	v_mov_b32_e32 v80, v68
	v_mov_b32_e32 v81, v69
	v_mov_b32_e32 v68, v70
	v_mov_b32_e32 v69, v71
	s_nop 0
	s_nop 0
	s_nop 0
	v_mfma_f32_16x16x32_bf16 v[20:23], v[130:133], v[148:151], v[20:23]
	s_add_u32 s30, s30, 0xfffe0000
	v_pk_mul_f32 v[10:11], v[10:11], v[68:69]
	v_pk_mul_f32 v[6:7], v[6:7], v[68:69]
	s_waitcnt lgkmcnt(0)
	v_mov_b32_e32 v68, v72
	v_mov_b32_e32 v69, v74
	v_mov_b32_e32 v76, v68
	v_mov_b32_e32 v68, v73
	v_mov_b32_e32 v78, v69
	s_nop 0
	v_mov_b32_e32 v79, v75
	v_mov_b32_e32 v77, v68
	ds_read_b128 v[68:71], v82 offset:4224
	ds_read_b128 v[72:75], v82 offset:4288
	v_pk_mul_f32 v[8:9], v[8:9], v[80:81]
	v_pk_mul_f32 v[4:5], v[4:5], v[80:81]
	v_pk_mul_f32 v[14:15], v[14:15], v[78:79]
	s_waitcnt lgkmcnt(1)
	s_nop 0
	v_mov_b32_e32 v80, v68
	v_mov_b32_e32 v81, v69
	v_mov_b32_e32 v68, v70
	v_mov_b32_e32 v69, v71
	s_nop 0
	s_nop 0
	v_pk_mul_f32 v[12:13], v[12:13], v[76:77]
	v_pk_mul_f32 v[38:39], v[38:39], v[78:79]
	v_pk_mul_f32 v[36:37], v[36:37], v[76:77]
	v_pk_mul_f32 v[26:27], v[26:27], v[68:69]
	v_pk_mul_f32 v[34:35], v[34:35], v[68:69]
	s_waitcnt lgkmcnt(0)
	v_mov_b32_e32 v68, v72
	v_mov_b32_e32 v69, v74
	v_mov_b32_e32 v76, v68
	v_mov_b32_e32 v68, v73
	v_mov_b32_e32 v78, v69
	s_nop 0
	v_mov_b32_e32 v79, v75
	v_mov_b32_e32 v77, v68
	ds_read_b128 v[68:71], v82 offset:4352
	ds_read_b128 v[72:75], v82 offset:4416
	s_nop 0
	v_mfma_f32_16x16x32_bf16 v[40:43], v[160:163], v[144:147], v[40:43]
	s_addc_u32 s31, s31, -1
	s_waitcnt lgkmcnt(1)
	s_nop 0
	v_pk_mul_f32 v[24:25], v[24:25], v[80:81]
	v_pk_mul_f32 v[32:33], v[32:33], v[80:81]
	v_mov_b32_e32 v80, v68
	v_mov_b32_e32 v81, v69
	v_mov_b32_e32 v68, v70
	v_mov_b32_e32 v69, v71
	s_nop 0
	s_nop 0
	v_mfma_f32_16x16x32_bf16 v[64:67], v[160:163], v[148:151], v[64:67]
	v_mul_f32_e64 v42, v42, v78
	v_mul_f32_e64 v43, v43, v79
	v_pk_mul_f32 v[40:41], v[40:41], v[76:77]
	v_pk_mul_f32 v[18:19], v[18:19], v[68:69]
	v_pk_mul_f32 v[22:23], v[22:23], v[68:69]
	s_waitcnt lgkmcnt(0)
	v_mov_b32_e32 v68, v72
	v_mov_b32_e32 v69, v74
	v_pk_mul_f32 v[66:67], v[66:67], v[78:79]
	v_pk_mul_f32 v[64:65], v[64:65], v[76:77]
	v_mov_b32_e32 v76, v68
	v_mov_b32_e32 v68, v73
	v_mov_b32_e32 v78, v69
	s_nop 0
	v_mov_b32_e32 v79, v75
	v_mov_b32_e32 v77, v68
	ds_read_b128 v[68:71], v82 offset:4480
	ds_read_b128 v[72:75], v82 offset:4544
	v_mfma_f32_16x16x32_bf16 v[44:47], v[86:89], v[90:93], v[44:47]
	s_nop 0
	v_pk_mul_f32 v[30:31], v[30:31], v[78:79]
	s_waitcnt lgkmcnt(1)
	s_nop 0
	v_mfma_f32_16x16x32_bf16 v[56:59], v[86:89], v[94:97], v[56:59]
	s_nop 0
	s_nop 0
	s_nop 0
	v_mfma_f32_16x16x32_bf16 v[52:55], v[126:129], v[90:93], v[52:55]
	s_waitcnt lgkmcnt(0)
	s_nop 0
	s_nop 0
	s_nop 0
	v_mfma_f32_16x16x32_bf16 v[60:63], v[126:129], v[94:97], v[60:63]
	s_nop 0
	s_nop 0
	s_nop 0
	v_mfma_f32_16x16x32_bf16 v[44:47], v[134:137], v[144:147], v[44:47]
	s_nop 0
	s_nop 0
	s_nop 0
	v_mfma_f32_16x16x32_bf16 v[56:59], v[134:137], v[148:151], v[56:59]
	s_nop 0
	s_nop 0
	s_nop 0
	v_mfma_f32_16x16x32_bf16 v[52:55], v[138:141], v[144:147], v[52:55]
	v_mul_f32_e64 v16, v16, v80
	v_mul_f32_e64 v17, v17, v81
	v_pk_mul_f32 v[20:21], v[20:21], v[80:81]
	v_pk_mul_f32 v[28:29], v[28:29], v[76:77]
	v_mfma_f32_16x16x32_bf16 v[60:63], v[138:141], v[148:151], v[60:63]
	v_mul_f32_e64 v50, v50, v78
	v_mul_f32_e64 v51, v51, v79
	v_pk_mul_f32 v[48:49], v[48:49], v[76:77]
	v_pk_mul_f32 v[46:47], v[46:47], v[70:71]
	v_pk_mul_f32 v[44:45], v[44:45], v[68:69]
	v_pk_mul_f32 v[58:59], v[58:59], v[70:71]
	v_pk_mul_f32 v[56:57], v[56:57], v[68:69]
	v_pk_mul_f32 v[54:55], v[54:55], v[74:75]
	v_pk_mul_f32 v[52:53], v[52:53], v[72:73]
	v_pk_mul_f32 v[62:63], v[62:63], v[74:75]
	s_cmp_eq_u32 s56, 4
	v_pk_mul_f32 v[60:61], v[60:61], v[72:73]
	s_cbranch_scc1 .LBB0_2200
.LBB0_2183:
	s_add_u32 s0, s48, s34
	s_addc_u32 s1, s49, s35
	s_add_u32 s58, s39, s34
	s_addc_u32 s59, s37, s35
	s_add_u32 s42, s58, s44
	s_addc_u32 s43, s59, 0
	s_add_u32 s60, s42, 0x16e40800
	s_addc_u32 s61, s43, 0
	s_and_b32 s57, s56, 1
	s_cmp_eq_u32 s57, 0
	s_cselect_b64 s[42:43], -1, 0
	s_and_b64 s[62:63], s[42:43], exec
	s_cselect_b32 s62, 0xf0, s52
	v_add3_u32 v136, s62, v171, v170
	ds_read2_b32 v[72:73], v136 offset1:4
	v_lshl_add_u64 v[74:75], s[0:1], 0, v[102:103]
	ds_read2_b32 v[80:81], v136 offset0:64 offset1:68
	global_load_dwordx4 v[92:95], v[74:75], off
	global_load_dwordx4 v[96:99], v[74:75], off offset:1024
	ds_read2_b32 v[132:133], v136 offset0:8 offset1:12
	v_lshl_add_u64 v[82:83], s[60:61], 0, v[104:105]
	s_waitcnt lgkmcnt(2)
	v_mfma_f32_16x16x4_f32 v[68:71], v72, v155, 0
	v_add_co_u32_e64 v72, s[0:1], s50, v74
	v_mfma_f32_16x16x4_f32 v[68:71], v73, v164, v[68:71]
	s_nop 0
	v_addc_co_u32_e64 v73, s[0:1], 0, v75, s[0:1]
	global_load_dwordx4 v[84:87], v[72:73], off
	global_load_dwordx4 v[88:91], v[72:73], off offset:1024
	v_add_co_u32_e64 v72, s[0:1], s45, v82
	s_nop 1
	v_addc_co_u32_e64 v73, s[0:1], 0, v83, s[0:1]
	s_waitcnt lgkmcnt(0)
	v_mfma_f32_16x16x4_f32 v[124:127], v132, v165, v[68:71]
	v_add_co_u32_e64 v134, s[0:1], s50, v82
	global_load_dwordx4 v[68:71], v[82:83], off
	s_nop 0
	global_load_dwordx4 v[72:75], v[72:73], off
	v_addc_co_u32_e64 v135, s[0:1], 0, v83, s[0:1]
	v_mfma_f32_16x16x4_f32 v[76:79], v80, v155, 0
	v_add_co_u32_e64 v80, s[0:1], s51, v82
	v_mfma_f32_16x16x4_f32 v[124:127], v133, v166, v[124:127]
	v_mfma_f32_16x16x4_f32 v[128:131], v81, v164, v[76:79]
	v_addc_co_u32_e64 v81, s[0:1], 0, v83, s[0:1]
	s_nop 5
	global_load_dwordx4 v[76:79], v[134:135], off
	s_nop 0
	global_load_dwordx4 v[80:83], v[80:81], off
	ds_read2_b32 v[134:135], v136 offset0:72 offset1:76
	v_add_f32_e32 v124, v167, v124
	v_min_f32_e32 v137, 0, v124
	v_mul_f32_e64 v124, |v124|, s53
	v_exp_f32_e32 v124, v124
	v_add_f32_e32 v126, v167, v126
	v_mul_f32_e64 v133, |v126|, s53
	v_exp_f32_e32 v133, v133
	v_add_f32_e32 v124, 1.0, v124
	v_log_f32_e32 v124, v124
	s_waitcnt lgkmcnt(0)
	v_mfma_f32_16x16x4_f32 v[128:131], v134, v165, v[128:131]
	v_add_f32_e32 v133, 1.0, v133
	v_min_f32_e32 v139, 0, v126
	v_fmac_f32_e32 v137, 0xbf317218, v124
	v_log_f32_e32 v124, v133
	v_add_f32_e32 v134, v167, v127
	v_add_f32_e32 v125, v167, v125
	v_mul_f32_e64 v132, |v125|, s53
	v_fmac_f32_e32 v139, 0xbf317218, v124
	v_mul_f32_e64 v124, |v134|, s53
	v_min_f32_e32 v138, 0, v125
	v_exp_f32_e32 v140, v124
	v_mfma_f32_16x16x4_f32 v[124:127], v135, v166, v[128:131]
	v_exp_f32_e32 v132, v132
	v_add_f32_e32 v129, 1.0, v140
	v_log_f32_e32 v129, v129
	v_add_f32_e32 v132, 1.0, v132
	v_log_f32_e32 v132, v132
	v_min_f32_e32 v140, 0, v134
	s_nop 3
	v_add_f32_e32 v124, v167, v124
	v_mul_f32_e64 v128, |v124|, s53
	v_fmac_f32_e32 v138, 0xbf317218, v132
	v_exp_f32_e32 v128, v128
	ds_read2_b32 v[132:133], v136 offset0:128 offset1:132
	v_min_f32_e32 v141, 0, v124
	v_fmac_f32_e32 v140, 0xbf317218, v129
	v_add_f32_e32 v128, 1.0, v128
	v_log_f32_e32 v128, v128
	ds_read2_b32 v[134:135], v136 offset0:136 offset1:140
	v_add_f32_e32 v124, v167, v125
	v_mul_f32_e64 v125, |v124|, s53
	v_fmac_f32_e32 v141, 0xbf317218, v128
	s_waitcnt lgkmcnt(1)
	v_mfma_f32_16x16x4_f32 v[128:131], v132, v155, 0
	v_add_f32_e32 v132, v167, v126
	v_exp_f32_e32 v125, v125
	v_mul_f32_e64 v126, |v132|, s53
	v_exp_f32_e32 v126, v126
	v_min_f32_e32 v142, 0, v124
	v_add_f32_e32 v124, 1.0, v125
	v_add_f32_e32 v144, v167, v127
	v_mfma_f32_16x16x4_f32 v[128:131], v133, v164, v[128:131]
	v_log_f32_e32 v133, v124
	v_add_f32_e32 v124, 1.0, v126
	v_log_f32_e32 v143, v124
	v_mul_f32_e64 v145, |v144|, s53
	v_fmac_f32_e32 v142, 0xbf317218, v133
	s_waitcnt lgkmcnt(0)
	v_mfma_f32_16x16x4_f32 v[124:127], v134, v165, v[128:131]
	s_nop 2
	v_exp_f32_e32 v128, v145
	v_min_f32_e32 v145, 0, v132
	ds_read2_b32 v[132:133], v136 offset0:192 offset1:196
	v_fmac_f32_e32 v145, 0xbf317218, v143
	v_add_f32_e32 v128, 1.0, v128
	v_log_f32_e32 v128, v128
	v_min_f32_e32 v143, 0, v144
	v_mfma_f32_16x16x4_f32 v[124:127], v135, v166, v[124:127]
	v_fmac_f32_e32 v143, 0xbf317218, v128
	s_nop 8
	v_add_f32_e32 v124, v167, v124
	v_mul_f32_e64 v128, |v124|, s53
	v_exp_f32_e32 v134, v128
	s_waitcnt lgkmcnt(0)
	v_mfma_f32_16x16x4_f32 v[128:131], v132, v155, 0
	v_add_f32_e32 v125, v167, v125
	v_mul_f32_e64 v135, |v125|, s53
	v_exp_f32_e32 v132, v135
	v_min_f32_e32 v144, 0, v124
	v_add_f32_e32 v124, 1.0, v134
	ds_read2_b32 v[134:135], v136 offset0:200 offset1:204
	v_add_f32_e32 v132, 1.0, v132
	v_mfma_f32_16x16x4_f32 v[128:131], v133, v164, v[128:131]
	v_log_f32_e32 v132, v132
	v_log_f32_e32 v124, v124
	v_min_f32_e32 v133, 0, v125
	v_add_f32_e32 v146, v167, v127
	v_fmac_f32_e32 v133, 0xbf317218, v132
	v_add_f32_e32 v132, v167, v126
	v_fmac_f32_e32 v144, 0xbf317218, v124
	v_mul_f32_e64 v124, |v132|, s53
	v_exp_f32_e32 v136, v124
	s_waitcnt lgkmcnt(0)
	v_mfma_f32_16x16x4_f32 v[124:127], v134, v165, v[128:131]
	v_mul_f32_e64 v128, |v146|, s53
	v_exp_f32_e32 v128, v128
	v_add_f32_e32 v130, 1.0, v136
	v_log_f32_e32 v130, v130
	v_min_f32_e32 v129, 0, v132
	v_add_f32_e32 v128, 1.0, v128
	v_log_f32_e32 v128, v128
	v_mfma_f32_16x16x4_f32 v[124:127], v135, v166, v[124:127]
	v_fmac_f32_e32 v129, 0xbf317218, v130
	v_min_f32_e32 v130, 0, v146
	v_fmac_f32_e32 v130, 0xbf317218, v128
	s_nop 6
	v_add_f32_e32 v124, v167, v124
	v_mul_f32_e64 v131, |v124|, s53
	v_exp_f32_e32 v131, v131
	v_add_f32_e32 v125, v167, v125
	v_min_f32_e32 v124, 0, v124
	v_add_f32_e32 v126, v167, v126
	v_add_f32_e32 v128, 1.0, v131
	v_mul_f32_e64 v131, |v125|, s53
	v_log_f32_e32 v128, v128
	v_exp_f32_e32 v131, v131
	v_add_f32_e32 v127, v167, v127
	v_mul_f32_e64 v132, |v127|, s53
	v_fmac_f32_e32 v124, 0xbf317218, v128
	v_add_f32_e32 v128, 1.0, v131
	v_mul_f32_e64 v131, |v126|, s53
	v_log_f32_e32 v128, v128
	v_exp_f32_e32 v131, v131
	v_exp_f32_e32 v132, v132
	v_min_f32_e32 v125, 0, v125
	v_fmac_f32_e32 v125, 0xbf317218, v128
	v_add_f32_e32 v128, 1.0, v131
	v_add_f32_e32 v131, 1.0, v132
	v_log_f32_e32 v131, v131
	v_log_f32_e32 v128, v128
	v_min_f32_e32 v127, 0, v127
	v_min_f32_e32 v126, 0, v126
	v_fmac_f32_e32 v127, 0xbf317218, v131
	v_fmac_f32_e32 v126, 0xbf317218, v128
	v_fma_f32 v127, v127, s54, 0
	v_fmamk_f32 v126, v126, 0x3d800000, v127
	v_fmamk_f32 v125, v125, 0x3d800000, v126
	v_fmamk_f32 v124, v124, 0x3d800000, v125
	v_fmamk_f32 v128, v130, 0x3d800000, v124
	v_fmamk_f32 v129, v129, 0x3d800000, v128
	v_fmamk_f32 v130, v133, 0x3d800000, v129
	v_fmamk_f32 v131, v144, 0x3d800000, v130
	v_fmamk_f32 v132, v143, 0x3d800000, v131
	v_fmamk_f32 v133, v145, 0x3d800000, v132
	v_fmamk_f32 v134, v142, 0x3d800000, v133
	v_fmamk_f32 v135, v141, 0x3d800000, v134
	v_fmamk_f32 v136, v140, 0x3d800000, v135
	v_fmamk_f32 v139, v139, 0x3d800000, v136
	v_fmamk_f32 v138, v138, 0x3d800000, v139
	v_fmamk_f32 v137, v137, 0x3d800000, v138
	ds_bpermute_b32 v140, v174, v137
	ds_bpermute_b32 v141, v173, v137
	ds_bpermute_b32 v142, v172, v137
	s_waitcnt lgkmcnt(2)
	v_cndmask_b32_e64 v140, v140, 0, s[2:3]
	s_waitcnt lgkmcnt(1)
	v_cndmask_b32_e64 v141, 0, v141, s[4:5]
	v_add_f32_e32 v140, v141, v140
	s_waitcnt lgkmcnt(0)
	v_cndmask_b32_e64 v141, 0, v142, s[6:7]
	v_add_f32_e32 v140, v141, v140
	v_add_f32_e32 v137, v140, v137
	v_add_f32_e32 v138, v140, v138
	v_add_f32_e32 v124, v140, v124
	v_add_f32_e32 v125, v140, v125
	ds_write2st64_b32 v184, v137, v138 offset0:24 offset1:26
	v_add_f32_e32 v137, v140, v139
	v_add_f32_e32 v136, v140, v136
	v_add_f32_e32 v135, v140, v135
	v_add_f32_e32 v134, v140, v134
	v_add_f32_e32 v133, v140, v133
	v_add_f32_e32 v132, v140, v132
	v_add_f32_e32 v131, v140, v131
	v_add_f32_e32 v130, v140, v130
	v_add_f32_e32 v129, v140, v129
	v_add_f32_e32 v128, v140, v128
	ds_write2st64_b32 v184, v124, v125 offset0:48 offset1:50
	v_add_f32_e32 v124, v140, v126
	v_add_f32_e32 v125, v140, v127
	ds_write2st64_b32 v184, v137, v136 offset0:28 offset1:30
	ds_write2st64_b32 v184, v135, v134 offset0:32 offset1:34
	ds_write2st64_b32 v184, v133, v132 offset0:36 offset1:38
	ds_write2st64_b32 v184, v131, v130 offset0:40 offset1:42
	ds_write2st64_b32 v184, v129, v128 offset0:44 offset1:46
	ds_write2st64_b32 v184, v124, v125 offset0:52 offset1:54
	s_waitcnt lgkmcnt(0)
	s_barrier
	s_and_saveexec_b64 s[0:1], s[8:9]
	s_cbranch_execz .LBB0_2185
	ds_read_b32 v124, v175 offset:6144
	v_lshl_add_u32 v125, s57, 9, v175
	s_waitcnt lgkmcnt(0)
	v_mul_f32_e32 v255, 0x3fb8aa3b, v124
	v_exp_f32_e32 v255, v255
	s_nop 0
	ds_write_b32 v125, v255 offset:4096

.LBB0_2266:
	ds_read_b128 v[138:141], v205 offset:6144
	ds_read_b128 v[142:145], v205 offset:6160
	s_waitcnt vmcnt(6)
	v_lshlrev_b32_e32 v146, 16, v98
	v_and_b32_e32 v147, 0xffff0000, v98
	v_add_u32_e32 v219, 0x9800, v216
	s_waitcnt lgkmcnt(1)
	v_mul_f32_e32 v107, 0xbfb8aa3b, v138
	v_exp_f32_e32 v108, v107
	v_mul_f32_e32 v107, 0xbfb8aa3b, v139
	v_exp_f32_e32 v109, v107
	v_mul_f32_e32 v107, 0xbfb8aa3b, v140
	v_cvt_pk_bf16_f32 v160, v10, v11
	v_cvt_pk_bf16_f32 v161, v12, v13
	v_pk_mul_f32 v[108:109], v[108:109], v[146:147]
	v_lshlrev_b32_e32 v146, 16, v99
	v_cvt_pk_bf16_f32 v98, v108, v109
	v_exp_f32_e32 v108, v107
	v_mul_f32_e32 v107, 0xbfb8aa3b, v141
	v_exp_f32_e32 v109, v107
	v_and_b32_e32 v147, 0xffff0000, v99
	s_waitcnt lgkmcnt(0)
	v_mul_f32_e32 v107, 0xbfb8aa3b, v142
	v_cvt_pk_bf16_f32 v162, v26, v27
	v_pk_mul_f32 v[108:109], v[108:109], v[146:147]
	v_lshlrev_b32_e32 v146, 16, v100
	v_cvt_pk_bf16_f32 v99, v108, v109
	v_exp_f32_e32 v108, v107
	v_mul_f32_e32 v107, 0xbfb8aa3b, v143
	v_exp_f32_e32 v109, v107
	v_and_b32_e32 v147, 0xffff0000, v100
	v_mul_f32_e32 v107, 0xbfb8aa3b, v144
	v_cvt_pk_bf16_f32 v163, v28, v29
	v_pk_mul_f32 v[108:109], v[108:109], v[146:147]
	v_lshlrev_b32_e32 v146, 16, v101
	v_cvt_pk_bf16_f32 v100, v108, v109
	v_exp_f32_e32 v108, v107
	v_mul_f32_e32 v107, 0xbfb8aa3b, v145
	v_exp_f32_e32 v109, v107
	v_and_b32_e32 v147, 0xffff0000, v101
	v_add_u32_e32 v220, 0xa800, v216
	v_add_u32_e32 v221, 0xb800, v216
	v_pk_mul_f32 v[108:109], v[108:109], v[146:147]
	v_add_u32_e32 v222, 0xc800, v216
	v_cvt_pk_bf16_f32 v101, v108, v109
	ds_write_b128 v184, v[98:101] offset:56320
	v_mul_f32_e32 v98, 0x3fb8aa3b, v138
	v_mul_f32_e32 v99, 0x3fb8aa3b, v139
	v_exp_f32_e32 v98, v98
	v_exp_f32_e32 v99, v99
	v_lshlrev_b32_e32 v100, 16, v94
	v_and_b32_e32 v101, 0xffff0000, v94
	s_waitcnt vmcnt(4)
	v_lshlrev_b32_e32 v138, 16, v90
	v_pk_mul_f32 v[98:99], v[98:99], s[48:49] op_sel_hi:[1,0]
	v_and_b32_e32 v139, 0xffff0000, v90
	v_pk_mul_f32 v[98:99], v[98:99], v[100:101]
	v_lshlrev_b32_e32 v100, 16, v95
	v_cvt_pk_bf16_f32 v94, v98, v99
	v_mul_f32_e32 v98, 0x3fb8aa3b, v140
	v_mul_f32_e32 v99, 0x3fb8aa3b, v141
	v_exp_f32_e32 v98, v98
	v_exp_f32_e32 v99, v99
	v_and_b32_e32 v101, 0xffff0000, v95
	s_mov_b32 s61, 0x8000
	s_add_u32 s74, s74, 0x60000
	v_pk_mul_f32 v[98:99], v[98:99], s[48:49] op_sel_hi:[1,0]
	s_addc_u32 s75, s75, 0
	v_pk_mul_f32 v[98:99], v[98:99], v[100:101]
	v_lshlrev_b32_e32 v100, 16, v96
	v_cvt_pk_bf16_f32 v95, v98, v99
	v_mul_f32_e32 v98, 0x3fb8aa3b, v142
	v_mul_f32_e32 v99, 0x3fb8aa3b, v143
	v_exp_f32_e32 v98, v98
	v_exp_f32_e32 v99, v99
	v_and_b32_e32 v101, 0xffff0000, v96
	s_add_i32 s60, s60, 64
	v_pk_mul_f32 v[98:99], v[98:99], s[48:49] op_sel_hi:[1,0]
	s_nop 0
	v_pk_mul_f32 v[98:99], v[98:99], v[100:101]
	v_lshlrev_b32_e32 v100, 16, v97
	v_cvt_pk_bf16_f32 v96, v98, v99
	v_mul_f32_e32 v98, 0x3fb8aa3b, v144
	v_mul_f32_e32 v99, 0x3fb8aa3b, v145
	v_exp_f32_e32 v98, v98
	v_exp_f32_e32 v99, v99
	v_and_b32_e32 v101, 0xffff0000, v97
	v_pk_mul_f32 v[98:99], v[98:99], s[48:49] op_sel_hi:[1,0]
	s_nop 0
	v_pk_mul_f32 v[98:99], v[98:99], v[100:101]
	s_nop 0
	v_cvt_pk_bf16_f32 v97, v98, v99
	ds_write_b128 v184, v[94:97] offset:38912
	ds_read_b128 v[94:97], v206 offset:6144
	ds_read_b128 v[98:101], v206 offset:6160
	s_waitcnt lgkmcnt(1)
	v_mul_f32_e32 v107, 0xbfb8aa3b, v94
	v_exp_f32_e32 v108, v107
	v_mul_f32_e32 v107, 0xbfb8aa3b, v95
	v_exp_f32_e32 v109, v107
	v_mul_f32_e32 v107, 0xbfb8aa3b, v96
	v_pk_mul_f32 v[108:109], v[108:109], v[138:139]
	s_nop 0
	v_cvt_pk_bf16_f32 v90, v108, v109
	v_exp_f32_e32 v108, v107
	v_mul_f32_e32 v107, 0xbfb8aa3b, v97
	v_exp_f32_e32 v109, v107
	v_lshlrev_b32_e32 v138, 16, v91
	v_and_b32_e32 v139, 0xffff0000, v91
	s_waitcnt lgkmcnt(0)
	v_mul_f32_e32 v107, 0xbfb8aa3b, v98
	v_pk_mul_f32 v[108:109], v[108:109], v[138:139]
	v_lshlrev_b32_e32 v138, 16, v92
	v_cvt_pk_bf16_f32 v91, v108, v109
	v_exp_f32_e32 v108, v107
	v_mul_f32_e32 v107, 0xbfb8aa3b, v99
	v_exp_f32_e32 v109, v107
	v_and_b32_e32 v139, 0xffff0000, v92
	v_mul_f32_e32 v107, 0xbfb8aa3b, v100
	v_pk_mul_f32 v[108:109], v[108:109], v[138:139]
	s_nop 0
	v_cvt_pk_bf16_f32 v92, v108, v109
	v_exp_f32_e32 v108, v107
	v_mul_f32_e32 v107, 0xbfb8aa3b, v101
	v_exp_f32_e32 v109, v107
	v_lshlrev_b32_e32 v138, 16, v93
	v_and_b32_e32 v139, 0xffff0000, v93
	v_pk_mul_f32 v[108:109], v[108:109], v[138:139]
	s_nop 0
	v_cvt_pk_bf16_f32 v93, v108, v109
	ds_write_b128 v185, v[90:93] offset:56320
	v_mul_f32_e32 v90, 0x3fb8aa3b, v94
	v_mul_f32_e32 v91, 0x3fb8aa3b, v95
	v_exp_f32_e32 v90, v90
	v_exp_f32_e32 v91, v91
	v_lshlrev_b32_e32 v92, 16, v70
	v_and_b32_e32 v93, 0xffff0000, v70
	v_pk_mul_f32 v[90:91], v[90:91], s[48:49] op_sel_hi:[1,0]
	s_nop 0
	v_pk_mul_f32 v[90:91], v[90:91], v[92:93]
	v_lshlrev_b32_e32 v92, 16, v71
	v_cvt_pk_bf16_f32 v70, v90, v91
	v_mul_f32_e32 v90, 0x3fb8aa3b, v96
	v_mul_f32_e32 v91, 0x3fb8aa3b, v97
	v_exp_f32_e32 v90, v90
	v_exp_f32_e32 v91, v91
	v_and_b32_e32 v93, 0xffff0000, v71
	v_pk_mul_f32 v[90:91], v[90:91], s[48:49] op_sel_hi:[1,0]
	s_nop 0
	v_pk_mul_f32 v[90:91], v[90:91], v[92:93]
	v_lshlrev_b32_e32 v92, 16, v72
	v_cvt_pk_bf16_f32 v71, v90, v91
	v_mul_f32_e32 v90, 0x3fb8aa3b, v98
	v_mul_f32_e32 v91, 0x3fb8aa3b, v99
	v_exp_f32_e32 v90, v90
	v_exp_f32_e32 v91, v91
	v_and_b32_e32 v93, 0xffff0000, v72
	v_pk_mul_f32 v[90:91], v[90:91], s[48:49] op_sel_hi:[1,0]
	s_nop 0
	v_pk_mul_f32 v[90:91], v[90:91], v[92:93]
	v_lshlrev_b32_e32 v92, 16, v73
	v_cvt_pk_bf16_f32 v72, v90, v91
	v_mul_f32_e32 v90, 0x3fb8aa3b, v100
	v_mul_f32_e32 v91, 0x3fb8aa3b, v101
	v_exp_f32_e32 v90, v90
	v_exp_f32_e32 v91, v91
	v_and_b32_e32 v93, 0xffff0000, v73
	v_pk_mul_f32 v[90:91], v[90:91], s[48:49] op_sel_hi:[1,0]
	s_nop 0
	v_pk_mul_f32 v[90:91], v[90:91], v[92:93]
	s_nop 0
	v_cvt_pk_bf16_f32 v73, v90, v91
	ds_write_b128 v185, v[70:73] offset:38912
	s_waitcnt vmcnt(3)
	ds_write_b128 v207, v[74:77]
	s_waitcnt vmcnt(2)
	ds_write_b128 v208, v[78:81]
	s_waitcnt vmcnt(1)
	ds_write_b128 v207, v[82:85] offset:16896
	s_waitcnt vmcnt(0)
	ds_write_b128 v209, v[86:89]
	s_waitcnt lgkmcnt(0)
	s_barrier
	ds_read_b128 v[70:73], v210 offset:56320
	ds_read_b128 v[74:77], v183 offset:38912
	ds_read_b128 v[78:81], v210 offset:56384
	ds_read_b128 v[82:85], v183 offset:38976
	s_waitcnt lgkmcnt(2)
	v_mfma_f32_16x16x32_bf16 v[70:73], v[70:73], v[74:77], 0
	s_waitcnt lgkmcnt(0)
	v_mfma_f32_16x16x32_bf16 v[70:73], v[78:81], v[82:85], v[70:73]
	ds_read_b128 v[78:81], v210 offset:56448
	ds_read_b128 v[86:89], v183 offset:39040
	s_waitcnt lgkmcnt(0)
	v_mfma_f32_16x16x32_bf16 v[70:73], v[78:81], v[86:89], v[70:73]
	ds_read_b128 v[78:81], v210 offset:56512
	ds_read_b128 v[90:93], v183 offset:39104
	s_waitcnt lgkmcnt(0)
	v_mfma_f32_16x16x32_bf16 v[70:73], v[78:81], v[90:93], v[70:73]
	v_mov_b32_e32 v78, s93
	s_nop 6
	v_cndmask_b32_e64 v78, v70, v78, s[12:13]
	v_cndmask_b32_e64 v70, v78, v70, s[14:15]
	v_cndmask_b32_e64 v71, 0, v71, s[14:15]
	v_cndmask_b32_e64 v72, v72, 0, s[16:17]
	v_cndmask_b32_e64 v73, v73, 0, s[18:19]
	v_cvt_pk_bf16_f32 v70, v70, v71
	v_cvt_pk_bf16_f32 v71, v72, v73
	ds_write_b64 v211, v[70:71]
	ds_read_b128 v[70:73], v212 offset:56320
	s_waitcnt lgkmcnt(0)
	v_mfma_f32_16x16x32_bf16 v[70:73], v[70:73], v[74:77], 0
	ds_read_b128 v[74:77], v212 offset:56384
	s_waitcnt lgkmcnt(0)
	v_mfma_f32_16x16x32_bf16 v[70:73], v[74:77], v[82:85], v[70:73]
	ds_read_b128 v[74:77], v212 offset:56448
	s_waitcnt lgkmcnt(0)
	v_mfma_f32_16x16x32_bf16 v[70:73], v[74:77], v[86:89], v[70:73]
	ds_read_b128 v[74:77], v212 offset:56512
	s_waitcnt lgkmcnt(0)
	v_mfma_f32_16x16x32_bf16 v[70:73], v[74:77], v[90:93], v[70:73]
	v_mov_b32_e32 v74, s93
	s_nop 6
	v_cndmask_b32_e64 v74, v70, v74, s[20:21]
	v_cndmask_b32_e64 v70, v74, v70, s[22:23]
	v_cndmask_b32_e64 v71, 0, v71, s[22:23]
	v_cndmask_b32_e64 v72, v72, 0, s[24:25]
	v_cndmask_b32_e64 v73, v73, 0, s[26:27]
	v_cvt_pk_bf16_f32 v70, v70, v71
	v_cvt_pk_bf16_f32 v71, v72, v73
	ds_write_b64 v213, v[70:71]
	s_waitcnt lgkmcnt(0)
	s_barrier
	ds_read_b64_tr_b16 v[80:81], v214 offset:2112
	ds_read_b64_tr_b16 v[78:79], v214
	ds_read_b64_tr_b16 v[82:83], v214 offset:32
	ds_read_b64_tr_b16 v[70:71], v214 offset:16896
	ds_read_b64_tr_b16 v[72:73], v214 offset:19008
	ds_read_b64_tr_b16 v[84:85], v214 offset:2144
	ds_read_b64_tr_b16 v[74:75], v214 offset:16928
	ds_read_b64_tr_b16 v[76:77], v214 offset:19040
	ds_read_b128 v[86:89], v215
	ds_read_b128 v[94:97], v215 offset:64
	ds_read_b128 v[138:141], v215 offset:2368
	s_waitcnt lgkmcnt(2)
	v_mfma_f32_16x16x32_bf16 v[90:93], v[78:81], v[86:89], 0
	ds_read_b128 v[146:149], v215 offset:4672
	ds_read_b128 v[156:159], v215 offset:6976
	ds_read2_b64 v[164:167], v219 offset1:4
	v_mfma_f32_16x16x32_bf16 v[86:89], v[82:85], v[86:89], 0
	s_waitcnt lgkmcnt(4)
	v_mfma_f32_16x16x32_bf16 v[90:93], v[70:73], v[94:97], v[90:93]
	v_mfma_f32_16x16x32_bf16 v[86:89], v[74:77], v[94:97], v[86:89]
	ds_read_b128 v[94:97], v215 offset:2304
	s_waitcnt lgkmcnt(0)
	v_mfma_f32_16x16x32_bf16 v[98:101], v[78:81], v[94:97], 0
	v_mfma_f32_16x16x32_bf16 v[94:97], v[82:85], v[94:97], 0
	v_mfma_f32_16x16x32_bf16 v[98:101], v[70:73], v[138:141], v[98:101]
	v_mfma_f32_16x16x32_bf16 v[94:97], v[74:77], v[138:141], v[94:97]
	ds_read_b128 v[138:141], v215 offset:4608
	s_waitcnt lgkmcnt(0)
	v_mfma_f32_16x16x32_bf16 v[142:145], v[78:81], v[138:141], 0
	v_mfma_f32_16x16x32_bf16 v[138:141], v[82:85], v[138:141], 0
	v_mfma_f32_16x16x32_bf16 v[142:145], v[70:73], v[146:149], v[142:145]
	v_mfma_f32_16x16x32_bf16 v[138:141], v[74:77], v[146:149], v[138:141]
	ds_read_b128 v[146:149], v215 offset:6912
	s_waitcnt lgkmcnt(0)
	v_mfma_f32_16x16x32_bf16 v[150:153], v[78:81], v[146:149], 0
	v_mfma_f32_16x16x32_bf16 v[146:149], v[82:85], v[146:149], 0
	v_mfma_f32_16x16x32_bf16 v[150:153], v[70:73], v[156:159], v[150:153]
	v_mfma_f32_16x16x32_bf16 v[146:149], v[74:77], v[156:159], v[146:149]
	v_cvt_pk_bf16_f32 v156, v6, v7
	v_cvt_pk_bf16_f32 v157, v8, v9
	v_cvt_pk_bf16_f32 v158, v22, v23
	v_cvt_pk_bf16_f32 v159, v24, v25
	v_mfma_f32_16x16x32_bf16 v[86:89], v[160:163], v[164:167], v[86:89]
	s_nop 0
	v_mfma_f32_16x16x32_bf16 v[90:93], v[156:159], v[164:167], v[90:93]
	ds_read2_b64 v[164:167], v220 offset0:32 offset1:36
	s_waitcnt lgkmcnt(0)
	v_mfma_f32_16x16x32_bf16 v[98:101], v[156:159], v[164:167], v[98:101]
	v_mfma_f32_16x16x32_bf16 v[94:97], v[160:163], v[164:167], v[94:97]
	ds_read2_b64 v[164:167], v221 offset0:64 offset1:68
	s_waitcnt lgkmcnt(0)
	v_mfma_f32_16x16x32_bf16 v[142:145], v[156:159], v[164:167], v[142:145]
	v_mfma_f32_16x16x32_bf16 v[138:141], v[160:163], v[164:167], v[138:141]
	ds_read2_b64 v[164:167], v222 offset0:96 offset1:100
	s_waitcnt lgkmcnt(0)
	v_mfma_f32_16x16x32_bf16 v[150:153], v[156:159], v[164:167], v[150:153]
	v_cvt_pk_bf16_f32 v156, v14, v15
	v_cvt_pk_bf16_f32 v157, v16, v17
	v_cvt_pk_bf16_f32 v158, v38, v39
	v_mfma_f32_16x16x32_bf16 v[146:149], v[160:163], v[164:167], v[146:149]
	v_cvt_pk_bf16_f32 v159, v40, v41
	v_cvt_pk_bf16_f32 v160, v18, v19
	v_cvt_pk_bf16_f32 v161, v20, v21
	v_cvt_pk_bf16_f32 v162, v42, v43
	v_cvt_pk_bf16_f32 v163, v44, v45
	ds_read2_b64 v[164:167], v219 offset0:8 offset1:12
	s_waitcnt lgkmcnt(0)
	v_mfma_f32_16x16x32_bf16 v[90:93], v[156:159], v[164:167], v[90:93]
	v_mfma_f32_16x16x32_bf16 v[86:89], v[160:163], v[164:167], v[86:89]
	ds_read2_b64 v[164:167], v220 offset0:40 offset1:44
	s_waitcnt lgkmcnt(0)
	v_mfma_f32_16x16x32_bf16 v[98:101], v[156:159], v[164:167], v[98:101]
	v_mfma_f32_16x16x32_bf16 v[94:97], v[160:163], v[164:167], v[94:97]
	ds_read2_b64 v[164:167], v221 offset0:72 offset1:76
	s_waitcnt lgkmcnt(0)
	v_mfma_f32_16x16x32_bf16 v[142:145], v[156:159], v[164:167], v[142:145]
	v_mfma_f32_16x16x32_bf16 v[138:141], v[160:163], v[164:167], v[138:141]
	ds_read2_b64 v[164:167], v222 offset0:104 offset1:108
	s_waitcnt lgkmcnt(0)
	v_mfma_f32_16x16x32_bf16 v[150:153], v[156:159], v[164:167], v[150:153]
	v_cvt_pk_bf16_f32 v156, v30, v31
	v_cvt_pk_bf16_f32 v157, v32, v33
	v_cvt_pk_bf16_f32 v158, v46, v47
	v_mfma_f32_16x16x32_bf16 v[146:149], v[160:163], v[164:167], v[146:149]
	v_cvt_pk_bf16_f32 v159, v48, v49
	v_cvt_pk_bf16_f32 v160, v34, v35
	v_cvt_pk_bf16_f32 v161, v36, v37
	v_cvt_pk_bf16_f32 v162, v54, v55
	v_cvt_pk_bf16_f32 v163, v56, v57
	ds_read2_b64 v[164:167], v219 offset0:16 offset1:20
	s_waitcnt lgkmcnt(0)
	v_mfma_f32_16x16x32_bf16 v[90:93], v[156:159], v[164:167], v[90:93]
	v_mfma_f32_16x16x32_bf16 v[86:89], v[160:163], v[164:167], v[86:89]
	ds_read2_b64 v[164:167], v220 offset0:48 offset1:52
	s_waitcnt lgkmcnt(0)
	v_mfma_f32_16x16x32_bf16 v[98:101], v[156:159], v[164:167], v[98:101]
	v_mfma_f32_16x16x32_bf16 v[94:97], v[160:163], v[164:167], v[94:97]
	ds_read2_b64 v[164:167], v221 offset0:80 offset1:84
	s_waitcnt lgkmcnt(0)
	v_mfma_f32_16x16x32_bf16 v[142:145], v[156:159], v[164:167], v[142:145]
	v_mfma_f32_16x16x32_bf16 v[138:141], v[160:163], v[164:167], v[138:141]
	ds_read2_b64 v[164:167], v222 offset0:112 offset1:116
	s_waitcnt lgkmcnt(0)
	v_mfma_f32_16x16x32_bf16 v[150:153], v[156:159], v[164:167], v[150:153]
	v_cvt_pk_bf16_f32 v156, v50, v51
	v_cvt_pk_bf16_f32 v157, v52, v53
	v_cvt_pk_bf16_f32 v158, v62, v63
	v_mfma_f32_16x16x32_bf16 v[146:149], v[160:163], v[164:167], v[146:149]
	v_cvt_pk_bf16_f32 v159, v64, v65
	v_cvt_pk_bf16_f32 v160, v58, v59
	v_cvt_pk_bf16_f32 v161, v60, v61
	v_cvt_pk_bf16_f32 v162, v66, v67
	v_cvt_pk_bf16_f32 v163, v68, v69
	ds_read2_b64 v[164:167], v219 offset0:24 offset1:28
	s_waitcnt lgkmcnt(0)
	v_mfma_f32_16x16x32_bf16 v[90:93], v[156:159], v[164:167], v[90:93]
	v_mfma_f32_16x16x32_bf16 v[86:89], v[160:163], v[164:167], v[86:89]
	ds_read2_b64 v[164:167], v220 offset0:56 offset1:60
	s_nop 5
	v_cvt_pk_bf16_f32 v90, v90, v91
	v_cvt_pk_bf16_f32 v91, v92, v93
	s_waitcnt lgkmcnt(0)
	v_mfma_f32_16x16x32_bf16 v[98:101], v[156:159], v[164:167], v[98:101]
	v_lshl_add_u64 v[92:93], s[64:65], 0, v[118:119]
	v_cvt_pk_bf16_f32 v86, v86, v87
	v_cvt_pk_bf16_f32 v87, v88, v89
	v_mfma_f32_16x16x32_bf16 v[94:97], v[160:163], v[164:167], v[94:97]
	ds_read2_b64 v[164:167], v221 offset0:88 offset1:92
	v_add_co_u32_e32 v88, vcc, s61, v92
	s_waitcnt lgkmcnt(0)
	v_mfma_f32_16x16x32_bf16 v[142:145], v[156:159], v[164:167], v[142:145]
	global_store_dwordx2 v[92:93], v[86:87], off offset:32
	v_cvt_pk_bf16_f32 v86, v98, v99
	v_cvt_pk_bf16_f32 v87, v100, v101
	v_mfma_f32_16x16x32_bf16 v[138:141], v[160:163], v[164:167], v[138:141]
	ds_read2_b64 v[164:167], v222 offset0:120 offset1:124
	v_addc_co_u32_e32 v89, vcc, 0, v93, vcc
	global_store_dwordx2 v[88:89], v[86:87], off
	v_cvt_pk_bf16_f32 v86, v94, v95
	v_cvt_pk_bf16_f32 v87, v96, v97
	s_mov_b32 s61, 0x10000
	s_waitcnt lgkmcnt(0)
	v_mfma_f32_16x16x32_bf16 v[150:153], v[156:159], v[164:167], v[150:153]
	global_store_dwordx2 v[88:89], v[86:87], off offset:32
	v_add_co_u32_e32 v88, vcc, s61, v92
	v_mfma_f32_16x16x32_bf16 v[146:149], v[160:163], v[164:167], v[146:149]
	v_cvt_pk_bf16_f32 v86, v142, v143
	v_cvt_pk_bf16_f32 v87, v144, v145
	v_addc_co_u32_e32 v89, vcc, 0, v93, vcc
	global_store_dwordx2 v[88:89], v[86:87], off
	v_cvt_pk_bf16_f32 v86, v138, v139
	v_cvt_pk_bf16_f32 v87, v140, v141
	global_store_dwordx2 v[88:89], v[86:87], off offset:32
	v_add_co_u32_e32 v88, vcc, s81, v92
	v_cvt_pk_bf16_f32 v86, v150, v151
	v_cvt_pk_bf16_f32 v87, v152, v153
	v_addc_co_u32_e32 v89, vcc, 0, v93, vcc
	global_store_dwordx2 v[88:89], v[86:87], off
	v_cvt_pk_bf16_f32 v86, v146, v147
	v_cvt_pk_bf16_f32 v87, v148, v149
	global_store_dwordx2 v[92:93], v[90:91], off
	global_store_dwordx2 v[88:89], v[86:87], off offset:32
	ds_read_b64_tr_b16 v[88:89], v217 offset:57408
	ds_read_b64_tr_b16 v[86:87], v217 offset:56320
	ds_read_b64_tr_b16 v[90:91], v217 offset:56352
	s_waitcnt lgkmcnt(1)
	v_mfma_f32_16x16x32_bf16 v[6:9], v[86:89], v[78:81], v[6:9]
	s_add_u32 s64, s64, 0x20000
	s_addc_u32 s65, s65, 0
	s_add_i32 s95, s95, 1
	v_mfma_f32_16x16x32_bf16 v[10:13], v[86:89], v[82:85], v[10:13]
	ds_read_b64_tr_b16 v[86:87], v217 offset:65024
	ds_read_b64_tr_b16 v[88:89], v218 offset:57408
	ds_read_b64_tr_b16 v[94:95], v218 offset:57440
	ds_read_b64_tr_b16 v[92:93], v217 offset:57440
	s_cmp_lg_u32 s74, 0x300000
	s_waitcnt lgkmcnt(2)
	v_mfma_f32_16x16x32_bf16 v[6:9], v[86:89], v[70:73], v[6:9]
	v_mfma_f32_16x16x32_bf16 v[10:13], v[86:89], v[74:77], v[10:13]
	s_waitcnt lgkmcnt(0)
	v_mfma_f32_16x16x32_bf16 v[22:25], v[90:93], v[78:81], v[22:25]
	v_mfma_f32_16x16x32_bf16 v[26:29], v[90:93], v[82:85], v[26:29]
	ds_read_b64_tr_b16 v[92:93], v217 offset:65056
	ds_read_b64_tr_b16 v[86:87], v217 offset:56384
	ds_read_b64_tr_b16 v[88:89], v217 offset:57472
	s_waitcnt lgkmcnt(0)
	v_mfma_f32_16x16x32_bf16 v[14:17], v[86:89], v[78:81], v[14:17]
	v_mfma_f32_16x16x32_bf16 v[18:21], v[86:89], v[82:85], v[18:21]
	ds_read_b64_tr_b16 v[86:87], v217 offset:65088
	ds_read_b64_tr_b16 v[88:89], v218 offset:57472
	s_waitcnt lgkmcnt(0)
	v_mfma_f32_16x16x32_bf16 v[14:17], v[86:89], v[70:73], v[14:17]
	v_mfma_f32_16x16x32_bf16 v[18:21], v[86:89], v[74:77], v[18:21]
	ds_read_b64_tr_b16 v[86:87], v217 offset:56416
	ds_read_b64_tr_b16 v[88:89], v217 offset:57504
	s_waitcnt lgkmcnt(0)
	v_mfma_f32_16x16x32_bf16 v[38:41], v[86:89], v[78:81], v[38:41]
	v_mfma_f32_16x16x32_bf16 v[42:45], v[86:89], v[82:85], v[42:45]
	ds_read_b64_tr_b16 v[86:87], v217 offset:65120
	ds_read_b64_tr_b16 v[88:89], v218 offset:57504
	s_waitcnt lgkmcnt(0)
	v_mfma_f32_16x16x32_bf16 v[38:41], v[86:89], v[70:73], v[38:41]
	v_mfma_f32_16x16x32_bf16 v[42:45], v[86:89], v[74:77], v[42:45]
	ds_read_b64_tr_b16 v[86:87], v217 offset:56448
	ds_read_b64_tr_b16 v[88:89], v217 offset:57536
	s_waitcnt lgkmcnt(0)
	v_mfma_f32_16x16x32_bf16 v[30:33], v[86:89], v[78:81], v[30:33]
	v_mfma_f32_16x16x32_bf16 v[34:37], v[86:89], v[82:85], v[34:37]
	ds_read_b64_tr_b16 v[86:87], v217 offset:65152
	ds_read_b64_tr_b16 v[88:89], v218 offset:57536
	s_waitcnt lgkmcnt(0)
	v_mfma_f32_16x16x32_bf16 v[30:33], v[86:89], v[70:73], v[30:33]
	v_mfma_f32_16x16x32_bf16 v[34:37], v[86:89], v[74:77], v[34:37]
	ds_read_b64_tr_b16 v[86:87], v217 offset:56480
	ds_read_b64_tr_b16 v[88:89], v217 offset:57568
	s_waitcnt lgkmcnt(0)
	v_mfma_f32_16x16x32_bf16 v[46:49], v[86:89], v[78:81], v[46:49]
	v_mfma_f32_16x16x32_bf16 v[54:57], v[86:89], v[82:85], v[54:57]
	ds_read_b64_tr_b16 v[86:87], v217 offset:65184
	ds_read_b64_tr_b16 v[88:89], v218 offset:57568
	s_waitcnt lgkmcnt(0)
	v_mfma_f32_16x16x32_bf16 v[46:49], v[86:89], v[70:73], v[46:49]
	v_mfma_f32_16x16x32_bf16 v[54:57], v[86:89], v[74:77], v[54:57]
	ds_read_b64_tr_b16 v[86:87], v217 offset:56512
	ds_read_b64_tr_b16 v[88:89], v217 offset:57600
	s_waitcnt lgkmcnt(0)
	v_mfma_f32_16x16x32_bf16 v[50:53], v[86:89], v[78:81], v[50:53]
	v_mfma_f32_16x16x32_bf16 v[58:61], v[86:89], v[82:85], v[58:61]
	ds_read_b64_tr_b16 v[86:87], v217 offset:65216
	ds_read_b64_tr_b16 v[88:89], v218 offset:57600
	s_waitcnt lgkmcnt(0)
	v_mfma_f32_16x16x32_bf16 v[50:53], v[86:89], v[70:73], v[50:53]
	v_mfma_f32_16x16x32_bf16 v[58:61], v[86:89], v[74:77], v[58:61]
	ds_read_b64_tr_b16 v[86:87], v217 offset:56544
	ds_read_b64_tr_b16 v[88:89], v217 offset:57632
	s_waitcnt lgkmcnt(0)
	v_mfma_f32_16x16x32_bf16 v[62:65], v[86:89], v[78:81], v[62:65]
	ds_read_b64_tr_b16 v[78:79], v217 offset:65248
	ds_read_b64_tr_b16 v[80:81], v218 offset:57632
	v_mfma_f32_16x16x32_bf16 v[66:69], v[86:89], v[82:85], v[66:69]
	v_mfma_f32_16x16x32_bf16 v[22:25], v[92:95], v[70:73], v[22:25]
	s_waitcnt lgkmcnt(0)
	v_mfma_f32_16x16x32_bf16 v[62:65], v[78:81], v[70:73], v[62:65]
	v_lshl_add_u32 v70, s49, 9, v182
	v_mfma_f32_16x16x32_bf16 v[26:29], v[92:95], v[74:77], v[26:29]
	v_mfma_f32_16x16x32_bf16 v[66:69], v[78:81], v[74:77], v[66:69]
	ds_read_b128 v[72:75], v70 offset:4096
	s_waitcnt lgkmcnt(0)
	s_nop 0
	v_mov_b32_e32 v72, v72
	s_nop 0
	v_mov_b32_e32 v73, v73
	s_nop 0
	v_mov_b32_e32 v74, v74
	s_nop 0
	v_mov_b32_e32 v75, v75
	v_pk_mul_f32 v[6:7], v[6:7], v[72:73]
	v_pk_mul_f32 v[10:11], v[10:11], v[72:73]
	v_pk_mul_f32 v[8:9], v[8:9], v[74:75]
	v_pk_mul_f32 v[12:13], v[12:13], v[74:75]
	ds_read_b128 v[72:75], v70 offset:4160
	s_waitcnt lgkmcnt(0)
	s_nop 0
	v_mov_b32_e32 v72, v72
	s_nop 0
	v_mov_b32_e32 v73, v73
	s_nop 0
	v_mov_b32_e32 v74, v74
	s_nop 0
	v_mov_b32_e32 v75, v75
	v_pk_mul_f32 v[22:23], v[22:23], v[72:73]
	v_pk_mul_f32 v[26:27], v[26:27], v[72:73]
	v_pk_mul_f32 v[24:25], v[24:25], v[74:75]
	v_pk_mul_f32 v[28:29], v[28:29], v[74:75]
	ds_read_b128 v[72:75], v70 offset:4224
	s_waitcnt lgkmcnt(0)
	s_nop 0
	v_mov_b32_e32 v72, v72
	s_nop 0
	v_mov_b32_e32 v73, v73
	s_nop 0
	v_mov_b32_e32 v74, v74
	s_nop 0
	v_mov_b32_e32 v75, v75
	v_pk_mul_f32 v[14:15], v[14:15], v[72:73]
	v_pk_mul_f32 v[18:19], v[18:19], v[72:73]
	v_pk_mul_f32 v[16:17], v[16:17], v[74:75]
	v_pk_mul_f32 v[20:21], v[20:21], v[74:75]
	ds_read_b128 v[72:75], v70 offset:4288
	s_waitcnt lgkmcnt(0)
	s_nop 0
	v_mov_b32_e32 v72, v72
	s_nop 0
	v_mov_b32_e32 v73, v73
	s_nop 0
	v_mov_b32_e32 v74, v74
	s_nop 0
	v_mov_b32_e32 v75, v75
	v_pk_mul_f32 v[38:39], v[38:39], v[72:73]
	v_pk_mul_f32 v[42:43], v[42:43], v[72:73]
	v_pk_mul_f32 v[40:41], v[40:41], v[74:75]
	v_pk_mul_f32 v[44:45], v[44:45], v[74:75]
	ds_read_b128 v[72:75], v70 offset:4352
	s_waitcnt lgkmcnt(0)
	s_nop 0
	v_mov_b32_e32 v72, v72
	s_nop 0
	v_mov_b32_e32 v73, v73
	s_nop 0
	v_mov_b32_e32 v74, v74
	s_nop 0
	v_mov_b32_e32 v75, v75
	v_pk_mul_f32 v[30:31], v[30:31], v[72:73]
	v_pk_mul_f32 v[34:35], v[34:35], v[72:73]
	v_pk_mul_f32 v[32:33], v[32:33], v[74:75]
	v_pk_mul_f32 v[36:37], v[36:37], v[74:75]
	ds_read_b128 v[72:75], v70 offset:4416
	s_waitcnt lgkmcnt(0)
	s_nop 0
	v_mov_b32_e32 v72, v72
	s_nop 0
	v_mov_b32_e32 v73, v73
	s_nop 0
	v_mov_b32_e32 v74, v74
	s_nop 0
	v_mov_b32_e32 v75, v75
	v_pk_mul_f32 v[46:47], v[46:47], v[72:73]
	v_pk_mul_f32 v[54:55], v[54:55], v[72:73]
	v_pk_mul_f32 v[48:49], v[48:49], v[74:75]
	v_pk_mul_f32 v[56:57], v[56:57], v[74:75]
	ds_read_b128 v[72:75], v70 offset:4480
	s_waitcnt lgkmcnt(0)
	s_nop 0
	v_mov_b32_e32 v72, v72
	s_nop 0
	v_mov_b32_e32 v73, v73
	s_nop 0
	v_mov_b32_e32 v74, v74
	s_nop 0
	v_mov_b32_e32 v75, v75
	v_pk_mul_f32 v[50:51], v[50:51], v[72:73]
	v_pk_mul_f32 v[58:59], v[58:59], v[72:73]
	ds_read_b128 v[70:73], v70 offset:4544
	v_pk_mul_f32 v[52:53], v[52:53], v[74:75]
	v_pk_mul_f32 v[60:61], v[60:61], v[74:75]
	s_waitcnt lgkmcnt(0)
	s_nop 0
	s_nop 0
	s_nop 0
	s_nop 0
	s_nop 0
	s_nop 0
	s_nop 0
	s_nop 0
	v_pk_mul_f32 v[62:63], v[62:63], v[70:71]
	v_pk_mul_f32 v[66:67], v[66:67], v[70:71]
	v_pk_mul_f32 v[64:65], v[64:65], v[72:73]
	v_pk_mul_f32 v[68:69], v[68:69], v[72:73]
	s_cbranch_scc0 .LBB0_2275
.LBB0_2267:
	s_add_u32 s62, s92, s74
	s_addc_u32 s63, s94, s75
	s_add_u32 s49, s53, s74
	s_addc_u32 s61, s55, s75
	v_lshl_add_u64 v[70:71], s[62:63], 0, v[112:113]
	s_add_u32 s62, s49, s0
	v_add_co_u32_e32 v74, vcc, s72, v70
	s_addc_u32 s63, s61, 0
	s_nop 0
	v_addc_co_u32_e32 v75, vcc, 0, v71, vcc
	v_lshl_add_u64 v[86:87], s[62:63], 0, v[114:115]
	v_add_co_u32_e32 v78, vcc, s81, v86
	s_and_b32 s49, s95, 1
	s_add_i32 s89, s1, 0xf0
	v_addc_co_u32_e32 v79, vcc, 0, v87, vcc
	s_cmp_eq_u32 s49, 0
	v_add_co_u32_e32 v82, vcc, s72, v86
	s_cselect_b64 s[76:77], -1, 0
	s_nop 0
	v_addc_co_u32_e32 v83, vcc, 0, v87, vcc
	s_and_b64 s[62:63], s[76:77], exec
	global_load_dwordx4 v[94:97], v[70:71], off
	global_load_dwordx4 v[98:101], v[70:71], off offset:1024
	s_nop 0
	global_load_dwordx4 v[70:73], v[74:75], off
	global_load_dwordx4 v[90:93], v[74:75], off offset:1024
	s_cselect_b32 s61, 0xf0, s89
	global_load_dwordx4 v[74:77], v[86:87], off
	v_add_co_u32_e32 v86, vcc, s73, v86
	v_add3_u32 v137, s61, v180, v116
	s_nop 0
	v_addc_co_u32_e32 v87, vcc, 0, v87, vcc
	global_load_dwordx4 v[78:81], v[78:79], off
	s_nop 0
	global_load_dwordx4 v[82:85], v[82:83], off
	s_nop 0
	global_load_dwordx4 v[86:89], v[86:87], off
	ds_read2_b32 v[108:109], v137 offset1:4
	ds_read2_b32 v[142:143], v137 offset0:8 offset1:12
	s_waitcnt lgkmcnt(1)
	v_mfma_f32_16x16x4_f32 v[138:141], v108, v102, 0
	ds_read2_b32 v[146:147], v137 offset0:128 offset1:132
	v_mfma_f32_16x16x4_f32 v[138:141], v109, v103, v[138:141]
	s_waitcnt lgkmcnt(1)
	v_mfma_f32_16x16x4_f32 v[138:141], v142, v104, v[138:141]
	v_mfma_f32_16x16x4_f32 v[138:141], v143, v105, v[138:141]
	ds_read2_b32 v[142:143], v137 offset0:64 offset1:68
	s_nop 8
	v_add_f32_e32 v108, v106, v138
	v_min_f32_e32 v107, 0, v108
	v_mul_f32_e64 v108, |v108|, s66
	v_exp_f32_e32 v108, v108
	v_add_f32_e32 v109, v106, v139
	v_add_f32_e32 v135, v106, v140
	v_add_f32_e32 v138, v106, v141
	v_add_f32_e32 v108, 1.0, v108
	v_log_f32_e32 v108, v108
	s_nop 0
	v_fmac_f32_e32 v107, 0xbf317218, v108
	v_min_f32_e32 v108, 0, v109
	v_mul_f32_e64 v109, |v109|, s66
	v_exp_f32_e32 v109, v109
	v_fma_f32 v107, v107, s67, 0
	v_add_f32_e32 v109, 1.0, v109
	v_log_f32_e32 v109, v109
	s_nop 0
	v_fmac_f32_e32 v108, 0xbf317218, v109
	v_min_f32_e32 v109, 0, v135
	v_mul_f32_e64 v135, |v135|, s66
	v_exp_f32_e32 v135, v135
	v_fmamk_f32 v108, v108, 0x3d800000, v107
	v_add_f32_e32 v135, 1.0, v135
	v_log_f32_e32 v135, v135
	s_nop 0
	v_fmac_f32_e32 v109, 0xbf317218, v135
	v_min_f32_e32 v135, 0, v138
	v_mul_f32_e64 v138, |v138|, s66
	v_exp_f32_e32 v138, v138
	v_fmamk_f32 v109, v109, 0x3d800000, v108
	v_add_f32_e32 v138, 1.0, v138
	v_log_f32_e32 v138, v138
	s_nop 0
	v_fmac_f32_e32 v135, 0xbf317218, v138
	s_waitcnt lgkmcnt(0)
	v_mfma_f32_16x16x4_f32 v[138:141], v142, v102, 0
	v_fmamk_f32 v135, v135, 0x3d800000, v109
	v_mfma_f32_16x16x4_f32 v[138:141], v143, v103, v[138:141]
	ds_read2_b32 v[142:143], v137 offset0:72 offset1:76
	s_waitcnt lgkmcnt(0)
	v_mfma_f32_16x16x4_f32 v[138:141], v142, v104, v[138:141]
	v_mfma_f32_16x16x4_f32 v[138:141], v143, v105, v[138:141]
	s_nop 9
	v_add_f32_e32 v142, v106, v138
	v_min_f32_e32 v138, 0, v142
	v_mul_f32_e64 v142, |v142|, s66
	v_exp_f32_e32 v142, v142
	s_nop 0
	v_add_f32_e32 v142, 1.0, v142
	v_log_f32_e32 v142, v142
	s_nop 0
	v_fmac_f32_e32 v138, 0xbf317218, v142
	v_add_f32_e32 v142, v106, v139
	v_min_f32_e32 v139, 0, v142
	v_mul_f32_e64 v142, |v142|, s66
	v_exp_f32_e32 v142, v142
	s_nop 0
	v_add_f32_e32 v142, 1.0, v142
	v_log_f32_e32 v142, v142
	s_nop 0
	v_fmac_f32_e32 v139, 0xbf317218, v142
	v_add_f32_e32 v142, v106, v140
	v_min_f32_e32 v140, 0, v142
	v_mul_f32_e64 v142, |v142|, s66
	v_exp_f32_e32 v142, v142
	s_nop 0
	v_add_f32_e32 v142, 1.0, v142
	v_log_f32_e32 v142, v142
	s_nop 0
	v_fmac_f32_e32 v140, 0xbf317218, v142
	v_add_f32_e32 v142, v106, v141
	v_min_f32_e32 v141, 0, v142
	v_mul_f32_e64 v142, |v142|, s66
	v_exp_f32_e32 v142, v142
	s_nop 0
	v_add_f32_e32 v142, 1.0, v142
	v_log_f32_e32 v142, v142
	s_nop 0
	v_fmac_f32_e32 v141, 0xbf317218, v142
	v_mfma_f32_16x16x4_f32 v[142:145], v146, v102, 0
	v_mfma_f32_16x16x4_f32 v[142:145], v147, v103, v[142:145]
	ds_read2_b32 v[146:147], v137 offset0:136 offset1:140
	s_waitcnt lgkmcnt(0)
	v_mfma_f32_16x16x4_f32 v[142:145], v146, v104, v[142:145]
	v_mfma_f32_16x16x4_f32 v[142:145], v147, v105, v[142:145]
	ds_read2_b32 v[146:147], v137 offset0:192 offset1:196
	s_nop 8
	v_add_f32_e32 v142, v106, v142
	v_min_f32_e32 v148, 0, v142
	v_mul_f32_e64 v142, |v142|, s66
	v_exp_f32_e32 v142, v142
	s_nop 0
	v_add_f32_e32 v142, 1.0, v142
	v_log_f32_e32 v142, v142
	s_nop 0
	v_fmac_f32_e32 v148, 0xbf317218, v142
	v_add_f32_e32 v142, v106, v143
	v_min_f32_e32 v149, 0, v142
	v_mul_f32_e64 v142, |v142|, s66
	v_exp_f32_e32 v142, v142
	s_nop 0
	v_add_f32_e32 v142, 1.0, v142
	v_log_f32_e32 v142, v142
	s_nop 0
	v_fmac_f32_e32 v149, 0xbf317218, v142
	v_add_f32_e32 v142, v106, v144
	v_min_f32_e32 v150, 0, v142
	v_mul_f32_e64 v142, |v142|, s66
	v_exp_f32_e32 v142, v142
	s_nop 0
	v_add_f32_e32 v142, 1.0, v142
	v_log_f32_e32 v142, v142
	s_nop 0
	v_fmac_f32_e32 v150, 0xbf317218, v142
	v_add_f32_e32 v142, v106, v145
	v_min_f32_e32 v151, 0, v142
	v_mul_f32_e64 v142, |v142|, s66
	v_exp_f32_e32 v142, v142
	s_nop 0
	v_add_f32_e32 v142, 1.0, v142
	v_log_f32_e32 v142, v142
	s_nop 0
	v_fmac_f32_e32 v151, 0xbf317218, v142
	s_waitcnt lgkmcnt(0)
	v_mfma_f32_16x16x4_f32 v[142:145], v146, v102, 0
	v_mfma_f32_16x16x4_f32 v[142:145], v147, v103, v[142:145]
	ds_read2_b32 v[146:147], v137 offset0:200 offset1:204
	s_waitcnt lgkmcnt(0)
	v_mfma_f32_16x16x4_f32 v[142:145], v146, v104, v[142:145]
	v_mfma_f32_16x16x4_f32 v[142:145], v147, v105, v[142:145]
	s_nop 9
	v_add_f32_e32 v137, v106, v142
	v_min_f32_e32 v142, 0, v137
	v_mul_f32_e64 v137, |v137|, s66
	v_exp_f32_e32 v137, v137
	s_nop 0
	v_add_f32_e32 v137, 1.0, v137
	v_log_f32_e32 v137, v137
	s_nop 0
	v_fmac_f32_e32 v142, 0xbf317218, v137
	v_add_f32_e32 v137, v106, v143
	v_min_f32_e32 v143, 0, v137
	v_mul_f32_e64 v137, |v137|, s66
	v_exp_f32_e32 v137, v137
	s_nop 0
	v_add_f32_e32 v137, 1.0, v137
	v_log_f32_e32 v137, v137
	s_nop 0
	v_fmac_f32_e32 v143, 0xbf317218, v137
	v_add_f32_e32 v137, v106, v144
	v_min_f32_e32 v144, 0, v137
	v_mul_f32_e64 v137, |v137|, s66
	v_exp_f32_e32 v137, v137
	s_nop 0
	v_add_f32_e32 v137, 1.0, v137
	v_log_f32_e32 v137, v137
	s_nop 0
	v_fmac_f32_e32 v144, 0xbf317218, v137
	v_add_f32_e32 v137, v106, v145
	v_min_f32_e32 v145, 0, v137
	v_mul_f32_e64 v137, |v137|, s66
	v_exp_f32_e32 v137, v137
	s_nop 0
	v_add_f32_e32 v137, 1.0, v137
	v_log_f32_e32 v137, v137
	s_nop 0
	v_fmac_f32_e32 v145, 0xbf317218, v137
	v_fmamk_f32 v137, v138, 0x3d800000, v135
	v_fmamk_f32 v138, v139, 0x3d800000, v137
	v_fmamk_f32 v139, v140, 0x3d800000, v138
	v_fmamk_f32 v140, v141, 0x3d800000, v139
	v_fmamk_f32 v141, v148, 0x3d800000, v140
	v_fmamk_f32 v146, v149, 0x3d800000, v141
	v_fmamk_f32 v147, v150, 0x3d800000, v146
	v_fmamk_f32 v148, v151, 0x3d800000, v147
	v_fmamk_f32 v142, v142, 0x3d800000, v148
	v_fmamk_f32 v143, v143, 0x3d800000, v142
	v_fmamk_f32 v144, v144, 0x3d800000, v143
	v_fmamk_f32 v145, v145, 0x3d800000, v144
	ds_bpermute_b32 v149, v190, v145
	ds_bpermute_b32 v150, v191, v145
	ds_bpermute_b32 v151, v192, v145
	s_waitcnt lgkmcnt(2)
	v_cndmask_b32_e64 v149, v149, 0, s[4:5]
	s_waitcnt lgkmcnt(1)
	v_cndmask_b32_e64 v150, 0, v150, s[6:7]
	v_add_f32_e32 v149, v149, v150
	s_waitcnt lgkmcnt(0)
	v_cndmask_b32_e64 v150, 0, v151, s[8:9]
	v_add_f32_e32 v149, v149, v150
	v_add_f32_e32 v107, v107, v149
	v_add_f32_e32 v108, v108, v149
	ds_write2st64_b32 v204, v107, v108 offset0:24 offset1:26
	v_add_f32_e32 v107, v109, v149
	v_add_f32_e32 v108, v135, v149
	ds_write2st64_b32 v204, v107, v108 offset0:28 offset1:30
	v_add_f32_e32 v107, v137, v149
	v_add_f32_e32 v108, v138, v149
	ds_write2st64_b32 v204, v107, v108 offset0:32 offset1:34
	v_add_f32_e32 v107, v139, v149
	v_add_f32_e32 v108, v140, v149
	ds_write2st64_b32 v204, v107, v108 offset0:36 offset1:38
	v_add_f32_e32 v107, v141, v149
	v_add_f32_e32 v108, v146, v149
	ds_write2st64_b32 v204, v107, v108 offset0:40 offset1:42
	v_add_f32_e32 v107, v149, v147
	v_add_f32_e32 v108, v149, v148
	ds_write2st64_b32 v204, v107, v108 offset0:44 offset1:46
	v_add_f32_e32 v107, v149, v142
	v_add_f32_e32 v108, v149, v143
	ds_write2st64_b32 v204, v107, v108 offset0:48 offset1:50
	v_add_f32_e32 v107, v149, v144
	v_add_f32_e32 v108, v149, v145
	ds_write2st64_b32 v204, v107, v108 offset0:52 offset1:54
	s_waitcnt lgkmcnt(0)
	s_barrier
	s_and_saveexec_b64 s[62:63], s[10:11]
	s_cbranch_execz .LBB0_2269
	ds_read_b32 v107, v181 offset:38400
	v_lshl_add_u32 v108, s49, 9, v181
	s_waitcnt lgkmcnt(0)
	v_mul_f32_e32 v255, 0x3fb8aa3b, v107
	v_exp_f32_e32 v255, v255
	s_nop 0
	ds_write_b32 v108, v255 offset:4096

.LBB0_2282:
	s_or_b64 exec, exec, s[60:61]
	s_waitcnt lgkmcnt(0)
	s_barrier
	ds_read_b128 v[140:143], v188
	ds_read_b128 v[146:149], v188 offset:16
	s_waitcnt vmcnt(8)
	v_lshlrev_b32_e32 v160, 16, v170
	v_and_b32_e32 v161, 0xffff0000, v170
	v_lshlrev_b32_e32 v170, 16, v171
	s_waitcnt lgkmcnt(1)
	v_mov_b32_e32 v81, v142
	v_lshlrev_b32_e32 v142, 16, v172
	v_mov_b32_e32 v80, v141
	v_mov_b32_e32 v141, v143
	v_and_b32_e32 v143, 0xffff0000, v172
	v_mul_f32_e32 v0, 0xbfb8aa3b, v142
	v_exp_f32_e32 v0, v0
	v_mul_f32_e32 v135, 0xbfb8aa3b, v143
	v_exp_f32_e32 v135, v135
	v_pk_add_f32 v[80:81], v[80:81], v[140:141]
	s_waitcnt lgkmcnt(0)
	v_mov_b32_e32 v140, v148
	v_mov_b32_e32 v141, v146
	v_mov_b32_e32 v146, v149
	v_add_f32_e32 v0, 1.0, v0
	v_pk_add_f32 v[150:151], v[140:141], v[146:147]
	v_rcp_f32_e32 v140, v0
	v_add_f32_e32 v0, 1.0, v135
	v_lshlrev_b32_e32 v146, 16, v173
	v_rcp_f32_e32 v141, v0
	v_and_b32_e32 v147, 0xffff0000, v173
	v_mul_f32_e32 v0, 0xbfb8aa3b, v146
	v_exp_f32_e32 v0, v0
	v_mul_f32_e32 v135, 0xbfb8aa3b, v147
	v_exp_f32_e32 v135, v135
	v_pk_mul_f32 v[152:153], v[140:141], v[142:143]
	v_add_f32_e32 v0, 1.0, v0
	v_rcp_f32_e32 v140, v0
	v_add_f32_e32 v0, 1.0, v135
	v_rcp_f32_e32 v141, v0
	v_mul_f32_e32 v0, 0xbfb8aa3b, v160
	v_exp_f32_e32 v0, v0
	v_mul_f32_e32 v135, 0xbfb8aa3b, v161
	v_exp_f32_e32 v135, v135
	v_pk_mul_f32 v[172:173], v[140:141], v[146:147]
	ds_read_b128 v[140:143], v188 offset:512
	ds_read_b128 v[146:149], v188 offset:528
	v_add_f32_e32 v0, 1.0, v0
	v_rcp_f32_e32 v228, v0
	v_add_f32_e32 v0, 1.0, v135
	v_rcp_f32_e32 v229, v0
	v_mul_f32_e32 v0, 0xbfb8aa3b, v170
	v_and_b32_e32 v171, 0xffff0000, v171
	s_waitcnt lgkmcnt(1)
	v_mov_b32_e32 v232, v141
	v_mov_b32_e32 v233, v142
	v_mov_b32_e32 v141, v143
	v_exp_f32_e32 v0, v0
	v_mul_f32_e32 v135, 0xbfb8aa3b, v171
	v_pk_add_f32 v[140:141], v[232:233], v[140:141]
	s_waitcnt lgkmcnt(0)
	v_mov_b32_e32 v142, v148
	v_mov_b32_e32 v143, v146
	v_mov_b32_e32 v146, v149
	v_exp_f32_e32 v135, v135
	v_pk_add_f32 v[142:143], v[142:143], v[146:147]
	v_mov_b32_e32 v146, v140
	v_mov_b32_e32 v147, v80
	v_mov_b32_e32 v80, v141
	v_pk_add_f32 v[80:81], v[146:147], v[80:81]
	v_mov_b32_e32 v140, v143
	v_mov_b32_e32 v141, v151
	v_pk_add_f32 v[80:81], v[80:81], v[140:141]
	v_mov_b32_e32 v143, v150
	s_mov_b32 s60, 0x358637bd
	v_add_f32_e32 v0, 1.0, v0
	v_pk_add_f32 v[140:141], v[142:143], v[80:81]
	v_mov_b64_e32 v[80:81], s[60:61]
	v_rcp_f32_e32 v230, v0
	v_add_f32_e32 v0, 1.0, v135
	v_pk_fma_f32 v[140:141], v[140:141], s[50:51], v[80:81] op_sel_hi:[1,0,0]
	v_rcp_f32_e32 v231, v0
	v_mul_f32_e32 v0, 0x4b800000, v141
	v_cmp_gt_f32_e32 vcc, s80, v141
	v_pk_mul_f32 v[146:147], v[228:229], v[160:161]
	v_pk_mul_f32 v[148:149], v[230:231], v[170:171]
	v_cndmask_b32_e32 v0, v141, v0, vcc
	v_rsq_f32_e32 v0, v0
	v_lshl_add_u64 v[142:143], s[54:55], 0, v[118:119]
	s_waitcnt vmcnt(4)
	v_lshlrev_b32_e32 v150, 16, v163
	v_and_b32_e32 v151, 0xffff0000, v163
	v_mul_f32_e32 v135, 0x45800000, v0
	v_cndmask_b32_e32 v0, v0, v135, vcc
	v_pk_mul_f32 v[106:107], v[106:107], v[0:1] op_sel_hi:[1,0]
	v_pk_mul_f32 v[108:109], v[108:109], v[0:1] op_sel_hi:[1,0]
	v_pk_mul_f32 v[102:103], v[102:103], v[0:1] op_sel_hi:[1,0]
	v_pk_mul_f32 v[104:105], v[104:105], v[0:1] op_sel_hi:[1,0]
	v_mul_f32_e32 v0, 0x4b800000, v140
	v_cmp_gt_f32_e32 vcc, s80, v140
	s_waitcnt vmcnt(0)
	v_pk_mul_f32 v[102:103], v[70:71], v[102:103]
	v_pk_mul_f32 v[104:105], v[72:73], v[104:105]
	v_cndmask_b32_e32 v0, v140, v0, vcc
	v_pk_mul_f32 v[102:103], v[146:147], v[102:103]
	v_pk_mul_f32 v[104:105], v[148:149], v[104:105]
	v_rsq_f32_e32 v0, v0
	v_cvt_pk_bf16_f32 v102, v102, v103
	v_cvt_pk_bf16_f32 v103, v104, v105
	global_store_dwordx2 v[142:143], v[102:103], off offset:32
	v_lshlrev_b32_e32 v102, 16, v168
	v_mul_f32_e32 v103, 0xbfb8aa3b, v102
	v_exp_f32_e32 v104, v103
	v_mul_f32_e32 v103, 0x45800000, v0
	v_cndmask_b32_e32 v0, v0, v103, vcc
	v_and_b32_e32 v103, 0xffff0000, v168
	v_mul_f32_e32 v105, 0xbfb8aa3b, v103
	v_exp_f32_e32 v105, v105
	v_pk_mul_f32 v[106:107], v[74:75], v[106:107]
	v_pk_mul_f32 v[108:109], v[76:77], v[108:109]
	v_pk_mul_f32 v[106:107], v[152:153], v[106:107]
	v_pk_mul_f32 v[108:109], v[172:173], v[108:109]
	v_cvt_pk_bf16_f32 v106, v106, v107
	v_cvt_pk_bf16_f32 v107, v108, v109
	v_lshlrev_b32_e32 v108, 16, v169
	v_and_b32_e32 v109, 0xffff0000, v169
	v_add_f32_e32 v104, 1.0, v104
	v_add_f32_e32 v105, 1.0, v105
	v_mul_f32_e32 v135, 0xbfb8aa3b, v108
	v_mul_f32_e32 v137, 0xbfb8aa3b, v109
	v_rcp_f32_e32 v104, v104
	v_rcp_f32_e32 v105, v105
	v_exp_f32_e32 v135, v135
	v_exp_f32_e32 v137, v137
	global_store_dwordx2 v[142:143], v[106:107], off
	v_pk_mul_f32 v[102:103], v[104:105], v[102:103]
	v_add_f32_e32 v104, 1.0, v135
	v_add_f32_e32 v105, 1.0, v137
	v_rcp_f32_e32 v104, v104
	v_rcp_f32_e32 v105, v105
	v_pk_mul_f32 v[106:107], v[158:159], v[0:1] op_sel_hi:[1,0]
	v_pk_mul_f32 v[100:101], v[100:101], v[0:1] op_sel_hi:[1,0]
	v_pk_mul_f32 v[106:107], v[74:75], v[106:107]
	v_pk_mul_f32 v[100:101], v[76:77], v[100:101]
	v_pk_mul_f32 v[104:105], v[104:105], v[108:109]
	v_pk_mul_f32 v[102:103], v[102:103], v[106:107]
	v_pk_mul_f32 v[100:101], v[104:105], v[100:101]
	v_cvt_pk_bf16_f32 v102, v102, v103
	v_cvt_pk_bf16_f32 v103, v100, v101
	v_lshlrev_b32_e32 v100, 16, v166
	v_mul_f32_e32 v101, 0xbfb8aa3b, v100
	v_exp_f32_e32 v106, v101
	v_lshl_add_u64 v[104:105], s[54:55], 0, v[122:123]
	v_and_b32_e32 v101, 0xffff0000, v166
	global_store_dwordx2 v[104:105], v[102:103], off
	v_mul_f32_e32 v103, 0xbfb8aa3b, v101
	v_exp_f32_e32 v103, v103
	v_lshlrev_b32_e32 v104, 16, v167
	v_and_b32_e32 v105, 0xffff0000, v167
	v_add_f32_e32 v102, 1.0, v106
	v_add_f32_e32 v103, 1.0, v103
	v_mul_f32_e32 v106, 0xbfb8aa3b, v104
	v_mul_f32_e32 v107, 0xbfb8aa3b, v105
	v_rcp_f32_e32 v102, v102
	v_rcp_f32_e32 v103, v103
	v_exp_f32_e32 v106, v106
	v_exp_f32_e32 v107, v107
	v_pk_mul_f32 v[98:99], v[98:99], v[0:1] op_sel_hi:[1,0]
	v_pk_mul_f32 v[100:101], v[102:103], v[100:101]
	v_add_f32_e32 v102, 1.0, v106
	v_add_f32_e32 v103, 1.0, v107
	v_rcp_f32_e32 v102, v102
	v_rcp_f32_e32 v103, v103
	v_pk_mul_f32 v[98:99], v[70:71], v[98:99]
	v_pk_mul_f32 v[96:97], v[96:97], v[0:1] op_sel_hi:[1,0]
	v_pk_mul_f32 v[98:99], v[100:101], v[98:99]
	v_pk_mul_f32 v[96:97], v[72:73], v[96:97]
	v_pk_mul_f32 v[100:101], v[102:103], v[104:105]
	v_cvt_pk_bf16_f32 v102, v98, v99
	v_pk_mul_f32 v[100:101], v[100:101], v[96:97]
	ds_read_b128 v[96:99], v188 offset:1024
	v_cvt_pk_bf16_f32 v103, v100, v101
	v_lshl_add_u64 v[100:101], s[54:55], 0, v[124:125]
	global_store_dwordx2 v[100:101], v[102:103], off
	ds_read_b128 v[100:103], v188 offset:1040
	s_waitcnt lgkmcnt(1)
	v_mov_b32_e32 v105, v98
	v_lshlrev_b32_e32 v98, 16, v164
	v_mov_b32_e32 v104, v97
	v_mov_b32_e32 v97, v99
	v_and_b32_e32 v99, 0xffff0000, v164
	v_mul_f32_e32 v0, 0xbfb8aa3b, v98
	v_pk_add_f32 v[104:105], v[104:105], v[96:97]
	v_exp_f32_e32 v0, v0
	v_mul_f32_e32 v97, 0xbfb8aa3b, v99
	s_waitcnt lgkmcnt(0)
	v_mov_b32_e32 v96, v102
	v_exp_f32_e32 v102, v97
	v_lshlrev_b32_e32 v108, 16, v165
	v_mov_b32_e32 v97, v100
	v_add_f32_e32 v0, 1.0, v0
	v_and_b32_e32 v109, 0xffff0000, v165
	v_mul_f32_e32 v100, 0xbfb8aa3b, v108
	v_rcp_f32_e32 v106, v0
	v_add_f32_e32 v0, 1.0, v102
	v_exp_f32_e32 v100, v100
	v_mul_f32_e32 v102, 0xbfb8aa3b, v109
	v_exp_f32_e32 v102, v102
	v_rcp_f32_e32 v107, v0
	v_add_f32_e32 v0, 1.0, v100
	v_rcp_f32_e32 v140, v0
	v_add_f32_e32 v0, 1.0, v102
	v_rcp_f32_e32 v141, v0
	v_mov_b32_e32 v100, v103
	v_pk_add_f32 v[142:143], v[96:97], v[100:101]
	v_pk_mul_f32 v[106:107], v[106:107], v[98:99]
	v_pk_mul_f32 v[108:109], v[140:141], v[108:109]
	v_lshlrev_b32_e32 v140, 16, v162
	v_and_b32_e32 v141, 0xffff0000, v162
	v_mul_f32_e32 v0, 0xbfb8aa3b, v140
	v_exp_f32_e32 v0, v0
	v_mul_f32_e32 v96, 0xbfb8aa3b, v141
	v_exp_f32_e32 v96, v96
	v_lshl_add_u64 v[146:147], s[54:55], 0, v[126:127]
	v_add_f32_e32 v0, 1.0, v0
	v_rcp_f32_e32 v148, v0
	v_add_f32_e32 v0, 1.0, v96
	v_rcp_f32_e32 v149, v0
	v_mul_f32_e32 v0, 0xbfb8aa3b, v150
	v_exp_f32_e32 v0, v0
	v_mul_f32_e32 v96, 0xbfb8aa3b, v151
	v_exp_f32_e32 v100, v96
	ds_read_b128 v[96:99], v188 offset:1536
	v_add_f32_e32 v0, 1.0, v0
	v_rcp_f32_e32 v152, v0
	v_add_f32_e32 v0, 1.0, v100
	ds_read_b128 v[100:103], v188 offset:1552
	s_waitcnt lgkmcnt(1)
	v_mov_b32_e32 v158, v97
	v_mov_b32_e32 v159, v98
	v_mov_b32_e32 v97, v99
	v_pk_add_f32 v[96:97], v[158:159], v[96:97]
	s_waitcnt lgkmcnt(0)
	v_mov_b32_e32 v98, v102
	v_mov_b32_e32 v99, v100
	v_mov_b32_e32 v100, v103
	v_pk_add_f32 v[98:99], v[98:99], v[100:101]
	v_mov_b32_e32 v100, v96
	v_mov_b32_e32 v101, v104
	v_mov_b32_e32 v104, v97
	v_pk_add_f32 v[96:97], v[100:101], v[104:105]
	v_mov_b32_e32 v100, v99
	v_mov_b32_e32 v101, v143
	v_pk_add_f32 v[96:97], v[96:97], v[100:101]
	v_mov_b32_e32 v99, v142
	v_pk_add_f32 v[96:97], v[98:99], v[96:97]
	v_rcp_f32_e32 v153, v0
	v_pk_fma_f32 v[80:81], v[96:97], s[50:51], v[80:81] op_sel_hi:[1,0,0]
	v_pk_mul_f32 v[96:97], v[148:149], v[140:141]
	v_mul_f32_e32 v0, 0x4b800000, v81
	v_cmp_gt_f32_e32 vcc, s80, v81
	v_pk_mul_f32 v[170:171], v[152:153], v[150:151]
	v_lshl_add_u64 v[172:173], s[54:55], 0, v[128:129]
	v_cndmask_b32_e32 v0, v81, v0, vcc
	v_rsq_f32_e32 v0, v0
	s_add_i32 s74, s74, 1
	s_add_u32 s58, s58, 0xfffa0000
	s_addc_u32 s59, s59, -1
	v_mul_f32_e32 v81, 0x45800000, v0
	v_cndmask_b32_e32 v0, v0, v81, vcc
	v_pk_mul_f32 v[90:91], v[90:91], v[0:1] op_sel_hi:[1,0]
	v_pk_mul_f32 v[94:95], v[94:95], v[0:1] op_sel_hi:[1,0]
	v_pk_mul_f32 v[90:91], v[74:75], v[90:91]
	v_pk_mul_f32 v[94:95], v[76:77], v[94:95]
	v_pk_mul_f32 v[90:91], v[106:107], v[90:91]
	v_pk_mul_f32 v[94:95], v[108:109], v[94:95]
	v_cvt_pk_bf16_f32 v90, v90, v91
	v_cvt_pk_bf16_f32 v91, v94, v95
	global_store_dwordx2 v[146:147], v[90:91], off
	v_pk_mul_f32 v[90:91], v[92:93], v[0:1] op_sel_hi:[1,0]
	v_pk_mul_f32 v[88:89], v[88:89], v[0:1] op_sel_hi:[1,0]
	v_mul_f32_e32 v0, 0x4b800000, v80
	v_cmp_gt_f32_e32 vcc, s80, v80
	v_pk_mul_f32 v[90:91], v[70:71], v[90:91]
	v_pk_mul_f32 v[228:229], v[72:73], v[88:89]
	v_cndmask_b32_e32 v0, v80, v0, vcc
	v_pk_mul_f32 v[108:109], v[96:97], v[90:91]
	ds_read_b64_tr_b16 v[90:91], v217 offset:57408
	ds_read_b64_tr_b16 v[88:89], v217 offset:56320
	ds_read_b64_tr_b16 v[94:95], v214 offset:2112
	ds_read_b64_tr_b16 v[92:93], v214
	ds_read_b64_tr_b16 v[98:99], v214 offset:2144
	ds_read_b64_tr_b16 v[96:97], v214 offset:32
	ds_read_b64_tr_b16 v[100:101], v217 offset:56352
	ds_read_b64_tr_b16 v[104:105], v217 offset:56384
	ds_read_b64_tr_b16 v[140:141], v217 offset:56416
	ds_read_b64_tr_b16 v[102:103], v217 offset:57440
	ds_read_b64_tr_b16 v[106:107], v217 offset:57472
	ds_read_b64_tr_b16 v[142:143], v217 offset:57504
	v_rsq_f32_e32 v0, v0
	ds_read_b64_tr_b16 v[146:147], v217 offset:65024
	ds_read_b64_tr_b16 v[148:149], v218 offset:57408
	ds_read_b64_tr_b16 v[150:151], v214 offset:16896
	ds_read_b64_tr_b16 v[152:153], v214 offset:19008
	ds_read_b64_tr_b16 v[160:161], v214 offset:19040
	ds_read_b64_tr_b16 v[158:159], v214 offset:16928
	s_waitcnt lgkmcnt(8)
	v_mfma_f32_16x16x32_bf16 v[10:13], v[100:103], v[92:95], v[10:13]
	v_and_b32_e32 v81, 0xffff0000, v156
	v_mul_f32_e32 v80, 0x45800000, v0
	v_cndmask_b32_e32 v0, v0, v80, vcc
	v_mfma_f32_16x16x32_bf16 v[18:21], v[100:103], v[96:99], v[18:21]
	v_lshlrev_b32_e32 v80, 16, v156
	v_mul_f32_e32 v100, 0xbfb8aa3b, v80
	v_mul_f32_e32 v101, 0xbfb8aa3b, v81
	v_mfma_f32_16x16x32_bf16 v[30:33], v[88:91], v[92:95], v[30:33]
	v_exp_f32_e32 v100, v100
	v_pk_mul_f32 v[86:87], v[86:87], v[0:1] op_sel_hi:[1,0]
	v_pk_mul_f32 v[170:171], v[170:171], v[228:229]
	v_mfma_f32_16x16x32_bf16 v[6:9], v[88:91], v[96:99], v[6:9]
	ds_read_b64_tr_b16 v[88:89], v217 offset:65056
	ds_read_b64_tr_b16 v[162:163], v217 offset:65088
	ds_read_b64_tr_b16 v[166:167], v217 offset:65120
	ds_read_b64_tr_b16 v[90:91], v218 offset:57440
	ds_read_b64_tr_b16 v[164:165], v218 offset:57472
	ds_read_b64_tr_b16 v[168:169], v218 offset:57504
	v_pk_mul_f32 v[74:75], v[74:75], v[86:87]
	v_lshlrev_b32_e32 v86, 16, v157
	s_waitcnt lgkmcnt(2)
	v_mfma_f32_16x16x32_bf16 v[10:13], v[88:91], v[150:153], v[10:13]
	v_mul_f32_e32 v87, 0xbfb8aa3b, v86
	v_cvt_pk_bf16_f32 v108, v108, v109
	v_cvt_pk_bf16_f32 v109, v170, v171
	v_mfma_f32_16x16x32_bf16 v[18:21], v[88:91], v[158:161], v[18:21]
	v_exp_f32_e32 v89, v101
	v_add_f32_e32 v88, 1.0, v100
	v_rcp_f32_e32 v88, v88
	global_store_dwordx2 v[172:173], v[108:109], off
	v_add_f32_e32 v89, 1.0, v89
	v_rcp_f32_e32 v89, v89
	v_mfma_f32_16x16x32_bf16 v[14:17], v[104:107], v[92:95], v[14:17]
	v_mul_f32_e64 v82, v82, v0
	v_mul_f32_e64 v83, v83, v0
	v_pk_mul_f32 v[78:79], v[78:79], v[0:1] op_sel_hi:[1,0]
	v_pk_mul_f32 v[80:81], v[88:89], v[80:81]
	v_exp_f32_e32 v88, v87
	v_pk_mul_f32 v[80:81], v[80:81], v[74:75]
	v_and_b32_e32 v87, 0xffff0000, v157
	v_mfma_f32_16x16x32_bf16 v[26:29], v[104:107], v[96:99], v[26:29]
	v_add_f32_e32 v74, 1.0, v88
	v_rcp_f32_e32 v88, v74
	v_mul_f32_e32 v74, 0xbfb8aa3b, v87
	v_exp_f32_e32 v89, v74
	v_pk_mul_f32 v[74:75], v[84:85], v[0:1] op_sel_hi:[1,0]
	v_mfma_f32_16x16x32_bf16 v[38:41], v[140:143], v[92:95], v[38:41]
	v_mul_f32_e64 v108, v76, v74
	v_mul_f32_e64 v109, v77, v75
	v_add_f32_e32 v74, 1.0, v89
	v_rcp_f32_e32 v89, v74
	ds_read_b64_tr_b16 v[74:75], v217 offset:56448
	ds_read_b64_tr_b16 v[76:77], v217 offset:57536
	v_mfma_f32_16x16x32_bf16 v[50:53], v[140:143], v[96:99], v[50:53]
	v_cvt_pk_bf16_f32 v80, v80, v81
	v_pk_mul_f32 v[140:141], v[88:89], v[86:87]
	ds_read_b64_tr_b16 v[84:85], v217 offset:56480
	ds_read_b64_tr_b16 v[88:89], v217 offset:56512
	ds_read_b64_tr_b16 v[100:101], v217 offset:56544
	ds_read_b64_tr_b16 v[86:87], v217 offset:57568
	ds_read_b64_tr_b16 v[90:91], v217 offset:57600
	ds_read_b64_tr_b16 v[102:103], v217 offset:57632
	ds_read_b64_tr_b16 v[104:105], v217 offset:65152
	ds_read_b64_tr_b16 v[106:107], v218 offset:57536
	s_waitcnt lgkmcnt(8)
	v_mfma_f32_16x16x32_bf16 v[22:25], v[74:77], v[92:95], v[22:25]
	v_mul_f32_e64 v108, v140, v108
	v_mul_f32_e64 v109, v141, v109
	v_pk_mul_f32 v[70:71], v[70:71], v[82:83]
	v_cvt_pk_bf16_f32 v81, v108, v109
	v_mfma_f32_16x16x32_bf16 v[34:37], v[74:77], v[96:99], v[34:37]
	v_lshl_add_u64 v[108:109], s[54:55], 0, v[130:131]
	v_pk_mul_f32 v[72:73], v[72:73], v[78:79]
	v_lshl_add_u32 v0, s68, 9, v182
	v_mfma_f32_16x16x32_bf16 v[30:33], v[146:149], v[150:153], v[30:33]
	s_sub_i32 s52, s52, 64
	v_mfma_f32_16x16x32_bf16 v[6:9], v[146:149], v[158:161], v[6:9]
	ds_read_b64_tr_b16 v[74:75], v217 offset:65184
	ds_read_b64_tr_b16 v[140:141], v217 offset:65216
	ds_read_b64_tr_b16 v[146:147], v217 offset:65248
	ds_read_b64_tr_b16 v[76:77], v218 offset:57568
	ds_read_b64_tr_b16 v[142:143], v218 offset:57600
	ds_read_b64_tr_b16 v[148:149], v218 offset:57632
	global_store_dwordx2 v[108:109], v[80:81], off
	v_lshlrev_b32_e32 v80, 16, v144
	v_and_b32_e32 v81, 0xffff0000, v144
	s_waitcnt lgkmcnt(6)
	v_mfma_f32_16x16x32_bf16 v[22:25], v[104:107], v[150:153], v[22:25]
	v_mfma_f32_16x16x32_bf16 v[34:37], v[104:107], v[158:161], v[34:37]
	v_mul_f32_e32 v104, 0xbfb8aa3b, v80
	v_mul_f32_e32 v105, 0xbfb8aa3b, v81
	v_exp_f32_e32 v104, v104
	v_mfma_f32_16x16x32_bf16 v[42:45], v[84:87], v[92:95], v[42:45]
	v_mfma_f32_16x16x32_bf16 v[54:57], v[84:87], v[96:99], v[54:57]
	v_exp_f32_e32 v85, v105
	v_add_f32_e32 v84, 1.0, v104
	v_rcp_f32_e32 v84, v84
	s_waitcnt lgkmcnt(2)
	v_mfma_f32_16x16x32_bf16 v[42:45], v[74:77], v[150:153], v[42:45]
	v_add_f32_e32 v85, 1.0, v85
	v_rcp_f32_e32 v85, v85
	v_mfma_f32_16x16x32_bf16 v[54:57], v[74:77], v[158:161], v[54:57]
	v_mul_f32_e64 v74, v84, v80
	v_mul_f32_e64 v75, v85, v81
	v_pk_mul_f32 v[70:71], v[74:75], v[70:71]
	v_lshlrev_b32_e32 v74, 16, v145
	v_and_b32_e32 v75, 0xffff0000, v145
	v_mul_f32_e32 v76, 0xbfb8aa3b, v74
	v_mul_f32_e32 v77, 0xbfb8aa3b, v75
	v_exp_f32_e32 v76, v76
	v_exp_f32_e32 v77, v77
	v_cvt_pk_bf16_f32 v78, v70, v71
	v_lshl_add_u64 v[80:81], s[54:55], 0, v[132:133]
	v_add_f32_e32 v76, 1.0, v76
	v_add_f32_e32 v77, 1.0, v77
	v_rcp_f32_e32 v76, v76
	v_rcp_f32_e32 v77, v77
	v_mfma_f32_16x16x32_bf16 v[14:17], v[162:165], v[150:153], v[14:17]
	s_add_u32 s54, s54, 0xfffe0000
	s_addc_u32 s55, s55, -1
	v_pk_mul_f32 v[74:75], v[76:77], v[74:75]
	v_mfma_f32_16x16x32_bf16 v[26:29], v[162:165], v[158:161], v[26:29]
	v_mul_f32_e64 v74, v74, v72
	v_mul_f32_e64 v75, v75, v73
	ds_read_b128 v[70:73], v0 offset:4096
	v_cvt_pk_bf16_f32 v79, v74, v75
	ds_read_b128 v[74:77], v0 offset:4160
	global_store_dwordx2 v[80:81], v[78:79], off
	v_mfma_f32_16x16x32_bf16 v[38:41], v[166:169], v[150:153], v[38:41]
	s_waitcnt lgkmcnt(1)
	s_nop 0
	v_mov_b32_e32 v82, v70
	v_mov_b32_e32 v83, v71
	v_mov_b32_e32 v70, v72
	v_mov_b32_e32 v71, v73
	s_nop 0
	s_nop 0
	s_nop 0
	v_mfma_f32_16x16x32_bf16 v[50:53], v[166:169], v[158:161], v[50:53]
	s_add_u32 s56, s56, 0xfffe0000
	v_pk_mul_f32 v[32:33], v[32:33], v[70:71]
	v_pk_mul_f32 v[8:9], v[8:9], v[70:71]
	s_waitcnt lgkmcnt(0)
	v_mov_b32_e32 v70, v74
	v_mov_b32_e32 v71, v76
	v_mov_b32_e32 v78, v70
	v_mov_b32_e32 v70, v75
	v_mov_b32_e32 v80, v71
	s_nop 0
	v_mov_b32_e32 v81, v77
	v_mov_b32_e32 v79, v70
	ds_read_b128 v[70:73], v0 offset:4224
	ds_read_b128 v[74:77], v0 offset:4288
	v_pk_mul_f32 v[30:31], v[30:31], v[82:83]
	v_pk_mul_f32 v[6:7], v[6:7], v[82:83]
	v_pk_mul_f32 v[12:13], v[12:13], v[80:81]
	s_waitcnt lgkmcnt(1)
	s_nop 0
	v_mov_b32_e32 v82, v70
	v_mov_b32_e32 v83, v71
	v_mov_b32_e32 v70, v72
	v_mov_b32_e32 v71, v73
	s_nop 0
	s_nop 0
	v_pk_mul_f32 v[10:11], v[10:11], v[78:79]
	v_pk_mul_f32 v[20:21], v[20:21], v[80:81]
	v_pk_mul_f32 v[18:19], v[18:19], v[78:79]
	v_pk_mul_f32 v[16:17], v[16:17], v[70:71]
	v_pk_mul_f32 v[28:29], v[28:29], v[70:71]
	s_waitcnt lgkmcnt(0)
	v_mov_b32_e32 v70, v74
	v_mov_b32_e32 v71, v76
	v_mov_b32_e32 v78, v70
	v_mov_b32_e32 v70, v75
	v_mov_b32_e32 v80, v71
	s_nop 0
	v_mov_b32_e32 v81, v77
	v_mov_b32_e32 v79, v70
	ds_read_b128 v[70:73], v0 offset:4352
	ds_read_b128 v[74:77], v0 offset:4416
	s_nop 0
	v_pk_mul_f32 v[40:41], v[40:41], v[80:81]
	v_pk_mul_f32 v[38:39], v[38:39], v[78:79]
	s_waitcnt lgkmcnt(1)
	s_nop 0
	v_pk_mul_f32 v[14:15], v[14:15], v[82:83]
	v_pk_mul_f32 v[26:27], v[26:27], v[82:83]
	v_mov_b32_e32 v82, v70
	v_mov_b32_e32 v83, v71
	v_mov_b32_e32 v70, v72
	v_mov_b32_e32 v71, v73
	s_nop 0
	s_nop 0
	v_pk_mul_f32 v[52:53], v[52:53], v[80:81]
	v_pk_mul_f32 v[50:51], v[50:51], v[78:79]
	v_mfma_f32_16x16x32_bf16 v[46:49], v[88:91], v[92:95], v[46:49]
	v_mul_f32_e64 v24, v24, v70
	v_mul_f32_e64 v25, v25, v71
	v_pk_mul_f32 v[36:37], v[36:37], v[70:71]
	s_waitcnt lgkmcnt(0)
	v_mov_b32_e32 v70, v74
	v_mov_b32_e32 v71, v76
	v_mov_b32_e32 v78, v70
	v_mov_b32_e32 v70, v75
	v_mov_b32_e32 v80, v71
	s_nop 0
	v_mov_b32_e32 v81, v77
	v_mov_b32_e32 v79, v70
	ds_read_b128 v[70:73], v0 offset:4480
	ds_read_b128 v[74:77], v0 offset:4544
	v_mfma_f32_16x16x32_bf16 v[62:65], v[88:91], v[96:99], v[62:65]
	s_nop 0
	s_addc_u32 s57, s57, -1
	s_waitcnt lgkmcnt(1)
	s_nop 0
	v_mov_b32_e32 v70, v70
	v_mov_b32_e32 v0, v71
	v_mov_b32_e32 v71, v72
	v_mfma_f32_16x16x32_bf16 v[58:61], v[100:103], v[92:95], v[58:61]
	v_mov_b32_e32 v72, v71
	s_nop 0
	v_mov_b32_e32 v73, v73
	v_mfma_f32_16x16x32_bf16 v[66:69], v[100:103], v[96:99], v[66:69]
	v_mov_b32_e32 v71, v0
	s_waitcnt lgkmcnt(0)
	s_nop 0
	v_mov_b32_e32 v74, v74
	v_mov_b32_e32 v0, v75
	v_mov_b32_e32 v75, v76
	v_mov_b32_e32 v76, v75
	v_mov_b32_e32 v75, v77
	v_mfma_f32_16x16x32_bf16 v[46:49], v[140:143], v[150:153], v[46:49]
	v_mov_b32_e32 v77, v75
	v_mov_b32_e32 v75, v0
	v_pk_mul_f32 v[22:23], v[22:23], v[82:83]
	v_mfma_f32_16x16x32_bf16 v[62:65], v[140:143], v[158:161], v[62:65]
	v_mul_f32_e64 v34, v34, v82
	v_mul_f32_e64 v35, v35, v83
	v_pk_mul_f32 v[44:45], v[44:45], v[80:81]
	v_pk_mul_f32 v[42:43], v[42:43], v[78:79]
	v_mfma_f32_16x16x32_bf16 v[58:61], v[146:149], v[150:153], v[58:61]
	v_mul_f32_e64 v56, v56, v80
	v_mul_f32_e64 v57, v57, v81
	v_pk_mul_f32 v[54:55], v[54:55], v[78:79]
	v_pk_mul_f32 v[48:49], v[48:49], v[72:73]
	v_mfma_f32_16x16x32_bf16 v[66:69], v[146:149], v[158:161], v[66:69]
	v_mul_f32_e64 v46, v46, v70
	v_mul_f32_e64 v47, v47, v71
	v_pk_mul_f32 v[64:65], v[64:65], v[72:73]
	v_pk_mul_f32 v[62:63], v[62:63], v[70:71]
	v_pk_mul_f32 v[60:61], v[60:61], v[76:77]
	v_pk_mul_f32 v[58:59], v[58:59], v[74:75]
	s_nop 1
	v_pk_mul_f32 v[68:69], v[68:69], v[76:77]
	s_cmp_lg_u32 s74, 8
	v_pk_mul_f32 v[66:67], v[66:67], v[74:75]
	s_cbranch_scc0 .LBB0_2257
.LBB0_2283:
	s_add_u32 s60, s70, s58
	s_addc_u32 s61, s71, s59
	s_add_u32 s49, s64, s58
	s_addc_u32 s69, s65, s59
	s_add_u32 s53, s49, s0
	v_lshl_add_u64 v[70:71], s[60:61], 0, v[112:113]
	s_addc_u32 s61, s69, 0
	s_add_u32 s60, s53, 0xafc0800
	v_add_co_u32_e32 v74, vcc, s72, v70
	s_addc_u32 s61, s61, 0
	s_nop 0
	v_addc_co_u32_e32 v75, vcc, 0, v71, vcc
	v_lshl_add_u64 v[86:87], s[60:61], 0, v[114:115]
	v_add_co_u32_e32 v78, vcc, s81, v86
	s_and_b32 s68, s74, 1
	s_nop 0
	v_addc_co_u32_e32 v79, vcc, 0, v87, vcc
	s_cmp_eq_u32 s68, 0
	v_add_co_u32_e32 v82, vcc, s72, v86
	s_cselect_b64 s[60:61], -1, 0
	s_nop 0
	v_addc_co_u32_e32 v83, vcc, 0, v87, vcc
	s_and_b64 s[62:63], s[60:61], exec
	global_load_dwordx4 v[94:97], v[70:71], off
	global_load_dwordx4 v[98:101], v[70:71], off offset:1024
	s_nop 0
	global_load_dwordx4 v[70:73], v[74:75], off
	global_load_dwordx4 v[90:93], v[74:75], off offset:1024
	s_cselect_b32 s53, 0xf0, s89
	global_load_dwordx4 v[74:77], v[86:87], off
	v_add_co_u32_e32 v86, vcc, s73, v86
	v_add3_u32 v105, s53, v180, v116
	s_nop 0
	v_addc_co_u32_e32 v87, vcc, 0, v87, vcc
	global_load_dwordx4 v[78:81], v[78:79], off
	s_nop 0
	global_load_dwordx4 v[82:85], v[82:83], off
	s_nop 0
	global_load_dwordx4 v[86:89], v[86:87], off
	ds_read2_b32 v[102:103], v105 offset1:4
	ds_read2_b32 v[140:141], v105 offset0:8 offset1:12
	s_waitcnt vmcnt(12) lgkmcnt(1)
	v_mfma_f32_16x16x4_f32 v[106:109], v102, v223, 0
	ds_read2_b32 v[144:145], v105 offset0:128 offset1:132
	s_waitcnt vmcnt(11)
	v_mfma_f32_16x16x4_f32 v[106:109], v103, v224, v[106:109]
	s_waitcnt vmcnt(10) lgkmcnt(1)
	v_mfma_f32_16x16x4_f32 v[106:109], v140, v225, v[106:109]
	s_waitcnt vmcnt(9)
	v_mfma_f32_16x16x4_f32 v[106:109], v141, v226, v[106:109]
	ds_read2_b32 v[140:141], v105 offset0:64 offset1:68
	s_waitcnt vmcnt(8)
	s_nop 7
	v_add_f32_e32 v102, v227, v106
	v_min_f32_e32 v0, 0, v102
	v_mul_f32_e64 v102, |v102|, s66
	v_exp_f32_e32 v102, v102
	v_add_f32_e32 v103, v227, v107
	v_add_f32_e32 v104, v227, v108
	v_add_f32_e32 v106, v227, v109
	v_add_f32_e32 v102, 1.0, v102
	v_log_f32_e32 v102, v102
	s_nop 0
	v_fmac_f32_e32 v0, 0xbf317218, v102
	v_min_f32_e32 v102, 0, v103
	v_mul_f32_e64 v103, |v103|, s66
	v_exp_f32_e32 v103, v103
	s_nop 0
	v_add_f32_e32 v103, 1.0, v103
	v_log_f32_e32 v103, v103
	s_nop 0
	v_fmac_f32_e32 v102, 0xbf317218, v103
	v_min_f32_e32 v103, 0, v104
	v_mul_f32_e64 v104, |v104|, s66
	v_exp_f32_e32 v104, v104
	s_nop 0
	v_add_f32_e32 v104, 1.0, v104
	v_log_f32_e32 v104, v104
	s_nop 0
	v_fmac_f32_e32 v103, 0xbf317218, v104
	v_min_f32_e32 v104, 0, v106
	v_mul_f32_e64 v106, |v106|, s66
	v_exp_f32_e32 v106, v106
	s_nop 0
	v_add_f32_e32 v106, 1.0, v106
	v_log_f32_e32 v106, v106
	s_nop 0
	v_fmac_f32_e32 v104, 0xbf317218, v106
	s_waitcnt lgkmcnt(0)
	v_mfma_f32_16x16x4_f32 v[106:109], v140, v223, 0
	v_mfma_f32_16x16x4_f32 v[106:109], v141, v224, v[106:109]
	ds_read2_b32 v[140:141], v105 offset0:72 offset1:76
	s_waitcnt lgkmcnt(0)
	v_mfma_f32_16x16x4_f32 v[106:109], v140, v225, v[106:109]
	v_mfma_f32_16x16x4_f32 v[106:109], v141, v226, v[106:109]
	v_mfma_f32_16x16x4_f32 v[140:143], v144, v223, 0
	s_nop 8
	v_add_f32_e32 v135, v227, v106
	v_min_f32_e32 v106, 0, v135
	v_mul_f32_e64 v135, |v135|, s66
	v_exp_f32_e32 v135, v135
	s_nop 0
	v_add_f32_e32 v135, 1.0, v135
	v_log_f32_e32 v135, v135
	v_mfma_f32_16x16x4_f32 v[140:143], v145, v224, v[140:143]
	ds_read2_b32 v[144:145], v105 offset0:136 offset1:140
	v_fmac_f32_e32 v106, 0xbf317218, v135
	v_add_f32_e32 v135, v227, v107
	v_min_f32_e32 v107, 0, v135
	v_mul_f32_e64 v135, |v135|, s66
	v_exp_f32_e32 v135, v135
	s_waitcnt lgkmcnt(0)
	v_mfma_f32_16x16x4_f32 v[140:143], v144, v225, v[140:143]
	v_add_f32_e32 v135, 1.0, v135
	v_log_f32_e32 v135, v135
	s_nop 0
	v_fmac_f32_e32 v107, 0xbf317218, v135
	v_add_f32_e32 v135, v227, v108
	v_min_f32_e32 v108, 0, v135
	v_mul_f32_e64 v135, |v135|, s66
	v_exp_f32_e32 v135, v135
	v_mfma_f32_16x16x4_f32 v[140:143], v145, v226, v[140:143]
	ds_read2_b32 v[144:145], v105 offset0:192 offset1:196
	v_add_f32_e32 v135, 1.0, v135
	v_log_f32_e32 v135, v135
	s_nop 0
	v_fmac_f32_e32 v108, 0xbf317218, v135
	v_add_f32_e32 v135, v227, v109
	v_min_f32_e32 v109, 0, v135
	v_mul_f32_e64 v135, |v135|, s66
	v_exp_f32_e32 v135, v135
	s_nop 0
	v_add_f32_e32 v135, 1.0, v135
	v_log_f32_e32 v135, v135
	s_nop 0
	v_fmac_f32_e32 v109, 0xbf317218, v135
	v_add_f32_e32 v135, v227, v140
	v_min_f32_e32 v137, 0, v135
	v_mul_f32_e64 v135, |v135|, s66
	v_exp_f32_e32 v135, v135
	s_nop 0
	v_add_f32_e32 v135, 1.0, v135
	v_log_f32_e32 v135, v135
	s_nop 0
	v_fmac_f32_e32 v137, 0xbf317218, v135
	v_add_f32_e32 v135, v227, v141
	v_min_f32_e32 v146, 0, v135
	v_mul_f32_e64 v135, |v135|, s66
	v_exp_f32_e32 v135, v135
	s_nop 0
	v_add_f32_e32 v135, 1.0, v135
	v_log_f32_e32 v135, v135
	s_nop 0
	v_fmac_f32_e32 v146, 0xbf317218, v135
	v_add_f32_e32 v135, v227, v142
	v_min_f32_e32 v147, 0, v135
	v_mul_f32_e64 v135, |v135|, s66
	v_exp_f32_e32 v135, v135
	s_nop 0
	v_add_f32_e32 v135, 1.0, v135
	v_log_f32_e32 v135, v135
	s_nop 0
	v_fmac_f32_e32 v147, 0xbf317218, v135
	v_add_f32_e32 v135, v227, v143
	s_waitcnt lgkmcnt(0)
	v_mfma_f32_16x16x4_f32 v[140:143], v144, v223, 0
	v_min_f32_e32 v148, 0, v135
	v_mul_f32_e64 v135, |v135|, s66
	v_exp_f32_e32 v135, v135
	s_nop 0
	v_add_f32_e32 v135, 1.0, v135
	v_mfma_f32_16x16x4_f32 v[140:143], v145, v224, v[140:143]
	ds_read2_b32 v[144:145], v105 offset0:200 offset1:204
	v_log_f32_e32 v135, v135
	s_nop 0
	v_fmac_f32_e32 v148, 0xbf317218, v135
	s_waitcnt lgkmcnt(0)
	v_mfma_f32_16x16x4_f32 v[140:143], v144, v225, v[140:143]
	v_mfma_f32_16x16x4_f32 v[140:143], v145, v226, v[140:143]
	s_nop 9
	v_add_f32_e32 v105, v227, v140
	v_min_f32_e32 v135, 0, v105
	v_mul_f32_e64 v105, |v105|, s66
	v_exp_f32_e32 v105, v105
	s_nop 0
	v_add_f32_e32 v105, 1.0, v105
	v_log_f32_e32 v105, v105
	s_nop 0
	v_fmac_f32_e32 v135, 0xbf317218, v105
	v_add_f32_e32 v105, v227, v141
	v_min_f32_e32 v140, 0, v105
	v_mul_f32_e64 v105, |v105|, s66
	v_exp_f32_e32 v105, v105
	s_nop 0
	v_add_f32_e32 v105, 1.0, v105
	v_log_f32_e32 v105, v105
	s_nop 0
	v_fmac_f32_e32 v140, 0xbf317218, v105
	v_add_f32_e32 v105, v227, v142
	v_min_f32_e32 v141, 0, v105
	v_mul_f32_e64 v105, |v105|, s66
	v_exp_f32_e32 v105, v105
	s_nop 0
	v_add_f32_e32 v105, 1.0, v105
	v_log_f32_e32 v105, v105
	s_nop 0
	v_fmac_f32_e32 v141, 0xbf317218, v105
	v_add_f32_e32 v105, v227, v143
	v_min_f32_e32 v142, 0, v105
	v_mul_f32_e64 v105, |v105|, s66
	v_exp_f32_e32 v105, v105
	s_nop 0
	v_add_f32_e32 v105, 1.0, v105
	v_log_f32_e32 v105, v105
	s_nop 0
	v_fmac_f32_e32 v142, 0xbf317218, v105
	v_fma_f32 v105, v142, s67, 0
	v_fmamk_f32 v141, v141, 0x3d800000, v105
	v_fmamk_f32 v140, v140, 0x3d800000, v141
	v_fmamk_f32 v135, v135, 0x3d800000, v140
	v_fmamk_f32 v142, v148, 0x3d800000, v135
	v_fmamk_f32 v143, v147, 0x3d800000, v142
	v_fmamk_f32 v144, v146, 0x3d800000, v143
	v_fmamk_f32 v137, v137, 0x3d800000, v144
	v_fmamk_f32 v109, v109, 0x3d800000, v137
	v_fmamk_f32 v108, v108, 0x3d800000, v109
	v_fmamk_f32 v107, v107, 0x3d800000, v108
	v_fmamk_f32 v106, v106, 0x3d800000, v107
	v_fmamk_f32 v104, v104, 0x3d800000, v106
	v_fmamk_f32 v103, v103, 0x3d800000, v104
	v_fmamk_f32 v102, v102, 0x3d800000, v103
	v_fmamk_f32 v0, v0, 0x3d800000, v102
	ds_bpermute_b32 v146, v192, v0
	ds_bpermute_b32 v147, v193, v0
	ds_bpermute_b32 v145, v191, v0
	s_waitcnt lgkmcnt(2)
	v_cndmask_b32_e64 v146, 0, v146, s[28:29]
	s_waitcnt lgkmcnt(1)
	v_cndmask_b32_e64 v147, v147, 0, s[8:9]
	v_add_f32_e32 v146, v146, v147
	s_waitcnt lgkmcnt(0)
	v_cndmask_b32_e64 v145, 0, v145, s[4:5]
	v_add_f32_e32 v145, v145, v146
	v_add_f32_e32 v0, v145, v0
	v_add_f32_e32 v102, v145, v102
	ds_write2st64_b32 v204, v0, v102 offset0:24 offset1:26
	v_add_f32_e32 v0, v145, v103
	v_add_f32_e32 v102, v145, v104
	ds_write2st64_b32 v204, v0, v102 offset0:28 offset1:30
	v_add_f32_e32 v0, v145, v106
	v_add_f32_e32 v102, v145, v107
	ds_write2st64_b32 v204, v0, v102 offset0:32 offset1:34
	v_add_f32_e32 v0, v145, v108
	v_add_f32_e32 v102, v145, v109
	ds_write2st64_b32 v204, v0, v102 offset0:36 offset1:38
	v_add_f32_e32 v0, v145, v137
	v_add_f32_e32 v102, v145, v144
	ds_write2st64_b32 v204, v0, v102 offset0:40 offset1:42
	v_add_f32_e32 v0, v145, v143
	v_add_f32_e32 v102, v145, v142
	ds_write2st64_b32 v204, v0, v102 offset0:44 offset1:46
	v_add_f32_e32 v0, v145, v135
	v_add_f32_e32 v102, v145, v140
	ds_write2st64_b32 v204, v0, v102 offset0:48 offset1:50
	v_add_f32_e32 v0, v145, v141
	v_add_f32_e32 v102, v145, v105
	ds_write2st64_b32 v204, v0, v102 offset0:52 offset1:54
	s_waitcnt lgkmcnt(0)
	s_barrier
	s_and_saveexec_b64 s[62:63], s[10:11]
	s_cbranch_execz .LBB0_2285
	ds_read_b32 v0, v181 offset:6144
	v_lshl_add_u32 v102, s68, 9, v181
	s_waitcnt lgkmcnt(0)
	v_mul_f32_e32 v255, 0x3fb8aa3b, v0
	v_exp_f32_e32 v255, v255
	s_nop 0
	ds_write_b32 v102, v255 offset:4096
